# v15 + residual-add GEMM epilogues read 14/16 fp16 residual chunks from LDS, staged by the redirected re-stage DMAs of the peeled last K-loop iteration
# baseline (speedup 1.0000x reference)
.LBB0_995:
	ds_read_b128 v[146:149], v164
	ds_read_b128 v[150:153], v164 offset:1024
	ds_read_b128 v[154:157], v164 offset:2048
	ds_read_b128 v[158:161], v164 offset:3072
	ds_read_b128 v[168:171], v165
	ds_read_b128 v[172:175], v165 offset:1024
	ds_read_b128 v[176:179], v165 offset:2048
	ds_read_b128 v[180:183], v165 offset:3072
	s_add_u32 s34, s88, 0xfff80080
	s_addc_u32 s35, s89, -1
	s_cmp_eq_u32 s81, 28
	s_cselect_b32 s91, s0, s35
	s_cselect_b32 s90, s1, s34
	s_cselect_b32 s35, s52, s77
	s_cselect_b32 s34, s74, s75
	v_lshl_add_u64 v[218:219], s[88:89], 0, v[138:139]
	s_add_i32 m0, s33, 0xc000
	ds_read_b128 v[184:187], v166
	ds_read_b128 v[188:191], v166 offset:1024
	ds_read_b128 v[192:195], v166 offset:2048
	ds_read_b128 v[196:199], v166 offset:3072
	ds_read_b128 v[200:203], v166 offset:4096
	ds_read_b128 v[204:207], v166 offset:5120
	ds_read_b128 v[208:211], v166 offset:6144
	ds_read_b128 v[212:215], v166 offset:7168
	global_load_lds_dwordx4 v[218:219], off
	v_lshl_add_u64 v[218:219], s[88:89], 0, v[140:141]
	s_add_i32 m0, s33, 0xe000
	s_nop 0
	global_load_lds_dwordx4 v[218:219], off
	s_waitcnt vmcnt(8)
	s_waitcnt lgkmcnt(0)
	s_barrier
	s_setprio 1
	s_waitcnt lgkmcnt(0)
	v_mfma_f32_16x16x32_bf16 v[126:129], v[146:149], v[184:187], v[126:129]
	v_mfma_f32_16x16x32_bf16 v[122:125], v[154:157], v[184:187], v[122:125]
	v_mfma_f32_16x16x32_bf16 v[110:113], v[146:149], v[192:195], v[110:113]
	v_mfma_f32_16x16x32_bf16 v[106:109], v[154:157], v[192:195], v[106:109]
	v_mfma_f32_16x16x32_bf16 v[94:97], v[146:149], v[200:203], v[94:97]
	v_mfma_f32_16x16x32_bf16 v[90:93], v[154:157], v[200:203], v[90:93]
	v_mfma_f32_16x16x32_bf16 v[78:81], v[146:149], v[208:211], v[78:81]
	v_mfma_f32_16x16x32_bf16 v[74:77], v[154:157], v[208:211], v[74:77]
	v_mfma_f32_16x16x32_bf16 v[126:129], v[150:153], v[188:191], v[126:129]
	v_mfma_f32_16x16x32_bf16 v[122:125], v[158:161], v[188:191], v[122:125]
	v_mfma_f32_16x16x32_bf16 v[110:113], v[150:153], v[196:199], v[110:113]
	v_mfma_f32_16x16x32_bf16 v[106:109], v[158:161], v[196:199], v[106:109]
	v_mfma_f32_16x16x32_bf16 v[94:97], v[150:153], v[204:207], v[94:97]
	v_mfma_f32_16x16x32_bf16 v[90:93], v[158:161], v[204:207], v[90:93]
	v_mfma_f32_16x16x32_bf16 v[78:81], v[150:153], v[212:215], v[78:81]
	v_mfma_f32_16x16x32_bf16 v[74:77], v[158:161], v[212:215], v[74:77]
	s_setprio 0
	s_setprio 1
	v_mfma_f32_16x16x32_bf16 v[118:121], v[168:171], v[184:187], v[118:121]
	v_mfma_f32_16x16x32_bf16 v[114:117], v[176:179], v[184:187], v[114:117]
	v_mfma_f32_16x16x32_bf16 v[102:105], v[168:171], v[192:195], v[102:105]
	v_mfma_f32_16x16x32_bf16 v[98:101], v[176:179], v[192:195], v[98:101]
	v_mfma_f32_16x16x32_bf16 v[86:89], v[168:171], v[200:203], v[86:89]
	v_mfma_f32_16x16x32_bf16 v[82:85], v[176:179], v[200:203], v[82:85]
	v_mfma_f32_16x16x32_bf16 v[70:73], v[168:171], v[208:211], v[70:73]
	v_mfma_f32_16x16x32_bf16 v[66:69], v[176:179], v[208:211], v[66:69]
	v_mfma_f32_16x16x32_bf16 v[118:121], v[172:175], v[188:191], v[118:121]
	v_mfma_f32_16x16x32_bf16 v[114:117], v[180:183], v[188:191], v[114:117]
	v_mfma_f32_16x16x32_bf16 v[102:105], v[172:175], v[196:199], v[102:105]
	v_mfma_f32_16x16x32_bf16 v[98:101], v[180:183], v[196:199], v[98:101]
	v_mfma_f32_16x16x32_bf16 v[86:89], v[172:175], v[204:207], v[86:89]
	v_mfma_f32_16x16x32_bf16 v[82:85], v[180:183], v[204:207], v[82:85]
	v_mfma_f32_16x16x32_bf16 v[70:73], v[172:175], v[212:215], v[70:73]
	v_mfma_f32_16x16x32_bf16 v[66:69], v[180:183], v[212:215], v[66:69]
	s_setprio 0
	s_barrier
	s_add_i32 s53, s71, s31
	v_lshl_add_u64 v[218:219], s[34:35], 0, v[132:133]
	s_mov_b32 m0, s53
	ds_read_b128 v[184:187], v166 offset:16384
	ds_read_b128 v[188:191], v166 offset:17408
	ds_read_b128 v[192:195], v166 offset:18432
	ds_read_b128 v[196:199], v166 offset:19456
	ds_read_b128 v[200:203], v166 offset:20480
	ds_read_b128 v[204:207], v166 offset:21504
	ds_read_b128 v[208:211], v166 offset:22528
	ds_read_b128 v[212:215], v166 offset:23552
	global_load_lds_dwordx4 v[218:219], off
	s_add_i32 m0, s53, 0x2000
	s_add_u32 s54, s34, 0x80000
	v_lshl_add_u64 v[220:221], s[34:35], 0, v[136:137]
	s_addc_u32 s55, s35, 0
	s_add_i32 s53, s72, s31
	global_load_lds_dwordx4 v[220:221], off
	v_lshl_add_u64 v[222:223], s[54:55], 0, v[132:133]
	s_mov_b32 m0, s53
	v_lshl_add_u64 v[224:225], s[90:91], 0, v[134:135]
	global_load_lds_dwordx4 v[222:223], off
	v_lshl_add_u64 v[222:223], s[54:55], 0, v[136:137]
	s_add_i32 m0, s53, 0x2000
	s_nop 0
	global_load_lds_dwordx4 v[222:223], off
	v_lshl_add_u64 v[222:223], s[90:91], 0, v[130:131]
	s_mov_b32 m0, s33
	s_nop 0
	global_load_lds_dwordx4 v[222:223], off
	s_mov_b32 m0, s56
	s_nop 0
	global_load_lds_dwordx4 v[224:225], off
	s_waitcnt vmcnt(8)
	s_waitcnt lgkmcnt(0)
	s_barrier
	s_setprio 1
	s_waitcnt lgkmcnt(0)
	v_mfma_f32_16x16x32_bf16 v[62:65], v[146:149], v[184:187], v[62:65]
	v_mfma_f32_16x16x32_bf16 v[58:61], v[154:157], v[184:187], v[58:61]
	v_mfma_f32_16x16x32_bf16 v[46:49], v[146:149], v[192:195], v[46:49]
	v_mfma_f32_16x16x32_bf16 v[42:45], v[154:157], v[192:195], v[42:45]
	v_mfma_f32_16x16x32_bf16 v[30:33], v[146:149], v[200:203], v[30:33]
	v_mfma_f32_16x16x32_bf16 v[26:29], v[154:157], v[200:203], v[26:29]
	v_mfma_f32_16x16x32_bf16 v[14:17], v[146:149], v[208:211], v[14:17]
	v_mfma_f32_16x16x32_bf16 v[10:13], v[154:157], v[208:211], v[10:13]
	v_mfma_f32_16x16x32_bf16 v[62:65], v[150:153], v[188:191], v[62:65]
	v_mfma_f32_16x16x32_bf16 v[58:61], v[158:161], v[188:191], v[58:61]
	v_mfma_f32_16x16x32_bf16 v[46:49], v[150:153], v[196:199], v[46:49]
	v_mfma_f32_16x16x32_bf16 v[42:45], v[158:161], v[196:199], v[42:45]
	v_mfma_f32_16x16x32_bf16 v[30:33], v[150:153], v[204:207], v[30:33]
	v_mfma_f32_16x16x32_bf16 v[26:29], v[158:161], v[204:207], v[26:29]
	v_mfma_f32_16x16x32_bf16 v[14:17], v[150:153], v[212:215], v[14:17]
	v_mfma_f32_16x16x32_bf16 v[10:13], v[158:161], v[212:215], v[10:13]
	s_setprio 0
	s_setprio 1
	v_mfma_f32_16x16x32_bf16 v[54:57], v[168:171], v[184:187], v[54:57]
	v_mfma_f32_16x16x32_bf16 v[50:53], v[176:179], v[184:187], v[50:53]
	v_mfma_f32_16x16x32_bf16 v[38:41], v[168:171], v[192:195], v[38:41]
	v_mfma_f32_16x16x32_bf16 v[34:37], v[176:179], v[192:195], v[34:37]
	v_mfma_f32_16x16x32_bf16 v[22:25], v[168:171], v[200:203], v[22:25]
	v_mfma_f32_16x16x32_bf16 v[18:21], v[176:179], v[200:203], v[18:21]
	v_mfma_f32_16x16x32_bf16 v[6:9], v[168:171], v[208:211], v[6:9]
	v_mfma_f32_16x16x32_bf16 v[2:5], v[176:179], v[208:211], v[2:5]
	v_mfma_f32_16x16x32_bf16 v[54:57], v[172:175], v[188:191], v[54:57]
	v_mfma_f32_16x16x32_bf16 v[50:53], v[180:183], v[188:191], v[50:53]
	v_mfma_f32_16x16x32_bf16 v[38:41], v[172:175], v[196:199], v[38:41]
	v_mfma_f32_16x16x32_bf16 v[34:37], v[180:183], v[196:199], v[34:37]
	v_mfma_f32_16x16x32_bf16 v[22:25], v[172:175], v[204:207], v[22:25]
	v_mfma_f32_16x16x32_bf16 v[18:21], v[180:183], v[204:207], v[18:21]
	v_mfma_f32_16x16x32_bf16 v[6:9], v[172:175], v[212:215], v[6:9]
	v_mfma_f32_16x16x32_bf16 v[2:5], v[180:183], v[212:215], v[2:5]
	s_setprio 0
	s_barrier
	s_add_i32 s53, 0, 0x18000
	s_add_i32 s62, 0, 0x1c000
	v_add_u32_e32 v158, s53, v162
	v_add_u32_e32 v167, s62, v162
	ds_read_b128 v[146:149], v158
	ds_read_b128 v[150:153], v158 offset:1024
	ds_read_b128 v[154:157], v158 offset:2048
	ds_read_b128 v[158:161], v158 offset:3072
	ds_read_b128 v[168:171], v167
	ds_read_b128 v[172:175], v167 offset:1024
	ds_read_b128 v[176:179], v167 offset:2048
	ds_read_b128 v[180:183], v167 offset:3072
	s_add_u32 s54, s90, 0x80000
	s_addc_u32 s55, s91, 0
	s_mov_b32 m0, s57
	v_lshl_add_u64 v[226:227], s[54:55], 0, v[130:131]
	ds_read_b128 v[184:187], v166 offset:32768
	ds_read_b128 v[188:191], v166 offset:33792
	ds_read_b128 v[192:195], v166 offset:34816
	ds_read_b128 v[196:199], v166 offset:35840
	ds_read_b128 v[200:203], v166 offset:36864
	ds_read_b128 v[204:207], v166 offset:37888
	ds_read_b128 v[208:211], v166 offset:38912
	ds_read_b128 v[212:215], v166 offset:39936
	global_load_lds_dwordx4 v[226:227], off
	v_lshl_add_u64 v[226:227], s[54:55], 0, v[134:135]
	s_mov_b32 m0, s58
	s_nop 0
	global_load_lds_dwordx4 v[226:227], off
	s_waitcnt vmcnt(8)
	s_waitcnt lgkmcnt(0)
	s_barrier
	s_setprio 1
	s_waitcnt lgkmcnt(0)
	v_mfma_f32_16x16x32_bf16 v[126:129], v[146:149], v[184:187], v[126:129]
	v_mfma_f32_16x16x32_bf16 v[122:125], v[154:157], v[184:187], v[122:125]
	v_mfma_f32_16x16x32_bf16 v[110:113], v[146:149], v[192:195], v[110:113]
	v_mfma_f32_16x16x32_bf16 v[106:109], v[154:157], v[192:195], v[106:109]
	v_mfma_f32_16x16x32_bf16 v[94:97], v[146:149], v[200:203], v[94:97]
	v_mfma_f32_16x16x32_bf16 v[90:93], v[154:157], v[200:203], v[90:93]
	v_mfma_f32_16x16x32_bf16 v[78:81], v[146:149], v[208:211], v[78:81]
	v_mfma_f32_16x16x32_bf16 v[74:77], v[154:157], v[208:211], v[74:77]
	v_mfma_f32_16x16x32_bf16 v[126:129], v[150:153], v[188:191], v[126:129]
	v_mfma_f32_16x16x32_bf16 v[122:125], v[158:161], v[188:191], v[122:125]
	v_mfma_f32_16x16x32_bf16 v[110:113], v[150:153], v[196:199], v[110:113]
	v_mfma_f32_16x16x32_bf16 v[106:109], v[158:161], v[196:199], v[106:109]
	v_mfma_f32_16x16x32_bf16 v[94:97], v[150:153], v[204:207], v[94:97]
	v_mfma_f32_16x16x32_bf16 v[90:93], v[158:161], v[204:207], v[90:93]
	v_mfma_f32_16x16x32_bf16 v[78:81], v[150:153], v[212:215], v[78:81]
	v_mfma_f32_16x16x32_bf16 v[74:77], v[158:161], v[212:215], v[74:77]
	s_setprio 0
	s_setprio 1
	v_mfma_f32_16x16x32_bf16 v[118:121], v[168:171], v[184:187], v[118:121]
	v_mfma_f32_16x16x32_bf16 v[114:117], v[176:179], v[184:187], v[114:117]
	v_mfma_f32_16x16x32_bf16 v[102:105], v[168:171], v[192:195], v[102:105]
	v_mfma_f32_16x16x32_bf16 v[98:101], v[176:179], v[192:195], v[98:101]
	v_mfma_f32_16x16x32_bf16 v[86:89], v[168:171], v[200:203], v[86:89]
	v_mfma_f32_16x16x32_bf16 v[82:85], v[176:179], v[200:203], v[82:85]
	v_mfma_f32_16x16x32_bf16 v[70:73], v[168:171], v[208:211], v[70:73]
	v_mfma_f32_16x16x32_bf16 v[66:69], v[176:179], v[208:211], v[66:69]
	v_mfma_f32_16x16x32_bf16 v[118:121], v[172:175], v[188:191], v[118:121]
	v_mfma_f32_16x16x32_bf16 v[114:117], v[180:183], v[188:191], v[114:117]
	v_mfma_f32_16x16x32_bf16 v[102:105], v[172:175], v[196:199], v[102:105]
	v_mfma_f32_16x16x32_bf16 v[98:101], v[180:183], v[196:199], v[98:101]
	v_mfma_f32_16x16x32_bf16 v[86:89], v[172:175], v[204:207], v[86:89]
	v_mfma_f32_16x16x32_bf16 v[82:85], v[180:183], v[204:207], v[82:85]
	v_mfma_f32_16x16x32_bf16 v[70:73], v[172:175], v[212:215], v[70:73]
	v_mfma_f32_16x16x32_bf16 v[66:69], v[180:183], v[212:215], v[66:69]
	s_setprio 0
	s_barrier
	s_add_i32 s53, s53, s31
	v_lshl_add_u64 v[218:219], v[218:219], 0, s[8:9]
	s_mov_b32 m0, s53
	ds_read_b128 v[184:187], v166 offset:49152
	ds_read_b128 v[188:191], v166 offset:50176
	ds_read_b128 v[192:195], v166 offset:51200
	ds_read_b128 v[196:199], v166 offset:52224
	ds_read_b128 v[200:203], v166 offset:53248
	ds_read_b128 v[204:207], v166 offset:54272
	ds_read_b128 v[208:211], v166 offset:55296
	ds_read_b128 v[212:215], v166 offset:56320
	global_load_lds_dwordx4 v[218:219], off
	s_add_i32 m0, s53, 0x2000
	s_add_u32 s34, s34, 0x80080
	v_lshl_add_u64 v[218:219], v[220:221], 0, s[8:9]
	s_addc_u32 s35, s35, 0
	s_add_i32 s53, s62, s31
	global_load_lds_dwordx4 v[218:219], off
	v_lshl_add_u64 v[218:219], s[34:35], 0, v[132:133]
	s_mov_b32 m0, s53
	s_nop 0
	global_load_lds_dwordx4 v[218:219], off
	v_lshl_add_u64 v[218:219], s[34:35], 0, v[136:137]
	s_add_i32 m0, s53, 0x2000
	s_nop 0
	global_load_lds_dwordx4 v[218:219], off
	v_lshl_add_u64 v[218:219], v[222:223], 0, s[8:9]
	s_mov_b32 m0, s60
	s_nop 0
	global_load_lds_dwordx4 v[218:219], off
	v_lshl_add_u64 v[218:219], v[224:225], 0, s[8:9]
	s_mov_b32 m0, s61
	s_nop 0
	global_load_lds_dwordx4 v[218:219], off
	s_waitcnt vmcnt(8)
	s_waitcnt lgkmcnt(0)
	s_barrier
	s_setprio 1
	s_waitcnt lgkmcnt(0)
	v_mfma_f32_16x16x32_bf16 v[62:65], v[146:149], v[184:187], v[62:65]
	v_mfma_f32_16x16x32_bf16 v[58:61], v[154:157], v[184:187], v[58:61]
	v_mfma_f32_16x16x32_bf16 v[46:49], v[146:149], v[192:195], v[46:49]
	v_mfma_f32_16x16x32_bf16 v[42:45], v[154:157], v[192:195], v[42:45]
	v_mfma_f32_16x16x32_bf16 v[30:33], v[146:149], v[200:203], v[30:33]
	v_mfma_f32_16x16x32_bf16 v[26:29], v[154:157], v[200:203], v[26:29]
	v_mfma_f32_16x16x32_bf16 v[14:17], v[146:149], v[208:211], v[14:17]
	v_mfma_f32_16x16x32_bf16 v[10:13], v[154:157], v[208:211], v[10:13]
	v_mfma_f32_16x16x32_bf16 v[62:65], v[150:153], v[188:191], v[62:65]
	v_mfma_f32_16x16x32_bf16 v[58:61], v[158:161], v[188:191], v[58:61]
	v_mfma_f32_16x16x32_bf16 v[46:49], v[150:153], v[196:199], v[46:49]
	v_mfma_f32_16x16x32_bf16 v[42:45], v[158:161], v[196:199], v[42:45]
	v_mfma_f32_16x16x32_bf16 v[30:33], v[150:153], v[204:207], v[30:33]
	v_mfma_f32_16x16x32_bf16 v[26:29], v[158:161], v[204:207], v[26:29]
	v_mfma_f32_16x16x32_bf16 v[14:17], v[150:153], v[212:215], v[14:17]
	v_mfma_f32_16x16x32_bf16 v[10:13], v[158:161], v[212:215], v[10:13]
	s_setprio 0
	s_setprio 1
	v_mfma_f32_16x16x32_bf16 v[54:57], v[168:171], v[184:187], v[54:57]
	v_mfma_f32_16x16x32_bf16 v[50:53], v[176:179], v[184:187], v[50:53]
	v_mfma_f32_16x16x32_bf16 v[38:41], v[168:171], v[192:195], v[38:41]
	v_mfma_f32_16x16x32_bf16 v[34:37], v[176:179], v[192:195], v[34:37]
	v_mfma_f32_16x16x32_bf16 v[22:25], v[168:171], v[200:203], v[22:25]
	v_mfma_f32_16x16x32_bf16 v[18:21], v[176:179], v[200:203], v[18:21]
	v_mfma_f32_16x16x32_bf16 v[6:9], v[168:171], v[208:211], v[6:9]
	v_mfma_f32_16x16x32_bf16 v[2:5], v[176:179], v[208:211], v[2:5]
	v_mfma_f32_16x16x32_bf16 v[54:57], v[172:175], v[188:191], v[54:57]
	v_mfma_f32_16x16x32_bf16 v[50:53], v[180:183], v[188:191], v[50:53]
	v_mfma_f32_16x16x32_bf16 v[38:41], v[172:175], v[196:199], v[38:41]
	v_mfma_f32_16x16x32_bf16 v[34:37], v[180:183], v[196:199], v[34:37]
	v_mfma_f32_16x16x32_bf16 v[22:25], v[172:175], v[204:207], v[22:25]
	v_mfma_f32_16x16x32_bf16 v[18:21], v[180:183], v[204:207], v[18:21]
	v_mfma_f32_16x16x32_bf16 v[6:9], v[172:175], v[212:215], v[6:9]
	v_mfma_f32_16x16x32_bf16 v[2:5], v[180:183], v[212:215], v[2:5]
	s_setprio 0
	s_barrier
	s_add_i32 s81, s81, 2
	s_add_u32 s88, s88, 0x100
	s_addc_u32 s89, s89, 0
	s_add_u32 s75, s75, 0x100
	s_addc_u32 s77, s77, 0
	s_cmp_gt_u32 s81, 27
	s_cbranch_scc0 .LBB0_995
	v_lshl_add_u32 v234, s76, 8, v1
	v_lshl_or_b32 v236, s73, 8, v163
	v_ashrrev_i32_e32 v235, 31, v234
	v_ashrrev_i32_e32 v237, 31, v236
	v_lshlrev_b64 v[228:229], 12, v[234:235]
	v_lshl_add_u64 v[228:229], s[64:65], 0, v[228:229]
	v_lshlrev_b64 v[236:237], 1, v[236:237]
	v_lshl_add_u64 v[228:229], v[228:229], 0, v[236:237]
	v_mov_b32_e32 v231, 0
	ds_read_b128 v[146:149], v164
	ds_read_b128 v[150:153], v164 offset:1024
	ds_read_b128 v[154:157], v164 offset:2048
	ds_read_b128 v[158:161], v164 offset:3072
	ds_read_b128 v[168:171], v165
	ds_read_b128 v[172:175], v165 offset:1024
	ds_read_b128 v[176:179], v165 offset:2048
	ds_read_b128 v[180:183], v165 offset:3072
	s_add_u32 s34, s88, 0xfff80080
	s_addc_u32 s35, s89, -1
	s_cmp_eq_u32 s81, 28
	s_cselect_b32 s91, s0, s35
	s_cselect_b32 s90, s1, s34
	s_cselect_b32 s35, s52, s77
	s_cselect_b32 s34, s74, s75
	v_lshl_add_u64 v[218:219], s[88:89], 0, v[138:139]
	s_add_i32 m0, s33, 0xc000
	ds_read_b128 v[184:187], v166
	ds_read_b128 v[188:191], v166 offset:1024
	ds_read_b128 v[192:195], v166 offset:2048
	ds_read_b128 v[196:199], v166 offset:3072
	ds_read_b128 v[200:203], v166 offset:4096
	ds_read_b128 v[204:207], v166 offset:5120
	ds_read_b128 v[208:211], v166 offset:6144
	ds_read_b128 v[212:215], v166 offset:7168
	global_load_lds_dwordx4 v[218:219], off
	v_lshl_add_u64 v[218:219], s[88:89], 0, v[140:141]
	s_add_i32 m0, s33, 0xe000
	s_nop 0
	global_load_lds_dwordx4 v[218:219], off
	s_waitcnt vmcnt(8)
	s_waitcnt lgkmcnt(0)
	s_barrier
	s_setprio 1
	s_waitcnt lgkmcnt(0)
	v_mfma_f32_16x16x32_bf16 v[126:129], v[146:149], v[184:187], v[126:129]
	v_mfma_f32_16x16x32_bf16 v[122:125], v[154:157], v[184:187], v[122:125]
	v_mfma_f32_16x16x32_bf16 v[110:113], v[146:149], v[192:195], v[110:113]
	v_mfma_f32_16x16x32_bf16 v[106:109], v[154:157], v[192:195], v[106:109]
	v_mfma_f32_16x16x32_bf16 v[94:97], v[146:149], v[200:203], v[94:97]
	v_mfma_f32_16x16x32_bf16 v[90:93], v[154:157], v[200:203], v[90:93]
	v_mfma_f32_16x16x32_bf16 v[78:81], v[146:149], v[208:211], v[78:81]
	v_mfma_f32_16x16x32_bf16 v[74:77], v[154:157], v[208:211], v[74:77]
	v_mfma_f32_16x16x32_bf16 v[126:129], v[150:153], v[188:191], v[126:129]
	v_mfma_f32_16x16x32_bf16 v[122:125], v[158:161], v[188:191], v[122:125]
	v_mfma_f32_16x16x32_bf16 v[110:113], v[150:153], v[196:199], v[110:113]
	v_mfma_f32_16x16x32_bf16 v[106:109], v[158:161], v[196:199], v[106:109]
	v_mfma_f32_16x16x32_bf16 v[94:97], v[150:153], v[204:207], v[94:97]
	v_mfma_f32_16x16x32_bf16 v[90:93], v[158:161], v[204:207], v[90:93]
	v_mfma_f32_16x16x32_bf16 v[78:81], v[150:153], v[212:215], v[78:81]
	v_mfma_f32_16x16x32_bf16 v[74:77], v[158:161], v[212:215], v[74:77]
	s_setprio 0
	s_setprio 1
	v_mfma_f32_16x16x32_bf16 v[118:121], v[168:171], v[184:187], v[118:121]
	v_mfma_f32_16x16x32_bf16 v[114:117], v[176:179], v[184:187], v[114:117]
	v_mfma_f32_16x16x32_bf16 v[102:105], v[168:171], v[192:195], v[102:105]
	v_mfma_f32_16x16x32_bf16 v[98:101], v[176:179], v[192:195], v[98:101]
	v_mfma_f32_16x16x32_bf16 v[86:89], v[168:171], v[200:203], v[86:89]
	v_mfma_f32_16x16x32_bf16 v[82:85], v[176:179], v[200:203], v[82:85]
	v_mfma_f32_16x16x32_bf16 v[70:73], v[168:171], v[208:211], v[70:73]
	v_mfma_f32_16x16x32_bf16 v[66:69], v[176:179], v[208:211], v[66:69]
	v_mfma_f32_16x16x32_bf16 v[118:121], v[172:175], v[188:191], v[118:121]
	v_mfma_f32_16x16x32_bf16 v[114:117], v[180:183], v[188:191], v[114:117]
	v_mfma_f32_16x16x32_bf16 v[102:105], v[172:175], v[196:199], v[102:105]
	v_mfma_f32_16x16x32_bf16 v[98:101], v[180:183], v[196:199], v[98:101]
	v_mfma_f32_16x16x32_bf16 v[86:89], v[172:175], v[204:207], v[86:89]
	v_mfma_f32_16x16x32_bf16 v[82:85], v[180:183], v[204:207], v[82:85]
	v_mfma_f32_16x16x32_bf16 v[70:73], v[172:175], v[212:215], v[70:73]
	v_mfma_f32_16x16x32_bf16 v[66:69], v[180:183], v[212:215], v[66:69]
	s_setprio 0
	s_barrier
	s_add_i32 s53, s71, s31
	v_lshl_add_u64 v[218:219], s[34:35], 0, v[132:133]
	s_mov_b32 m0, s53
	ds_read_b128 v[184:187], v166 offset:16384
	ds_read_b128 v[188:191], v166 offset:17408
	ds_read_b128 v[192:195], v166 offset:18432
	ds_read_b128 v[196:199], v166 offset:19456
	ds_read_b128 v[200:203], v166 offset:20480
	ds_read_b128 v[204:207], v166 offset:21504
	ds_read_b128 v[208:211], v166 offset:22528
	ds_read_b128 v[212:215], v166 offset:23552
	v_mov_b32_e32 v230, 0x0
	v_lshl_add_u64 v[232:233], v[230:231], 0, v[228:229]
	global_load_lds_dwordx4 v[232:233], off
	s_add_i32 m0, s53, 0x2000
	s_add_u32 s54, s34, 0x80000
	v_lshl_add_u64 v[220:221], s[34:35], 0, v[136:137]
	s_addc_u32 s55, s35, 0
	s_add_i32 s53, s72, s31
	v_mov_b32_e32 v230, 0x100
	v_lshl_add_u64 v[232:233], v[230:231], 0, v[228:229]
	global_load_lds_dwordx4 v[232:233], off
	v_lshl_add_u64 v[222:223], s[54:55], 0, v[132:133]
	s_mov_b32 m0, s53
	v_lshl_add_u64 v[224:225], s[90:91], 0, v[134:135]
	v_mov_b32_e32 v230, 0x10000
	v_lshl_add_u64 v[232:233], v[230:231], 0, v[228:229]
	global_load_lds_dwordx4 v[232:233], off
	v_lshl_add_u64 v[222:223], s[54:55], 0, v[136:137]
	s_add_i32 m0, s53, 0x2000
	s_nop 0
	v_mov_b32_e32 v230, 0x10100
	v_lshl_add_u64 v[232:233], v[230:231], 0, v[228:229]
	global_load_lds_dwordx4 v[232:233], off
	v_lshl_add_u64 v[222:223], s[90:91], 0, v[130:131]
	s_mov_b32 m0, s33
	s_nop 0
	v_mov_b32_e32 v230, 0x20000
	v_lshl_add_u64 v[232:233], v[230:231], 0, v[228:229]
	global_load_lds_dwordx4 v[232:233], off
	s_mov_b32 m0, s56
	s_nop 0
	v_mov_b32_e32 v230, 0x20100
	v_lshl_add_u64 v[232:233], v[230:231], 0, v[228:229]
	global_load_lds_dwordx4 v[232:233], off
	s_waitcnt vmcnt(8)
	s_waitcnt lgkmcnt(0)
	s_barrier
	s_setprio 1
	s_waitcnt lgkmcnt(0)
	v_mfma_f32_16x16x32_bf16 v[62:65], v[146:149], v[184:187], v[62:65]
	v_mfma_f32_16x16x32_bf16 v[58:61], v[154:157], v[184:187], v[58:61]
	v_mfma_f32_16x16x32_bf16 v[46:49], v[146:149], v[192:195], v[46:49]
	v_mfma_f32_16x16x32_bf16 v[42:45], v[154:157], v[192:195], v[42:45]
	v_mfma_f32_16x16x32_bf16 v[30:33], v[146:149], v[200:203], v[30:33]
	v_mfma_f32_16x16x32_bf16 v[26:29], v[154:157], v[200:203], v[26:29]
	v_mfma_f32_16x16x32_bf16 v[14:17], v[146:149], v[208:211], v[14:17]
	v_mfma_f32_16x16x32_bf16 v[10:13], v[154:157], v[208:211], v[10:13]
	v_mfma_f32_16x16x32_bf16 v[62:65], v[150:153], v[188:191], v[62:65]
	v_mfma_f32_16x16x32_bf16 v[58:61], v[158:161], v[188:191], v[58:61]
	v_mfma_f32_16x16x32_bf16 v[46:49], v[150:153], v[196:199], v[46:49]
	v_mfma_f32_16x16x32_bf16 v[42:45], v[158:161], v[196:199], v[42:45]
	v_mfma_f32_16x16x32_bf16 v[30:33], v[150:153], v[204:207], v[30:33]
	v_mfma_f32_16x16x32_bf16 v[26:29], v[158:161], v[204:207], v[26:29]
	v_mfma_f32_16x16x32_bf16 v[14:17], v[150:153], v[212:215], v[14:17]
	v_mfma_f32_16x16x32_bf16 v[10:13], v[158:161], v[212:215], v[10:13]
	s_setprio 0
	s_setprio 1
	v_mfma_f32_16x16x32_bf16 v[54:57], v[168:171], v[184:187], v[54:57]
	v_mfma_f32_16x16x32_bf16 v[50:53], v[176:179], v[184:187], v[50:53]
	v_mfma_f32_16x16x32_bf16 v[38:41], v[168:171], v[192:195], v[38:41]
	v_mfma_f32_16x16x32_bf16 v[34:37], v[176:179], v[192:195], v[34:37]
	v_mfma_f32_16x16x32_bf16 v[22:25], v[168:171], v[200:203], v[22:25]
	v_mfma_f32_16x16x32_bf16 v[18:21], v[176:179], v[200:203], v[18:21]
	v_mfma_f32_16x16x32_bf16 v[6:9], v[168:171], v[208:211], v[6:9]
	v_mfma_f32_16x16x32_bf16 v[2:5], v[176:179], v[208:211], v[2:5]
	v_mfma_f32_16x16x32_bf16 v[54:57], v[172:175], v[188:191], v[54:57]
	v_mfma_f32_16x16x32_bf16 v[50:53], v[180:183], v[188:191], v[50:53]
	v_mfma_f32_16x16x32_bf16 v[38:41], v[172:175], v[196:199], v[38:41]
	v_mfma_f32_16x16x32_bf16 v[34:37], v[180:183], v[196:199], v[34:37]
	v_mfma_f32_16x16x32_bf16 v[22:25], v[172:175], v[204:207], v[22:25]
	v_mfma_f32_16x16x32_bf16 v[18:21], v[180:183], v[204:207], v[18:21]
	v_mfma_f32_16x16x32_bf16 v[6:9], v[172:175], v[212:215], v[6:9]
	v_mfma_f32_16x16x32_bf16 v[2:5], v[180:183], v[212:215], v[2:5]
	s_setprio 0
	s_barrier
	s_add_i32 s53, 0, 0x18000
	s_add_i32 s62, 0, 0x1c000
	v_add_u32_e32 v158, s53, v162
	v_add_u32_e32 v167, s62, v162
	ds_read_b128 v[146:149], v158
	ds_read_b128 v[150:153], v158 offset:1024
	ds_read_b128 v[154:157], v158 offset:2048
	ds_read_b128 v[158:161], v158 offset:3072
	ds_read_b128 v[168:171], v167
	ds_read_b128 v[172:175], v167 offset:1024
	ds_read_b128 v[176:179], v167 offset:2048
	ds_read_b128 v[180:183], v167 offset:3072
	s_add_u32 s54, s90, 0x80000
	s_addc_u32 s55, s91, 0
	s_mov_b32 m0, s57
	v_lshl_add_u64 v[226:227], s[54:55], 0, v[130:131]
	ds_read_b128 v[184:187], v166 offset:32768
	ds_read_b128 v[188:191], v166 offset:33792
	ds_read_b128 v[192:195], v166 offset:34816
	ds_read_b128 v[196:199], v166 offset:35840
	ds_read_b128 v[200:203], v166 offset:36864
	ds_read_b128 v[204:207], v166 offset:37888
	ds_read_b128 v[208:211], v166 offset:38912
	ds_read_b128 v[212:215], v166 offset:39936
	v_mov_b32_e32 v230, 0x30000
	v_lshl_add_u64 v[232:233], v[230:231], 0, v[228:229]
	global_load_lds_dwordx4 v[232:233], off
	v_lshl_add_u64 v[226:227], s[54:55], 0, v[134:135]
	s_mov_b32 m0, s58
	s_nop 0
	v_mov_b32_e32 v230, 0x30100
	v_lshl_add_u64 v[232:233], v[230:231], 0, v[228:229]
	global_load_lds_dwordx4 v[232:233], off
	s_waitcnt vmcnt(8)
	s_waitcnt lgkmcnt(0)
	s_barrier
	s_setprio 1
	s_waitcnt lgkmcnt(0)
	v_mfma_f32_16x16x32_bf16 v[126:129], v[146:149], v[184:187], v[126:129]
	v_mfma_f32_16x16x32_bf16 v[122:125], v[154:157], v[184:187], v[122:125]
	v_mfma_f32_16x16x32_bf16 v[110:113], v[146:149], v[192:195], v[110:113]
	v_mfma_f32_16x16x32_bf16 v[106:109], v[154:157], v[192:195], v[106:109]
	v_mfma_f32_16x16x32_bf16 v[94:97], v[146:149], v[200:203], v[94:97]
	v_mfma_f32_16x16x32_bf16 v[90:93], v[154:157], v[200:203], v[90:93]
	v_mfma_f32_16x16x32_bf16 v[78:81], v[146:149], v[208:211], v[78:81]
	v_mfma_f32_16x16x32_bf16 v[74:77], v[154:157], v[208:211], v[74:77]
	v_mfma_f32_16x16x32_bf16 v[126:129], v[150:153], v[188:191], v[126:129]
	v_mfma_f32_16x16x32_bf16 v[122:125], v[158:161], v[188:191], v[122:125]
	v_mfma_f32_16x16x32_bf16 v[110:113], v[150:153], v[196:199], v[110:113]
	v_mfma_f32_16x16x32_bf16 v[106:109], v[158:161], v[196:199], v[106:109]
	v_mfma_f32_16x16x32_bf16 v[94:97], v[150:153], v[204:207], v[94:97]
	v_mfma_f32_16x16x32_bf16 v[90:93], v[158:161], v[204:207], v[90:93]
	v_mfma_f32_16x16x32_bf16 v[78:81], v[150:153], v[212:215], v[78:81]
	v_mfma_f32_16x16x32_bf16 v[74:77], v[158:161], v[212:215], v[74:77]
	s_setprio 0
	s_setprio 1
	v_mfma_f32_16x16x32_bf16 v[118:121], v[168:171], v[184:187], v[118:121]
	v_mfma_f32_16x16x32_bf16 v[114:117], v[176:179], v[184:187], v[114:117]
	v_mfma_f32_16x16x32_bf16 v[102:105], v[168:171], v[192:195], v[102:105]
	v_mfma_f32_16x16x32_bf16 v[98:101], v[176:179], v[192:195], v[98:101]
	v_mfma_f32_16x16x32_bf16 v[86:89], v[168:171], v[200:203], v[86:89]
	v_mfma_f32_16x16x32_bf16 v[82:85], v[176:179], v[200:203], v[82:85]
	v_mfma_f32_16x16x32_bf16 v[70:73], v[168:171], v[208:211], v[70:73]
	v_mfma_f32_16x16x32_bf16 v[66:69], v[176:179], v[208:211], v[66:69]
	v_mfma_f32_16x16x32_bf16 v[118:121], v[172:175], v[188:191], v[118:121]
	v_mfma_f32_16x16x32_bf16 v[114:117], v[180:183], v[188:191], v[114:117]
	v_mfma_f32_16x16x32_bf16 v[102:105], v[172:175], v[196:199], v[102:105]
	v_mfma_f32_16x16x32_bf16 v[98:101], v[180:183], v[196:199], v[98:101]
	v_mfma_f32_16x16x32_bf16 v[86:89], v[172:175], v[204:207], v[86:89]
	v_mfma_f32_16x16x32_bf16 v[82:85], v[180:183], v[204:207], v[82:85]
	v_mfma_f32_16x16x32_bf16 v[70:73], v[172:175], v[212:215], v[70:73]
	v_mfma_f32_16x16x32_bf16 v[66:69], v[180:183], v[212:215], v[66:69]
	s_setprio 0
	s_barrier
	s_add_i32 s53, s53, s31
	v_lshl_add_u64 v[218:219], v[218:219], 0, s[8:9]
	s_mov_b32 m0, s53
	ds_read_b128 v[184:187], v166 offset:49152
	ds_read_b128 v[188:191], v166 offset:50176
	ds_read_b128 v[192:195], v166 offset:51200
	ds_read_b128 v[196:199], v166 offset:52224
	ds_read_b128 v[200:203], v166 offset:53248
	ds_read_b128 v[204:207], v166 offset:54272
	ds_read_b128 v[208:211], v166 offset:55296
	ds_read_b128 v[212:215], v166 offset:56320
	v_mov_b32_e32 v230, 0x80000
	v_lshl_add_u64 v[232:233], v[230:231], 0, v[228:229]
	global_load_lds_dwordx4 v[232:233], off
	s_add_i32 m0, s53, 0x2000
	s_add_u32 s34, s34, 0x80080
	v_lshl_add_u64 v[218:219], v[220:221], 0, s[8:9]
	s_addc_u32 s35, s35, 0
	s_add_i32 s53, s62, s31
	v_mov_b32_e32 v230, 0x80100
	v_lshl_add_u64 v[232:233], v[230:231], 0, v[228:229]
	global_load_lds_dwordx4 v[232:233], off
	v_lshl_add_u64 v[218:219], s[34:35], 0, v[132:133]
	s_mov_b32 m0, s53
	s_nop 0
	v_mov_b32_e32 v230, 0x90000
	v_lshl_add_u64 v[232:233], v[230:231], 0, v[228:229]
	global_load_lds_dwordx4 v[232:233], off
	v_lshl_add_u64 v[218:219], s[34:35], 0, v[136:137]
	s_add_i32 m0, s53, 0x2000
	s_nop 0
	v_mov_b32_e32 v230, 0x90100
	v_lshl_add_u64 v[232:233], v[230:231], 0, v[228:229]
	global_load_lds_dwordx4 v[232:233], off
	v_lshl_add_u64 v[218:219], v[222:223], 0, s[8:9]
	s_mov_b32 m0, s60
	s_nop 0
	v_mov_b32_e32 v230, 0xa0000
	v_lshl_add_u64 v[232:233], v[230:231], 0, v[228:229]
	global_load_lds_dwordx4 v[232:233], off
	v_lshl_add_u64 v[218:219], v[224:225], 0, s[8:9]
	s_mov_b32 m0, s61
	s_nop 0
	v_mov_b32_e32 v230, 0xa0100
	v_lshl_add_u64 v[232:233], v[230:231], 0, v[228:229]
	global_load_lds_dwordx4 v[232:233], off
	s_waitcnt vmcnt(8)
	s_waitcnt lgkmcnt(0)
	s_barrier
	s_setprio 1
	s_waitcnt lgkmcnt(0)
	v_mfma_f32_16x16x32_bf16 v[62:65], v[146:149], v[184:187], v[62:65]
	v_mfma_f32_16x16x32_bf16 v[58:61], v[154:157], v[184:187], v[58:61]
	v_mfma_f32_16x16x32_bf16 v[46:49], v[146:149], v[192:195], v[46:49]
	v_mfma_f32_16x16x32_bf16 v[42:45], v[154:157], v[192:195], v[42:45]
	v_mfma_f32_16x16x32_bf16 v[30:33], v[146:149], v[200:203], v[30:33]
	v_mfma_f32_16x16x32_bf16 v[26:29], v[154:157], v[200:203], v[26:29]
	v_mfma_f32_16x16x32_bf16 v[14:17], v[146:149], v[208:211], v[14:17]
	v_mfma_f32_16x16x32_bf16 v[10:13], v[154:157], v[208:211], v[10:13]
	v_mfma_f32_16x16x32_bf16 v[62:65], v[150:153], v[188:191], v[62:65]
	v_mfma_f32_16x16x32_bf16 v[58:61], v[158:161], v[188:191], v[58:61]
	v_mfma_f32_16x16x32_bf16 v[46:49], v[150:153], v[196:199], v[46:49]
	v_mfma_f32_16x16x32_bf16 v[42:45], v[158:161], v[196:199], v[42:45]
	v_mfma_f32_16x16x32_bf16 v[30:33], v[150:153], v[204:207], v[30:33]
	v_mfma_f32_16x16x32_bf16 v[26:29], v[158:161], v[204:207], v[26:29]
	v_mfma_f32_16x16x32_bf16 v[14:17], v[150:153], v[212:215], v[14:17]
	v_mfma_f32_16x16x32_bf16 v[10:13], v[158:161], v[212:215], v[10:13]
	s_setprio 0
	s_setprio 1
	v_mfma_f32_16x16x32_bf16 v[54:57], v[168:171], v[184:187], v[54:57]
	v_mfma_f32_16x16x32_bf16 v[50:53], v[176:179], v[184:187], v[50:53]
	v_mfma_f32_16x16x32_bf16 v[38:41], v[168:171], v[192:195], v[38:41]
	v_mfma_f32_16x16x32_bf16 v[34:37], v[176:179], v[192:195], v[34:37]
	v_mfma_f32_16x16x32_bf16 v[22:25], v[168:171], v[200:203], v[22:25]
	v_mfma_f32_16x16x32_bf16 v[18:21], v[176:179], v[200:203], v[18:21]
	v_mfma_f32_16x16x32_bf16 v[6:9], v[168:171], v[208:211], v[6:9]
	v_mfma_f32_16x16x32_bf16 v[2:5], v[176:179], v[208:211], v[2:5]
	v_mfma_f32_16x16x32_bf16 v[54:57], v[172:175], v[188:191], v[54:57]
	v_mfma_f32_16x16x32_bf16 v[50:53], v[180:183], v[188:191], v[50:53]
	v_mfma_f32_16x16x32_bf16 v[38:41], v[172:175], v[196:199], v[38:41]
	v_mfma_f32_16x16x32_bf16 v[34:37], v[180:183], v[196:199], v[34:37]
	v_mfma_f32_16x16x32_bf16 v[22:25], v[172:175], v[204:207], v[22:25]
	v_mfma_f32_16x16x32_bf16 v[18:21], v[180:183], v[204:207], v[18:21]
	v_mfma_f32_16x16x32_bf16 v[6:9], v[172:175], v[212:215], v[6:9]
	v_mfma_f32_16x16x32_bf16 v[2:5], v[180:183], v[212:215], v[2:5]
	s_setprio 0
	s_barrier
	s_add_i32 s81, s81, 2
	s_add_u32 s88, s88, 0x100
	s_addc_u32 s89, s89, 0
	s_add_u32 s75, s75, 0x100
	s_addc_u32 s77, s77, 0
	s_and_b64 vcc, exec, s[78:79]
	s_cbranch_vccz .LBB0_998
	s_barrier
.LBB0_998:
	v_lshl_add_u32 v146, s76, 8, v1
	v_lshl_or_b32 v148, s73, 8, v163
	v_ashrrev_i32_e32 v147, 31, v146
	v_ashrrev_i32_e32 v149, 31, v148
	v_lshlrev_b64 v[150:151], 12, v[146:147]
	v_lshl_add_u64 v[150:151], s[64:65], 0, v[150:151]
	v_lshlrev_b64 v[148:149], 1, v[148:149]
	v_lshl_add_u64 v[150:151], v[150:151], 0, v[148:149]
	s_waitcnt vmcnt(0)
	v_mov_b32_e32 v237, 0
	v_mov_b32_e32 v236, 0x10000
	v_lshl_add_u64 v[186:187], v[236:237], 0, v[150:151]
	v_mov_b32_e32 v236, 0x20000
	v_lshl_add_u64 v[188:189], v[236:237], 0, v[150:151]
	v_mov_b32_e32 v236, 0x30000
	v_lshl_add_u64 v[190:191], v[236:237], 0, v[150:151]
	v_mov_b32_e32 v236, 0x80000
	v_lshl_add_u64 v[228:229], v[236:237], 0, v[150:151]
	v_mov_b32_e32 v236, 0x90000
	v_lshl_add_u64 v[230:231], v[236:237], 0, v[150:151]
	v_mov_b32_e32 v236, 0xa0000
	v_lshl_add_u64 v[232:233], v[236:237], 0, v[150:151]
	v_mov_b32_e32 v236, 0xb0000
	v_lshl_add_u64 v[234:235], v[236:237], 0, v[150:151]
	v_lshlrev_b32_e32 v238, 4, v0
	v_add_u32_e32 v239, 0x10000, v238
	global_load_dwordx4 v[172:175], v[234:235], off
	global_load_dwordx4 v[176:179], v[234:235], off offset:256
	ds_read_b128 v[146:149], v239 offset:0
	ds_read_b128 v[152:155], v239 offset:8192
	ds_read_b128 v[156:159], v239 offset:16384
	ds_read_b128 v[168:171], v239 offset:24576
	s_waitcnt lgkmcnt(3)
	v_cvt_f32_f16_e32 v160, v146
	v_cvt_f32_f16_sdwa v161, v146 dst_sel:DWORD dst_unused:UNUSED_PAD src0_sel:WORD_1
	v_cvt_f32_f16_e32 v180, v147
	v_cvt_f32_f16_sdwa v181, v147 dst_sel:DWORD dst_unused:UNUSED_PAD src0_sel:WORD_1
	v_cvt_f32_f16_e32 v182, v148
	v_cvt_f32_f16_sdwa v183, v148 dst_sel:DWORD dst_unused:UNUSED_PAD src0_sel:WORD_1
	v_cvt_f32_f16_e32 v184, v149
	v_cvt_f32_f16_sdwa v185, v149 dst_sel:DWORD dst_unused:UNUSED_PAD src0_sel:WORD_1
	ds_read_b128 v[146:149], v238 offset:0
	v_pk_add_f32 v[126:127], v[160:161], v[126:127]
	v_pk_add_f32 v[128:129], v[180:181], v[128:129]
	v_pk_add_f32 v[122:123], v[182:183], v[122:123]
	v_pk_add_f32 v[124:125], v[184:185], v[124:125]
	v_cvt_pk_f16_f32 v125, v124, v125
	v_cvt_pk_f16_f32 v124, v122, v123
	v_cvt_pk_f16_f32 v123, v128, v129
	v_cvt_pk_f16_f32 v122, v126, v127
	global_store_dwordx4 v[150:151], v[122:125], off
	s_waitcnt lgkmcnt(3)
	v_cvt_f32_f16_e32 v160, v152
	v_cvt_f32_f16_sdwa v161, v152 dst_sel:DWORD dst_unused:UNUSED_PAD src0_sel:WORD_1
	v_cvt_f32_f16_e32 v180, v153
	v_cvt_f32_f16_sdwa v181, v153 dst_sel:DWORD dst_unused:UNUSED_PAD src0_sel:WORD_1
	v_cvt_f32_f16_e32 v182, v154
	v_cvt_f32_f16_sdwa v183, v154 dst_sel:DWORD dst_unused:UNUSED_PAD src0_sel:WORD_1
	v_cvt_f32_f16_e32 v184, v155
	v_cvt_f32_f16_sdwa v185, v155 dst_sel:DWORD dst_unused:UNUSED_PAD src0_sel:WORD_1
	ds_read_b128 v[152:155], v238 offset:8192
	v_pk_add_f32 v[118:119], v[160:161], v[118:119]
	v_pk_add_f32 v[120:121], v[180:181], v[120:121]
	v_pk_add_f32 v[114:115], v[182:183], v[114:115]
	v_pk_add_f32 v[116:117], v[184:185], v[116:117]
	v_cvt_pk_f16_f32 v117, v116, v117
	v_cvt_pk_f16_f32 v116, v114, v115
	v_cvt_pk_f16_f32 v115, v120, v121
	v_cvt_pk_f16_f32 v114, v118, v119
	global_store_dwordx4 v[150:151], v[114:117], off offset:256
	s_waitcnt lgkmcnt(3)
	v_cvt_f32_f16_e32 v160, v156
	v_cvt_f32_f16_sdwa v161, v156 dst_sel:DWORD dst_unused:UNUSED_PAD src0_sel:WORD_1
	v_cvt_f32_f16_e32 v180, v157
	v_cvt_f32_f16_sdwa v181, v157 dst_sel:DWORD dst_unused:UNUSED_PAD src0_sel:WORD_1
	v_cvt_f32_f16_e32 v182, v158
	v_cvt_f32_f16_sdwa v183, v158 dst_sel:DWORD dst_unused:UNUSED_PAD src0_sel:WORD_1
	v_cvt_f32_f16_e32 v184, v159
	v_cvt_f32_f16_sdwa v185, v159 dst_sel:DWORD dst_unused:UNUSED_PAD src0_sel:WORD_1
	ds_read_b128 v[156:159], v238 offset:16384
	v_pk_add_f32 v[110:111], v[160:161], v[110:111]
	v_pk_add_f32 v[112:113], v[180:181], v[112:113]
	v_pk_add_f32 v[106:107], v[182:183], v[106:107]
	v_pk_add_f32 v[108:109], v[184:185], v[108:109]
	v_cvt_pk_f16_f32 v109, v108, v109
	v_cvt_pk_f16_f32 v108, v106, v107
	v_cvt_pk_f16_f32 v107, v112, v113
	v_cvt_pk_f16_f32 v106, v110, v111
	global_store_dwordx4 v[186:187], v[106:109], off
	s_waitcnt lgkmcnt(3)
	v_cvt_f32_f16_e32 v160, v168
	v_cvt_f32_f16_sdwa v161, v168 dst_sel:DWORD dst_unused:UNUSED_PAD src0_sel:WORD_1
	v_cvt_f32_f16_e32 v180, v169
	v_cvt_f32_f16_sdwa v181, v169 dst_sel:DWORD dst_unused:UNUSED_PAD src0_sel:WORD_1
	v_cvt_f32_f16_e32 v182, v170
	v_cvt_f32_f16_sdwa v183, v170 dst_sel:DWORD dst_unused:UNUSED_PAD src0_sel:WORD_1
	v_cvt_f32_f16_e32 v184, v171
	v_cvt_f32_f16_sdwa v185, v171 dst_sel:DWORD dst_unused:UNUSED_PAD src0_sel:WORD_1
	ds_read_b128 v[168:171], v238 offset:24576
	v_pk_add_f32 v[102:103], v[160:161], v[102:103]
	v_pk_add_f32 v[104:105], v[180:181], v[104:105]
	v_pk_add_f32 v[98:99], v[182:183], v[98:99]
	v_pk_add_f32 v[100:101], v[184:185], v[100:101]
	v_cvt_pk_f16_f32 v101, v100, v101
	v_cvt_pk_f16_f32 v100, v98, v99
	v_cvt_pk_f16_f32 v99, v104, v105
	v_cvt_pk_f16_f32 v98, v102, v103
	global_store_dwordx4 v[186:187], v[98:101], off offset:256
	s_waitcnt lgkmcnt(3)
	v_cvt_f32_f16_e32 v160, v146
	v_cvt_f32_f16_sdwa v161, v146 dst_sel:DWORD dst_unused:UNUSED_PAD src0_sel:WORD_1
	v_cvt_f32_f16_e32 v180, v147
	v_cvt_f32_f16_sdwa v181, v147 dst_sel:DWORD dst_unused:UNUSED_PAD src0_sel:WORD_1
	v_cvt_f32_f16_e32 v182, v148
	v_cvt_f32_f16_sdwa v183, v148 dst_sel:DWORD dst_unused:UNUSED_PAD src0_sel:WORD_1
	v_cvt_f32_f16_e32 v184, v149
	v_cvt_f32_f16_sdwa v185, v149 dst_sel:DWORD dst_unused:UNUSED_PAD src0_sel:WORD_1
	ds_read_b128 v[146:149], v239 offset:32768
	v_pk_add_f32 v[94:95], v[160:161], v[94:95]
	v_pk_add_f32 v[96:97], v[180:181], v[96:97]
	v_pk_add_f32 v[90:91], v[182:183], v[90:91]
	v_pk_add_f32 v[92:93], v[184:185], v[92:93]
	v_cvt_pk_f16_f32 v93, v92, v93
	v_cvt_pk_f16_f32 v92, v90, v91
	v_cvt_pk_f16_f32 v91, v96, v97
	v_cvt_pk_f16_f32 v90, v94, v95
	global_store_dwordx4 v[188:189], v[90:93], off
	s_waitcnt lgkmcnt(3)
	v_cvt_f32_f16_e32 v160, v152
	v_cvt_f32_f16_sdwa v161, v152 dst_sel:DWORD dst_unused:UNUSED_PAD src0_sel:WORD_1
	v_cvt_f32_f16_e32 v180, v153
	v_cvt_f32_f16_sdwa v181, v153 dst_sel:DWORD dst_unused:UNUSED_PAD src0_sel:WORD_1
	v_cvt_f32_f16_e32 v182, v154
	v_cvt_f32_f16_sdwa v183, v154 dst_sel:DWORD dst_unused:UNUSED_PAD src0_sel:WORD_1
	v_cvt_f32_f16_e32 v184, v155
	v_cvt_f32_f16_sdwa v185, v155 dst_sel:DWORD dst_unused:UNUSED_PAD src0_sel:WORD_1
	ds_read_b128 v[152:155], v239 offset:40960
	v_pk_add_f32 v[86:87], v[160:161], v[86:87]
	v_pk_add_f32 v[88:89], v[180:181], v[88:89]
	v_pk_add_f32 v[82:83], v[182:183], v[82:83]
	v_pk_add_f32 v[84:85], v[184:185], v[84:85]
	v_cvt_pk_f16_f32 v85, v84, v85
	v_cvt_pk_f16_f32 v84, v82, v83
	v_cvt_pk_f16_f32 v83, v88, v89
	v_cvt_pk_f16_f32 v82, v86, v87
	global_store_dwordx4 v[188:189], v[82:85], off offset:256
	s_waitcnt lgkmcnt(3)
	v_cvt_f32_f16_e32 v160, v156
	v_cvt_f32_f16_sdwa v161, v156 dst_sel:DWORD dst_unused:UNUSED_PAD src0_sel:WORD_1
	v_cvt_f32_f16_e32 v180, v157
	v_cvt_f32_f16_sdwa v181, v157 dst_sel:DWORD dst_unused:UNUSED_PAD src0_sel:WORD_1
	v_cvt_f32_f16_e32 v182, v158
	v_cvt_f32_f16_sdwa v183, v158 dst_sel:DWORD dst_unused:UNUSED_PAD src0_sel:WORD_1
	v_cvt_f32_f16_e32 v184, v159
	v_cvt_f32_f16_sdwa v185, v159 dst_sel:DWORD dst_unused:UNUSED_PAD src0_sel:WORD_1
	ds_read_b128 v[156:159], v239 offset:49152
	v_pk_add_f32 v[78:79], v[160:161], v[78:79]
	v_pk_add_f32 v[80:81], v[180:181], v[80:81]
	v_pk_add_f32 v[74:75], v[182:183], v[74:75]
	v_pk_add_f32 v[76:77], v[184:185], v[76:77]
	v_cvt_pk_f16_f32 v77, v76, v77
	v_cvt_pk_f16_f32 v76, v74, v75
	v_cvt_pk_f16_f32 v75, v80, v81
	v_cvt_pk_f16_f32 v74, v78, v79
	global_store_dwordx4 v[190:191], v[74:77], off
	s_waitcnt lgkmcnt(3)
	v_cvt_f32_f16_e32 v160, v168
	v_cvt_f32_f16_sdwa v161, v168 dst_sel:DWORD dst_unused:UNUSED_PAD src0_sel:WORD_1
	v_cvt_f32_f16_e32 v180, v169
	v_cvt_f32_f16_sdwa v181, v169 dst_sel:DWORD dst_unused:UNUSED_PAD src0_sel:WORD_1
	v_cvt_f32_f16_e32 v182, v170
	v_cvt_f32_f16_sdwa v183, v170 dst_sel:DWORD dst_unused:UNUSED_PAD src0_sel:WORD_1
	v_cvt_f32_f16_e32 v184, v171
	v_cvt_f32_f16_sdwa v185, v171 dst_sel:DWORD dst_unused:UNUSED_PAD src0_sel:WORD_1
	ds_read_b128 v[168:171], v239 offset:57344
	v_pk_add_f32 v[70:71], v[160:161], v[70:71]
	v_pk_add_f32 v[72:73], v[180:181], v[72:73]
	v_pk_add_f32 v[66:67], v[182:183], v[66:67]
	v_pk_add_f32 v[68:69], v[184:185], v[68:69]
	v_cvt_pk_f16_f32 v69, v68, v69
	v_cvt_pk_f16_f32 v68, v66, v67
	v_cvt_pk_f16_f32 v67, v72, v73
	v_cvt_pk_f16_f32 v66, v70, v71
	global_store_dwordx4 v[190:191], v[66:69], off offset:256
	s_waitcnt lgkmcnt(3)
	v_cvt_f32_f16_e32 v160, v146
	v_cvt_f32_f16_sdwa v161, v146 dst_sel:DWORD dst_unused:UNUSED_PAD src0_sel:WORD_1
	v_cvt_f32_f16_e32 v180, v147
	v_cvt_f32_f16_sdwa v181, v147 dst_sel:DWORD dst_unused:UNUSED_PAD src0_sel:WORD_1
	v_cvt_f32_f16_e32 v182, v148
	v_cvt_f32_f16_sdwa v183, v148 dst_sel:DWORD dst_unused:UNUSED_PAD src0_sel:WORD_1
	v_cvt_f32_f16_e32 v184, v149
	v_cvt_f32_f16_sdwa v185, v149 dst_sel:DWORD dst_unused:UNUSED_PAD src0_sel:WORD_1
	ds_read_b128 v[146:149], v238 offset:32768
	v_pk_add_f32 v[62:63], v[160:161], v[62:63]
	v_pk_add_f32 v[64:65], v[180:181], v[64:65]
	v_pk_add_f32 v[58:59], v[182:183], v[58:59]
	v_pk_add_f32 v[60:61], v[184:185], v[60:61]
	v_cvt_pk_f16_f32 v61, v60, v61
	v_cvt_pk_f16_f32 v60, v58, v59
	v_cvt_pk_f16_f32 v59, v64, v65
	v_cvt_pk_f16_f32 v58, v62, v63
	global_store_dwordx4 v[228:229], v[58:61], off
	s_waitcnt lgkmcnt(3)
	v_cvt_f32_f16_e32 v160, v152
	v_cvt_f32_f16_sdwa v161, v152 dst_sel:DWORD dst_unused:UNUSED_PAD src0_sel:WORD_1
	v_cvt_f32_f16_e32 v180, v153
	v_cvt_f32_f16_sdwa v181, v153 dst_sel:DWORD dst_unused:UNUSED_PAD src0_sel:WORD_1
	v_cvt_f32_f16_e32 v182, v154
	v_cvt_f32_f16_sdwa v183, v154 dst_sel:DWORD dst_unused:UNUSED_PAD src0_sel:WORD_1
	v_cvt_f32_f16_e32 v184, v155
	v_cvt_f32_f16_sdwa v185, v155 dst_sel:DWORD dst_unused:UNUSED_PAD src0_sel:WORD_1
	ds_read_b128 v[152:155], v238 offset:40960
	v_pk_add_f32 v[54:55], v[160:161], v[54:55]
	v_pk_add_f32 v[56:57], v[180:181], v[56:57]
	v_pk_add_f32 v[50:51], v[182:183], v[50:51]
	v_pk_add_f32 v[52:53], v[184:185], v[52:53]
	v_cvt_pk_f16_f32 v53, v52, v53
	v_cvt_pk_f16_f32 v52, v50, v51
	v_cvt_pk_f16_f32 v51, v56, v57
	v_cvt_pk_f16_f32 v50, v54, v55
	global_store_dwordx4 v[228:229], v[50:53], off offset:256
	s_waitcnt lgkmcnt(3)
	v_cvt_f32_f16_e32 v160, v156
	v_cvt_f32_f16_sdwa v161, v156 dst_sel:DWORD dst_unused:UNUSED_PAD src0_sel:WORD_1
	v_cvt_f32_f16_e32 v180, v157
	v_cvt_f32_f16_sdwa v181, v157 dst_sel:DWORD dst_unused:UNUSED_PAD src0_sel:WORD_1
	v_cvt_f32_f16_e32 v182, v158
	v_cvt_f32_f16_sdwa v183, v158 dst_sel:DWORD dst_unused:UNUSED_PAD src0_sel:WORD_1
	v_cvt_f32_f16_e32 v184, v159
	v_cvt_f32_f16_sdwa v185, v159 dst_sel:DWORD dst_unused:UNUSED_PAD src0_sel:WORD_1
	v_pk_add_f32 v[46:47], v[160:161], v[46:47]
	v_pk_add_f32 v[48:49], v[180:181], v[48:49]
	v_pk_add_f32 v[42:43], v[182:183], v[42:43]
	v_pk_add_f32 v[44:45], v[184:185], v[44:45]
	v_cvt_pk_f16_f32 v45, v44, v45
	v_cvt_pk_f16_f32 v44, v42, v43
	v_cvt_pk_f16_f32 v43, v48, v49
	v_cvt_pk_f16_f32 v42, v46, v47
	global_store_dwordx4 v[230:231], v[42:45], off
	s_waitcnt lgkmcnt(2)
	v_cvt_f32_f16_e32 v160, v168
	v_cvt_f32_f16_sdwa v161, v168 dst_sel:DWORD dst_unused:UNUSED_PAD src0_sel:WORD_1
	v_cvt_f32_f16_e32 v180, v169
	v_cvt_f32_f16_sdwa v181, v169 dst_sel:DWORD dst_unused:UNUSED_PAD src0_sel:WORD_1
	v_cvt_f32_f16_e32 v182, v170
	v_cvt_f32_f16_sdwa v183, v170 dst_sel:DWORD dst_unused:UNUSED_PAD src0_sel:WORD_1
	v_cvt_f32_f16_e32 v184, v171
	v_cvt_f32_f16_sdwa v185, v171 dst_sel:DWORD dst_unused:UNUSED_PAD src0_sel:WORD_1
	v_pk_add_f32 v[38:39], v[160:161], v[38:39]
	v_pk_add_f32 v[40:41], v[180:181], v[40:41]
	v_pk_add_f32 v[34:35], v[182:183], v[34:35]
	v_pk_add_f32 v[36:37], v[184:185], v[36:37]
	v_cvt_pk_f16_f32 v37, v36, v37
	v_cvt_pk_f16_f32 v36, v34, v35
	v_cvt_pk_f16_f32 v35, v40, v41
	v_cvt_pk_f16_f32 v34, v38, v39
	global_store_dwordx4 v[230:231], v[34:37], off offset:256
	s_waitcnt lgkmcnt(1)
	v_cvt_f32_f16_e32 v160, v146
	v_cvt_f32_f16_sdwa v161, v146 dst_sel:DWORD dst_unused:UNUSED_PAD src0_sel:WORD_1
	v_cvt_f32_f16_e32 v180, v147
	v_cvt_f32_f16_sdwa v181, v147 dst_sel:DWORD dst_unused:UNUSED_PAD src0_sel:WORD_1
	v_cvt_f32_f16_e32 v182, v148
	v_cvt_f32_f16_sdwa v183, v148 dst_sel:DWORD dst_unused:UNUSED_PAD src0_sel:WORD_1
	v_cvt_f32_f16_e32 v184, v149
	v_cvt_f32_f16_sdwa v185, v149 dst_sel:DWORD dst_unused:UNUSED_PAD src0_sel:WORD_1
	v_pk_add_f32 v[30:31], v[160:161], v[30:31]
	v_pk_add_f32 v[32:33], v[180:181], v[32:33]
	v_pk_add_f32 v[26:27], v[182:183], v[26:27]
	v_pk_add_f32 v[28:29], v[184:185], v[28:29]
	v_cvt_pk_f16_f32 v29, v28, v29
	v_cvt_pk_f16_f32 v28, v26, v27
	v_cvt_pk_f16_f32 v27, v32, v33
	v_cvt_pk_f16_f32 v26, v30, v31
	global_store_dwordx4 v[232:233], v[26:29], off
	s_waitcnt lgkmcnt(0)
	v_cvt_f32_f16_e32 v160, v152
	v_cvt_f32_f16_sdwa v161, v152 dst_sel:DWORD dst_unused:UNUSED_PAD src0_sel:WORD_1
	v_cvt_f32_f16_e32 v180, v153
	v_cvt_f32_f16_sdwa v181, v153 dst_sel:DWORD dst_unused:UNUSED_PAD src0_sel:WORD_1
	v_cvt_f32_f16_e32 v182, v154
	v_cvt_f32_f16_sdwa v183, v154 dst_sel:DWORD dst_unused:UNUSED_PAD src0_sel:WORD_1
	v_cvt_f32_f16_e32 v184, v155
	v_cvt_f32_f16_sdwa v185, v155 dst_sel:DWORD dst_unused:UNUSED_PAD src0_sel:WORD_1
	v_pk_add_f32 v[22:23], v[160:161], v[22:23]
	v_pk_add_f32 v[24:25], v[180:181], v[24:25]
	v_pk_add_f32 v[18:19], v[182:183], v[18:19]
	v_pk_add_f32 v[20:21], v[184:185], v[20:21]
	v_cvt_pk_f16_f32 v21, v20, v21
	v_cvt_pk_f16_f32 v20, v18, v19
	v_cvt_pk_f16_f32 v19, v24, v25
	v_cvt_pk_f16_f32 v18, v22, v23
	global_store_dwordx4 v[232:233], v[18:21], off offset:256
	s_waitcnt vmcnt(15)
	v_cvt_f32_f16_e32 v160, v172
	v_cvt_f32_f16_sdwa v161, v172 dst_sel:DWORD dst_unused:UNUSED_PAD src0_sel:WORD_1
	v_cvt_f32_f16_e32 v180, v173
	v_cvt_f32_f16_sdwa v181, v173 dst_sel:DWORD dst_unused:UNUSED_PAD src0_sel:WORD_1
	v_cvt_f32_f16_e32 v182, v174
	v_cvt_f32_f16_sdwa v183, v174 dst_sel:DWORD dst_unused:UNUSED_PAD src0_sel:WORD_1
	v_cvt_f32_f16_e32 v184, v175
	v_cvt_f32_f16_sdwa v185, v175 dst_sel:DWORD dst_unused:UNUSED_PAD src0_sel:WORD_1
	v_pk_add_f32 v[14:15], v[160:161], v[14:15]
	v_pk_add_f32 v[16:17], v[180:181], v[16:17]
	v_pk_add_f32 v[10:11], v[182:183], v[10:11]
	v_pk_add_f32 v[12:13], v[184:185], v[12:13]
	v_cvt_pk_f16_f32 v13, v12, v13
	v_cvt_pk_f16_f32 v12, v10, v11
	v_cvt_pk_f16_f32 v11, v16, v17
	v_cvt_pk_f16_f32 v10, v14, v15
	global_store_dwordx4 v[234:235], v[10:13], off
	s_waitcnt vmcnt(15)
	v_cvt_f32_f16_e32 v160, v176
	v_cvt_f32_f16_sdwa v161, v176 dst_sel:DWORD dst_unused:UNUSED_PAD src0_sel:WORD_1
	v_cvt_f32_f16_e32 v180, v177
	v_cvt_f32_f16_sdwa v181, v177 dst_sel:DWORD dst_unused:UNUSED_PAD src0_sel:WORD_1
	v_cvt_f32_f16_e32 v182, v178
	v_cvt_f32_f16_sdwa v183, v178 dst_sel:DWORD dst_unused:UNUSED_PAD src0_sel:WORD_1
	v_cvt_f32_f16_e32 v184, v179
	v_cvt_f32_f16_sdwa v185, v179 dst_sel:DWORD dst_unused:UNUSED_PAD src0_sel:WORD_1
	v_pk_add_f32 v[6:7], v[160:161], v[6:7]
	v_pk_add_f32 v[8:9], v[180:181], v[8:9]
	v_pk_add_f32 v[2:3], v[182:183], v[2:3]
	v_pk_add_f32 v[4:5], v[184:185], v[4:5]
	v_cvt_pk_f16_f32 v5, v4, v5
	v_cvt_pk_f16_f32 v4, v2, v3
	v_cvt_pk_f16_f32 v3, v8, v9
	v_cvt_pk_f16_f32 v2, v6, v7
	global_store_dwordx4 v[234:235], v[2:5], off offset:256
	s_mov_b64 s[0:1], -1
	s_andn2_b64 vcc, exec, s[2:3]
	s_cbranch_vccnz .LBB0_987
	s_andn2_b64 vcc, exec, s[6:7]
	s_cbranch_vccnz .LBB0_986
	s_barrier
	s_branch .LBB0_986

.LBB0_1237:
	ds_read_b128 v[146:149], v164
	ds_read_b128 v[150:153], v164 offset:1024
	ds_read_b128 v[154:157], v164 offset:2048
	ds_read_b128 v[158:161], v164 offset:3072
	ds_read_b128 v[168:171], v165
	ds_read_b128 v[172:175], v165 offset:1024
	ds_read_b128 v[176:179], v165 offset:2048
	ds_read_b128 v[180:183], v165 offset:3072
	s_add_u32 s34, s76, 0xffea0080
	s_addc_u32 s35, s77, -1
	s_cmpk_eq_i32 s52, 0x54
	s_cselect_b32 s85, s5, s35
	s_cselect_b32 s84, s4, s34
	s_cselect_b32 s35, s83, s1
	s_cselect_b32 s34, s82, s0
	v_lshl_add_u64 v[218:219], s[76:77], 0, v[138:139]
	s_add_i32 m0, s33, 0xc000
	ds_read_b128 v[184:187], v166
	ds_read_b128 v[188:191], v166 offset:1024
	ds_read_b128 v[192:195], v166 offset:2048
	ds_read_b128 v[196:199], v166 offset:3072
	ds_read_b128 v[200:203], v166 offset:4096
	ds_read_b128 v[204:207], v166 offset:5120
	ds_read_b128 v[208:211], v166 offset:6144
	ds_read_b128 v[212:215], v166 offset:7168
	global_load_lds_dwordx4 v[218:219], off
	v_lshl_add_u64 v[218:219], s[76:77], 0, v[140:141]
	s_add_i32 m0, s33, 0xe000
	s_nop 0
	global_load_lds_dwordx4 v[218:219], off
	s_waitcnt vmcnt(8)
	s_waitcnt lgkmcnt(0)
	s_barrier
	s_setprio 1
	s_waitcnt lgkmcnt(0)
	v_mfma_f32_16x16x32_bf16 v[126:129], v[146:149], v[184:187], v[126:129]
	v_mfma_f32_16x16x32_bf16 v[122:125], v[154:157], v[184:187], v[122:125]
	v_mfma_f32_16x16x32_bf16 v[110:113], v[146:149], v[192:195], v[110:113]
	v_mfma_f32_16x16x32_bf16 v[106:109], v[154:157], v[192:195], v[106:109]
	v_mfma_f32_16x16x32_bf16 v[94:97], v[146:149], v[200:203], v[94:97]
	v_mfma_f32_16x16x32_bf16 v[90:93], v[154:157], v[200:203], v[90:93]
	v_mfma_f32_16x16x32_bf16 v[78:81], v[146:149], v[208:211], v[78:81]
	v_mfma_f32_16x16x32_bf16 v[74:77], v[154:157], v[208:211], v[74:77]
	v_mfma_f32_16x16x32_bf16 v[126:129], v[150:153], v[188:191], v[126:129]
	v_mfma_f32_16x16x32_bf16 v[122:125], v[158:161], v[188:191], v[122:125]
	v_mfma_f32_16x16x32_bf16 v[110:113], v[150:153], v[196:199], v[110:113]
	v_mfma_f32_16x16x32_bf16 v[106:109], v[158:161], v[196:199], v[106:109]
	v_mfma_f32_16x16x32_bf16 v[94:97], v[150:153], v[204:207], v[94:97]
	v_mfma_f32_16x16x32_bf16 v[90:93], v[158:161], v[204:207], v[90:93]
	v_mfma_f32_16x16x32_bf16 v[78:81], v[150:153], v[212:215], v[78:81]
	v_mfma_f32_16x16x32_bf16 v[74:77], v[158:161], v[212:215], v[74:77]
	s_setprio 0
	s_setprio 1
	v_mfma_f32_16x16x32_bf16 v[118:121], v[168:171], v[184:187], v[118:121]
	v_mfma_f32_16x16x32_bf16 v[114:117], v[176:179], v[184:187], v[114:117]
	v_mfma_f32_16x16x32_bf16 v[102:105], v[168:171], v[192:195], v[102:105]
	v_mfma_f32_16x16x32_bf16 v[98:101], v[176:179], v[192:195], v[98:101]
	v_mfma_f32_16x16x32_bf16 v[86:89], v[168:171], v[200:203], v[86:89]
	v_mfma_f32_16x16x32_bf16 v[82:85], v[176:179], v[200:203], v[82:85]
	v_mfma_f32_16x16x32_bf16 v[70:73], v[168:171], v[208:211], v[70:73]
	v_mfma_f32_16x16x32_bf16 v[66:69], v[176:179], v[208:211], v[66:69]
	v_mfma_f32_16x16x32_bf16 v[118:121], v[172:175], v[188:191], v[118:121]
	v_mfma_f32_16x16x32_bf16 v[114:117], v[180:183], v[188:191], v[114:117]
	v_mfma_f32_16x16x32_bf16 v[102:105], v[172:175], v[196:199], v[102:105]
	v_mfma_f32_16x16x32_bf16 v[98:101], v[180:183], v[196:199], v[98:101]
	v_mfma_f32_16x16x32_bf16 v[86:89], v[172:175], v[204:207], v[86:89]
	v_mfma_f32_16x16x32_bf16 v[82:85], v[180:183], v[204:207], v[82:85]
	v_mfma_f32_16x16x32_bf16 v[70:73], v[172:175], v[212:215], v[70:73]
	v_mfma_f32_16x16x32_bf16 v[66:69], v[180:183], v[212:215], v[66:69]
	s_setprio 0
	s_barrier
	s_add_i32 s53, s71, s31
	v_lshl_add_u64 v[218:219], s[34:35], 0, v[132:133]
	s_mov_b32 m0, s53
	ds_read_b128 v[184:187], v166 offset:16384
	ds_read_b128 v[188:191], v166 offset:17408
	ds_read_b128 v[192:195], v166 offset:18432
	ds_read_b128 v[196:199], v166 offset:19456
	ds_read_b128 v[200:203], v166 offset:20480
	ds_read_b128 v[204:207], v166 offset:21504
	ds_read_b128 v[208:211], v166 offset:22528
	ds_read_b128 v[212:215], v166 offset:23552
	global_load_lds_dwordx4 v[218:219], off
	s_add_i32 m0, s53, 0x2000
	s_add_u32 s54, s34, 0x160000
	v_lshl_add_u64 v[220:221], s[34:35], 0, v[136:137]
	s_addc_u32 s55, s35, 0
	s_add_i32 s53, s72, s31
	global_load_lds_dwordx4 v[220:221], off
	v_lshl_add_u64 v[222:223], s[54:55], 0, v[132:133]
	s_mov_b32 m0, s53
	v_lshl_add_u64 v[224:225], s[84:85], 0, v[134:135]
	global_load_lds_dwordx4 v[222:223], off
	v_lshl_add_u64 v[222:223], s[54:55], 0, v[136:137]
	s_add_i32 m0, s53, 0x2000
	s_nop 0
	global_load_lds_dwordx4 v[222:223], off
	v_lshl_add_u64 v[222:223], s[84:85], 0, v[130:131]
	s_mov_b32 m0, s33
	s_nop 0
	global_load_lds_dwordx4 v[222:223], off
	s_mov_b32 m0, s56
	s_nop 0
	global_load_lds_dwordx4 v[224:225], off
	s_waitcnt vmcnt(8)
	s_waitcnt lgkmcnt(0)
	s_barrier
	s_setprio 1
	s_waitcnt lgkmcnt(0)
	v_mfma_f32_16x16x32_bf16 v[62:65], v[146:149], v[184:187], v[62:65]
	v_mfma_f32_16x16x32_bf16 v[58:61], v[154:157], v[184:187], v[58:61]
	v_mfma_f32_16x16x32_bf16 v[46:49], v[146:149], v[192:195], v[46:49]
	v_mfma_f32_16x16x32_bf16 v[42:45], v[154:157], v[192:195], v[42:45]
	v_mfma_f32_16x16x32_bf16 v[30:33], v[146:149], v[200:203], v[30:33]
	v_mfma_f32_16x16x32_bf16 v[26:29], v[154:157], v[200:203], v[26:29]
	v_mfma_f32_16x16x32_bf16 v[14:17], v[146:149], v[208:211], v[14:17]
	v_mfma_f32_16x16x32_bf16 v[10:13], v[154:157], v[208:211], v[10:13]
	v_mfma_f32_16x16x32_bf16 v[62:65], v[150:153], v[188:191], v[62:65]
	v_mfma_f32_16x16x32_bf16 v[58:61], v[158:161], v[188:191], v[58:61]
	v_mfma_f32_16x16x32_bf16 v[46:49], v[150:153], v[196:199], v[46:49]
	v_mfma_f32_16x16x32_bf16 v[42:45], v[158:161], v[196:199], v[42:45]
	v_mfma_f32_16x16x32_bf16 v[30:33], v[150:153], v[204:207], v[30:33]
	v_mfma_f32_16x16x32_bf16 v[26:29], v[158:161], v[204:207], v[26:29]
	v_mfma_f32_16x16x32_bf16 v[14:17], v[150:153], v[212:215], v[14:17]
	v_mfma_f32_16x16x32_bf16 v[10:13], v[158:161], v[212:215], v[10:13]
	s_setprio 0
	s_setprio 1
	v_mfma_f32_16x16x32_bf16 v[54:57], v[168:171], v[184:187], v[54:57]
	v_mfma_f32_16x16x32_bf16 v[50:53], v[176:179], v[184:187], v[50:53]
	v_mfma_f32_16x16x32_bf16 v[38:41], v[168:171], v[192:195], v[38:41]
	v_mfma_f32_16x16x32_bf16 v[34:37], v[176:179], v[192:195], v[34:37]
	v_mfma_f32_16x16x32_bf16 v[22:25], v[168:171], v[200:203], v[22:25]
	v_mfma_f32_16x16x32_bf16 v[18:21], v[176:179], v[200:203], v[18:21]
	v_mfma_f32_16x16x32_bf16 v[6:9], v[168:171], v[208:211], v[6:9]
	v_mfma_f32_16x16x32_bf16 v[2:5], v[176:179], v[208:211], v[2:5]
	v_mfma_f32_16x16x32_bf16 v[54:57], v[172:175], v[188:191], v[54:57]
	v_mfma_f32_16x16x32_bf16 v[50:53], v[180:183], v[188:191], v[50:53]
	v_mfma_f32_16x16x32_bf16 v[38:41], v[172:175], v[196:199], v[38:41]
	v_mfma_f32_16x16x32_bf16 v[34:37], v[180:183], v[196:199], v[34:37]
	v_mfma_f32_16x16x32_bf16 v[22:25], v[172:175], v[204:207], v[22:25]
	v_mfma_f32_16x16x32_bf16 v[18:21], v[180:183], v[204:207], v[18:21]
	v_mfma_f32_16x16x32_bf16 v[6:9], v[172:175], v[212:215], v[6:9]
	v_mfma_f32_16x16x32_bf16 v[2:5], v[180:183], v[212:215], v[2:5]
	s_setprio 0
	s_barrier
	s_add_i32 s53, 0, 0x18000
	s_add_i32 s62, 0, 0x1c000
	v_add_u32_e32 v158, s53, v162
	v_add_u32_e32 v167, s62, v162
	ds_read_b128 v[146:149], v158
	ds_read_b128 v[150:153], v158 offset:1024
	ds_read_b128 v[154:157], v158 offset:2048
	ds_read_b128 v[158:161], v158 offset:3072
	ds_read_b128 v[168:171], v167
	ds_read_b128 v[172:175], v167 offset:1024
	ds_read_b128 v[176:179], v167 offset:2048
	ds_read_b128 v[180:183], v167 offset:3072
	s_add_u32 s54, s84, 0x160000
	s_addc_u32 s55, s85, 0
	s_mov_b32 m0, s57
	v_lshl_add_u64 v[226:227], s[54:55], 0, v[130:131]
	ds_read_b128 v[184:187], v166 offset:32768
	ds_read_b128 v[188:191], v166 offset:33792
	ds_read_b128 v[192:195], v166 offset:34816
	ds_read_b128 v[196:199], v166 offset:35840
	ds_read_b128 v[200:203], v166 offset:36864
	ds_read_b128 v[204:207], v166 offset:37888
	ds_read_b128 v[208:211], v166 offset:38912
	ds_read_b128 v[212:215], v166 offset:39936
	global_load_lds_dwordx4 v[226:227], off
	v_lshl_add_u64 v[226:227], s[54:55], 0, v[134:135]
	s_mov_b32 m0, s58
	s_nop 0
	global_load_lds_dwordx4 v[226:227], off
	s_waitcnt vmcnt(8)
	s_waitcnt lgkmcnt(0)
	s_barrier
	s_setprio 1
	s_waitcnt lgkmcnt(0)
	v_mfma_f32_16x16x32_bf16 v[126:129], v[146:149], v[184:187], v[126:129]
	v_mfma_f32_16x16x32_bf16 v[122:125], v[154:157], v[184:187], v[122:125]
	v_mfma_f32_16x16x32_bf16 v[110:113], v[146:149], v[192:195], v[110:113]
	v_mfma_f32_16x16x32_bf16 v[106:109], v[154:157], v[192:195], v[106:109]
	v_mfma_f32_16x16x32_bf16 v[94:97], v[146:149], v[200:203], v[94:97]
	v_mfma_f32_16x16x32_bf16 v[90:93], v[154:157], v[200:203], v[90:93]
	v_mfma_f32_16x16x32_bf16 v[78:81], v[146:149], v[208:211], v[78:81]
	v_mfma_f32_16x16x32_bf16 v[74:77], v[154:157], v[208:211], v[74:77]
	v_mfma_f32_16x16x32_bf16 v[126:129], v[150:153], v[188:191], v[126:129]
	v_mfma_f32_16x16x32_bf16 v[122:125], v[158:161], v[188:191], v[122:125]
	v_mfma_f32_16x16x32_bf16 v[110:113], v[150:153], v[196:199], v[110:113]
	v_mfma_f32_16x16x32_bf16 v[106:109], v[158:161], v[196:199], v[106:109]
	v_mfma_f32_16x16x32_bf16 v[94:97], v[150:153], v[204:207], v[94:97]
	v_mfma_f32_16x16x32_bf16 v[90:93], v[158:161], v[204:207], v[90:93]
	v_mfma_f32_16x16x32_bf16 v[78:81], v[150:153], v[212:215], v[78:81]
	v_mfma_f32_16x16x32_bf16 v[74:77], v[158:161], v[212:215], v[74:77]
	s_setprio 0
	s_setprio 1
	v_mfma_f32_16x16x32_bf16 v[118:121], v[168:171], v[184:187], v[118:121]
	v_mfma_f32_16x16x32_bf16 v[114:117], v[176:179], v[184:187], v[114:117]
	v_mfma_f32_16x16x32_bf16 v[102:105], v[168:171], v[192:195], v[102:105]
	v_mfma_f32_16x16x32_bf16 v[98:101], v[176:179], v[192:195], v[98:101]
	v_mfma_f32_16x16x32_bf16 v[86:89], v[168:171], v[200:203], v[86:89]
	v_mfma_f32_16x16x32_bf16 v[82:85], v[176:179], v[200:203], v[82:85]
	v_mfma_f32_16x16x32_bf16 v[70:73], v[168:171], v[208:211], v[70:73]
	v_mfma_f32_16x16x32_bf16 v[66:69], v[176:179], v[208:211], v[66:69]
	v_mfma_f32_16x16x32_bf16 v[118:121], v[172:175], v[188:191], v[118:121]
	v_mfma_f32_16x16x32_bf16 v[114:117], v[180:183], v[188:191], v[114:117]
	v_mfma_f32_16x16x32_bf16 v[102:105], v[172:175], v[196:199], v[102:105]
	v_mfma_f32_16x16x32_bf16 v[98:101], v[180:183], v[196:199], v[98:101]
	v_mfma_f32_16x16x32_bf16 v[86:89], v[172:175], v[204:207], v[86:89]
	v_mfma_f32_16x16x32_bf16 v[82:85], v[180:183], v[204:207], v[82:85]
	v_mfma_f32_16x16x32_bf16 v[70:73], v[172:175], v[212:215], v[70:73]
	v_mfma_f32_16x16x32_bf16 v[66:69], v[180:183], v[212:215], v[66:69]
	s_setprio 0
	s_barrier
	s_add_i32 s53, s53, s31
	v_lshl_add_u64 v[218:219], v[218:219], 0, s[78:79]
	s_mov_b32 m0, s53
	ds_read_b128 v[184:187], v166 offset:49152
	ds_read_b128 v[188:191], v166 offset:50176
	ds_read_b128 v[192:195], v166 offset:51200
	ds_read_b128 v[196:199], v166 offset:52224
	ds_read_b128 v[200:203], v166 offset:53248
	ds_read_b128 v[204:207], v166 offset:54272
	ds_read_b128 v[208:211], v166 offset:55296
	ds_read_b128 v[212:215], v166 offset:56320
	global_load_lds_dwordx4 v[218:219], off
	s_add_i32 m0, s53, 0x2000
	s_add_u32 s34, s34, 0x160080
	v_lshl_add_u64 v[218:219], v[220:221], 0, s[78:79]
	s_addc_u32 s35, s35, 0
	s_add_i32 s53, s62, s31
	global_load_lds_dwordx4 v[218:219], off
	v_lshl_add_u64 v[218:219], s[34:35], 0, v[132:133]
	s_mov_b32 m0, s53
	s_nop 0
	global_load_lds_dwordx4 v[218:219], off
	v_lshl_add_u64 v[218:219], s[34:35], 0, v[136:137]
	s_add_i32 m0, s53, 0x2000
	s_nop 0
	global_load_lds_dwordx4 v[218:219], off
	v_lshl_add_u64 v[218:219], v[222:223], 0, s[78:79]
	s_mov_b32 m0, s60
	s_nop 0
	global_load_lds_dwordx4 v[218:219], off
	v_lshl_add_u64 v[218:219], v[224:225], 0, s[78:79]
	s_mov_b32 m0, s61
	s_nop 0
	global_load_lds_dwordx4 v[218:219], off
	s_waitcnt vmcnt(8)
	s_waitcnt lgkmcnt(0)
	s_barrier
	s_setprio 1
	s_waitcnt lgkmcnt(0)
	v_mfma_f32_16x16x32_bf16 v[62:65], v[146:149], v[184:187], v[62:65]
	v_mfma_f32_16x16x32_bf16 v[58:61], v[154:157], v[184:187], v[58:61]
	v_mfma_f32_16x16x32_bf16 v[46:49], v[146:149], v[192:195], v[46:49]
	v_mfma_f32_16x16x32_bf16 v[42:45], v[154:157], v[192:195], v[42:45]
	v_mfma_f32_16x16x32_bf16 v[30:33], v[146:149], v[200:203], v[30:33]
	v_mfma_f32_16x16x32_bf16 v[26:29], v[154:157], v[200:203], v[26:29]
	v_mfma_f32_16x16x32_bf16 v[14:17], v[146:149], v[208:211], v[14:17]
	v_mfma_f32_16x16x32_bf16 v[10:13], v[154:157], v[208:211], v[10:13]
	v_mfma_f32_16x16x32_bf16 v[62:65], v[150:153], v[188:191], v[62:65]
	v_mfma_f32_16x16x32_bf16 v[58:61], v[158:161], v[188:191], v[58:61]
	v_mfma_f32_16x16x32_bf16 v[46:49], v[150:153], v[196:199], v[46:49]
	v_mfma_f32_16x16x32_bf16 v[42:45], v[158:161], v[196:199], v[42:45]
	v_mfma_f32_16x16x32_bf16 v[30:33], v[150:153], v[204:207], v[30:33]
	v_mfma_f32_16x16x32_bf16 v[26:29], v[158:161], v[204:207], v[26:29]
	v_mfma_f32_16x16x32_bf16 v[14:17], v[150:153], v[212:215], v[14:17]
	v_mfma_f32_16x16x32_bf16 v[10:13], v[158:161], v[212:215], v[10:13]
	s_setprio 0
	s_setprio 1
	v_mfma_f32_16x16x32_bf16 v[54:57], v[168:171], v[184:187], v[54:57]
	v_mfma_f32_16x16x32_bf16 v[50:53], v[176:179], v[184:187], v[50:53]
	v_mfma_f32_16x16x32_bf16 v[38:41], v[168:171], v[192:195], v[38:41]
	v_mfma_f32_16x16x32_bf16 v[34:37], v[176:179], v[192:195], v[34:37]
	v_mfma_f32_16x16x32_bf16 v[22:25], v[168:171], v[200:203], v[22:25]
	v_mfma_f32_16x16x32_bf16 v[18:21], v[176:179], v[200:203], v[18:21]
	v_mfma_f32_16x16x32_bf16 v[6:9], v[168:171], v[208:211], v[6:9]
	v_mfma_f32_16x16x32_bf16 v[2:5], v[176:179], v[208:211], v[2:5]
	v_mfma_f32_16x16x32_bf16 v[54:57], v[172:175], v[188:191], v[54:57]
	v_mfma_f32_16x16x32_bf16 v[50:53], v[180:183], v[188:191], v[50:53]
	v_mfma_f32_16x16x32_bf16 v[38:41], v[172:175], v[196:199], v[38:41]
	v_mfma_f32_16x16x32_bf16 v[34:37], v[180:183], v[196:199], v[34:37]
	v_mfma_f32_16x16x32_bf16 v[22:25], v[172:175], v[204:207], v[22:25]
	v_mfma_f32_16x16x32_bf16 v[18:21], v[180:183], v[204:207], v[18:21]
	v_mfma_f32_16x16x32_bf16 v[6:9], v[172:175], v[212:215], v[6:9]
	v_mfma_f32_16x16x32_bf16 v[2:5], v[180:183], v[212:215], v[2:5]
	s_setprio 0
	s_barrier
	s_add_i32 s52, s52, 2
	s_add_u32 s76, s76, 0x100
	s_addc_u32 s77, s77, 0
	s_add_u32 s0, s0, 0x100
	s_addc_u32 s1, s1, 0
	s_cmpk_gt_u32 s52, 0x53
	s_cbranch_scc0 .LBB0_1237
	v_lshl_add_u32 v234, s75, 8, v1
	v_lshl_or_b32 v236, s86, 8, v163
	v_ashrrev_i32_e32 v235, 31, v234
	v_ashrrev_i32_e32 v237, 31, v236
	v_lshlrev_b64 v[228:229], 12, v[234:235]
	v_lshl_add_u64 v[228:229], s[64:65], 0, v[228:229]
	v_lshlrev_b64 v[236:237], 1, v[236:237]
	v_lshl_add_u64 v[228:229], v[228:229], 0, v[236:237]
	v_mov_b32_e32 v231, 0
	ds_read_b128 v[146:149], v164
	ds_read_b128 v[150:153], v164 offset:1024
	ds_read_b128 v[154:157], v164 offset:2048
	ds_read_b128 v[158:161], v164 offset:3072
	ds_read_b128 v[168:171], v165
	ds_read_b128 v[172:175], v165 offset:1024
	ds_read_b128 v[176:179], v165 offset:2048
	ds_read_b128 v[180:183], v165 offset:3072
	s_add_u32 s34, s76, 0xffea0080
	s_addc_u32 s35, s77, -1
	s_cmpk_eq_i32 s52, 0x54
	s_cselect_b32 s85, s5, s35
	s_cselect_b32 s84, s4, s34
	s_cselect_b32 s35, s83, s1
	s_cselect_b32 s34, s82, s0
	v_lshl_add_u64 v[218:219], s[76:77], 0, v[138:139]
	s_add_i32 m0, s33, 0xc000
	ds_read_b128 v[184:187], v166
	ds_read_b128 v[188:191], v166 offset:1024
	ds_read_b128 v[192:195], v166 offset:2048
	ds_read_b128 v[196:199], v166 offset:3072
	ds_read_b128 v[200:203], v166 offset:4096
	ds_read_b128 v[204:207], v166 offset:5120
	ds_read_b128 v[208:211], v166 offset:6144
	ds_read_b128 v[212:215], v166 offset:7168
	global_load_lds_dwordx4 v[218:219], off
	v_lshl_add_u64 v[218:219], s[76:77], 0, v[140:141]
	s_add_i32 m0, s33, 0xe000
	s_nop 0
	global_load_lds_dwordx4 v[218:219], off
	s_waitcnt vmcnt(8)
	s_waitcnt lgkmcnt(0)
	s_barrier
	s_setprio 1
	s_waitcnt lgkmcnt(0)
	v_mfma_f32_16x16x32_bf16 v[126:129], v[146:149], v[184:187], v[126:129]
	v_mfma_f32_16x16x32_bf16 v[122:125], v[154:157], v[184:187], v[122:125]
	v_mfma_f32_16x16x32_bf16 v[110:113], v[146:149], v[192:195], v[110:113]
	v_mfma_f32_16x16x32_bf16 v[106:109], v[154:157], v[192:195], v[106:109]
	v_mfma_f32_16x16x32_bf16 v[94:97], v[146:149], v[200:203], v[94:97]
	v_mfma_f32_16x16x32_bf16 v[90:93], v[154:157], v[200:203], v[90:93]
	v_mfma_f32_16x16x32_bf16 v[78:81], v[146:149], v[208:211], v[78:81]
	v_mfma_f32_16x16x32_bf16 v[74:77], v[154:157], v[208:211], v[74:77]
	v_mfma_f32_16x16x32_bf16 v[126:129], v[150:153], v[188:191], v[126:129]
	v_mfma_f32_16x16x32_bf16 v[122:125], v[158:161], v[188:191], v[122:125]
	v_mfma_f32_16x16x32_bf16 v[110:113], v[150:153], v[196:199], v[110:113]
	v_mfma_f32_16x16x32_bf16 v[106:109], v[158:161], v[196:199], v[106:109]
	v_mfma_f32_16x16x32_bf16 v[94:97], v[150:153], v[204:207], v[94:97]
	v_mfma_f32_16x16x32_bf16 v[90:93], v[158:161], v[204:207], v[90:93]
	v_mfma_f32_16x16x32_bf16 v[78:81], v[150:153], v[212:215], v[78:81]
	v_mfma_f32_16x16x32_bf16 v[74:77], v[158:161], v[212:215], v[74:77]
	s_setprio 0
	s_setprio 1
	v_mfma_f32_16x16x32_bf16 v[118:121], v[168:171], v[184:187], v[118:121]
	v_mfma_f32_16x16x32_bf16 v[114:117], v[176:179], v[184:187], v[114:117]
	v_mfma_f32_16x16x32_bf16 v[102:105], v[168:171], v[192:195], v[102:105]
	v_mfma_f32_16x16x32_bf16 v[98:101], v[176:179], v[192:195], v[98:101]
	v_mfma_f32_16x16x32_bf16 v[86:89], v[168:171], v[200:203], v[86:89]
	v_mfma_f32_16x16x32_bf16 v[82:85], v[176:179], v[200:203], v[82:85]
	v_mfma_f32_16x16x32_bf16 v[70:73], v[168:171], v[208:211], v[70:73]
	v_mfma_f32_16x16x32_bf16 v[66:69], v[176:179], v[208:211], v[66:69]
	v_mfma_f32_16x16x32_bf16 v[118:121], v[172:175], v[188:191], v[118:121]
	v_mfma_f32_16x16x32_bf16 v[114:117], v[180:183], v[188:191], v[114:117]
	v_mfma_f32_16x16x32_bf16 v[102:105], v[172:175], v[196:199], v[102:105]
	v_mfma_f32_16x16x32_bf16 v[98:101], v[180:183], v[196:199], v[98:101]
	v_mfma_f32_16x16x32_bf16 v[86:89], v[172:175], v[204:207], v[86:89]
	v_mfma_f32_16x16x32_bf16 v[82:85], v[180:183], v[204:207], v[82:85]
	v_mfma_f32_16x16x32_bf16 v[70:73], v[172:175], v[212:215], v[70:73]
	v_mfma_f32_16x16x32_bf16 v[66:69], v[180:183], v[212:215], v[66:69]
	s_setprio 0
	s_barrier
	s_add_i32 s53, s71, s31
	v_lshl_add_u64 v[218:219], s[34:35], 0, v[132:133]
	s_mov_b32 m0, s53
	ds_read_b128 v[184:187], v166 offset:16384
	ds_read_b128 v[188:191], v166 offset:17408
	ds_read_b128 v[192:195], v166 offset:18432
	ds_read_b128 v[196:199], v166 offset:19456
	ds_read_b128 v[200:203], v166 offset:20480
	ds_read_b128 v[204:207], v166 offset:21504
	ds_read_b128 v[208:211], v166 offset:22528
	ds_read_b128 v[212:215], v166 offset:23552
	v_mov_b32_e32 v230, 0x0
	v_lshl_add_u64 v[232:233], v[230:231], 0, v[228:229]
	global_load_lds_dwordx4 v[232:233], off
	s_add_i32 m0, s53, 0x2000
	s_add_u32 s54, s34, 0x160000
	v_lshl_add_u64 v[220:221], s[34:35], 0, v[136:137]
	s_addc_u32 s55, s35, 0
	s_add_i32 s53, s72, s31
	v_mov_b32_e32 v230, 0x100
	v_lshl_add_u64 v[232:233], v[230:231], 0, v[228:229]
	global_load_lds_dwordx4 v[232:233], off
	v_lshl_add_u64 v[222:223], s[54:55], 0, v[132:133]
	s_mov_b32 m0, s53
	v_lshl_add_u64 v[224:225], s[84:85], 0, v[134:135]
	v_mov_b32_e32 v230, 0x10000
	v_lshl_add_u64 v[232:233], v[230:231], 0, v[228:229]
	global_load_lds_dwordx4 v[232:233], off
	v_lshl_add_u64 v[222:223], s[54:55], 0, v[136:137]
	s_add_i32 m0, s53, 0x2000
	s_nop 0
	v_mov_b32_e32 v230, 0x10100
	v_lshl_add_u64 v[232:233], v[230:231], 0, v[228:229]
	global_load_lds_dwordx4 v[232:233], off
	v_lshl_add_u64 v[222:223], s[84:85], 0, v[130:131]
	s_mov_b32 m0, s33
	s_nop 0
	v_mov_b32_e32 v230, 0x20000
	v_lshl_add_u64 v[232:233], v[230:231], 0, v[228:229]
	global_load_lds_dwordx4 v[232:233], off
	s_mov_b32 m0, s56
	s_nop 0
	v_mov_b32_e32 v230, 0x20100
	v_lshl_add_u64 v[232:233], v[230:231], 0, v[228:229]
	global_load_lds_dwordx4 v[232:233], off
	s_waitcnt vmcnt(8)
	s_waitcnt lgkmcnt(0)
	s_barrier
	s_setprio 1
	s_waitcnt lgkmcnt(0)
	v_mfma_f32_16x16x32_bf16 v[62:65], v[146:149], v[184:187], v[62:65]
	v_mfma_f32_16x16x32_bf16 v[58:61], v[154:157], v[184:187], v[58:61]
	v_mfma_f32_16x16x32_bf16 v[46:49], v[146:149], v[192:195], v[46:49]
	v_mfma_f32_16x16x32_bf16 v[42:45], v[154:157], v[192:195], v[42:45]
	v_mfma_f32_16x16x32_bf16 v[30:33], v[146:149], v[200:203], v[30:33]
	v_mfma_f32_16x16x32_bf16 v[26:29], v[154:157], v[200:203], v[26:29]
	v_mfma_f32_16x16x32_bf16 v[14:17], v[146:149], v[208:211], v[14:17]
	v_mfma_f32_16x16x32_bf16 v[10:13], v[154:157], v[208:211], v[10:13]
	v_mfma_f32_16x16x32_bf16 v[62:65], v[150:153], v[188:191], v[62:65]
	v_mfma_f32_16x16x32_bf16 v[58:61], v[158:161], v[188:191], v[58:61]
	v_mfma_f32_16x16x32_bf16 v[46:49], v[150:153], v[196:199], v[46:49]
	v_mfma_f32_16x16x32_bf16 v[42:45], v[158:161], v[196:199], v[42:45]
	v_mfma_f32_16x16x32_bf16 v[30:33], v[150:153], v[204:207], v[30:33]
	v_mfma_f32_16x16x32_bf16 v[26:29], v[158:161], v[204:207], v[26:29]
	v_mfma_f32_16x16x32_bf16 v[14:17], v[150:153], v[212:215], v[14:17]
	v_mfma_f32_16x16x32_bf16 v[10:13], v[158:161], v[212:215], v[10:13]
	s_setprio 0
	s_setprio 1
	v_mfma_f32_16x16x32_bf16 v[54:57], v[168:171], v[184:187], v[54:57]
	v_mfma_f32_16x16x32_bf16 v[50:53], v[176:179], v[184:187], v[50:53]
	v_mfma_f32_16x16x32_bf16 v[38:41], v[168:171], v[192:195], v[38:41]
	v_mfma_f32_16x16x32_bf16 v[34:37], v[176:179], v[192:195], v[34:37]
	v_mfma_f32_16x16x32_bf16 v[22:25], v[168:171], v[200:203], v[22:25]
	v_mfma_f32_16x16x32_bf16 v[18:21], v[176:179], v[200:203], v[18:21]
	v_mfma_f32_16x16x32_bf16 v[6:9], v[168:171], v[208:211], v[6:9]
	v_mfma_f32_16x16x32_bf16 v[2:5], v[176:179], v[208:211], v[2:5]
	v_mfma_f32_16x16x32_bf16 v[54:57], v[172:175], v[188:191], v[54:57]
	v_mfma_f32_16x16x32_bf16 v[50:53], v[180:183], v[188:191], v[50:53]
	v_mfma_f32_16x16x32_bf16 v[38:41], v[172:175], v[196:199], v[38:41]
	v_mfma_f32_16x16x32_bf16 v[34:37], v[180:183], v[196:199], v[34:37]
	v_mfma_f32_16x16x32_bf16 v[22:25], v[172:175], v[204:207], v[22:25]
	v_mfma_f32_16x16x32_bf16 v[18:21], v[180:183], v[204:207], v[18:21]
	v_mfma_f32_16x16x32_bf16 v[6:9], v[172:175], v[212:215], v[6:9]
	v_mfma_f32_16x16x32_bf16 v[2:5], v[180:183], v[212:215], v[2:5]
	s_setprio 0
	s_barrier
	s_add_i32 s53, 0, 0x18000
	s_add_i32 s62, 0, 0x1c000
	v_add_u32_e32 v158, s53, v162
	v_add_u32_e32 v167, s62, v162
	ds_read_b128 v[146:149], v158
	ds_read_b128 v[150:153], v158 offset:1024
	ds_read_b128 v[154:157], v158 offset:2048
	ds_read_b128 v[158:161], v158 offset:3072
	ds_read_b128 v[168:171], v167
	ds_read_b128 v[172:175], v167 offset:1024
	ds_read_b128 v[176:179], v167 offset:2048
	ds_read_b128 v[180:183], v167 offset:3072
	s_add_u32 s54, s84, 0x160000
	s_addc_u32 s55, s85, 0
	s_mov_b32 m0, s57
	v_lshl_add_u64 v[226:227], s[54:55], 0, v[130:131]
	ds_read_b128 v[184:187], v166 offset:32768
	ds_read_b128 v[188:191], v166 offset:33792
	ds_read_b128 v[192:195], v166 offset:34816
	ds_read_b128 v[196:199], v166 offset:35840
	ds_read_b128 v[200:203], v166 offset:36864
	ds_read_b128 v[204:207], v166 offset:37888
	ds_read_b128 v[208:211], v166 offset:38912
	ds_read_b128 v[212:215], v166 offset:39936
	v_mov_b32_e32 v230, 0x30000
	v_lshl_add_u64 v[232:233], v[230:231], 0, v[228:229]
	global_load_lds_dwordx4 v[232:233], off
	v_lshl_add_u64 v[226:227], s[54:55], 0, v[134:135]
	s_mov_b32 m0, s58
	s_nop 0
	v_mov_b32_e32 v230, 0x30100
	v_lshl_add_u64 v[232:233], v[230:231], 0, v[228:229]
	global_load_lds_dwordx4 v[232:233], off
	s_waitcnt vmcnt(8)
	s_waitcnt lgkmcnt(0)
	s_barrier
	s_setprio 1
	s_waitcnt lgkmcnt(0)
	v_mfma_f32_16x16x32_bf16 v[126:129], v[146:149], v[184:187], v[126:129]
	v_mfma_f32_16x16x32_bf16 v[122:125], v[154:157], v[184:187], v[122:125]
	v_mfma_f32_16x16x32_bf16 v[110:113], v[146:149], v[192:195], v[110:113]
	v_mfma_f32_16x16x32_bf16 v[106:109], v[154:157], v[192:195], v[106:109]
	v_mfma_f32_16x16x32_bf16 v[94:97], v[146:149], v[200:203], v[94:97]
	v_mfma_f32_16x16x32_bf16 v[90:93], v[154:157], v[200:203], v[90:93]
	v_mfma_f32_16x16x32_bf16 v[78:81], v[146:149], v[208:211], v[78:81]
	v_mfma_f32_16x16x32_bf16 v[74:77], v[154:157], v[208:211], v[74:77]
	v_mfma_f32_16x16x32_bf16 v[126:129], v[150:153], v[188:191], v[126:129]
	v_mfma_f32_16x16x32_bf16 v[122:125], v[158:161], v[188:191], v[122:125]
	v_mfma_f32_16x16x32_bf16 v[110:113], v[150:153], v[196:199], v[110:113]
	v_mfma_f32_16x16x32_bf16 v[106:109], v[158:161], v[196:199], v[106:109]
	v_mfma_f32_16x16x32_bf16 v[94:97], v[150:153], v[204:207], v[94:97]
	v_mfma_f32_16x16x32_bf16 v[90:93], v[158:161], v[204:207], v[90:93]
	v_mfma_f32_16x16x32_bf16 v[78:81], v[150:153], v[212:215], v[78:81]
	v_mfma_f32_16x16x32_bf16 v[74:77], v[158:161], v[212:215], v[74:77]
	s_setprio 0
	s_setprio 1
	v_mfma_f32_16x16x32_bf16 v[118:121], v[168:171], v[184:187], v[118:121]
	v_mfma_f32_16x16x32_bf16 v[114:117], v[176:179], v[184:187], v[114:117]
	v_mfma_f32_16x16x32_bf16 v[102:105], v[168:171], v[192:195], v[102:105]
	v_mfma_f32_16x16x32_bf16 v[98:101], v[176:179], v[192:195], v[98:101]
	v_mfma_f32_16x16x32_bf16 v[86:89], v[168:171], v[200:203], v[86:89]
	v_mfma_f32_16x16x32_bf16 v[82:85], v[176:179], v[200:203], v[82:85]
	v_mfma_f32_16x16x32_bf16 v[70:73], v[168:171], v[208:211], v[70:73]
	v_mfma_f32_16x16x32_bf16 v[66:69], v[176:179], v[208:211], v[66:69]
	v_mfma_f32_16x16x32_bf16 v[118:121], v[172:175], v[188:191], v[118:121]
	v_mfma_f32_16x16x32_bf16 v[114:117], v[180:183], v[188:191], v[114:117]
	v_mfma_f32_16x16x32_bf16 v[102:105], v[172:175], v[196:199], v[102:105]
	v_mfma_f32_16x16x32_bf16 v[98:101], v[180:183], v[196:199], v[98:101]
	v_mfma_f32_16x16x32_bf16 v[86:89], v[172:175], v[204:207], v[86:89]
	v_mfma_f32_16x16x32_bf16 v[82:85], v[180:183], v[204:207], v[82:85]
	v_mfma_f32_16x16x32_bf16 v[70:73], v[172:175], v[212:215], v[70:73]
	v_mfma_f32_16x16x32_bf16 v[66:69], v[180:183], v[212:215], v[66:69]
	s_setprio 0
	s_barrier
	s_add_i32 s53, s53, s31
	v_lshl_add_u64 v[218:219], v[218:219], 0, s[78:79]
	s_mov_b32 m0, s53
	ds_read_b128 v[184:187], v166 offset:49152
	ds_read_b128 v[188:191], v166 offset:50176
	ds_read_b128 v[192:195], v166 offset:51200
	ds_read_b128 v[196:199], v166 offset:52224
	ds_read_b128 v[200:203], v166 offset:53248
	ds_read_b128 v[204:207], v166 offset:54272
	ds_read_b128 v[208:211], v166 offset:55296
	ds_read_b128 v[212:215], v166 offset:56320
	v_mov_b32_e32 v230, 0x80000
	v_lshl_add_u64 v[232:233], v[230:231], 0, v[228:229]
	global_load_lds_dwordx4 v[232:233], off
	s_add_i32 m0, s53, 0x2000
	s_add_u32 s34, s34, 0x160080
	v_lshl_add_u64 v[218:219], v[220:221], 0, s[78:79]
	s_addc_u32 s35, s35, 0
	s_add_i32 s53, s62, s31
	v_mov_b32_e32 v230, 0x80100
	v_lshl_add_u64 v[232:233], v[230:231], 0, v[228:229]
	global_load_lds_dwordx4 v[232:233], off
	v_lshl_add_u64 v[218:219], s[34:35], 0, v[132:133]
	s_mov_b32 m0, s53
	s_nop 0
	v_mov_b32_e32 v230, 0x90000
	v_lshl_add_u64 v[232:233], v[230:231], 0, v[228:229]
	global_load_lds_dwordx4 v[232:233], off
	v_lshl_add_u64 v[218:219], s[34:35], 0, v[136:137]
	s_add_i32 m0, s53, 0x2000
	s_nop 0
	v_mov_b32_e32 v230, 0x90100
	v_lshl_add_u64 v[232:233], v[230:231], 0, v[228:229]
	global_load_lds_dwordx4 v[232:233], off
	v_lshl_add_u64 v[218:219], v[222:223], 0, s[78:79]
	s_mov_b32 m0, s60
	s_nop 0
	v_mov_b32_e32 v230, 0xa0000
	v_lshl_add_u64 v[232:233], v[230:231], 0, v[228:229]
	global_load_lds_dwordx4 v[232:233], off
	v_lshl_add_u64 v[218:219], v[224:225], 0, s[78:79]
	s_mov_b32 m0, s61
	s_nop 0
	v_mov_b32_e32 v230, 0xa0100
	v_lshl_add_u64 v[232:233], v[230:231], 0, v[228:229]
	global_load_lds_dwordx4 v[232:233], off
	s_waitcnt vmcnt(8)
	s_waitcnt lgkmcnt(0)
	s_barrier
	s_setprio 1
	s_waitcnt lgkmcnt(0)
	v_mfma_f32_16x16x32_bf16 v[62:65], v[146:149], v[184:187], v[62:65]
	v_mfma_f32_16x16x32_bf16 v[58:61], v[154:157], v[184:187], v[58:61]
	v_mfma_f32_16x16x32_bf16 v[46:49], v[146:149], v[192:195], v[46:49]
	v_mfma_f32_16x16x32_bf16 v[42:45], v[154:157], v[192:195], v[42:45]
	v_mfma_f32_16x16x32_bf16 v[30:33], v[146:149], v[200:203], v[30:33]
	v_mfma_f32_16x16x32_bf16 v[26:29], v[154:157], v[200:203], v[26:29]
	v_mfma_f32_16x16x32_bf16 v[14:17], v[146:149], v[208:211], v[14:17]
	v_mfma_f32_16x16x32_bf16 v[10:13], v[154:157], v[208:211], v[10:13]
	v_mfma_f32_16x16x32_bf16 v[62:65], v[150:153], v[188:191], v[62:65]
	v_mfma_f32_16x16x32_bf16 v[58:61], v[158:161], v[188:191], v[58:61]
	v_mfma_f32_16x16x32_bf16 v[46:49], v[150:153], v[196:199], v[46:49]
	v_mfma_f32_16x16x32_bf16 v[42:45], v[158:161], v[196:199], v[42:45]
	v_mfma_f32_16x16x32_bf16 v[30:33], v[150:153], v[204:207], v[30:33]
	v_mfma_f32_16x16x32_bf16 v[26:29], v[158:161], v[204:207], v[26:29]
	v_mfma_f32_16x16x32_bf16 v[14:17], v[150:153], v[212:215], v[14:17]
	v_mfma_f32_16x16x32_bf16 v[10:13], v[158:161], v[212:215], v[10:13]
	s_setprio 0
	s_setprio 1
	v_mfma_f32_16x16x32_bf16 v[54:57], v[168:171], v[184:187], v[54:57]
	v_mfma_f32_16x16x32_bf16 v[50:53], v[176:179], v[184:187], v[50:53]
	v_mfma_f32_16x16x32_bf16 v[38:41], v[168:171], v[192:195], v[38:41]
	v_mfma_f32_16x16x32_bf16 v[34:37], v[176:179], v[192:195], v[34:37]
	v_mfma_f32_16x16x32_bf16 v[22:25], v[168:171], v[200:203], v[22:25]
	v_mfma_f32_16x16x32_bf16 v[18:21], v[176:179], v[200:203], v[18:21]
	v_mfma_f32_16x16x32_bf16 v[6:9], v[168:171], v[208:211], v[6:9]
	v_mfma_f32_16x16x32_bf16 v[2:5], v[176:179], v[208:211], v[2:5]
	v_mfma_f32_16x16x32_bf16 v[54:57], v[172:175], v[188:191], v[54:57]
	v_mfma_f32_16x16x32_bf16 v[50:53], v[180:183], v[188:191], v[50:53]
	v_mfma_f32_16x16x32_bf16 v[38:41], v[172:175], v[196:199], v[38:41]
	v_mfma_f32_16x16x32_bf16 v[34:37], v[180:183], v[196:199], v[34:37]
	v_mfma_f32_16x16x32_bf16 v[22:25], v[172:175], v[204:207], v[22:25]
	v_mfma_f32_16x16x32_bf16 v[18:21], v[180:183], v[204:207], v[18:21]
	v_mfma_f32_16x16x32_bf16 v[6:9], v[172:175], v[212:215], v[6:9]
	v_mfma_f32_16x16x32_bf16 v[2:5], v[180:183], v[212:215], v[2:5]
	s_setprio 0
	s_barrier
	s_add_i32 s52, s52, 2
	s_add_u32 s76, s76, 0x100
	s_addc_u32 s77, s77, 0
	s_add_u32 s0, s0, 0x100
	s_addc_u32 s1, s1, 0
	s_and_b64 vcc, exec, s[80:81]
	s_cbranch_vccz .LBB0_1240
	s_barrier
.LBB0_1240:
	v_lshl_add_u32 v146, s75, 8, v1
	v_lshl_or_b32 v148, s86, 8, v163
	v_ashrrev_i32_e32 v147, 31, v146
	v_ashrrev_i32_e32 v149, 31, v148
	v_lshlrev_b64 v[150:151], 12, v[146:147]
	v_lshl_add_u64 v[150:151], s[64:65], 0, v[150:151]
	v_lshlrev_b64 v[148:149], 1, v[148:149]
	v_lshl_add_u64 v[150:151], v[150:151], 0, v[148:149]
	s_waitcnt vmcnt(0)
	v_mov_b32_e32 v237, 0
	v_mov_b32_e32 v236, 0x10000
	v_lshl_add_u64 v[186:187], v[236:237], 0, v[150:151]
	v_mov_b32_e32 v236, 0x20000
	v_lshl_add_u64 v[188:189], v[236:237], 0, v[150:151]
	v_mov_b32_e32 v236, 0x30000
	v_lshl_add_u64 v[190:191], v[236:237], 0, v[150:151]
	v_mov_b32_e32 v236, 0x80000
	v_lshl_add_u64 v[228:229], v[236:237], 0, v[150:151]
	v_mov_b32_e32 v236, 0x90000
	v_lshl_add_u64 v[230:231], v[236:237], 0, v[150:151]
	v_mov_b32_e32 v236, 0xa0000
	v_lshl_add_u64 v[232:233], v[236:237], 0, v[150:151]
	v_mov_b32_e32 v236, 0xb0000
	v_lshl_add_u64 v[234:235], v[236:237], 0, v[150:151]
	v_lshlrev_b32_e32 v238, 4, v0
	v_add_u32_e32 v239, 0x10000, v238
	global_load_dwordx4 v[172:175], v[234:235], off
	global_load_dwordx4 v[176:179], v[234:235], off offset:256
	ds_read_b128 v[146:149], v239 offset:0
	ds_read_b128 v[152:155], v239 offset:8192
	ds_read_b128 v[156:159], v239 offset:16384
	ds_read_b128 v[168:171], v239 offset:24576
	s_waitcnt lgkmcnt(3)
	v_cvt_f32_f16_e32 v160, v146
	v_cvt_f32_f16_sdwa v161, v146 dst_sel:DWORD dst_unused:UNUSED_PAD src0_sel:WORD_1
	v_cvt_f32_f16_e32 v180, v147
	v_cvt_f32_f16_sdwa v181, v147 dst_sel:DWORD dst_unused:UNUSED_PAD src0_sel:WORD_1
	v_cvt_f32_f16_e32 v182, v148
	v_cvt_f32_f16_sdwa v183, v148 dst_sel:DWORD dst_unused:UNUSED_PAD src0_sel:WORD_1
	v_cvt_f32_f16_e32 v184, v149
	v_cvt_f32_f16_sdwa v185, v149 dst_sel:DWORD dst_unused:UNUSED_PAD src0_sel:WORD_1
	ds_read_b128 v[146:149], v238 offset:0
	v_pk_fma_f32 v[126:127], v[126:127], 0.5, v[160:161] op_sel_hi:[1,0,1]
	v_pk_fma_f32 v[128:129], v[128:129], 0.5, v[180:181] op_sel_hi:[1,0,1]
	v_pk_fma_f32 v[122:123], v[122:123], 0.5, v[182:183] op_sel_hi:[1,0,1]
	v_pk_fma_f32 v[124:125], v[124:125], 0.5, v[184:185] op_sel_hi:[1,0,1]
	v_cvt_pk_f16_f32 v125, v124, v125
	v_cvt_pk_f16_f32 v124, v122, v123
	v_cvt_pk_f16_f32 v123, v128, v129
	v_cvt_pk_f16_f32 v122, v126, v127
	global_store_dwordx4 v[150:151], v[122:125], off
	s_waitcnt lgkmcnt(3)
	v_cvt_f32_f16_e32 v160, v152
	v_cvt_f32_f16_sdwa v161, v152 dst_sel:DWORD dst_unused:UNUSED_PAD src0_sel:WORD_1
	v_cvt_f32_f16_e32 v180, v153
	v_cvt_f32_f16_sdwa v181, v153 dst_sel:DWORD dst_unused:UNUSED_PAD src0_sel:WORD_1
	v_cvt_f32_f16_e32 v182, v154
	v_cvt_f32_f16_sdwa v183, v154 dst_sel:DWORD dst_unused:UNUSED_PAD src0_sel:WORD_1
	v_cvt_f32_f16_e32 v184, v155
	v_cvt_f32_f16_sdwa v185, v155 dst_sel:DWORD dst_unused:UNUSED_PAD src0_sel:WORD_1
	ds_read_b128 v[152:155], v238 offset:8192
	v_pk_fma_f32 v[118:119], v[118:119], 0.5, v[160:161] op_sel_hi:[1,0,1]
	v_pk_fma_f32 v[120:121], v[120:121], 0.5, v[180:181] op_sel_hi:[1,0,1]
	v_pk_fma_f32 v[114:115], v[114:115], 0.5, v[182:183] op_sel_hi:[1,0,1]
	v_pk_fma_f32 v[116:117], v[116:117], 0.5, v[184:185] op_sel_hi:[1,0,1]
	v_cvt_pk_f16_f32 v117, v116, v117
	v_cvt_pk_f16_f32 v116, v114, v115
	v_cvt_pk_f16_f32 v115, v120, v121
	v_cvt_pk_f16_f32 v114, v118, v119
	global_store_dwordx4 v[150:151], v[114:117], off offset:256
	s_waitcnt lgkmcnt(3)
	v_cvt_f32_f16_e32 v160, v156
	v_cvt_f32_f16_sdwa v161, v156 dst_sel:DWORD dst_unused:UNUSED_PAD src0_sel:WORD_1
	v_cvt_f32_f16_e32 v180, v157
	v_cvt_f32_f16_sdwa v181, v157 dst_sel:DWORD dst_unused:UNUSED_PAD src0_sel:WORD_1
	v_cvt_f32_f16_e32 v182, v158
	v_cvt_f32_f16_sdwa v183, v158 dst_sel:DWORD dst_unused:UNUSED_PAD src0_sel:WORD_1
	v_cvt_f32_f16_e32 v184, v159
	v_cvt_f32_f16_sdwa v185, v159 dst_sel:DWORD dst_unused:UNUSED_PAD src0_sel:WORD_1
	ds_read_b128 v[156:159], v238 offset:16384
	v_pk_fma_f32 v[110:111], v[110:111], 0.5, v[160:161] op_sel_hi:[1,0,1]
	v_pk_fma_f32 v[112:113], v[112:113], 0.5, v[180:181] op_sel_hi:[1,0,1]
	v_pk_fma_f32 v[106:107], v[106:107], 0.5, v[182:183] op_sel_hi:[1,0,1]
	v_pk_fma_f32 v[108:109], v[108:109], 0.5, v[184:185] op_sel_hi:[1,0,1]
	v_cvt_pk_f16_f32 v109, v108, v109
	v_cvt_pk_f16_f32 v108, v106, v107
	v_cvt_pk_f16_f32 v107, v112, v113
	v_cvt_pk_f16_f32 v106, v110, v111
	global_store_dwordx4 v[186:187], v[106:109], off
	s_waitcnt lgkmcnt(3)
	v_cvt_f32_f16_e32 v160, v168
	v_cvt_f32_f16_sdwa v161, v168 dst_sel:DWORD dst_unused:UNUSED_PAD src0_sel:WORD_1
	v_cvt_f32_f16_e32 v180, v169
	v_cvt_f32_f16_sdwa v181, v169 dst_sel:DWORD dst_unused:UNUSED_PAD src0_sel:WORD_1
	v_cvt_f32_f16_e32 v182, v170
	v_cvt_f32_f16_sdwa v183, v170 dst_sel:DWORD dst_unused:UNUSED_PAD src0_sel:WORD_1
	v_cvt_f32_f16_e32 v184, v171
	v_cvt_f32_f16_sdwa v185, v171 dst_sel:DWORD dst_unused:UNUSED_PAD src0_sel:WORD_1
	ds_read_b128 v[168:171], v238 offset:24576
	v_pk_fma_f32 v[102:103], v[102:103], 0.5, v[160:161] op_sel_hi:[1,0,1]
	v_pk_fma_f32 v[104:105], v[104:105], 0.5, v[180:181] op_sel_hi:[1,0,1]
	v_pk_fma_f32 v[98:99], v[98:99], 0.5, v[182:183] op_sel_hi:[1,0,1]
	v_pk_fma_f32 v[100:101], v[100:101], 0.5, v[184:185] op_sel_hi:[1,0,1]
	v_cvt_pk_f16_f32 v101, v100, v101
	v_cvt_pk_f16_f32 v100, v98, v99
	v_cvt_pk_f16_f32 v99, v104, v105
	v_cvt_pk_f16_f32 v98, v102, v103
	global_store_dwordx4 v[186:187], v[98:101], off offset:256
	s_waitcnt lgkmcnt(3)
	v_cvt_f32_f16_e32 v160, v146
	v_cvt_f32_f16_sdwa v161, v146 dst_sel:DWORD dst_unused:UNUSED_PAD src0_sel:WORD_1
	v_cvt_f32_f16_e32 v180, v147
	v_cvt_f32_f16_sdwa v181, v147 dst_sel:DWORD dst_unused:UNUSED_PAD src0_sel:WORD_1
	v_cvt_f32_f16_e32 v182, v148
	v_cvt_f32_f16_sdwa v183, v148 dst_sel:DWORD dst_unused:UNUSED_PAD src0_sel:WORD_1
	v_cvt_f32_f16_e32 v184, v149
	v_cvt_f32_f16_sdwa v185, v149 dst_sel:DWORD dst_unused:UNUSED_PAD src0_sel:WORD_1
	ds_read_b128 v[146:149], v239 offset:32768
	v_pk_fma_f32 v[94:95], v[94:95], 0.5, v[160:161] op_sel_hi:[1,0,1]
	v_pk_fma_f32 v[96:97], v[96:97], 0.5, v[180:181] op_sel_hi:[1,0,1]
	v_pk_fma_f32 v[90:91], v[90:91], 0.5, v[182:183] op_sel_hi:[1,0,1]
	v_pk_fma_f32 v[92:93], v[92:93], 0.5, v[184:185] op_sel_hi:[1,0,1]
	v_cvt_pk_f16_f32 v93, v92, v93
	v_cvt_pk_f16_f32 v92, v90, v91
	v_cvt_pk_f16_f32 v91, v96, v97
	v_cvt_pk_f16_f32 v90, v94, v95
	global_store_dwordx4 v[188:189], v[90:93], off
	s_waitcnt lgkmcnt(3)
	v_cvt_f32_f16_e32 v160, v152
	v_cvt_f32_f16_sdwa v161, v152 dst_sel:DWORD dst_unused:UNUSED_PAD src0_sel:WORD_1
	v_cvt_f32_f16_e32 v180, v153
	v_cvt_f32_f16_sdwa v181, v153 dst_sel:DWORD dst_unused:UNUSED_PAD src0_sel:WORD_1
	v_cvt_f32_f16_e32 v182, v154
	v_cvt_f32_f16_sdwa v183, v154 dst_sel:DWORD dst_unused:UNUSED_PAD src0_sel:WORD_1
	v_cvt_f32_f16_e32 v184, v155
	v_cvt_f32_f16_sdwa v185, v155 dst_sel:DWORD dst_unused:UNUSED_PAD src0_sel:WORD_1
	ds_read_b128 v[152:155], v239 offset:40960
	v_pk_fma_f32 v[86:87], v[86:87], 0.5, v[160:161] op_sel_hi:[1,0,1]
	v_pk_fma_f32 v[88:89], v[88:89], 0.5, v[180:181] op_sel_hi:[1,0,1]
	v_pk_fma_f32 v[82:83], v[82:83], 0.5, v[182:183] op_sel_hi:[1,0,1]
	v_pk_fma_f32 v[84:85], v[84:85], 0.5, v[184:185] op_sel_hi:[1,0,1]
	v_cvt_pk_f16_f32 v85, v84, v85
	v_cvt_pk_f16_f32 v84, v82, v83
	v_cvt_pk_f16_f32 v83, v88, v89
	v_cvt_pk_f16_f32 v82, v86, v87
	global_store_dwordx4 v[188:189], v[82:85], off offset:256
	s_waitcnt lgkmcnt(3)
	v_cvt_f32_f16_e32 v160, v156
	v_cvt_f32_f16_sdwa v161, v156 dst_sel:DWORD dst_unused:UNUSED_PAD src0_sel:WORD_1
	v_cvt_f32_f16_e32 v180, v157
	v_cvt_f32_f16_sdwa v181, v157 dst_sel:DWORD dst_unused:UNUSED_PAD src0_sel:WORD_1
	v_cvt_f32_f16_e32 v182, v158
	v_cvt_f32_f16_sdwa v183, v158 dst_sel:DWORD dst_unused:UNUSED_PAD src0_sel:WORD_1
	v_cvt_f32_f16_e32 v184, v159
	v_cvt_f32_f16_sdwa v185, v159 dst_sel:DWORD dst_unused:UNUSED_PAD src0_sel:WORD_1
	ds_read_b128 v[156:159], v239 offset:49152
	v_pk_fma_f32 v[78:79], v[78:79], 0.5, v[160:161] op_sel_hi:[1,0,1]
	v_pk_fma_f32 v[80:81], v[80:81], 0.5, v[180:181] op_sel_hi:[1,0,1]
	v_pk_fma_f32 v[74:75], v[74:75], 0.5, v[182:183] op_sel_hi:[1,0,1]
	v_pk_fma_f32 v[76:77], v[76:77], 0.5, v[184:185] op_sel_hi:[1,0,1]
	v_cvt_pk_f16_f32 v77, v76, v77
	v_cvt_pk_f16_f32 v76, v74, v75
	v_cvt_pk_f16_f32 v75, v80, v81
	v_cvt_pk_f16_f32 v74, v78, v79
	global_store_dwordx4 v[190:191], v[74:77], off
	s_waitcnt lgkmcnt(3)
	v_cvt_f32_f16_e32 v160, v168
	v_cvt_f32_f16_sdwa v161, v168 dst_sel:DWORD dst_unused:UNUSED_PAD src0_sel:WORD_1
	v_cvt_f32_f16_e32 v180, v169
	v_cvt_f32_f16_sdwa v181, v169 dst_sel:DWORD dst_unused:UNUSED_PAD src0_sel:WORD_1
	v_cvt_f32_f16_e32 v182, v170
	v_cvt_f32_f16_sdwa v183, v170 dst_sel:DWORD dst_unused:UNUSED_PAD src0_sel:WORD_1
	v_cvt_f32_f16_e32 v184, v171
	v_cvt_f32_f16_sdwa v185, v171 dst_sel:DWORD dst_unused:UNUSED_PAD src0_sel:WORD_1
	ds_read_b128 v[168:171], v239 offset:57344
	v_pk_fma_f32 v[70:71], v[70:71], 0.5, v[160:161] op_sel_hi:[1,0,1]
	v_pk_fma_f32 v[72:73], v[72:73], 0.5, v[180:181] op_sel_hi:[1,0,1]
	v_pk_fma_f32 v[66:67], v[66:67], 0.5, v[182:183] op_sel_hi:[1,0,1]
	v_pk_fma_f32 v[68:69], v[68:69], 0.5, v[184:185] op_sel_hi:[1,0,1]
	v_cvt_pk_f16_f32 v69, v68, v69
	v_cvt_pk_f16_f32 v68, v66, v67
	v_cvt_pk_f16_f32 v67, v72, v73
	v_cvt_pk_f16_f32 v66, v70, v71
	global_store_dwordx4 v[190:191], v[66:69], off offset:256
	s_waitcnt lgkmcnt(3)
	v_cvt_f32_f16_e32 v160, v146
	v_cvt_f32_f16_sdwa v161, v146 dst_sel:DWORD dst_unused:UNUSED_PAD src0_sel:WORD_1
	v_cvt_f32_f16_e32 v180, v147
	v_cvt_f32_f16_sdwa v181, v147 dst_sel:DWORD dst_unused:UNUSED_PAD src0_sel:WORD_1
	v_cvt_f32_f16_e32 v182, v148
	v_cvt_f32_f16_sdwa v183, v148 dst_sel:DWORD dst_unused:UNUSED_PAD src0_sel:WORD_1
	v_cvt_f32_f16_e32 v184, v149
	v_cvt_f32_f16_sdwa v185, v149 dst_sel:DWORD dst_unused:UNUSED_PAD src0_sel:WORD_1
	ds_read_b128 v[146:149], v238 offset:32768
	v_pk_fma_f32 v[62:63], v[62:63], 0.5, v[160:161] op_sel_hi:[1,0,1]
	v_pk_fma_f32 v[64:65], v[64:65], 0.5, v[180:181] op_sel_hi:[1,0,1]
	v_pk_fma_f32 v[58:59], v[58:59], 0.5, v[182:183] op_sel_hi:[1,0,1]
	v_pk_fma_f32 v[60:61], v[60:61], 0.5, v[184:185] op_sel_hi:[1,0,1]
	v_cvt_pk_f16_f32 v61, v60, v61
	v_cvt_pk_f16_f32 v60, v58, v59
	v_cvt_pk_f16_f32 v59, v64, v65
	v_cvt_pk_f16_f32 v58, v62, v63
	global_store_dwordx4 v[228:229], v[58:61], off
	s_waitcnt lgkmcnt(3)
	v_cvt_f32_f16_e32 v160, v152
	v_cvt_f32_f16_sdwa v161, v152 dst_sel:DWORD dst_unused:UNUSED_PAD src0_sel:WORD_1
	v_cvt_f32_f16_e32 v180, v153
	v_cvt_f32_f16_sdwa v181, v153 dst_sel:DWORD dst_unused:UNUSED_PAD src0_sel:WORD_1
	v_cvt_f32_f16_e32 v182, v154
	v_cvt_f32_f16_sdwa v183, v154 dst_sel:DWORD dst_unused:UNUSED_PAD src0_sel:WORD_1
	v_cvt_f32_f16_e32 v184, v155
	v_cvt_f32_f16_sdwa v185, v155 dst_sel:DWORD dst_unused:UNUSED_PAD src0_sel:WORD_1
	ds_read_b128 v[152:155], v238 offset:40960
	v_pk_fma_f32 v[54:55], v[54:55], 0.5, v[160:161] op_sel_hi:[1,0,1]
	v_pk_fma_f32 v[56:57], v[56:57], 0.5, v[180:181] op_sel_hi:[1,0,1]
	v_pk_fma_f32 v[50:51], v[50:51], 0.5, v[182:183] op_sel_hi:[1,0,1]
	v_pk_fma_f32 v[52:53], v[52:53], 0.5, v[184:185] op_sel_hi:[1,0,1]
	v_cvt_pk_f16_f32 v53, v52, v53
	v_cvt_pk_f16_f32 v52, v50, v51
	v_cvt_pk_f16_f32 v51, v56, v57
	v_cvt_pk_f16_f32 v50, v54, v55
	global_store_dwordx4 v[228:229], v[50:53], off offset:256
	s_waitcnt lgkmcnt(3)
	v_cvt_f32_f16_e32 v160, v156
	v_cvt_f32_f16_sdwa v161, v156 dst_sel:DWORD dst_unused:UNUSED_PAD src0_sel:WORD_1
	v_cvt_f32_f16_e32 v180, v157
	v_cvt_f32_f16_sdwa v181, v157 dst_sel:DWORD dst_unused:UNUSED_PAD src0_sel:WORD_1
	v_cvt_f32_f16_e32 v182, v158
	v_cvt_f32_f16_sdwa v183, v158 dst_sel:DWORD dst_unused:UNUSED_PAD src0_sel:WORD_1
	v_cvt_f32_f16_e32 v184, v159
	v_cvt_f32_f16_sdwa v185, v159 dst_sel:DWORD dst_unused:UNUSED_PAD src0_sel:WORD_1
	v_pk_fma_f32 v[46:47], v[46:47], 0.5, v[160:161] op_sel_hi:[1,0,1]
	v_pk_fma_f32 v[48:49], v[48:49], 0.5, v[180:181] op_sel_hi:[1,0,1]
	v_pk_fma_f32 v[42:43], v[42:43], 0.5, v[182:183] op_sel_hi:[1,0,1]
	v_pk_fma_f32 v[44:45], v[44:45], 0.5, v[184:185] op_sel_hi:[1,0,1]
	v_cvt_pk_f16_f32 v45, v44, v45
	v_cvt_pk_f16_f32 v44, v42, v43
	v_cvt_pk_f16_f32 v43, v48, v49
	v_cvt_pk_f16_f32 v42, v46, v47
	global_store_dwordx4 v[230:231], v[42:45], off
	s_waitcnt lgkmcnt(2)
	v_cvt_f32_f16_e32 v160, v168
	v_cvt_f32_f16_sdwa v161, v168 dst_sel:DWORD dst_unused:UNUSED_PAD src0_sel:WORD_1
	v_cvt_f32_f16_e32 v180, v169
	v_cvt_f32_f16_sdwa v181, v169 dst_sel:DWORD dst_unused:UNUSED_PAD src0_sel:WORD_1
	v_cvt_f32_f16_e32 v182, v170
	v_cvt_f32_f16_sdwa v183, v170 dst_sel:DWORD dst_unused:UNUSED_PAD src0_sel:WORD_1
	v_cvt_f32_f16_e32 v184, v171
	v_cvt_f32_f16_sdwa v185, v171 dst_sel:DWORD dst_unused:UNUSED_PAD src0_sel:WORD_1
	v_pk_fma_f32 v[38:39], v[38:39], 0.5, v[160:161] op_sel_hi:[1,0,1]
	v_pk_fma_f32 v[40:41], v[40:41], 0.5, v[180:181] op_sel_hi:[1,0,1]
	v_pk_fma_f32 v[34:35], v[34:35], 0.5, v[182:183] op_sel_hi:[1,0,1]
	v_pk_fma_f32 v[36:37], v[36:37], 0.5, v[184:185] op_sel_hi:[1,0,1]
	v_cvt_pk_f16_f32 v37, v36, v37
	v_cvt_pk_f16_f32 v36, v34, v35
	v_cvt_pk_f16_f32 v35, v40, v41
	v_cvt_pk_f16_f32 v34, v38, v39
	global_store_dwordx4 v[230:231], v[34:37], off offset:256
	s_waitcnt lgkmcnt(1)
	v_cvt_f32_f16_e32 v160, v146
	v_cvt_f32_f16_sdwa v161, v146 dst_sel:DWORD dst_unused:UNUSED_PAD src0_sel:WORD_1
	v_cvt_f32_f16_e32 v180, v147
	v_cvt_f32_f16_sdwa v181, v147 dst_sel:DWORD dst_unused:UNUSED_PAD src0_sel:WORD_1
	v_cvt_f32_f16_e32 v182, v148
	v_cvt_f32_f16_sdwa v183, v148 dst_sel:DWORD dst_unused:UNUSED_PAD src0_sel:WORD_1
	v_cvt_f32_f16_e32 v184, v149
	v_cvt_f32_f16_sdwa v185, v149 dst_sel:DWORD dst_unused:UNUSED_PAD src0_sel:WORD_1
	v_pk_fma_f32 v[30:31], v[30:31], 0.5, v[160:161] op_sel_hi:[1,0,1]
	v_pk_fma_f32 v[32:33], v[32:33], 0.5, v[180:181] op_sel_hi:[1,0,1]
	v_pk_fma_f32 v[26:27], v[26:27], 0.5, v[182:183] op_sel_hi:[1,0,1]
	v_pk_fma_f32 v[28:29], v[28:29], 0.5, v[184:185] op_sel_hi:[1,0,1]
	v_cvt_pk_f16_f32 v29, v28, v29
	v_cvt_pk_f16_f32 v28, v26, v27
	v_cvt_pk_f16_f32 v27, v32, v33
	v_cvt_pk_f16_f32 v26, v30, v31
	global_store_dwordx4 v[232:233], v[26:29], off
	s_waitcnt lgkmcnt(0)
	v_cvt_f32_f16_e32 v160, v152
	v_cvt_f32_f16_sdwa v161, v152 dst_sel:DWORD dst_unused:UNUSED_PAD src0_sel:WORD_1
	v_cvt_f32_f16_e32 v180, v153
	v_cvt_f32_f16_sdwa v181, v153 dst_sel:DWORD dst_unused:UNUSED_PAD src0_sel:WORD_1
	v_cvt_f32_f16_e32 v182, v154
	v_cvt_f32_f16_sdwa v183, v154 dst_sel:DWORD dst_unused:UNUSED_PAD src0_sel:WORD_1
	v_cvt_f32_f16_e32 v184, v155
	v_cvt_f32_f16_sdwa v185, v155 dst_sel:DWORD dst_unused:UNUSED_PAD src0_sel:WORD_1
	v_pk_fma_f32 v[22:23], v[22:23], 0.5, v[160:161] op_sel_hi:[1,0,1]
	v_pk_fma_f32 v[24:25], v[24:25], 0.5, v[180:181] op_sel_hi:[1,0,1]
	v_pk_fma_f32 v[18:19], v[18:19], 0.5, v[182:183] op_sel_hi:[1,0,1]
	v_pk_fma_f32 v[20:21], v[20:21], 0.5, v[184:185] op_sel_hi:[1,0,1]
	v_cvt_pk_f16_f32 v21, v20, v21
	v_cvt_pk_f16_f32 v20, v18, v19
	v_cvt_pk_f16_f32 v19, v24, v25
	v_cvt_pk_f16_f32 v18, v22, v23
	global_store_dwordx4 v[232:233], v[18:21], off offset:256
	s_waitcnt vmcnt(15)
	v_cvt_f32_f16_e32 v160, v172
	v_cvt_f32_f16_sdwa v161, v172 dst_sel:DWORD dst_unused:UNUSED_PAD src0_sel:WORD_1
	v_cvt_f32_f16_e32 v180, v173
	v_cvt_f32_f16_sdwa v181, v173 dst_sel:DWORD dst_unused:UNUSED_PAD src0_sel:WORD_1
	v_cvt_f32_f16_e32 v182, v174
	v_cvt_f32_f16_sdwa v183, v174 dst_sel:DWORD dst_unused:UNUSED_PAD src0_sel:WORD_1
	v_cvt_f32_f16_e32 v184, v175
	v_cvt_f32_f16_sdwa v185, v175 dst_sel:DWORD dst_unused:UNUSED_PAD src0_sel:WORD_1
	v_pk_fma_f32 v[14:15], v[14:15], 0.5, v[160:161] op_sel_hi:[1,0,1]
	v_pk_fma_f32 v[16:17], v[16:17], 0.5, v[180:181] op_sel_hi:[1,0,1]
	v_pk_fma_f32 v[10:11], v[10:11], 0.5, v[182:183] op_sel_hi:[1,0,1]
	v_pk_fma_f32 v[12:13], v[12:13], 0.5, v[184:185] op_sel_hi:[1,0,1]
	v_cvt_pk_f16_f32 v13, v12, v13
	v_cvt_pk_f16_f32 v12, v10, v11
	v_cvt_pk_f16_f32 v11, v16, v17
	v_cvt_pk_f16_f32 v10, v14, v15
	global_store_dwordx4 v[234:235], v[10:13], off
	s_waitcnt vmcnt(15)
	v_cvt_f32_f16_e32 v160, v176
	v_cvt_f32_f16_sdwa v161, v176 dst_sel:DWORD dst_unused:UNUSED_PAD src0_sel:WORD_1
	v_cvt_f32_f16_e32 v180, v177
	v_cvt_f32_f16_sdwa v181, v177 dst_sel:DWORD dst_unused:UNUSED_PAD src0_sel:WORD_1
	v_cvt_f32_f16_e32 v182, v178
	v_cvt_f32_f16_sdwa v183, v178 dst_sel:DWORD dst_unused:UNUSED_PAD src0_sel:WORD_1
	v_cvt_f32_f16_e32 v184, v179
	v_cvt_f32_f16_sdwa v185, v179 dst_sel:DWORD dst_unused:UNUSED_PAD src0_sel:WORD_1
	v_pk_fma_f32 v[6:7], v[6:7], 0.5, v[160:161] op_sel_hi:[1,0,1]
	v_pk_fma_f32 v[8:9], v[8:9], 0.5, v[180:181] op_sel_hi:[1,0,1]
	v_pk_fma_f32 v[2:3], v[2:3], 0.5, v[182:183] op_sel_hi:[1,0,1]
	v_pk_fma_f32 v[4:5], v[4:5], 0.5, v[184:185] op_sel_hi:[1,0,1]
	v_cvt_pk_f16_f32 v5, v4, v5
	v_cvt_pk_f16_f32 v4, v2, v3
	v_cvt_pk_f16_f32 v3, v8, v9
	v_cvt_pk_f16_f32 v2, v6, v7
	global_store_dwordx4 v[234:235], v[2:5], off offset:256
	s_mov_b64 s[0:1], -1
	s_and_b64 vcc, exec, s[2:3]
	s_cbranch_vccnz .LBB0_1225
	s_andn2_b64 vcc, exec, s[8:9]
	s_cbranch_vccnz .LBB0_1224
	s_barrier
	s_branch .LBB0_1224

.LBB0_2089:
	ds_read_b128 v[130:133], v178
	ds_read_b128 v[134:137], v178 offset:1024
	ds_read_b128 v[138:141], v178 offset:2048
	ds_read_b128 v[142:145], v178 offset:3072
	ds_read_b128 v[162:165], v179
	ds_read_b128 v[166:169], v179 offset:1024
	ds_read_b128 v[170:173], v179 offset:2048
	ds_read_b128 v[182:185], v179 offset:3072
	s_add_u32 s34, s38, 0xffea0080
	s_addc_u32 s35, s39, -1
	s_cmpk_eq_i32 s52, 0x54
	s_cselect_b32 s41, s5, s35
	s_cselect_b32 s40, s4, s34
	s_cselect_b32 s35, s37, s1
	s_cselect_b32 s34, s36, s0
	v_lshl_add_u64 v[174:175], s[38:39], 0, v[154:155]
	s_add_i32 m0, s33, 0xc000
	ds_read_b128 v[186:189], v180
	ds_read_b128 v[190:193], v180 offset:1024
	ds_read_b128 v[194:197], v180 offset:2048
	ds_read_b128 v[198:201], v180 offset:3072
	ds_read_b128 v[202:205], v180 offset:4096
	ds_read_b128 v[206:209], v180 offset:5120
	ds_read_b128 v[210:213], v180 offset:6144
	ds_read_b128 v[218:221], v180 offset:7168
	global_load_lds_dwordx4 v[174:175], off
	v_lshl_add_u64 v[174:175], s[38:39], 0, v[156:157]
	s_add_i32 m0, s33, 0xe000
	s_nop 0
	global_load_lds_dwordx4 v[174:175], off
	s_waitcnt vmcnt(8)
	s_waitcnt lgkmcnt(0)
	s_barrier
	s_setprio 1
	s_waitcnt lgkmcnt(0)
	v_mfma_f32_16x16x32_bf16 v[126:129], v[130:133], v[186:189], v[126:129]
	v_mfma_f32_16x16x32_bf16 v[122:125], v[138:141], v[186:189], v[122:125]
	v_mfma_f32_16x16x32_bf16 v[110:113], v[130:133], v[194:197], v[110:113]
	v_mfma_f32_16x16x32_bf16 v[106:109], v[138:141], v[194:197], v[106:109]
	v_mfma_f32_16x16x32_bf16 v[94:97], v[130:133], v[202:205], v[94:97]
	v_mfma_f32_16x16x32_bf16 v[90:93], v[138:141], v[202:205], v[90:93]
	v_mfma_f32_16x16x32_bf16 v[78:81], v[130:133], v[210:213], v[78:81]
	v_mfma_f32_16x16x32_bf16 v[74:77], v[138:141], v[210:213], v[74:77]
	v_mfma_f32_16x16x32_bf16 v[126:129], v[134:137], v[190:193], v[126:129]
	v_mfma_f32_16x16x32_bf16 v[122:125], v[142:145], v[190:193], v[122:125]
	v_mfma_f32_16x16x32_bf16 v[110:113], v[134:137], v[198:201], v[110:113]
	v_mfma_f32_16x16x32_bf16 v[106:109], v[142:145], v[198:201], v[106:109]
	v_mfma_f32_16x16x32_bf16 v[94:97], v[134:137], v[206:209], v[94:97]
	v_mfma_f32_16x16x32_bf16 v[90:93], v[142:145], v[206:209], v[90:93]
	v_mfma_f32_16x16x32_bf16 v[78:81], v[134:137], v[218:221], v[78:81]
	v_mfma_f32_16x16x32_bf16 v[74:77], v[142:145], v[218:221], v[74:77]
	s_setprio 0
	s_setprio 1
	v_mfma_f32_16x16x32_bf16 v[118:121], v[162:165], v[186:189], v[118:121]
	v_mfma_f32_16x16x32_bf16 v[114:117], v[170:173], v[186:189], v[114:117]
	v_mfma_f32_16x16x32_bf16 v[102:105], v[162:165], v[194:197], v[102:105]
	v_mfma_f32_16x16x32_bf16 v[98:101], v[170:173], v[194:197], v[98:101]
	v_mfma_f32_16x16x32_bf16 v[86:89], v[162:165], v[202:205], v[86:89]
	v_mfma_f32_16x16x32_bf16 v[82:85], v[170:173], v[202:205], v[82:85]
	v_mfma_f32_16x16x32_bf16 v[70:73], v[162:165], v[210:213], v[70:73]
	v_mfma_f32_16x16x32_bf16 v[66:69], v[170:173], v[210:213], v[66:69]
	v_mfma_f32_16x16x32_bf16 v[118:121], v[166:169], v[190:193], v[118:121]
	v_mfma_f32_16x16x32_bf16 v[114:117], v[182:185], v[190:193], v[114:117]
	v_mfma_f32_16x16x32_bf16 v[102:105], v[166:169], v[198:201], v[102:105]
	v_mfma_f32_16x16x32_bf16 v[98:101], v[182:185], v[198:201], v[98:101]
	v_mfma_f32_16x16x32_bf16 v[86:89], v[166:169], v[206:209], v[86:89]
	v_mfma_f32_16x16x32_bf16 v[82:85], v[182:185], v[206:209], v[82:85]
	v_mfma_f32_16x16x32_bf16 v[70:73], v[166:169], v[218:221], v[70:73]
	v_mfma_f32_16x16x32_bf16 v[66:69], v[182:185], v[218:221], v[66:69]
	s_setprio 0
	s_barrier
	s_add_i32 s53, s61, s31
	v_lshl_add_u64 v[174:175], s[34:35], 0, v[148:149]
	s_mov_b32 m0, s53
	ds_read_b128 v[186:189], v180 offset:16384
	ds_read_b128 v[190:193], v180 offset:17408
	ds_read_b128 v[194:197], v180 offset:18432
	ds_read_b128 v[198:201], v180 offset:19456
	ds_read_b128 v[202:205], v180 offset:20480
	ds_read_b128 v[206:209], v180 offset:21504
	ds_read_b128 v[210:213], v180 offset:22528
	ds_read_b128 v[218:221], v180 offset:23552
	global_load_lds_dwordx4 v[174:175], off
	s_add_i32 m0, s53, 0x2000
	s_add_u32 s54, s34, 0x160000
	v_lshl_add_u64 v[214:215], s[34:35], 0, v[152:153]
	s_addc_u32 s55, s35, 0
	s_add_i32 s53, s70, s31
	global_load_lds_dwordx4 v[214:215], off
	v_lshl_add_u64 v[222:223], s[54:55], 0, v[148:149]
	s_mov_b32 m0, s53
	v_lshl_add_u64 v[224:225], s[40:41], 0, v[150:151]
	global_load_lds_dwordx4 v[222:223], off
	v_lshl_add_u64 v[222:223], s[54:55], 0, v[152:153]
	s_add_i32 m0, s53, 0x2000
	s_nop 0
	global_load_lds_dwordx4 v[222:223], off
	v_lshl_add_u64 v[222:223], s[40:41], 0, v[146:147]
	s_mov_b32 m0, s33
	s_nop 0
	global_load_lds_dwordx4 v[222:223], off
	s_mov_b32 m0, s46
	s_nop 0
	global_load_lds_dwordx4 v[224:225], off
	s_waitcnt vmcnt(8)
	s_waitcnt lgkmcnt(0)
	s_barrier
	s_setprio 1
	s_waitcnt lgkmcnt(0)
	v_mfma_f32_16x16x32_bf16 v[62:65], v[130:133], v[186:189], v[62:65]
	v_mfma_f32_16x16x32_bf16 v[58:61], v[138:141], v[186:189], v[58:61]
	v_mfma_f32_16x16x32_bf16 v[50:53], v[130:133], v[194:197], v[50:53]
	v_mfma_f32_16x16x32_bf16 v[42:45], v[138:141], v[194:197], v[42:45]
	v_mfma_f32_16x16x32_bf16 v[38:41], v[130:133], v[202:205], v[38:41]
	v_mfma_f32_16x16x32_bf16 v[34:37], v[138:141], v[202:205], v[34:37]
	v_mfma_f32_16x16x32_bf16 v[14:17], v[130:133], v[210:213], v[14:17]
	v_mfma_f32_16x16x32_bf16 v[10:13], v[138:141], v[210:213], v[10:13]
	v_mfma_f32_16x16x32_bf16 v[62:65], v[134:137], v[190:193], v[62:65]
	v_mfma_f32_16x16x32_bf16 v[58:61], v[142:145], v[190:193], v[58:61]
	v_mfma_f32_16x16x32_bf16 v[50:53], v[134:137], v[198:201], v[50:53]
	v_mfma_f32_16x16x32_bf16 v[42:45], v[142:145], v[198:201], v[42:45]
	v_mfma_f32_16x16x32_bf16 v[38:41], v[134:137], v[206:209], v[38:41]
	v_mfma_f32_16x16x32_bf16 v[34:37], v[142:145], v[206:209], v[34:37]
	v_mfma_f32_16x16x32_bf16 v[14:17], v[134:137], v[218:221], v[14:17]
	v_mfma_f32_16x16x32_bf16 v[10:13], v[142:145], v[218:221], v[10:13]
	s_setprio 0
	s_setprio 1
	v_mfma_f32_16x16x32_bf16 v[54:57], v[162:165], v[186:189], v[54:57]
	v_mfma_f32_16x16x32_bf16 v[46:49], v[170:173], v[186:189], v[46:49]
	v_mfma_f32_16x16x32_bf16 v[30:33], v[162:165], v[194:197], v[30:33]
	v_mfma_f32_16x16x32_bf16 v[26:29], v[170:173], v[194:197], v[26:29]
	v_mfma_f32_16x16x32_bf16 v[22:25], v[162:165], v[202:205], v[22:25]
	v_mfma_f32_16x16x32_bf16 v[18:21], v[170:173], v[202:205], v[18:21]
	v_mfma_f32_16x16x32_bf16 v[6:9], v[162:165], v[210:213], v[6:9]
	v_mfma_f32_16x16x32_bf16 v[2:5], v[170:173], v[210:213], v[2:5]
	v_mfma_f32_16x16x32_bf16 v[54:57], v[166:169], v[190:193], v[54:57]
	v_mfma_f32_16x16x32_bf16 v[46:49], v[182:185], v[190:193], v[46:49]
	v_mfma_f32_16x16x32_bf16 v[30:33], v[166:169], v[198:201], v[30:33]
	v_mfma_f32_16x16x32_bf16 v[26:29], v[182:185], v[198:201], v[26:29]
	v_mfma_f32_16x16x32_bf16 v[22:25], v[166:169], v[206:209], v[22:25]
	v_mfma_f32_16x16x32_bf16 v[18:21], v[182:185], v[206:209], v[18:21]
	v_mfma_f32_16x16x32_bf16 v[6:9], v[166:169], v[218:221], v[6:9]
	v_mfma_f32_16x16x32_bf16 v[2:5], v[182:185], v[218:221], v[2:5]
	s_setprio 0
	s_barrier
	s_add_i32 s53, 0, 0x18000
	s_add_i32 s54, 0, 0x1c000
	v_add_u32_e32 v142, s53, v176
	v_add_u32_e32 v181, s54, v176
	ds_read_b128 v[130:133], v142
	ds_read_b128 v[134:137], v142 offset:1024
	ds_read_b128 v[138:141], v142 offset:2048
	ds_read_b128 v[142:145], v142 offset:3072
	ds_read_b128 v[162:165], v181
	ds_read_b128 v[166:169], v181 offset:1024
	ds_read_b128 v[170:173], v181 offset:2048
	ds_read_b128 v[182:185], v181 offset:3072
	s_add_u32 s40, s40, 0x160000
	s_addc_u32 s41, s41, 0
	s_mov_b32 m0, s47
	v_lshl_add_u64 v[226:227], s[40:41], 0, v[146:147]
	ds_read_b128 v[186:189], v180 offset:32768
	ds_read_b128 v[190:193], v180 offset:33792
	ds_read_b128 v[194:197], v180 offset:34816
	ds_read_b128 v[198:201], v180 offset:35840
	ds_read_b128 v[202:205], v180 offset:36864
	ds_read_b128 v[206:209], v180 offset:37888
	ds_read_b128 v[210:213], v180 offset:38912
	ds_read_b128 v[218:221], v180 offset:39936
	global_load_lds_dwordx4 v[226:227], off
	v_lshl_add_u64 v[226:227], s[40:41], 0, v[150:151]
	s_mov_b32 m0, s56
	s_nop 0
	global_load_lds_dwordx4 v[226:227], off
	s_waitcnt vmcnt(8)
	s_waitcnt lgkmcnt(0)
	s_barrier
	s_setprio 1
	s_waitcnt lgkmcnt(0)
	v_mfma_f32_16x16x32_bf16 v[126:129], v[130:133], v[186:189], v[126:129]
	v_mfma_f32_16x16x32_bf16 v[122:125], v[138:141], v[186:189], v[122:125]
	v_mfma_f32_16x16x32_bf16 v[110:113], v[130:133], v[194:197], v[110:113]
	v_mfma_f32_16x16x32_bf16 v[106:109], v[138:141], v[194:197], v[106:109]
	v_mfma_f32_16x16x32_bf16 v[94:97], v[130:133], v[202:205], v[94:97]
	v_mfma_f32_16x16x32_bf16 v[90:93], v[138:141], v[202:205], v[90:93]
	v_mfma_f32_16x16x32_bf16 v[78:81], v[130:133], v[210:213], v[78:81]
	v_mfma_f32_16x16x32_bf16 v[74:77], v[138:141], v[210:213], v[74:77]
	v_mfma_f32_16x16x32_bf16 v[126:129], v[134:137], v[190:193], v[126:129]
	v_mfma_f32_16x16x32_bf16 v[122:125], v[142:145], v[190:193], v[122:125]
	v_mfma_f32_16x16x32_bf16 v[110:113], v[134:137], v[198:201], v[110:113]
	v_mfma_f32_16x16x32_bf16 v[106:109], v[142:145], v[198:201], v[106:109]
	v_mfma_f32_16x16x32_bf16 v[94:97], v[134:137], v[206:209], v[94:97]
	v_mfma_f32_16x16x32_bf16 v[90:93], v[142:145], v[206:209], v[90:93]
	v_mfma_f32_16x16x32_bf16 v[78:81], v[134:137], v[218:221], v[78:81]
	v_mfma_f32_16x16x32_bf16 v[74:77], v[142:145], v[218:221], v[74:77]
	s_setprio 0
	s_setprio 1
	v_mfma_f32_16x16x32_bf16 v[118:121], v[162:165], v[186:189], v[118:121]
	v_mfma_f32_16x16x32_bf16 v[114:117], v[170:173], v[186:189], v[114:117]
	v_mfma_f32_16x16x32_bf16 v[102:105], v[162:165], v[194:197], v[102:105]
	v_mfma_f32_16x16x32_bf16 v[98:101], v[170:173], v[194:197], v[98:101]
	v_mfma_f32_16x16x32_bf16 v[86:89], v[162:165], v[202:205], v[86:89]
	v_mfma_f32_16x16x32_bf16 v[82:85], v[170:173], v[202:205], v[82:85]
	v_mfma_f32_16x16x32_bf16 v[70:73], v[162:165], v[210:213], v[70:73]
	v_mfma_f32_16x16x32_bf16 v[66:69], v[170:173], v[210:213], v[66:69]
	v_mfma_f32_16x16x32_bf16 v[118:121], v[166:169], v[190:193], v[118:121]
	v_mfma_f32_16x16x32_bf16 v[114:117], v[182:185], v[190:193], v[114:117]
	v_mfma_f32_16x16x32_bf16 v[102:105], v[166:169], v[198:201], v[102:105]
	v_mfma_f32_16x16x32_bf16 v[98:101], v[182:185], v[198:201], v[98:101]
	v_mfma_f32_16x16x32_bf16 v[86:89], v[166:169], v[206:209], v[86:89]
	v_mfma_f32_16x16x32_bf16 v[82:85], v[182:185], v[206:209], v[82:85]
	v_mfma_f32_16x16x32_bf16 v[70:73], v[166:169], v[218:221], v[70:73]
	v_mfma_f32_16x16x32_bf16 v[66:69], v[182:185], v[218:221], v[66:69]
	s_setprio 0
	s_barrier
	s_add_i32 s40, s53, s31
	v_lshl_add_u64 v[174:175], v[174:175], 0, s[24:25]
	s_mov_b32 m0, s40
	ds_read_b128 v[186:189], v180 offset:49152
	ds_read_b128 v[190:193], v180 offset:50176
	ds_read_b128 v[194:197], v180 offset:51200
	ds_read_b128 v[198:201], v180 offset:52224
	ds_read_b128 v[202:205], v180 offset:53248
	ds_read_b128 v[206:209], v180 offset:54272
	ds_read_b128 v[210:213], v180 offset:55296
	ds_read_b128 v[218:221], v180 offset:56320
	global_load_lds_dwordx4 v[174:175], off
	s_add_i32 m0, s40, 0x2000
	s_add_u32 s34, s34, 0x160080
	v_lshl_add_u64 v[174:175], v[214:215], 0, s[24:25]
	s_addc_u32 s35, s35, 0
	s_add_i32 s40, s54, s31
	global_load_lds_dwordx4 v[174:175], off
	v_lshl_add_u64 v[174:175], s[34:35], 0, v[148:149]
	s_mov_b32 m0, s40
	s_nop 0
	global_load_lds_dwordx4 v[174:175], off
	v_lshl_add_u64 v[174:175], s[34:35], 0, v[152:153]
	s_add_i32 m0, s40, 0x2000
	s_nop 0
	global_load_lds_dwordx4 v[174:175], off
	v_lshl_add_u64 v[174:175], v[222:223], 0, s[24:25]
	s_mov_b32 m0, s58
	s_nop 0
	global_load_lds_dwordx4 v[174:175], off
	v_lshl_add_u64 v[174:175], v[224:225], 0, s[24:25]
	s_mov_b32 m0, s59
	s_nop 0
	global_load_lds_dwordx4 v[174:175], off
	s_waitcnt vmcnt(8)
	s_waitcnt lgkmcnt(0)
	s_barrier
	s_setprio 1
	s_waitcnt lgkmcnt(0)
	v_mfma_f32_16x16x32_bf16 v[62:65], v[130:133], v[186:189], v[62:65]
	v_mfma_f32_16x16x32_bf16 v[58:61], v[138:141], v[186:189], v[58:61]
	v_mfma_f32_16x16x32_bf16 v[50:53], v[130:133], v[194:197], v[50:53]
	v_mfma_f32_16x16x32_bf16 v[42:45], v[138:141], v[194:197], v[42:45]
	v_mfma_f32_16x16x32_bf16 v[38:41], v[130:133], v[202:205], v[38:41]
	v_mfma_f32_16x16x32_bf16 v[34:37], v[138:141], v[202:205], v[34:37]
	v_mfma_f32_16x16x32_bf16 v[14:17], v[130:133], v[210:213], v[14:17]
	v_mfma_f32_16x16x32_bf16 v[10:13], v[138:141], v[210:213], v[10:13]
	v_mfma_f32_16x16x32_bf16 v[62:65], v[134:137], v[190:193], v[62:65]
	v_mfma_f32_16x16x32_bf16 v[58:61], v[142:145], v[190:193], v[58:61]
	v_mfma_f32_16x16x32_bf16 v[50:53], v[134:137], v[198:201], v[50:53]
	v_mfma_f32_16x16x32_bf16 v[42:45], v[142:145], v[198:201], v[42:45]
	v_mfma_f32_16x16x32_bf16 v[38:41], v[134:137], v[206:209], v[38:41]
	v_mfma_f32_16x16x32_bf16 v[34:37], v[142:145], v[206:209], v[34:37]
	v_mfma_f32_16x16x32_bf16 v[14:17], v[134:137], v[218:221], v[14:17]
	v_mfma_f32_16x16x32_bf16 v[10:13], v[142:145], v[218:221], v[10:13]
	s_setprio 0
	s_setprio 1
	v_mfma_f32_16x16x32_bf16 v[54:57], v[162:165], v[186:189], v[54:57]
	v_mfma_f32_16x16x32_bf16 v[46:49], v[170:173], v[186:189], v[46:49]
	v_mfma_f32_16x16x32_bf16 v[30:33], v[162:165], v[194:197], v[30:33]
	v_mfma_f32_16x16x32_bf16 v[26:29], v[170:173], v[194:197], v[26:29]
	v_mfma_f32_16x16x32_bf16 v[22:25], v[162:165], v[202:205], v[22:25]
	v_mfma_f32_16x16x32_bf16 v[18:21], v[170:173], v[202:205], v[18:21]
	v_mfma_f32_16x16x32_bf16 v[6:9], v[162:165], v[210:213], v[6:9]
	v_mfma_f32_16x16x32_bf16 v[2:5], v[170:173], v[210:213], v[2:5]
	v_mfma_f32_16x16x32_bf16 v[54:57], v[166:169], v[190:193], v[54:57]
	v_mfma_f32_16x16x32_bf16 v[46:49], v[182:185], v[190:193], v[46:49]
	v_mfma_f32_16x16x32_bf16 v[30:33], v[166:169], v[198:201], v[30:33]
	v_mfma_f32_16x16x32_bf16 v[26:29], v[182:185], v[198:201], v[26:29]
	v_mfma_f32_16x16x32_bf16 v[22:25], v[166:169], v[206:209], v[22:25]
	v_mfma_f32_16x16x32_bf16 v[18:21], v[182:185], v[206:209], v[18:21]
	v_mfma_f32_16x16x32_bf16 v[6:9], v[166:169], v[218:221], v[6:9]
	v_mfma_f32_16x16x32_bf16 v[2:5], v[182:185], v[218:221], v[2:5]
	s_setprio 0
	s_barrier
	s_add_i32 s52, s52, 2
	s_add_u32 s38, s38, 0x100
	s_addc_u32 s39, s39, 0
	s_add_u32 s0, s0, 0x100
	s_addc_u32 s1, s1, 0
	s_cmpk_gt_u32 s52, 0x53
	s_cbranch_scc0 .LBB0_2089
	v_lshl_add_u32 v234, s73, 8, v1
	v_lshl_or_b32 v236, s74, 8, v177
	v_ashrrev_i32_e32 v235, 31, v234
	v_ashrrev_i32_e32 v237, 31, v236
	v_lshlrev_b64 v[228:229], 12, v[234:235]
	v_lshl_add_u64 v[228:229], s[64:65], 0, v[228:229]
	v_lshlrev_b64 v[236:237], 1, v[236:237]
	v_lshl_add_u64 v[228:229], v[228:229], 0, v[236:237]
	v_mov_b32_e32 v231, 0
	ds_read_b128 v[130:133], v178
	ds_read_b128 v[134:137], v178 offset:1024
	ds_read_b128 v[138:141], v178 offset:2048
	ds_read_b128 v[142:145], v178 offset:3072
	ds_read_b128 v[162:165], v179
	ds_read_b128 v[166:169], v179 offset:1024
	ds_read_b128 v[170:173], v179 offset:2048
	ds_read_b128 v[182:185], v179 offset:3072
	s_add_u32 s34, s38, 0xffea0080
	s_addc_u32 s35, s39, -1
	s_cmpk_eq_i32 s52, 0x54
	s_cselect_b32 s41, s5, s35
	s_cselect_b32 s40, s4, s34
	s_cselect_b32 s35, s37, s1
	s_cselect_b32 s34, s36, s0
	v_lshl_add_u64 v[174:175], s[38:39], 0, v[154:155]
	s_add_i32 m0, s33, 0xc000
	ds_read_b128 v[186:189], v180
	ds_read_b128 v[190:193], v180 offset:1024
	ds_read_b128 v[194:197], v180 offset:2048
	ds_read_b128 v[198:201], v180 offset:3072
	ds_read_b128 v[202:205], v180 offset:4096
	ds_read_b128 v[206:209], v180 offset:5120
	ds_read_b128 v[210:213], v180 offset:6144
	ds_read_b128 v[218:221], v180 offset:7168
	global_load_lds_dwordx4 v[174:175], off
	v_lshl_add_u64 v[174:175], s[38:39], 0, v[156:157]
	s_add_i32 m0, s33, 0xe000
	s_nop 0
	global_load_lds_dwordx4 v[174:175], off
	s_waitcnt vmcnt(8)
	s_waitcnt lgkmcnt(0)
	s_barrier
	s_setprio 1
	s_waitcnt lgkmcnt(0)
	v_mfma_f32_16x16x32_bf16 v[126:129], v[130:133], v[186:189], v[126:129]
	v_mfma_f32_16x16x32_bf16 v[122:125], v[138:141], v[186:189], v[122:125]
	v_mfma_f32_16x16x32_bf16 v[110:113], v[130:133], v[194:197], v[110:113]
	v_mfma_f32_16x16x32_bf16 v[106:109], v[138:141], v[194:197], v[106:109]
	v_mfma_f32_16x16x32_bf16 v[94:97], v[130:133], v[202:205], v[94:97]
	v_mfma_f32_16x16x32_bf16 v[90:93], v[138:141], v[202:205], v[90:93]
	v_mfma_f32_16x16x32_bf16 v[78:81], v[130:133], v[210:213], v[78:81]
	v_mfma_f32_16x16x32_bf16 v[74:77], v[138:141], v[210:213], v[74:77]
	v_mfma_f32_16x16x32_bf16 v[126:129], v[134:137], v[190:193], v[126:129]
	v_mfma_f32_16x16x32_bf16 v[122:125], v[142:145], v[190:193], v[122:125]
	v_mfma_f32_16x16x32_bf16 v[110:113], v[134:137], v[198:201], v[110:113]
	v_mfma_f32_16x16x32_bf16 v[106:109], v[142:145], v[198:201], v[106:109]
	v_mfma_f32_16x16x32_bf16 v[94:97], v[134:137], v[206:209], v[94:97]
	v_mfma_f32_16x16x32_bf16 v[90:93], v[142:145], v[206:209], v[90:93]
	v_mfma_f32_16x16x32_bf16 v[78:81], v[134:137], v[218:221], v[78:81]
	v_mfma_f32_16x16x32_bf16 v[74:77], v[142:145], v[218:221], v[74:77]
	s_setprio 0
	s_setprio 1
	v_mfma_f32_16x16x32_bf16 v[118:121], v[162:165], v[186:189], v[118:121]
	v_mfma_f32_16x16x32_bf16 v[114:117], v[170:173], v[186:189], v[114:117]
	v_mfma_f32_16x16x32_bf16 v[102:105], v[162:165], v[194:197], v[102:105]
	v_mfma_f32_16x16x32_bf16 v[98:101], v[170:173], v[194:197], v[98:101]
	v_mfma_f32_16x16x32_bf16 v[86:89], v[162:165], v[202:205], v[86:89]
	v_mfma_f32_16x16x32_bf16 v[82:85], v[170:173], v[202:205], v[82:85]
	v_mfma_f32_16x16x32_bf16 v[70:73], v[162:165], v[210:213], v[70:73]
	v_mfma_f32_16x16x32_bf16 v[66:69], v[170:173], v[210:213], v[66:69]
	v_mfma_f32_16x16x32_bf16 v[118:121], v[166:169], v[190:193], v[118:121]
	v_mfma_f32_16x16x32_bf16 v[114:117], v[182:185], v[190:193], v[114:117]
	v_mfma_f32_16x16x32_bf16 v[102:105], v[166:169], v[198:201], v[102:105]
	v_mfma_f32_16x16x32_bf16 v[98:101], v[182:185], v[198:201], v[98:101]
	v_mfma_f32_16x16x32_bf16 v[86:89], v[166:169], v[206:209], v[86:89]
	v_mfma_f32_16x16x32_bf16 v[82:85], v[182:185], v[206:209], v[82:85]
	v_mfma_f32_16x16x32_bf16 v[70:73], v[166:169], v[218:221], v[70:73]
	v_mfma_f32_16x16x32_bf16 v[66:69], v[182:185], v[218:221], v[66:69]
	s_setprio 0
	s_barrier
	s_add_i32 s53, s61, s31
	v_lshl_add_u64 v[174:175], s[34:35], 0, v[148:149]
	s_mov_b32 m0, s53
	ds_read_b128 v[186:189], v180 offset:16384
	ds_read_b128 v[190:193], v180 offset:17408
	ds_read_b128 v[194:197], v180 offset:18432
	ds_read_b128 v[198:201], v180 offset:19456
	ds_read_b128 v[202:205], v180 offset:20480
	ds_read_b128 v[206:209], v180 offset:21504
	ds_read_b128 v[210:213], v180 offset:22528
	ds_read_b128 v[218:221], v180 offset:23552
	v_mov_b32_e32 v230, 0x0
	v_lshl_add_u64 v[232:233], v[230:231], 0, v[228:229]
	global_load_lds_dwordx4 v[232:233], off
	s_add_i32 m0, s53, 0x2000
	s_add_u32 s54, s34, 0x160000
	v_lshl_add_u64 v[214:215], s[34:35], 0, v[152:153]
	s_addc_u32 s55, s35, 0
	s_add_i32 s53, s70, s31
	v_mov_b32_e32 v230, 0x100
	v_lshl_add_u64 v[232:233], v[230:231], 0, v[228:229]
	global_load_lds_dwordx4 v[232:233], off
	v_lshl_add_u64 v[222:223], s[54:55], 0, v[148:149]
	s_mov_b32 m0, s53
	v_lshl_add_u64 v[224:225], s[40:41], 0, v[150:151]
	v_mov_b32_e32 v230, 0x10000
	v_lshl_add_u64 v[232:233], v[230:231], 0, v[228:229]
	global_load_lds_dwordx4 v[232:233], off
	v_lshl_add_u64 v[222:223], s[54:55], 0, v[152:153]
	s_add_i32 m0, s53, 0x2000
	s_nop 0
	v_mov_b32_e32 v230, 0x10100
	v_lshl_add_u64 v[232:233], v[230:231], 0, v[228:229]
	global_load_lds_dwordx4 v[232:233], off
	v_lshl_add_u64 v[222:223], s[40:41], 0, v[146:147]
	s_mov_b32 m0, s33
	s_nop 0
	v_mov_b32_e32 v230, 0x20000
	v_lshl_add_u64 v[232:233], v[230:231], 0, v[228:229]
	global_load_lds_dwordx4 v[232:233], off
	s_mov_b32 m0, s46
	s_nop 0
	v_mov_b32_e32 v230, 0x20100
	v_lshl_add_u64 v[232:233], v[230:231], 0, v[228:229]
	global_load_lds_dwordx4 v[232:233], off
	s_waitcnt vmcnt(8)
	s_waitcnt lgkmcnt(0)
	s_barrier
	s_setprio 1
	s_waitcnt lgkmcnt(0)
	v_mfma_f32_16x16x32_bf16 v[62:65], v[130:133], v[186:189], v[62:65]
	v_mfma_f32_16x16x32_bf16 v[58:61], v[138:141], v[186:189], v[58:61]
	v_mfma_f32_16x16x32_bf16 v[50:53], v[130:133], v[194:197], v[50:53]
	v_mfma_f32_16x16x32_bf16 v[42:45], v[138:141], v[194:197], v[42:45]
	v_mfma_f32_16x16x32_bf16 v[38:41], v[130:133], v[202:205], v[38:41]
	v_mfma_f32_16x16x32_bf16 v[34:37], v[138:141], v[202:205], v[34:37]
	v_mfma_f32_16x16x32_bf16 v[14:17], v[130:133], v[210:213], v[14:17]
	v_mfma_f32_16x16x32_bf16 v[10:13], v[138:141], v[210:213], v[10:13]
	v_mfma_f32_16x16x32_bf16 v[62:65], v[134:137], v[190:193], v[62:65]
	v_mfma_f32_16x16x32_bf16 v[58:61], v[142:145], v[190:193], v[58:61]
	v_mfma_f32_16x16x32_bf16 v[50:53], v[134:137], v[198:201], v[50:53]
	v_mfma_f32_16x16x32_bf16 v[42:45], v[142:145], v[198:201], v[42:45]
	v_mfma_f32_16x16x32_bf16 v[38:41], v[134:137], v[206:209], v[38:41]
	v_mfma_f32_16x16x32_bf16 v[34:37], v[142:145], v[206:209], v[34:37]
	v_mfma_f32_16x16x32_bf16 v[14:17], v[134:137], v[218:221], v[14:17]
	v_mfma_f32_16x16x32_bf16 v[10:13], v[142:145], v[218:221], v[10:13]
	s_setprio 0
	s_setprio 1
	v_mfma_f32_16x16x32_bf16 v[54:57], v[162:165], v[186:189], v[54:57]
	v_mfma_f32_16x16x32_bf16 v[46:49], v[170:173], v[186:189], v[46:49]
	v_mfma_f32_16x16x32_bf16 v[30:33], v[162:165], v[194:197], v[30:33]
	v_mfma_f32_16x16x32_bf16 v[26:29], v[170:173], v[194:197], v[26:29]
	v_mfma_f32_16x16x32_bf16 v[22:25], v[162:165], v[202:205], v[22:25]
	v_mfma_f32_16x16x32_bf16 v[18:21], v[170:173], v[202:205], v[18:21]
	v_mfma_f32_16x16x32_bf16 v[6:9], v[162:165], v[210:213], v[6:9]
	v_mfma_f32_16x16x32_bf16 v[2:5], v[170:173], v[210:213], v[2:5]
	v_mfma_f32_16x16x32_bf16 v[54:57], v[166:169], v[190:193], v[54:57]
	v_mfma_f32_16x16x32_bf16 v[46:49], v[182:185], v[190:193], v[46:49]
	v_mfma_f32_16x16x32_bf16 v[30:33], v[166:169], v[198:201], v[30:33]
	v_mfma_f32_16x16x32_bf16 v[26:29], v[182:185], v[198:201], v[26:29]
	v_mfma_f32_16x16x32_bf16 v[22:25], v[166:169], v[206:209], v[22:25]
	v_mfma_f32_16x16x32_bf16 v[18:21], v[182:185], v[206:209], v[18:21]
	v_mfma_f32_16x16x32_bf16 v[6:9], v[166:169], v[218:221], v[6:9]
	v_mfma_f32_16x16x32_bf16 v[2:5], v[182:185], v[218:221], v[2:5]
	s_setprio 0
	s_barrier
	s_add_i32 s53, 0, 0x18000
	s_add_i32 s54, 0, 0x1c000
	v_add_u32_e32 v142, s53, v176
	v_add_u32_e32 v181, s54, v176
	ds_read_b128 v[130:133], v142
	ds_read_b128 v[134:137], v142 offset:1024
	ds_read_b128 v[138:141], v142 offset:2048
	ds_read_b128 v[142:145], v142 offset:3072
	ds_read_b128 v[162:165], v181
	ds_read_b128 v[166:169], v181 offset:1024
	ds_read_b128 v[170:173], v181 offset:2048
	ds_read_b128 v[182:185], v181 offset:3072
	s_add_u32 s40, s40, 0x160000
	s_addc_u32 s41, s41, 0
	s_mov_b32 m0, s47
	v_lshl_add_u64 v[226:227], s[40:41], 0, v[146:147]
	ds_read_b128 v[186:189], v180 offset:32768
	ds_read_b128 v[190:193], v180 offset:33792
	ds_read_b128 v[194:197], v180 offset:34816
	ds_read_b128 v[198:201], v180 offset:35840
	ds_read_b128 v[202:205], v180 offset:36864
	ds_read_b128 v[206:209], v180 offset:37888
	ds_read_b128 v[210:213], v180 offset:38912
	ds_read_b128 v[218:221], v180 offset:39936
	v_mov_b32_e32 v230, 0x30000
	v_lshl_add_u64 v[232:233], v[230:231], 0, v[228:229]
	global_load_lds_dwordx4 v[232:233], off
	v_lshl_add_u64 v[226:227], s[40:41], 0, v[150:151]
	s_mov_b32 m0, s56
	s_nop 0
	v_mov_b32_e32 v230, 0x30100
	v_lshl_add_u64 v[232:233], v[230:231], 0, v[228:229]
	global_load_lds_dwordx4 v[232:233], off
	s_waitcnt vmcnt(8)
	s_waitcnt lgkmcnt(0)
	s_barrier
	s_setprio 1
	s_waitcnt lgkmcnt(0)
	v_mfma_f32_16x16x32_bf16 v[126:129], v[130:133], v[186:189], v[126:129]
	v_mfma_f32_16x16x32_bf16 v[122:125], v[138:141], v[186:189], v[122:125]
	v_mfma_f32_16x16x32_bf16 v[110:113], v[130:133], v[194:197], v[110:113]
	v_mfma_f32_16x16x32_bf16 v[106:109], v[138:141], v[194:197], v[106:109]
	v_mfma_f32_16x16x32_bf16 v[94:97], v[130:133], v[202:205], v[94:97]
	v_mfma_f32_16x16x32_bf16 v[90:93], v[138:141], v[202:205], v[90:93]
	v_mfma_f32_16x16x32_bf16 v[78:81], v[130:133], v[210:213], v[78:81]
	v_mfma_f32_16x16x32_bf16 v[74:77], v[138:141], v[210:213], v[74:77]
	v_mfma_f32_16x16x32_bf16 v[126:129], v[134:137], v[190:193], v[126:129]
	v_mfma_f32_16x16x32_bf16 v[122:125], v[142:145], v[190:193], v[122:125]
	v_mfma_f32_16x16x32_bf16 v[110:113], v[134:137], v[198:201], v[110:113]
	v_mfma_f32_16x16x32_bf16 v[106:109], v[142:145], v[198:201], v[106:109]
	v_mfma_f32_16x16x32_bf16 v[94:97], v[134:137], v[206:209], v[94:97]
	v_mfma_f32_16x16x32_bf16 v[90:93], v[142:145], v[206:209], v[90:93]
	v_mfma_f32_16x16x32_bf16 v[78:81], v[134:137], v[218:221], v[78:81]
	v_mfma_f32_16x16x32_bf16 v[74:77], v[142:145], v[218:221], v[74:77]
	s_setprio 0
	s_setprio 1
	v_mfma_f32_16x16x32_bf16 v[118:121], v[162:165], v[186:189], v[118:121]
	v_mfma_f32_16x16x32_bf16 v[114:117], v[170:173], v[186:189], v[114:117]
	v_mfma_f32_16x16x32_bf16 v[102:105], v[162:165], v[194:197], v[102:105]
	v_mfma_f32_16x16x32_bf16 v[98:101], v[170:173], v[194:197], v[98:101]
	v_mfma_f32_16x16x32_bf16 v[86:89], v[162:165], v[202:205], v[86:89]
	v_mfma_f32_16x16x32_bf16 v[82:85], v[170:173], v[202:205], v[82:85]
	v_mfma_f32_16x16x32_bf16 v[70:73], v[162:165], v[210:213], v[70:73]
	v_mfma_f32_16x16x32_bf16 v[66:69], v[170:173], v[210:213], v[66:69]
	v_mfma_f32_16x16x32_bf16 v[118:121], v[166:169], v[190:193], v[118:121]
	v_mfma_f32_16x16x32_bf16 v[114:117], v[182:185], v[190:193], v[114:117]
	v_mfma_f32_16x16x32_bf16 v[102:105], v[166:169], v[198:201], v[102:105]
	v_mfma_f32_16x16x32_bf16 v[98:101], v[182:185], v[198:201], v[98:101]
	v_mfma_f32_16x16x32_bf16 v[86:89], v[166:169], v[206:209], v[86:89]
	v_mfma_f32_16x16x32_bf16 v[82:85], v[182:185], v[206:209], v[82:85]
	v_mfma_f32_16x16x32_bf16 v[70:73], v[166:169], v[218:221], v[70:73]
	v_mfma_f32_16x16x32_bf16 v[66:69], v[182:185], v[218:221], v[66:69]
	s_setprio 0
	s_barrier
	s_add_i32 s40, s53, s31
	v_lshl_add_u64 v[174:175], v[174:175], 0, s[24:25]
	s_mov_b32 m0, s40
	ds_read_b128 v[186:189], v180 offset:49152
	ds_read_b128 v[190:193], v180 offset:50176
	ds_read_b128 v[194:197], v180 offset:51200
	ds_read_b128 v[198:201], v180 offset:52224
	ds_read_b128 v[202:205], v180 offset:53248
	ds_read_b128 v[206:209], v180 offset:54272
	ds_read_b128 v[210:213], v180 offset:55296
	ds_read_b128 v[218:221], v180 offset:56320
	v_mov_b32_e32 v230, 0x80000
	v_lshl_add_u64 v[232:233], v[230:231], 0, v[228:229]
	global_load_lds_dwordx4 v[232:233], off
	s_add_i32 m0, s40, 0x2000
	s_add_u32 s34, s34, 0x160080
	v_lshl_add_u64 v[174:175], v[214:215], 0, s[24:25]
	s_addc_u32 s35, s35, 0
	s_add_i32 s40, s54, s31
	v_mov_b32_e32 v230, 0x80100
	v_lshl_add_u64 v[232:233], v[230:231], 0, v[228:229]
	global_load_lds_dwordx4 v[232:233], off
	v_lshl_add_u64 v[174:175], s[34:35], 0, v[148:149]
	s_mov_b32 m0, s40
	s_nop 0
	v_mov_b32_e32 v230, 0x90000
	v_lshl_add_u64 v[232:233], v[230:231], 0, v[228:229]
	global_load_lds_dwordx4 v[232:233], off
	v_lshl_add_u64 v[174:175], s[34:35], 0, v[152:153]
	s_add_i32 m0, s40, 0x2000
	s_nop 0
	v_mov_b32_e32 v230, 0x90100
	v_lshl_add_u64 v[232:233], v[230:231], 0, v[228:229]
	global_load_lds_dwordx4 v[232:233], off
	v_lshl_add_u64 v[174:175], v[222:223], 0, s[24:25]
	s_mov_b32 m0, s58
	s_nop 0
	v_mov_b32_e32 v230, 0xa0000
	v_lshl_add_u64 v[232:233], v[230:231], 0, v[228:229]
	global_load_lds_dwordx4 v[232:233], off
	v_lshl_add_u64 v[174:175], v[224:225], 0, s[24:25]
	s_mov_b32 m0, s59
	s_nop 0
	v_mov_b32_e32 v230, 0xa0100
	v_lshl_add_u64 v[232:233], v[230:231], 0, v[228:229]
	global_load_lds_dwordx4 v[232:233], off
	s_waitcnt vmcnt(8)
	s_waitcnt lgkmcnt(0)
	s_barrier
	s_setprio 1
	s_waitcnt lgkmcnt(0)
	v_mfma_f32_16x16x32_bf16 v[62:65], v[130:133], v[186:189], v[62:65]
	v_mfma_f32_16x16x32_bf16 v[58:61], v[138:141], v[186:189], v[58:61]
	v_mfma_f32_16x16x32_bf16 v[50:53], v[130:133], v[194:197], v[50:53]
	v_mfma_f32_16x16x32_bf16 v[42:45], v[138:141], v[194:197], v[42:45]
	v_mfma_f32_16x16x32_bf16 v[38:41], v[130:133], v[202:205], v[38:41]
	v_mfma_f32_16x16x32_bf16 v[34:37], v[138:141], v[202:205], v[34:37]
	v_mfma_f32_16x16x32_bf16 v[14:17], v[130:133], v[210:213], v[14:17]
	v_mfma_f32_16x16x32_bf16 v[10:13], v[138:141], v[210:213], v[10:13]
	v_mfma_f32_16x16x32_bf16 v[62:65], v[134:137], v[190:193], v[62:65]
	v_mfma_f32_16x16x32_bf16 v[58:61], v[142:145], v[190:193], v[58:61]
	v_mfma_f32_16x16x32_bf16 v[50:53], v[134:137], v[198:201], v[50:53]
	v_mfma_f32_16x16x32_bf16 v[42:45], v[142:145], v[198:201], v[42:45]
	v_mfma_f32_16x16x32_bf16 v[38:41], v[134:137], v[206:209], v[38:41]
	v_mfma_f32_16x16x32_bf16 v[34:37], v[142:145], v[206:209], v[34:37]
	v_mfma_f32_16x16x32_bf16 v[14:17], v[134:137], v[218:221], v[14:17]
	v_mfma_f32_16x16x32_bf16 v[10:13], v[142:145], v[218:221], v[10:13]
	s_setprio 0
	s_setprio 1
	v_mfma_f32_16x16x32_bf16 v[54:57], v[162:165], v[186:189], v[54:57]
	v_mfma_f32_16x16x32_bf16 v[46:49], v[170:173], v[186:189], v[46:49]
	v_mfma_f32_16x16x32_bf16 v[30:33], v[162:165], v[194:197], v[30:33]
	v_mfma_f32_16x16x32_bf16 v[26:29], v[170:173], v[194:197], v[26:29]
	v_mfma_f32_16x16x32_bf16 v[22:25], v[162:165], v[202:205], v[22:25]
	v_mfma_f32_16x16x32_bf16 v[18:21], v[170:173], v[202:205], v[18:21]
	v_mfma_f32_16x16x32_bf16 v[6:9], v[162:165], v[210:213], v[6:9]
	v_mfma_f32_16x16x32_bf16 v[2:5], v[170:173], v[210:213], v[2:5]
	v_mfma_f32_16x16x32_bf16 v[54:57], v[166:169], v[190:193], v[54:57]
	v_mfma_f32_16x16x32_bf16 v[46:49], v[182:185], v[190:193], v[46:49]
	v_mfma_f32_16x16x32_bf16 v[30:33], v[166:169], v[198:201], v[30:33]
	v_mfma_f32_16x16x32_bf16 v[26:29], v[182:185], v[198:201], v[26:29]
	v_mfma_f32_16x16x32_bf16 v[22:25], v[166:169], v[206:209], v[22:25]
	v_mfma_f32_16x16x32_bf16 v[18:21], v[182:185], v[206:209], v[18:21]
	v_mfma_f32_16x16x32_bf16 v[6:9], v[166:169], v[218:221], v[6:9]
	v_mfma_f32_16x16x32_bf16 v[2:5], v[182:185], v[218:221], v[2:5]
	s_setprio 0
	s_barrier
	s_add_i32 s52, s52, 2
	s_add_u32 s38, s38, 0x100
	s_addc_u32 s39, s39, 0
	s_add_u32 s0, s0, 0x100
	s_addc_u32 s1, s1, 0
	s_and_b64 vcc, exec, s[26:27]
	s_cbranch_vccz .LBB0_2092
	s_barrier
.LBB0_2092:
	v_lshl_or_b32 v130, s74, 8, v177
	v_lshl_add_u32 v162, s73, 8, v1
	v_ashrrev_i32_e32 v131, 31, v130
	v_lshlrev_b64 v[164:165], 1, v[130:131]
	v_or_b32_e32 v130, 16, v162
	v_ashrrev_i32_e32 v163, 31, v162
	v_ashrrev_i32_e32 v131, 31, v130
	v_lshlrev_b64 v[132:133], 12, v[162:163]
	v_lshlrev_b64 v[130:131], 12, v[130:131]
	v_lshl_add_u64 v[132:133], s[64:65], 0, v[132:133]
	v_lshl_add_u64 v[130:131], s[64:65], 0, v[130:131]
	v_lshl_add_u64 v[174:175], v[132:133], 0, v[164:165]
	v_lshl_add_u64 v[172:173], v[130:131], 0, v[164:165]
	s_waitcnt vmcnt(0)
	v_mov_b32_e32 v201, 0
	v_mov_b32_e32 v200, 0x10000
	v_lshl_add_u64 v[186:187], v[200:201], 0, v[174:175]
	v_mov_b32_e32 v200, 0x20000
	v_lshl_add_u64 v[188:189], v[200:201], 0, v[174:175]
	v_mov_b32_e32 v200, 0x30000
	v_lshl_add_u64 v[190:191], v[200:201], 0, v[174:175]
	v_mov_b32_e32 v200, 0x80000
	v_lshl_add_u64 v[192:193], v[200:201], 0, v[174:175]
	v_mov_b32_e32 v200, 0x90000
	v_lshl_add_u64 v[194:195], v[200:201], 0, v[174:175]
	v_mov_b32_e32 v200, 0xa0000
	v_lshl_add_u64 v[196:197], v[200:201], 0, v[174:175]
	v_mov_b32_e32 v200, 0xb0000
	v_lshl_add_u64 v[198:199], v[200:201], 0, v[174:175]
	v_lshlrev_b32_e32 v202, 4, v0
	v_add_u32_e32 v203, 0x10000, v202
	global_load_dwordx4 v[162:165], v[198:199], off
	global_load_dwordx4 v[166:169], v[198:199], off offset:256
	ds_read_b128 v[130:133], v203 offset:0
	ds_read_b128 v[134:137], v203 offset:8192
	ds_read_b128 v[138:141], v203 offset:16384
	ds_read_b128 v[142:145], v203 offset:24576
	s_waitcnt lgkmcnt(3)
	v_cvt_f32_f16_e32 v170, v130
	v_cvt_f32_f16_sdwa v171, v130 dst_sel:DWORD dst_unused:UNUSED_PAD src0_sel:WORD_1
	v_cvt_f32_f16_e32 v172, v131
	v_cvt_f32_f16_sdwa v173, v131 dst_sel:DWORD dst_unused:UNUSED_PAD src0_sel:WORD_1
	v_cvt_f32_f16_e32 v182, v132
	v_cvt_f32_f16_sdwa v183, v132 dst_sel:DWORD dst_unused:UNUSED_PAD src0_sel:WORD_1
	v_cvt_f32_f16_e32 v184, v133
	v_cvt_f32_f16_sdwa v185, v133 dst_sel:DWORD dst_unused:UNUSED_PAD src0_sel:WORD_1
	ds_read_b128 v[130:133], v202 offset:0
	v_pk_fma_f32 v[126:127], v[126:127], 0.5, v[170:171] op_sel_hi:[1,0,1]
	v_pk_fma_f32 v[128:129], v[128:129], 0.5, v[172:173] op_sel_hi:[1,0,1]
	v_pk_fma_f32 v[122:123], v[122:123], 0.5, v[182:183] op_sel_hi:[1,0,1]
	v_pk_fma_f32 v[124:125], v[124:125], 0.5, v[184:185] op_sel_hi:[1,0,1]
	v_cvt_pk_f16_f32 v125, v124, v125
	v_cvt_pk_f16_f32 v124, v122, v123
	v_cvt_pk_f16_f32 v123, v128, v129
	v_cvt_pk_f16_f32 v122, v126, v127
	global_store_dwordx4 v[174:175], v[122:125], off
	s_waitcnt lgkmcnt(3)
	v_cvt_f32_f16_e32 v170, v134
	v_cvt_f32_f16_sdwa v171, v134 dst_sel:DWORD dst_unused:UNUSED_PAD src0_sel:WORD_1
	v_cvt_f32_f16_e32 v172, v135
	v_cvt_f32_f16_sdwa v173, v135 dst_sel:DWORD dst_unused:UNUSED_PAD src0_sel:WORD_1
	v_cvt_f32_f16_e32 v182, v136
	v_cvt_f32_f16_sdwa v183, v136 dst_sel:DWORD dst_unused:UNUSED_PAD src0_sel:WORD_1
	v_cvt_f32_f16_e32 v184, v137
	v_cvt_f32_f16_sdwa v185, v137 dst_sel:DWORD dst_unused:UNUSED_PAD src0_sel:WORD_1
	ds_read_b128 v[134:137], v202 offset:8192
	v_pk_fma_f32 v[118:119], v[118:119], 0.5, v[170:171] op_sel_hi:[1,0,1]
	v_pk_fma_f32 v[120:121], v[120:121], 0.5, v[172:173] op_sel_hi:[1,0,1]
	v_pk_fma_f32 v[114:115], v[114:115], 0.5, v[182:183] op_sel_hi:[1,0,1]
	v_pk_fma_f32 v[116:117], v[116:117], 0.5, v[184:185] op_sel_hi:[1,0,1]
	v_cvt_pk_f16_f32 v117, v116, v117
	v_cvt_pk_f16_f32 v116, v114, v115
	v_cvt_pk_f16_f32 v115, v120, v121
	v_cvt_pk_f16_f32 v114, v118, v119
	global_store_dwordx4 v[174:175], v[114:117], off offset:256
	s_waitcnt lgkmcnt(3)
	v_cvt_f32_f16_e32 v170, v138
	v_cvt_f32_f16_sdwa v171, v138 dst_sel:DWORD dst_unused:UNUSED_PAD src0_sel:WORD_1
	v_cvt_f32_f16_e32 v172, v139
	v_cvt_f32_f16_sdwa v173, v139 dst_sel:DWORD dst_unused:UNUSED_PAD src0_sel:WORD_1
	v_cvt_f32_f16_e32 v182, v140
	v_cvt_f32_f16_sdwa v183, v140 dst_sel:DWORD dst_unused:UNUSED_PAD src0_sel:WORD_1
	v_cvt_f32_f16_e32 v184, v141
	v_cvt_f32_f16_sdwa v185, v141 dst_sel:DWORD dst_unused:UNUSED_PAD src0_sel:WORD_1
	ds_read_b128 v[138:141], v202 offset:16384
	v_pk_fma_f32 v[110:111], v[110:111], 0.5, v[170:171] op_sel_hi:[1,0,1]
	v_pk_fma_f32 v[112:113], v[112:113], 0.5, v[172:173] op_sel_hi:[1,0,1]
	v_pk_fma_f32 v[106:107], v[106:107], 0.5, v[182:183] op_sel_hi:[1,0,1]
	v_pk_fma_f32 v[108:109], v[108:109], 0.5, v[184:185] op_sel_hi:[1,0,1]
	v_cvt_pk_f16_f32 v109, v108, v109
	v_cvt_pk_f16_f32 v108, v106, v107
	v_cvt_pk_f16_f32 v107, v112, v113
	v_cvt_pk_f16_f32 v106, v110, v111
	global_store_dwordx4 v[186:187], v[106:109], off
	s_waitcnt lgkmcnt(3)
	v_cvt_f32_f16_e32 v170, v142
	v_cvt_f32_f16_sdwa v171, v142 dst_sel:DWORD dst_unused:UNUSED_PAD src0_sel:WORD_1
	v_cvt_f32_f16_e32 v172, v143
	v_cvt_f32_f16_sdwa v173, v143 dst_sel:DWORD dst_unused:UNUSED_PAD src0_sel:WORD_1
	v_cvt_f32_f16_e32 v182, v144
	v_cvt_f32_f16_sdwa v183, v144 dst_sel:DWORD dst_unused:UNUSED_PAD src0_sel:WORD_1
	v_cvt_f32_f16_e32 v184, v145
	v_cvt_f32_f16_sdwa v185, v145 dst_sel:DWORD dst_unused:UNUSED_PAD src0_sel:WORD_1
	ds_read_b128 v[142:145], v202 offset:24576
	v_pk_fma_f32 v[102:103], v[102:103], 0.5, v[170:171] op_sel_hi:[1,0,1]
	v_pk_fma_f32 v[104:105], v[104:105], 0.5, v[172:173] op_sel_hi:[1,0,1]
	v_pk_fma_f32 v[98:99], v[98:99], 0.5, v[182:183] op_sel_hi:[1,0,1]
	v_pk_fma_f32 v[100:101], v[100:101], 0.5, v[184:185] op_sel_hi:[1,0,1]
	v_cvt_pk_f16_f32 v101, v100, v101
	v_cvt_pk_f16_f32 v100, v98, v99
	v_cvt_pk_f16_f32 v99, v104, v105
	v_cvt_pk_f16_f32 v98, v102, v103
	global_store_dwordx4 v[186:187], v[98:101], off offset:256
	s_waitcnt lgkmcnt(3)
	v_cvt_f32_f16_e32 v170, v130
	v_cvt_f32_f16_sdwa v171, v130 dst_sel:DWORD dst_unused:UNUSED_PAD src0_sel:WORD_1
	v_cvt_f32_f16_e32 v172, v131
	v_cvt_f32_f16_sdwa v173, v131 dst_sel:DWORD dst_unused:UNUSED_PAD src0_sel:WORD_1
	v_cvt_f32_f16_e32 v182, v132
	v_cvt_f32_f16_sdwa v183, v132 dst_sel:DWORD dst_unused:UNUSED_PAD src0_sel:WORD_1
	v_cvt_f32_f16_e32 v184, v133
	v_cvt_f32_f16_sdwa v185, v133 dst_sel:DWORD dst_unused:UNUSED_PAD src0_sel:WORD_1
	ds_read_b128 v[130:133], v203 offset:32768
	v_pk_fma_f32 v[94:95], v[94:95], 0.5, v[170:171] op_sel_hi:[1,0,1]
	v_pk_fma_f32 v[96:97], v[96:97], 0.5, v[172:173] op_sel_hi:[1,0,1]
	v_pk_fma_f32 v[90:91], v[90:91], 0.5, v[182:183] op_sel_hi:[1,0,1]
	v_pk_fma_f32 v[92:93], v[92:93], 0.5, v[184:185] op_sel_hi:[1,0,1]
	v_cvt_pk_f16_f32 v93, v92, v93
	v_cvt_pk_f16_f32 v92, v90, v91
	v_cvt_pk_f16_f32 v91, v96, v97
	v_cvt_pk_f16_f32 v90, v94, v95
	global_store_dwordx4 v[188:189], v[90:93], off
	s_waitcnt lgkmcnt(3)
	v_cvt_f32_f16_e32 v170, v134
	v_cvt_f32_f16_sdwa v171, v134 dst_sel:DWORD dst_unused:UNUSED_PAD src0_sel:WORD_1
	v_cvt_f32_f16_e32 v172, v135
	v_cvt_f32_f16_sdwa v173, v135 dst_sel:DWORD dst_unused:UNUSED_PAD src0_sel:WORD_1
	v_cvt_f32_f16_e32 v182, v136
	v_cvt_f32_f16_sdwa v183, v136 dst_sel:DWORD dst_unused:UNUSED_PAD src0_sel:WORD_1
	v_cvt_f32_f16_e32 v184, v137
	v_cvt_f32_f16_sdwa v185, v137 dst_sel:DWORD dst_unused:UNUSED_PAD src0_sel:WORD_1
	ds_read_b128 v[134:137], v203 offset:40960
	v_pk_fma_f32 v[86:87], v[86:87], 0.5, v[170:171] op_sel_hi:[1,0,1]
	v_pk_fma_f32 v[88:89], v[88:89], 0.5, v[172:173] op_sel_hi:[1,0,1]
	v_pk_fma_f32 v[82:83], v[82:83], 0.5, v[182:183] op_sel_hi:[1,0,1]
	v_pk_fma_f32 v[84:85], v[84:85], 0.5, v[184:185] op_sel_hi:[1,0,1]
	v_cvt_pk_f16_f32 v85, v84, v85
	v_cvt_pk_f16_f32 v84, v82, v83
	v_cvt_pk_f16_f32 v83, v88, v89
	v_cvt_pk_f16_f32 v82, v86, v87
	global_store_dwordx4 v[188:189], v[82:85], off offset:256
	s_waitcnt lgkmcnt(3)
	v_cvt_f32_f16_e32 v170, v138
	v_cvt_f32_f16_sdwa v171, v138 dst_sel:DWORD dst_unused:UNUSED_PAD src0_sel:WORD_1
	v_cvt_f32_f16_e32 v172, v139
	v_cvt_f32_f16_sdwa v173, v139 dst_sel:DWORD dst_unused:UNUSED_PAD src0_sel:WORD_1
	v_cvt_f32_f16_e32 v182, v140
	v_cvt_f32_f16_sdwa v183, v140 dst_sel:DWORD dst_unused:UNUSED_PAD src0_sel:WORD_1
	v_cvt_f32_f16_e32 v184, v141
	v_cvt_f32_f16_sdwa v185, v141 dst_sel:DWORD dst_unused:UNUSED_PAD src0_sel:WORD_1
	ds_read_b128 v[138:141], v203 offset:49152
	v_pk_fma_f32 v[78:79], v[78:79], 0.5, v[170:171] op_sel_hi:[1,0,1]
	v_pk_fma_f32 v[80:81], v[80:81], 0.5, v[172:173] op_sel_hi:[1,0,1]
	v_pk_fma_f32 v[74:75], v[74:75], 0.5, v[182:183] op_sel_hi:[1,0,1]
	v_pk_fma_f32 v[76:77], v[76:77], 0.5, v[184:185] op_sel_hi:[1,0,1]
	v_cvt_pk_f16_f32 v77, v76, v77
	v_cvt_pk_f16_f32 v76, v74, v75
	v_cvt_pk_f16_f32 v75, v80, v81
	v_cvt_pk_f16_f32 v74, v78, v79
	global_store_dwordx4 v[190:191], v[74:77], off
	s_waitcnt lgkmcnt(3)
	v_cvt_f32_f16_e32 v170, v142
	v_cvt_f32_f16_sdwa v171, v142 dst_sel:DWORD dst_unused:UNUSED_PAD src0_sel:WORD_1
	v_cvt_f32_f16_e32 v172, v143
	v_cvt_f32_f16_sdwa v173, v143 dst_sel:DWORD dst_unused:UNUSED_PAD src0_sel:WORD_1
	v_cvt_f32_f16_e32 v182, v144
	v_cvt_f32_f16_sdwa v183, v144 dst_sel:DWORD dst_unused:UNUSED_PAD src0_sel:WORD_1
	v_cvt_f32_f16_e32 v184, v145
	v_cvt_f32_f16_sdwa v185, v145 dst_sel:DWORD dst_unused:UNUSED_PAD src0_sel:WORD_1
	ds_read_b128 v[142:145], v203 offset:57344
	v_pk_fma_f32 v[70:71], v[70:71], 0.5, v[170:171] op_sel_hi:[1,0,1]
	v_pk_fma_f32 v[72:73], v[72:73], 0.5, v[172:173] op_sel_hi:[1,0,1]
	v_pk_fma_f32 v[66:67], v[66:67], 0.5, v[182:183] op_sel_hi:[1,0,1]
	v_pk_fma_f32 v[68:69], v[68:69], 0.5, v[184:185] op_sel_hi:[1,0,1]
	v_cvt_pk_f16_f32 v69, v68, v69
	v_cvt_pk_f16_f32 v68, v66, v67
	v_cvt_pk_f16_f32 v67, v72, v73
	v_cvt_pk_f16_f32 v66, v70, v71
	global_store_dwordx4 v[190:191], v[66:69], off offset:256
	s_waitcnt lgkmcnt(3)
	v_cvt_f32_f16_e32 v170, v130
	v_cvt_f32_f16_sdwa v171, v130 dst_sel:DWORD dst_unused:UNUSED_PAD src0_sel:WORD_1
	v_cvt_f32_f16_e32 v172, v131
	v_cvt_f32_f16_sdwa v173, v131 dst_sel:DWORD dst_unused:UNUSED_PAD src0_sel:WORD_1
	v_cvt_f32_f16_e32 v182, v132
	v_cvt_f32_f16_sdwa v183, v132 dst_sel:DWORD dst_unused:UNUSED_PAD src0_sel:WORD_1
	v_cvt_f32_f16_e32 v184, v133
	v_cvt_f32_f16_sdwa v185, v133 dst_sel:DWORD dst_unused:UNUSED_PAD src0_sel:WORD_1
	ds_read_b128 v[130:133], v202 offset:32768
	v_pk_fma_f32 v[62:63], v[62:63], 0.5, v[170:171] op_sel_hi:[1,0,1]
	v_pk_fma_f32 v[64:65], v[64:65], 0.5, v[172:173] op_sel_hi:[1,0,1]
	v_pk_fma_f32 v[58:59], v[58:59], 0.5, v[182:183] op_sel_hi:[1,0,1]
	v_pk_fma_f32 v[60:61], v[60:61], 0.5, v[184:185] op_sel_hi:[1,0,1]
	v_cvt_pk_f16_f32 v61, v60, v61
	v_cvt_pk_f16_f32 v60, v58, v59
	v_cvt_pk_f16_f32 v59, v64, v65
	v_cvt_pk_f16_f32 v58, v62, v63
	global_store_dwordx4 v[192:193], v[58:61], off
	s_waitcnt lgkmcnt(3)
	v_cvt_f32_f16_e32 v170, v134
	v_cvt_f32_f16_sdwa v171, v134 dst_sel:DWORD dst_unused:UNUSED_PAD src0_sel:WORD_1
	v_cvt_f32_f16_e32 v172, v135
	v_cvt_f32_f16_sdwa v173, v135 dst_sel:DWORD dst_unused:UNUSED_PAD src0_sel:WORD_1
	v_cvt_f32_f16_e32 v182, v136
	v_cvt_f32_f16_sdwa v183, v136 dst_sel:DWORD dst_unused:UNUSED_PAD src0_sel:WORD_1
	v_cvt_f32_f16_e32 v184, v137
	v_cvt_f32_f16_sdwa v185, v137 dst_sel:DWORD dst_unused:UNUSED_PAD src0_sel:WORD_1
	ds_read_b128 v[134:137], v202 offset:40960
	v_pk_fma_f32 v[54:55], v[54:55], 0.5, v[170:171] op_sel_hi:[1,0,1]
	v_pk_fma_f32 v[56:57], v[56:57], 0.5, v[172:173] op_sel_hi:[1,0,1]
	v_pk_fma_f32 v[46:47], v[46:47], 0.5, v[182:183] op_sel_hi:[1,0,1]
	v_pk_fma_f32 v[48:49], v[48:49], 0.5, v[184:185] op_sel_hi:[1,0,1]
	v_cvt_pk_f16_f32 v49, v48, v49
	v_cvt_pk_f16_f32 v48, v46, v47
	v_cvt_pk_f16_f32 v47, v56, v57
	v_cvt_pk_f16_f32 v46, v54, v55
	global_store_dwordx4 v[192:193], v[46:49], off offset:256
	s_waitcnt lgkmcnt(3)
	v_cvt_f32_f16_e32 v170, v138
	v_cvt_f32_f16_sdwa v171, v138 dst_sel:DWORD dst_unused:UNUSED_PAD src0_sel:WORD_1
	v_cvt_f32_f16_e32 v172, v139
	v_cvt_f32_f16_sdwa v173, v139 dst_sel:DWORD dst_unused:UNUSED_PAD src0_sel:WORD_1
	v_cvt_f32_f16_e32 v182, v140
	v_cvt_f32_f16_sdwa v183, v140 dst_sel:DWORD dst_unused:UNUSED_PAD src0_sel:WORD_1
	v_cvt_f32_f16_e32 v184, v141
	v_cvt_f32_f16_sdwa v185, v141 dst_sel:DWORD dst_unused:UNUSED_PAD src0_sel:WORD_1
	v_pk_fma_f32 v[50:51], v[50:51], 0.5, v[170:171] op_sel_hi:[1,0,1]
	v_pk_fma_f32 v[52:53], v[52:53], 0.5, v[172:173] op_sel_hi:[1,0,1]
	v_pk_fma_f32 v[42:43], v[42:43], 0.5, v[182:183] op_sel_hi:[1,0,1]
	v_pk_fma_f32 v[44:45], v[44:45], 0.5, v[184:185] op_sel_hi:[1,0,1]
	v_cvt_pk_f16_f32 v45, v44, v45
	v_cvt_pk_f16_f32 v44, v42, v43
	v_cvt_pk_f16_f32 v43, v52, v53
	v_cvt_pk_f16_f32 v42, v50, v51
	global_store_dwordx4 v[194:195], v[42:45], off
	s_waitcnt lgkmcnt(2)
	v_cvt_f32_f16_e32 v170, v142
	v_cvt_f32_f16_sdwa v171, v142 dst_sel:DWORD dst_unused:UNUSED_PAD src0_sel:WORD_1
	v_cvt_f32_f16_e32 v172, v143
	v_cvt_f32_f16_sdwa v173, v143 dst_sel:DWORD dst_unused:UNUSED_PAD src0_sel:WORD_1
	v_cvt_f32_f16_e32 v182, v144
	v_cvt_f32_f16_sdwa v183, v144 dst_sel:DWORD dst_unused:UNUSED_PAD src0_sel:WORD_1
	v_cvt_f32_f16_e32 v184, v145
	v_cvt_f32_f16_sdwa v185, v145 dst_sel:DWORD dst_unused:UNUSED_PAD src0_sel:WORD_1
	v_pk_fma_f32 v[30:31], v[30:31], 0.5, v[170:171] op_sel_hi:[1,0,1]
	v_pk_fma_f32 v[32:33], v[32:33], 0.5, v[172:173] op_sel_hi:[1,0,1]
	v_pk_fma_f32 v[26:27], v[26:27], 0.5, v[182:183] op_sel_hi:[1,0,1]
	v_pk_fma_f32 v[28:29], v[28:29], 0.5, v[184:185] op_sel_hi:[1,0,1]
	v_cvt_pk_f16_f32 v29, v28, v29
	v_cvt_pk_f16_f32 v28, v26, v27
	v_cvt_pk_f16_f32 v27, v32, v33
	v_cvt_pk_f16_f32 v26, v30, v31
	global_store_dwordx4 v[194:195], v[26:29], off offset:256
	s_waitcnt lgkmcnt(1)
	v_cvt_f32_f16_e32 v170, v130
	v_cvt_f32_f16_sdwa v171, v130 dst_sel:DWORD dst_unused:UNUSED_PAD src0_sel:WORD_1
	v_cvt_f32_f16_e32 v172, v131
	v_cvt_f32_f16_sdwa v173, v131 dst_sel:DWORD dst_unused:UNUSED_PAD src0_sel:WORD_1
	v_cvt_f32_f16_e32 v182, v132
	v_cvt_f32_f16_sdwa v183, v132 dst_sel:DWORD dst_unused:UNUSED_PAD src0_sel:WORD_1
	v_cvt_f32_f16_e32 v184, v133
	v_cvt_f32_f16_sdwa v185, v133 dst_sel:DWORD dst_unused:UNUSED_PAD src0_sel:WORD_1
	v_pk_fma_f32 v[38:39], v[38:39], 0.5, v[170:171] op_sel_hi:[1,0,1]
	v_pk_fma_f32 v[40:41], v[40:41], 0.5, v[172:173] op_sel_hi:[1,0,1]
	v_pk_fma_f32 v[34:35], v[34:35], 0.5, v[182:183] op_sel_hi:[1,0,1]
	v_pk_fma_f32 v[36:37], v[36:37], 0.5, v[184:185] op_sel_hi:[1,0,1]
	v_cvt_pk_f16_f32 v37, v36, v37
	v_cvt_pk_f16_f32 v36, v34, v35
	v_cvt_pk_f16_f32 v35, v40, v41
	v_cvt_pk_f16_f32 v34, v38, v39
	global_store_dwordx4 v[196:197], v[34:37], off
	s_waitcnt lgkmcnt(0)
	v_cvt_f32_f16_e32 v170, v134
	v_cvt_f32_f16_sdwa v171, v134 dst_sel:DWORD dst_unused:UNUSED_PAD src0_sel:WORD_1
	v_cvt_f32_f16_e32 v172, v135
	v_cvt_f32_f16_sdwa v173, v135 dst_sel:DWORD dst_unused:UNUSED_PAD src0_sel:WORD_1
	v_cvt_f32_f16_e32 v182, v136
	v_cvt_f32_f16_sdwa v183, v136 dst_sel:DWORD dst_unused:UNUSED_PAD src0_sel:WORD_1
	v_cvt_f32_f16_e32 v184, v137
	v_cvt_f32_f16_sdwa v185, v137 dst_sel:DWORD dst_unused:UNUSED_PAD src0_sel:WORD_1
	v_pk_fma_f32 v[22:23], v[22:23], 0.5, v[170:171] op_sel_hi:[1,0,1]
	v_pk_fma_f32 v[24:25], v[24:25], 0.5, v[172:173] op_sel_hi:[1,0,1]
	v_pk_fma_f32 v[18:19], v[18:19], 0.5, v[182:183] op_sel_hi:[1,0,1]
	v_pk_fma_f32 v[20:21], v[20:21], 0.5, v[184:185] op_sel_hi:[1,0,1]
	v_cvt_pk_f16_f32 v21, v20, v21
	v_cvt_pk_f16_f32 v20, v18, v19
	v_cvt_pk_f16_f32 v19, v24, v25
	v_cvt_pk_f16_f32 v18, v22, v23
	global_store_dwordx4 v[196:197], v[18:21], off offset:256
	s_waitcnt vmcnt(15)
	v_cvt_f32_f16_e32 v170, v162
	v_cvt_f32_f16_sdwa v171, v162 dst_sel:DWORD dst_unused:UNUSED_PAD src0_sel:WORD_1
	v_cvt_f32_f16_e32 v172, v163
	v_cvt_f32_f16_sdwa v173, v163 dst_sel:DWORD dst_unused:UNUSED_PAD src0_sel:WORD_1
	v_cvt_f32_f16_e32 v182, v164
	v_cvt_f32_f16_sdwa v183, v164 dst_sel:DWORD dst_unused:UNUSED_PAD src0_sel:WORD_1
	v_cvt_f32_f16_e32 v184, v165
	v_cvt_f32_f16_sdwa v185, v165 dst_sel:DWORD dst_unused:UNUSED_PAD src0_sel:WORD_1
	v_pk_fma_f32 v[14:15], v[14:15], 0.5, v[170:171] op_sel_hi:[1,0,1]
	v_pk_fma_f32 v[16:17], v[16:17], 0.5, v[172:173] op_sel_hi:[1,0,1]
	v_pk_fma_f32 v[10:11], v[10:11], 0.5, v[182:183] op_sel_hi:[1,0,1]
	v_pk_fma_f32 v[12:13], v[12:13], 0.5, v[184:185] op_sel_hi:[1,0,1]
	v_cvt_pk_f16_f32 v13, v12, v13
	v_cvt_pk_f16_f32 v12, v10, v11
	v_cvt_pk_f16_f32 v11, v16, v17
	v_cvt_pk_f16_f32 v10, v14, v15
	global_store_dwordx4 v[198:199], v[10:13], off
	s_waitcnt vmcnt(15)
	v_cvt_f32_f16_e32 v170, v166
	v_cvt_f32_f16_sdwa v171, v166 dst_sel:DWORD dst_unused:UNUSED_PAD src0_sel:WORD_1
	v_cvt_f32_f16_e32 v172, v167
	v_cvt_f32_f16_sdwa v173, v167 dst_sel:DWORD dst_unused:UNUSED_PAD src0_sel:WORD_1
	v_cvt_f32_f16_e32 v182, v168
	v_cvt_f32_f16_sdwa v183, v168 dst_sel:DWORD dst_unused:UNUSED_PAD src0_sel:WORD_1
	v_cvt_f32_f16_e32 v184, v169
	v_cvt_f32_f16_sdwa v185, v169 dst_sel:DWORD dst_unused:UNUSED_PAD src0_sel:WORD_1
	v_pk_fma_f32 v[6:7], v[6:7], 0.5, v[170:171] op_sel_hi:[1,0,1]
	v_pk_fma_f32 v[8:9], v[8:9], 0.5, v[172:173] op_sel_hi:[1,0,1]
	v_pk_fma_f32 v[2:3], v[2:3], 0.5, v[182:183] op_sel_hi:[1,0,1]
	v_pk_fma_f32 v[4:5], v[4:5], 0.5, v[184:185] op_sel_hi:[1,0,1]
	v_cvt_pk_f16_f32 v5, v4, v5
	v_cvt_pk_f16_f32 v4, v2, v3
	v_cvt_pk_f16_f32 v3, v8, v9
	v_cvt_pk_f16_f32 v2, v6, v7
	global_store_dwordx4 v[198:199], v[2:5], off offset:256
	s_and_b64 vcc, exec, s[2:3]
	s_mov_b64 s[0:1], -1
	s_cbranch_vccnz .LBB0_2077
	s_andn2_b64 vcc, exec, s[8:9]
	s_cbranch_vccnz .LBB0_2076
	s_barrier
	s_branch .LBB0_2076

.LBB0_2938:
	ds_read_b128 v[130:133], v174
	ds_read_b128 v[134:137], v174 offset:1024
	ds_read_b128 v[138:141], v174 offset:2048
	ds_read_b128 v[158:161], v174 offset:3072
	ds_read_b128 v[162:165], v175
	ds_read_b128 v[166:169], v175 offset:1024
	ds_read_b128 v[178:181], v175 offset:2048
	ds_read_b128 v[182:185], v175 offset:3072
	s_add_u32 s34, s46, 0xfff80080
	s_addc_u32 s35, s47, -1
	s_cmp_eq_u32 s72, 28
	s_cselect_b32 s69, s0, s35
	s_cselect_b32 s68, s1, s34
	s_cselect_b32 s35, s37, s71
	s_cselect_b32 s34, s39, s70
	v_lshl_add_u64 v[170:171], s[46:47], 0, v[150:151]
	s_add_i32 m0, s33, 0xc000
	ds_read_b128 v[186:189], v176
	ds_read_b128 v[190:193], v176 offset:1024
	ds_read_b128 v[194:197], v176 offset:2048
	ds_read_b128 v[198:201], v176 offset:3072
	ds_read_b128 v[202:205], v176 offset:4096
	ds_read_b128 v[206:209], v176 offset:5120
	ds_read_b128 v[210:213], v176 offset:6144
	ds_read_b128 v[218:221], v176 offset:7168
	global_load_lds_dwordx4 v[170:171], off
	v_lshl_add_u64 v[170:171], s[46:47], 0, v[152:153]
	s_add_i32 m0, s33, 0xe000
	s_nop 0
	global_load_lds_dwordx4 v[170:171], off
	s_waitcnt vmcnt(8)
	s_waitcnt lgkmcnt(0)
	s_barrier
	s_setprio 1
	s_waitcnt lgkmcnt(0)
	v_mfma_f32_16x16x32_bf16 v[126:129], v[130:133], v[186:189], v[126:129]
	v_mfma_f32_16x16x32_bf16 v[122:125], v[138:141], v[186:189], v[122:125]
	v_mfma_f32_16x16x32_bf16 v[110:113], v[130:133], v[194:197], v[110:113]
	v_mfma_f32_16x16x32_bf16 v[106:109], v[138:141], v[194:197], v[106:109]
	v_mfma_f32_16x16x32_bf16 v[94:97], v[130:133], v[202:205], v[94:97]
	v_mfma_f32_16x16x32_bf16 v[90:93], v[138:141], v[202:205], v[90:93]
	v_mfma_f32_16x16x32_bf16 v[78:81], v[130:133], v[210:213], v[78:81]
	v_mfma_f32_16x16x32_bf16 v[74:77], v[138:141], v[210:213], v[74:77]
	v_mfma_f32_16x16x32_bf16 v[126:129], v[134:137], v[190:193], v[126:129]
	v_mfma_f32_16x16x32_bf16 v[122:125], v[158:161], v[190:193], v[122:125]
	v_mfma_f32_16x16x32_bf16 v[110:113], v[134:137], v[198:201], v[110:113]
	v_mfma_f32_16x16x32_bf16 v[106:109], v[158:161], v[198:201], v[106:109]
	v_mfma_f32_16x16x32_bf16 v[94:97], v[134:137], v[206:209], v[94:97]
	v_mfma_f32_16x16x32_bf16 v[90:93], v[158:161], v[206:209], v[90:93]
	v_mfma_f32_16x16x32_bf16 v[78:81], v[134:137], v[218:221], v[78:81]
	v_mfma_f32_16x16x32_bf16 v[74:77], v[158:161], v[218:221], v[74:77]
	s_setprio 0
	s_setprio 1
	v_mfma_f32_16x16x32_bf16 v[118:121], v[162:165], v[186:189], v[118:121]
	v_mfma_f32_16x16x32_bf16 v[114:117], v[178:181], v[186:189], v[114:117]
	v_mfma_f32_16x16x32_bf16 v[102:105], v[162:165], v[194:197], v[102:105]
	v_mfma_f32_16x16x32_bf16 v[98:101], v[178:181], v[194:197], v[98:101]
	v_mfma_f32_16x16x32_bf16 v[86:89], v[162:165], v[202:205], v[86:89]
	v_mfma_f32_16x16x32_bf16 v[82:85], v[178:181], v[202:205], v[82:85]
	v_mfma_f32_16x16x32_bf16 v[70:73], v[162:165], v[210:213], v[70:73]
	v_mfma_f32_16x16x32_bf16 v[66:69], v[178:181], v[210:213], v[66:69]
	v_mfma_f32_16x16x32_bf16 v[118:121], v[166:169], v[190:193], v[118:121]
	v_mfma_f32_16x16x32_bf16 v[114:117], v[182:185], v[190:193], v[114:117]
	v_mfma_f32_16x16x32_bf16 v[102:105], v[166:169], v[198:201], v[102:105]
	v_mfma_f32_16x16x32_bf16 v[98:101], v[182:185], v[198:201], v[98:101]
	v_mfma_f32_16x16x32_bf16 v[86:89], v[166:169], v[206:209], v[86:89]
	v_mfma_f32_16x16x32_bf16 v[82:85], v[182:185], v[206:209], v[82:85]
	v_mfma_f32_16x16x32_bf16 v[70:73], v[166:169], v[218:221], v[70:73]
	v_mfma_f32_16x16x32_bf16 v[66:69], v[182:185], v[218:221], v[66:69]
	s_setprio 0
	s_barrier
	s_add_i32 s62, s58, s31
	v_lshl_add_u64 v[170:171], s[34:35], 0, v[144:145]
	s_mov_b32 m0, s62
	ds_read_b128 v[186:189], v176 offset:16384
	ds_read_b128 v[190:193], v176 offset:17408
	ds_read_b128 v[194:197], v176 offset:18432
	ds_read_b128 v[198:201], v176 offset:19456
	ds_read_b128 v[202:205], v176 offset:20480
	ds_read_b128 v[206:209], v176 offset:21504
	ds_read_b128 v[210:213], v176 offset:22528
	ds_read_b128 v[218:221], v176 offset:23552
	global_load_lds_dwordx4 v[170:171], off
	s_add_i32 m0, s62, 0x2000
	s_add_u32 s62, s34, 0x80000
	v_lshl_add_u64 v[214:215], s[34:35], 0, v[148:149]
	s_addc_u32 s63, s35, 0
	s_add_i32 s66, s59, s31
	global_load_lds_dwordx4 v[214:215], off
	v_lshl_add_u64 v[222:223], s[62:63], 0, v[144:145]
	s_mov_b32 m0, s66
	v_lshl_add_u64 v[224:225], s[68:69], 0, v[146:147]
	global_load_lds_dwordx4 v[222:223], off
	v_lshl_add_u64 v[222:223], s[62:63], 0, v[148:149]
	s_add_i32 m0, s66, 0x2000
	s_nop 0
	global_load_lds_dwordx4 v[222:223], off
	v_lshl_add_u64 v[222:223], s[68:69], 0, v[142:143]
	s_mov_b32 m0, s33
	s_nop 0
	global_load_lds_dwordx4 v[222:223], off
	s_mov_b32 m0, s45
	s_nop 0
	global_load_lds_dwordx4 v[224:225], off
	s_waitcnt vmcnt(8)
	s_waitcnt lgkmcnt(0)
	s_barrier
	s_setprio 1
	s_waitcnt lgkmcnt(0)
	v_mfma_f32_16x16x32_bf16 v[62:65], v[130:133], v[186:189], v[62:65]
	v_mfma_f32_16x16x32_bf16 v[58:61], v[138:141], v[186:189], v[58:61]
	v_mfma_f32_16x16x32_bf16 v[50:53], v[130:133], v[194:197], v[50:53]
	v_mfma_f32_16x16x32_bf16 v[42:45], v[138:141], v[194:197], v[42:45]
	v_mfma_f32_16x16x32_bf16 v[38:41], v[130:133], v[202:205], v[38:41]
	v_mfma_f32_16x16x32_bf16 v[34:37], v[138:141], v[202:205], v[34:37]
	v_mfma_f32_16x16x32_bf16 v[14:17], v[130:133], v[210:213], v[14:17]
	v_mfma_f32_16x16x32_bf16 v[10:13], v[138:141], v[210:213], v[10:13]
	v_mfma_f32_16x16x32_bf16 v[62:65], v[134:137], v[190:193], v[62:65]
	v_mfma_f32_16x16x32_bf16 v[58:61], v[158:161], v[190:193], v[58:61]
	v_mfma_f32_16x16x32_bf16 v[50:53], v[134:137], v[198:201], v[50:53]
	v_mfma_f32_16x16x32_bf16 v[42:45], v[158:161], v[198:201], v[42:45]
	v_mfma_f32_16x16x32_bf16 v[38:41], v[134:137], v[206:209], v[38:41]
	v_mfma_f32_16x16x32_bf16 v[34:37], v[158:161], v[206:209], v[34:37]
	v_mfma_f32_16x16x32_bf16 v[14:17], v[134:137], v[218:221], v[14:17]
	v_mfma_f32_16x16x32_bf16 v[10:13], v[158:161], v[218:221], v[10:13]
	s_setprio 0
	s_setprio 1
	v_mfma_f32_16x16x32_bf16 v[54:57], v[162:165], v[186:189], v[54:57]
	v_mfma_f32_16x16x32_bf16 v[46:49], v[178:181], v[186:189], v[46:49]
	v_mfma_f32_16x16x32_bf16 v[30:33], v[162:165], v[194:197], v[30:33]
	v_mfma_f32_16x16x32_bf16 v[26:29], v[178:181], v[194:197], v[26:29]
	v_mfma_f32_16x16x32_bf16 v[22:25], v[162:165], v[202:205], v[22:25]
	v_mfma_f32_16x16x32_bf16 v[18:21], v[178:181], v[202:205], v[18:21]
	v_mfma_f32_16x16x32_bf16 v[6:9], v[162:165], v[210:213], v[6:9]
	v_mfma_f32_16x16x32_bf16 v[2:5], v[178:181], v[210:213], v[2:5]
	v_mfma_f32_16x16x32_bf16 v[54:57], v[166:169], v[190:193], v[54:57]
	v_mfma_f32_16x16x32_bf16 v[46:49], v[182:185], v[190:193], v[46:49]
	v_mfma_f32_16x16x32_bf16 v[30:33], v[166:169], v[198:201], v[30:33]
	v_mfma_f32_16x16x32_bf16 v[26:29], v[182:185], v[198:201], v[26:29]
	v_mfma_f32_16x16x32_bf16 v[22:25], v[166:169], v[206:209], v[22:25]
	v_mfma_f32_16x16x32_bf16 v[18:21], v[182:185], v[206:209], v[18:21]
	v_mfma_f32_16x16x32_bf16 v[6:9], v[166:169], v[218:221], v[6:9]
	v_mfma_f32_16x16x32_bf16 v[2:5], v[182:185], v[218:221], v[2:5]
	s_setprio 0
	s_barrier
	s_add_i32 s66, 0, 0x18000
	s_add_i32 s67, 0, 0x1c000
	v_add_u32_e32 v158, s66, v172
	v_add_u32_e32 v177, s67, v172
	ds_read_b128 v[130:133], v158
	ds_read_b128 v[134:137], v158 offset:1024
	ds_read_b128 v[138:141], v158 offset:2048
	ds_read_b128 v[158:161], v158 offset:3072
	ds_read_b128 v[162:165], v177
	ds_read_b128 v[166:169], v177 offset:1024
	ds_read_b128 v[178:181], v177 offset:2048
	ds_read_b128 v[182:185], v177 offset:3072
	s_add_u32 s62, s68, 0x80000
	s_addc_u32 s63, s69, 0
	s_mov_b32 m0, s52
	v_lshl_add_u64 v[226:227], s[62:63], 0, v[142:143]
	ds_read_b128 v[186:189], v176 offset:32768
	ds_read_b128 v[190:193], v176 offset:33792
	ds_read_b128 v[194:197], v176 offset:34816
	ds_read_b128 v[198:201], v176 offset:35840
	ds_read_b128 v[202:205], v176 offset:36864
	ds_read_b128 v[206:209], v176 offset:37888
	ds_read_b128 v[210:213], v176 offset:38912
	ds_read_b128 v[218:221], v176 offset:39936
	global_load_lds_dwordx4 v[226:227], off
	v_lshl_add_u64 v[226:227], s[62:63], 0, v[146:147]
	s_mov_b32 m0, s53
	s_nop 0
	global_load_lds_dwordx4 v[226:227], off
	s_waitcnt vmcnt(8)
	s_waitcnt lgkmcnt(0)
	s_barrier
	s_setprio 1
	s_waitcnt lgkmcnt(0)
	v_mfma_f32_16x16x32_bf16 v[126:129], v[130:133], v[186:189], v[126:129]
	v_mfma_f32_16x16x32_bf16 v[122:125], v[138:141], v[186:189], v[122:125]
	v_mfma_f32_16x16x32_bf16 v[110:113], v[130:133], v[194:197], v[110:113]
	v_mfma_f32_16x16x32_bf16 v[106:109], v[138:141], v[194:197], v[106:109]
	v_mfma_f32_16x16x32_bf16 v[94:97], v[130:133], v[202:205], v[94:97]
	v_mfma_f32_16x16x32_bf16 v[90:93], v[138:141], v[202:205], v[90:93]
	v_mfma_f32_16x16x32_bf16 v[78:81], v[130:133], v[210:213], v[78:81]
	v_mfma_f32_16x16x32_bf16 v[74:77], v[138:141], v[210:213], v[74:77]
	v_mfma_f32_16x16x32_bf16 v[126:129], v[134:137], v[190:193], v[126:129]
	v_mfma_f32_16x16x32_bf16 v[122:125], v[158:161], v[190:193], v[122:125]
	v_mfma_f32_16x16x32_bf16 v[110:113], v[134:137], v[198:201], v[110:113]
	v_mfma_f32_16x16x32_bf16 v[106:109], v[158:161], v[198:201], v[106:109]
	v_mfma_f32_16x16x32_bf16 v[94:97], v[134:137], v[206:209], v[94:97]
	v_mfma_f32_16x16x32_bf16 v[90:93], v[158:161], v[206:209], v[90:93]
	v_mfma_f32_16x16x32_bf16 v[78:81], v[134:137], v[218:221], v[78:81]
	v_mfma_f32_16x16x32_bf16 v[74:77], v[158:161], v[218:221], v[74:77]
	s_setprio 0
	s_setprio 1
	v_mfma_f32_16x16x32_bf16 v[118:121], v[162:165], v[186:189], v[118:121]
	v_mfma_f32_16x16x32_bf16 v[114:117], v[178:181], v[186:189], v[114:117]
	v_mfma_f32_16x16x32_bf16 v[102:105], v[162:165], v[194:197], v[102:105]
	v_mfma_f32_16x16x32_bf16 v[98:101], v[178:181], v[194:197], v[98:101]
	v_mfma_f32_16x16x32_bf16 v[86:89], v[162:165], v[202:205], v[86:89]
	v_mfma_f32_16x16x32_bf16 v[82:85], v[178:181], v[202:205], v[82:85]
	v_mfma_f32_16x16x32_bf16 v[70:73], v[162:165], v[210:213], v[70:73]
	v_mfma_f32_16x16x32_bf16 v[66:69], v[178:181], v[210:213], v[66:69]
	v_mfma_f32_16x16x32_bf16 v[118:121], v[166:169], v[190:193], v[118:121]
	v_mfma_f32_16x16x32_bf16 v[114:117], v[182:185], v[190:193], v[114:117]
	v_mfma_f32_16x16x32_bf16 v[102:105], v[166:169], v[198:201], v[102:105]
	v_mfma_f32_16x16x32_bf16 v[98:101], v[182:185], v[198:201], v[98:101]
	v_mfma_f32_16x16x32_bf16 v[86:89], v[166:169], v[206:209], v[86:89]
	v_mfma_f32_16x16x32_bf16 v[82:85], v[182:185], v[206:209], v[82:85]
	v_mfma_f32_16x16x32_bf16 v[70:73], v[166:169], v[218:221], v[70:73]
	v_mfma_f32_16x16x32_bf16 v[66:69], v[182:185], v[218:221], v[66:69]
	s_setprio 0
	s_barrier
	s_add_i32 s62, s66, s31
	v_lshl_add_u64 v[170:171], v[170:171], 0, s[24:25]
	s_mov_b32 m0, s62
	ds_read_b128 v[186:189], v176 offset:49152
	ds_read_b128 v[190:193], v176 offset:50176
	ds_read_b128 v[194:197], v176 offset:51200
	ds_read_b128 v[198:201], v176 offset:52224
	ds_read_b128 v[202:205], v176 offset:53248
	ds_read_b128 v[206:209], v176 offset:54272
	ds_read_b128 v[210:213], v176 offset:55296
	ds_read_b128 v[218:221], v176 offset:56320
	global_load_lds_dwordx4 v[170:171], off
	s_add_i32 m0, s62, 0x2000
	s_add_u32 s34, s34, 0x80080
	v_lshl_add_u64 v[170:171], v[214:215], 0, s[24:25]
	s_addc_u32 s35, s35, 0
	s_add_i32 s62, s67, s31
	global_load_lds_dwordx4 v[170:171], off
	v_lshl_add_u64 v[170:171], s[34:35], 0, v[144:145]
	s_mov_b32 m0, s62
	s_nop 0
	global_load_lds_dwordx4 v[170:171], off
	v_lshl_add_u64 v[170:171], s[34:35], 0, v[148:149]
	s_add_i32 m0, s62, 0x2000
	s_nop 0
	global_load_lds_dwordx4 v[170:171], off
	v_lshl_add_u64 v[170:171], v[222:223], 0, s[24:25]
	s_mov_b32 m0, s55
	s_nop 0
	global_load_lds_dwordx4 v[170:171], off
	v_lshl_add_u64 v[170:171], v[224:225], 0, s[24:25]
	s_mov_b32 m0, s56
	s_nop 0
	global_load_lds_dwordx4 v[170:171], off
	s_waitcnt vmcnt(8)
	s_waitcnt lgkmcnt(0)
	s_barrier
	s_setprio 1
	s_waitcnt lgkmcnt(0)
	v_mfma_f32_16x16x32_bf16 v[62:65], v[130:133], v[186:189], v[62:65]
	v_mfma_f32_16x16x32_bf16 v[58:61], v[138:141], v[186:189], v[58:61]
	v_mfma_f32_16x16x32_bf16 v[50:53], v[130:133], v[194:197], v[50:53]
	v_mfma_f32_16x16x32_bf16 v[42:45], v[138:141], v[194:197], v[42:45]
	v_mfma_f32_16x16x32_bf16 v[38:41], v[130:133], v[202:205], v[38:41]
	v_mfma_f32_16x16x32_bf16 v[34:37], v[138:141], v[202:205], v[34:37]
	v_mfma_f32_16x16x32_bf16 v[14:17], v[130:133], v[210:213], v[14:17]
	v_mfma_f32_16x16x32_bf16 v[10:13], v[138:141], v[210:213], v[10:13]
	v_mfma_f32_16x16x32_bf16 v[62:65], v[134:137], v[190:193], v[62:65]
	v_mfma_f32_16x16x32_bf16 v[58:61], v[158:161], v[190:193], v[58:61]
	v_mfma_f32_16x16x32_bf16 v[50:53], v[134:137], v[198:201], v[50:53]
	v_mfma_f32_16x16x32_bf16 v[42:45], v[158:161], v[198:201], v[42:45]
	v_mfma_f32_16x16x32_bf16 v[38:41], v[134:137], v[206:209], v[38:41]
	v_mfma_f32_16x16x32_bf16 v[34:37], v[158:161], v[206:209], v[34:37]
	v_mfma_f32_16x16x32_bf16 v[14:17], v[134:137], v[218:221], v[14:17]
	v_mfma_f32_16x16x32_bf16 v[10:13], v[158:161], v[218:221], v[10:13]
	s_setprio 0
	s_setprio 1
	v_mfma_f32_16x16x32_bf16 v[54:57], v[162:165], v[186:189], v[54:57]
	v_mfma_f32_16x16x32_bf16 v[46:49], v[178:181], v[186:189], v[46:49]
	v_mfma_f32_16x16x32_bf16 v[30:33], v[162:165], v[194:197], v[30:33]
	v_mfma_f32_16x16x32_bf16 v[26:29], v[178:181], v[194:197], v[26:29]
	v_mfma_f32_16x16x32_bf16 v[22:25], v[162:165], v[202:205], v[22:25]
	v_mfma_f32_16x16x32_bf16 v[18:21], v[178:181], v[202:205], v[18:21]
	v_mfma_f32_16x16x32_bf16 v[6:9], v[162:165], v[210:213], v[6:9]
	v_mfma_f32_16x16x32_bf16 v[2:5], v[178:181], v[210:213], v[2:5]
	v_mfma_f32_16x16x32_bf16 v[54:57], v[166:169], v[190:193], v[54:57]
	v_mfma_f32_16x16x32_bf16 v[46:49], v[182:185], v[190:193], v[46:49]
	v_mfma_f32_16x16x32_bf16 v[30:33], v[166:169], v[198:201], v[30:33]
	v_mfma_f32_16x16x32_bf16 v[26:29], v[182:185], v[198:201], v[26:29]
	v_mfma_f32_16x16x32_bf16 v[22:25], v[166:169], v[206:209], v[22:25]
	v_mfma_f32_16x16x32_bf16 v[18:21], v[182:185], v[206:209], v[18:21]
	v_mfma_f32_16x16x32_bf16 v[6:9], v[166:169], v[218:221], v[6:9]
	v_mfma_f32_16x16x32_bf16 v[2:5], v[182:185], v[218:221], v[2:5]
	s_setprio 0
	s_barrier
	s_add_i32 s72, s72, 2
	s_add_u32 s46, s46, 0x100
	s_addc_u32 s47, s47, 0
	s_add_u32 s70, s70, 0x100
	s_addc_u32 s71, s71, 0
	s_cmp_gt_u32 s72, 27
	s_cbranch_scc0 .LBB0_2938
	v_lshl_add_u32 v234, s44, 8, v1
	v_lshl_or_b32 v236, s61, 8, v173
	v_ashrrev_i32_e32 v235, 31, v234
	v_ashrrev_i32_e32 v237, 31, v236
	v_lshlrev_b64 v[228:229], 12, v[234:235]
	v_lshl_add_u64 v[228:229], s[64:65], 0, v[228:229]
	v_lshlrev_b64 v[236:237], 1, v[236:237]
	v_lshl_add_u64 v[228:229], v[228:229], 0, v[236:237]
	v_mov_b32_e32 v231, 0
	ds_read_b128 v[130:133], v174
	ds_read_b128 v[134:137], v174 offset:1024
	ds_read_b128 v[138:141], v174 offset:2048
	ds_read_b128 v[158:161], v174 offset:3072
	ds_read_b128 v[162:165], v175
	ds_read_b128 v[166:169], v175 offset:1024
	ds_read_b128 v[178:181], v175 offset:2048
	ds_read_b128 v[182:185], v175 offset:3072
	s_add_u32 s34, s46, 0xfff80080
	s_addc_u32 s35, s47, -1
	s_cmp_eq_u32 s72, 28
	s_cselect_b32 s69, s0, s35
	s_cselect_b32 s68, s1, s34
	s_cselect_b32 s35, s37, s71
	s_cselect_b32 s34, s39, s70
	v_lshl_add_u64 v[170:171], s[46:47], 0, v[150:151]
	s_add_i32 m0, s33, 0xc000
	ds_read_b128 v[186:189], v176
	ds_read_b128 v[190:193], v176 offset:1024
	ds_read_b128 v[194:197], v176 offset:2048
	ds_read_b128 v[198:201], v176 offset:3072
	ds_read_b128 v[202:205], v176 offset:4096
	ds_read_b128 v[206:209], v176 offset:5120
	ds_read_b128 v[210:213], v176 offset:6144
	ds_read_b128 v[218:221], v176 offset:7168
	global_load_lds_dwordx4 v[170:171], off
	v_lshl_add_u64 v[170:171], s[46:47], 0, v[152:153]
	s_add_i32 m0, s33, 0xe000
	s_nop 0
	global_load_lds_dwordx4 v[170:171], off
	s_waitcnt vmcnt(8)
	s_waitcnt lgkmcnt(0)
	s_barrier
	s_setprio 1
	s_waitcnt lgkmcnt(0)
	v_mfma_f32_16x16x32_bf16 v[126:129], v[130:133], v[186:189], v[126:129]
	v_mfma_f32_16x16x32_bf16 v[122:125], v[138:141], v[186:189], v[122:125]
	v_mfma_f32_16x16x32_bf16 v[110:113], v[130:133], v[194:197], v[110:113]
	v_mfma_f32_16x16x32_bf16 v[106:109], v[138:141], v[194:197], v[106:109]
	v_mfma_f32_16x16x32_bf16 v[94:97], v[130:133], v[202:205], v[94:97]
	v_mfma_f32_16x16x32_bf16 v[90:93], v[138:141], v[202:205], v[90:93]
	v_mfma_f32_16x16x32_bf16 v[78:81], v[130:133], v[210:213], v[78:81]
	v_mfma_f32_16x16x32_bf16 v[74:77], v[138:141], v[210:213], v[74:77]
	v_mfma_f32_16x16x32_bf16 v[126:129], v[134:137], v[190:193], v[126:129]
	v_mfma_f32_16x16x32_bf16 v[122:125], v[158:161], v[190:193], v[122:125]
	v_mfma_f32_16x16x32_bf16 v[110:113], v[134:137], v[198:201], v[110:113]
	v_mfma_f32_16x16x32_bf16 v[106:109], v[158:161], v[198:201], v[106:109]
	v_mfma_f32_16x16x32_bf16 v[94:97], v[134:137], v[206:209], v[94:97]
	v_mfma_f32_16x16x32_bf16 v[90:93], v[158:161], v[206:209], v[90:93]
	v_mfma_f32_16x16x32_bf16 v[78:81], v[134:137], v[218:221], v[78:81]
	v_mfma_f32_16x16x32_bf16 v[74:77], v[158:161], v[218:221], v[74:77]
	s_setprio 0
	s_setprio 1
	v_mfma_f32_16x16x32_bf16 v[118:121], v[162:165], v[186:189], v[118:121]
	v_mfma_f32_16x16x32_bf16 v[114:117], v[178:181], v[186:189], v[114:117]
	v_mfma_f32_16x16x32_bf16 v[102:105], v[162:165], v[194:197], v[102:105]
	v_mfma_f32_16x16x32_bf16 v[98:101], v[178:181], v[194:197], v[98:101]
	v_mfma_f32_16x16x32_bf16 v[86:89], v[162:165], v[202:205], v[86:89]
	v_mfma_f32_16x16x32_bf16 v[82:85], v[178:181], v[202:205], v[82:85]
	v_mfma_f32_16x16x32_bf16 v[70:73], v[162:165], v[210:213], v[70:73]
	v_mfma_f32_16x16x32_bf16 v[66:69], v[178:181], v[210:213], v[66:69]
	v_mfma_f32_16x16x32_bf16 v[118:121], v[166:169], v[190:193], v[118:121]
	v_mfma_f32_16x16x32_bf16 v[114:117], v[182:185], v[190:193], v[114:117]
	v_mfma_f32_16x16x32_bf16 v[102:105], v[166:169], v[198:201], v[102:105]
	v_mfma_f32_16x16x32_bf16 v[98:101], v[182:185], v[198:201], v[98:101]
	v_mfma_f32_16x16x32_bf16 v[86:89], v[166:169], v[206:209], v[86:89]
	v_mfma_f32_16x16x32_bf16 v[82:85], v[182:185], v[206:209], v[82:85]
	v_mfma_f32_16x16x32_bf16 v[70:73], v[166:169], v[218:221], v[70:73]
	v_mfma_f32_16x16x32_bf16 v[66:69], v[182:185], v[218:221], v[66:69]
	s_setprio 0
	s_barrier
	s_add_i32 s62, s58, s31
	v_lshl_add_u64 v[170:171], s[34:35], 0, v[144:145]
	s_mov_b32 m0, s62
	ds_read_b128 v[186:189], v176 offset:16384
	ds_read_b128 v[190:193], v176 offset:17408
	ds_read_b128 v[194:197], v176 offset:18432
	ds_read_b128 v[198:201], v176 offset:19456
	ds_read_b128 v[202:205], v176 offset:20480
	ds_read_b128 v[206:209], v176 offset:21504
	ds_read_b128 v[210:213], v176 offset:22528
	ds_read_b128 v[218:221], v176 offset:23552
	v_mov_b32_e32 v230, 0x0
	v_lshl_add_u64 v[232:233], v[230:231], 0, v[228:229]
	global_load_lds_dwordx4 v[232:233], off
	s_add_i32 m0, s62, 0x2000
	s_add_u32 s62, s34, 0x80000
	v_lshl_add_u64 v[214:215], s[34:35], 0, v[148:149]
	s_addc_u32 s63, s35, 0
	s_add_i32 s66, s59, s31
	v_mov_b32_e32 v230, 0x100
	v_lshl_add_u64 v[232:233], v[230:231], 0, v[228:229]
	global_load_lds_dwordx4 v[232:233], off
	v_lshl_add_u64 v[222:223], s[62:63], 0, v[144:145]
	s_mov_b32 m0, s66
	v_lshl_add_u64 v[224:225], s[68:69], 0, v[146:147]
	v_mov_b32_e32 v230, 0x10000
	v_lshl_add_u64 v[232:233], v[230:231], 0, v[228:229]
	global_load_lds_dwordx4 v[232:233], off
	v_lshl_add_u64 v[222:223], s[62:63], 0, v[148:149]
	s_add_i32 m0, s66, 0x2000
	s_nop 0
	v_mov_b32_e32 v230, 0x10100
	v_lshl_add_u64 v[232:233], v[230:231], 0, v[228:229]
	global_load_lds_dwordx4 v[232:233], off
	v_lshl_add_u64 v[222:223], s[68:69], 0, v[142:143]
	s_mov_b32 m0, s33
	s_nop 0
	v_mov_b32_e32 v230, 0x20000
	v_lshl_add_u64 v[232:233], v[230:231], 0, v[228:229]
	global_load_lds_dwordx4 v[232:233], off
	s_mov_b32 m0, s45
	s_nop 0
	v_mov_b32_e32 v230, 0x20100
	v_lshl_add_u64 v[232:233], v[230:231], 0, v[228:229]
	global_load_lds_dwordx4 v[232:233], off
	s_waitcnt vmcnt(8)
	s_waitcnt lgkmcnt(0)
	s_barrier
	s_setprio 1
	s_waitcnt lgkmcnt(0)
	v_mfma_f32_16x16x32_bf16 v[62:65], v[130:133], v[186:189], v[62:65]
	v_mfma_f32_16x16x32_bf16 v[58:61], v[138:141], v[186:189], v[58:61]
	v_mfma_f32_16x16x32_bf16 v[50:53], v[130:133], v[194:197], v[50:53]
	v_mfma_f32_16x16x32_bf16 v[42:45], v[138:141], v[194:197], v[42:45]
	v_mfma_f32_16x16x32_bf16 v[38:41], v[130:133], v[202:205], v[38:41]
	v_mfma_f32_16x16x32_bf16 v[34:37], v[138:141], v[202:205], v[34:37]
	v_mfma_f32_16x16x32_bf16 v[14:17], v[130:133], v[210:213], v[14:17]
	v_mfma_f32_16x16x32_bf16 v[10:13], v[138:141], v[210:213], v[10:13]
	v_mfma_f32_16x16x32_bf16 v[62:65], v[134:137], v[190:193], v[62:65]
	v_mfma_f32_16x16x32_bf16 v[58:61], v[158:161], v[190:193], v[58:61]
	v_mfma_f32_16x16x32_bf16 v[50:53], v[134:137], v[198:201], v[50:53]
	v_mfma_f32_16x16x32_bf16 v[42:45], v[158:161], v[198:201], v[42:45]
	v_mfma_f32_16x16x32_bf16 v[38:41], v[134:137], v[206:209], v[38:41]
	v_mfma_f32_16x16x32_bf16 v[34:37], v[158:161], v[206:209], v[34:37]
	v_mfma_f32_16x16x32_bf16 v[14:17], v[134:137], v[218:221], v[14:17]
	v_mfma_f32_16x16x32_bf16 v[10:13], v[158:161], v[218:221], v[10:13]
	s_setprio 0
	s_setprio 1
	v_mfma_f32_16x16x32_bf16 v[54:57], v[162:165], v[186:189], v[54:57]
	v_mfma_f32_16x16x32_bf16 v[46:49], v[178:181], v[186:189], v[46:49]
	v_mfma_f32_16x16x32_bf16 v[30:33], v[162:165], v[194:197], v[30:33]
	v_mfma_f32_16x16x32_bf16 v[26:29], v[178:181], v[194:197], v[26:29]
	v_mfma_f32_16x16x32_bf16 v[22:25], v[162:165], v[202:205], v[22:25]
	v_mfma_f32_16x16x32_bf16 v[18:21], v[178:181], v[202:205], v[18:21]
	v_mfma_f32_16x16x32_bf16 v[6:9], v[162:165], v[210:213], v[6:9]
	v_mfma_f32_16x16x32_bf16 v[2:5], v[178:181], v[210:213], v[2:5]
	v_mfma_f32_16x16x32_bf16 v[54:57], v[166:169], v[190:193], v[54:57]
	v_mfma_f32_16x16x32_bf16 v[46:49], v[182:185], v[190:193], v[46:49]
	v_mfma_f32_16x16x32_bf16 v[30:33], v[166:169], v[198:201], v[30:33]
	v_mfma_f32_16x16x32_bf16 v[26:29], v[182:185], v[198:201], v[26:29]
	v_mfma_f32_16x16x32_bf16 v[22:25], v[166:169], v[206:209], v[22:25]
	v_mfma_f32_16x16x32_bf16 v[18:21], v[182:185], v[206:209], v[18:21]
	v_mfma_f32_16x16x32_bf16 v[6:9], v[166:169], v[218:221], v[6:9]
	v_mfma_f32_16x16x32_bf16 v[2:5], v[182:185], v[218:221], v[2:5]
	s_setprio 0
	s_barrier
	s_add_i32 s66, 0, 0x18000
	s_add_i32 s67, 0, 0x1c000
	v_add_u32_e32 v158, s66, v172
	v_add_u32_e32 v177, s67, v172
	ds_read_b128 v[130:133], v158
	ds_read_b128 v[134:137], v158 offset:1024
	ds_read_b128 v[138:141], v158 offset:2048
	ds_read_b128 v[158:161], v158 offset:3072
	ds_read_b128 v[162:165], v177
	ds_read_b128 v[166:169], v177 offset:1024
	ds_read_b128 v[178:181], v177 offset:2048
	ds_read_b128 v[182:185], v177 offset:3072
	s_add_u32 s62, s68, 0x80000
	s_addc_u32 s63, s69, 0
	s_mov_b32 m0, s52
	v_lshl_add_u64 v[226:227], s[62:63], 0, v[142:143]
	ds_read_b128 v[186:189], v176 offset:32768
	ds_read_b128 v[190:193], v176 offset:33792
	ds_read_b128 v[194:197], v176 offset:34816
	ds_read_b128 v[198:201], v176 offset:35840
	ds_read_b128 v[202:205], v176 offset:36864
	ds_read_b128 v[206:209], v176 offset:37888
	ds_read_b128 v[210:213], v176 offset:38912
	ds_read_b128 v[218:221], v176 offset:39936
	v_mov_b32_e32 v230, 0x30000
	v_lshl_add_u64 v[232:233], v[230:231], 0, v[228:229]
	global_load_lds_dwordx4 v[232:233], off
	v_lshl_add_u64 v[226:227], s[62:63], 0, v[146:147]
	s_mov_b32 m0, s53
	s_nop 0
	v_mov_b32_e32 v230, 0x30100
	v_lshl_add_u64 v[232:233], v[230:231], 0, v[228:229]
	global_load_lds_dwordx4 v[232:233], off
	s_waitcnt vmcnt(8)
	s_waitcnt lgkmcnt(0)
	s_barrier
	s_setprio 1
	s_waitcnt lgkmcnt(0)
	v_mfma_f32_16x16x32_bf16 v[126:129], v[130:133], v[186:189], v[126:129]
	v_mfma_f32_16x16x32_bf16 v[122:125], v[138:141], v[186:189], v[122:125]
	v_mfma_f32_16x16x32_bf16 v[110:113], v[130:133], v[194:197], v[110:113]
	v_mfma_f32_16x16x32_bf16 v[106:109], v[138:141], v[194:197], v[106:109]
	v_mfma_f32_16x16x32_bf16 v[94:97], v[130:133], v[202:205], v[94:97]
	v_mfma_f32_16x16x32_bf16 v[90:93], v[138:141], v[202:205], v[90:93]
	v_mfma_f32_16x16x32_bf16 v[78:81], v[130:133], v[210:213], v[78:81]
	v_mfma_f32_16x16x32_bf16 v[74:77], v[138:141], v[210:213], v[74:77]
	v_mfma_f32_16x16x32_bf16 v[126:129], v[134:137], v[190:193], v[126:129]
	v_mfma_f32_16x16x32_bf16 v[122:125], v[158:161], v[190:193], v[122:125]
	v_mfma_f32_16x16x32_bf16 v[110:113], v[134:137], v[198:201], v[110:113]
	v_mfma_f32_16x16x32_bf16 v[106:109], v[158:161], v[198:201], v[106:109]
	v_mfma_f32_16x16x32_bf16 v[94:97], v[134:137], v[206:209], v[94:97]
	v_mfma_f32_16x16x32_bf16 v[90:93], v[158:161], v[206:209], v[90:93]
	v_mfma_f32_16x16x32_bf16 v[78:81], v[134:137], v[218:221], v[78:81]
	v_mfma_f32_16x16x32_bf16 v[74:77], v[158:161], v[218:221], v[74:77]
	s_setprio 0
	s_setprio 1
	v_mfma_f32_16x16x32_bf16 v[118:121], v[162:165], v[186:189], v[118:121]
	v_mfma_f32_16x16x32_bf16 v[114:117], v[178:181], v[186:189], v[114:117]
	v_mfma_f32_16x16x32_bf16 v[102:105], v[162:165], v[194:197], v[102:105]
	v_mfma_f32_16x16x32_bf16 v[98:101], v[178:181], v[194:197], v[98:101]
	v_mfma_f32_16x16x32_bf16 v[86:89], v[162:165], v[202:205], v[86:89]
	v_mfma_f32_16x16x32_bf16 v[82:85], v[178:181], v[202:205], v[82:85]
	v_mfma_f32_16x16x32_bf16 v[70:73], v[162:165], v[210:213], v[70:73]
	v_mfma_f32_16x16x32_bf16 v[66:69], v[178:181], v[210:213], v[66:69]
	v_mfma_f32_16x16x32_bf16 v[118:121], v[166:169], v[190:193], v[118:121]
	v_mfma_f32_16x16x32_bf16 v[114:117], v[182:185], v[190:193], v[114:117]
	v_mfma_f32_16x16x32_bf16 v[102:105], v[166:169], v[198:201], v[102:105]
	v_mfma_f32_16x16x32_bf16 v[98:101], v[182:185], v[198:201], v[98:101]
	v_mfma_f32_16x16x32_bf16 v[86:89], v[166:169], v[206:209], v[86:89]
	v_mfma_f32_16x16x32_bf16 v[82:85], v[182:185], v[206:209], v[82:85]
	v_mfma_f32_16x16x32_bf16 v[70:73], v[166:169], v[218:221], v[70:73]
	v_mfma_f32_16x16x32_bf16 v[66:69], v[182:185], v[218:221], v[66:69]
	s_setprio 0
	s_barrier
	s_add_i32 s62, s66, s31
	v_lshl_add_u64 v[170:171], v[170:171], 0, s[24:25]
	s_mov_b32 m0, s62
	ds_read_b128 v[186:189], v176 offset:49152
	ds_read_b128 v[190:193], v176 offset:50176
	ds_read_b128 v[194:197], v176 offset:51200
	ds_read_b128 v[198:201], v176 offset:52224
	ds_read_b128 v[202:205], v176 offset:53248
	ds_read_b128 v[206:209], v176 offset:54272
	ds_read_b128 v[210:213], v176 offset:55296
	ds_read_b128 v[218:221], v176 offset:56320
	v_mov_b32_e32 v230, 0x80000
	v_lshl_add_u64 v[232:233], v[230:231], 0, v[228:229]
	global_load_lds_dwordx4 v[232:233], off
	s_add_i32 m0, s62, 0x2000
	s_add_u32 s34, s34, 0x80080
	v_lshl_add_u64 v[170:171], v[214:215], 0, s[24:25]
	s_addc_u32 s35, s35, 0
	s_add_i32 s62, s67, s31
	v_mov_b32_e32 v230, 0x80100
	v_lshl_add_u64 v[232:233], v[230:231], 0, v[228:229]
	global_load_lds_dwordx4 v[232:233], off
	v_lshl_add_u64 v[170:171], s[34:35], 0, v[144:145]
	s_mov_b32 m0, s62
	s_nop 0
	v_mov_b32_e32 v230, 0x90000
	v_lshl_add_u64 v[232:233], v[230:231], 0, v[228:229]
	global_load_lds_dwordx4 v[232:233], off
	v_lshl_add_u64 v[170:171], s[34:35], 0, v[148:149]
	s_add_i32 m0, s62, 0x2000
	s_nop 0
	v_mov_b32_e32 v230, 0x90100
	v_lshl_add_u64 v[232:233], v[230:231], 0, v[228:229]
	global_load_lds_dwordx4 v[232:233], off
	v_lshl_add_u64 v[170:171], v[222:223], 0, s[24:25]
	s_mov_b32 m0, s55
	s_nop 0
	v_mov_b32_e32 v230, 0xa0000
	v_lshl_add_u64 v[232:233], v[230:231], 0, v[228:229]
	global_load_lds_dwordx4 v[232:233], off
	v_lshl_add_u64 v[170:171], v[224:225], 0, s[24:25]
	s_mov_b32 m0, s56
	s_nop 0
	v_mov_b32_e32 v230, 0xa0100
	v_lshl_add_u64 v[232:233], v[230:231], 0, v[228:229]
	global_load_lds_dwordx4 v[232:233], off
	s_waitcnt vmcnt(8)
	s_waitcnt lgkmcnt(0)
	s_barrier
	s_setprio 1
	s_waitcnt lgkmcnt(0)
	v_mfma_f32_16x16x32_bf16 v[62:65], v[130:133], v[186:189], v[62:65]
	v_mfma_f32_16x16x32_bf16 v[58:61], v[138:141], v[186:189], v[58:61]
	v_mfma_f32_16x16x32_bf16 v[50:53], v[130:133], v[194:197], v[50:53]
	v_mfma_f32_16x16x32_bf16 v[42:45], v[138:141], v[194:197], v[42:45]
	v_mfma_f32_16x16x32_bf16 v[38:41], v[130:133], v[202:205], v[38:41]
	v_mfma_f32_16x16x32_bf16 v[34:37], v[138:141], v[202:205], v[34:37]
	v_mfma_f32_16x16x32_bf16 v[14:17], v[130:133], v[210:213], v[14:17]
	v_mfma_f32_16x16x32_bf16 v[10:13], v[138:141], v[210:213], v[10:13]
	v_mfma_f32_16x16x32_bf16 v[62:65], v[134:137], v[190:193], v[62:65]
	v_mfma_f32_16x16x32_bf16 v[58:61], v[158:161], v[190:193], v[58:61]
	v_mfma_f32_16x16x32_bf16 v[50:53], v[134:137], v[198:201], v[50:53]
	v_mfma_f32_16x16x32_bf16 v[42:45], v[158:161], v[198:201], v[42:45]
	v_mfma_f32_16x16x32_bf16 v[38:41], v[134:137], v[206:209], v[38:41]
	v_mfma_f32_16x16x32_bf16 v[34:37], v[158:161], v[206:209], v[34:37]
	v_mfma_f32_16x16x32_bf16 v[14:17], v[134:137], v[218:221], v[14:17]
	v_mfma_f32_16x16x32_bf16 v[10:13], v[158:161], v[218:221], v[10:13]
	s_setprio 0
	s_setprio 1
	v_mfma_f32_16x16x32_bf16 v[54:57], v[162:165], v[186:189], v[54:57]
	v_mfma_f32_16x16x32_bf16 v[46:49], v[178:181], v[186:189], v[46:49]
	v_mfma_f32_16x16x32_bf16 v[30:33], v[162:165], v[194:197], v[30:33]
	v_mfma_f32_16x16x32_bf16 v[26:29], v[178:181], v[194:197], v[26:29]
	v_mfma_f32_16x16x32_bf16 v[22:25], v[162:165], v[202:205], v[22:25]
	v_mfma_f32_16x16x32_bf16 v[18:21], v[178:181], v[202:205], v[18:21]
	v_mfma_f32_16x16x32_bf16 v[6:9], v[162:165], v[210:213], v[6:9]
	v_mfma_f32_16x16x32_bf16 v[2:5], v[178:181], v[210:213], v[2:5]
	v_mfma_f32_16x16x32_bf16 v[54:57], v[166:169], v[190:193], v[54:57]
	v_mfma_f32_16x16x32_bf16 v[46:49], v[182:185], v[190:193], v[46:49]
	v_mfma_f32_16x16x32_bf16 v[30:33], v[166:169], v[198:201], v[30:33]
	v_mfma_f32_16x16x32_bf16 v[26:29], v[182:185], v[198:201], v[26:29]
	v_mfma_f32_16x16x32_bf16 v[22:25], v[166:169], v[206:209], v[22:25]
	v_mfma_f32_16x16x32_bf16 v[18:21], v[182:185], v[206:209], v[18:21]
	v_mfma_f32_16x16x32_bf16 v[6:9], v[166:169], v[218:221], v[6:9]
	v_mfma_f32_16x16x32_bf16 v[2:5], v[182:185], v[218:221], v[2:5]
	s_setprio 0
	s_barrier
	s_add_i32 s72, s72, 2
	s_add_u32 s46, s46, 0x100
	s_addc_u32 s47, s47, 0
	s_add_u32 s70, s70, 0x100
	s_addc_u32 s71, s71, 0
	s_and_b64 vcc, exec, s[26:27]
	s_cbranch_vccz .LBB0_2941
	s_barrier
.LBB0_2941:
	v_lshl_or_b32 v130, s61, 8, v173
	v_lshl_add_u32 v158, s44, 8, v1
	v_ashrrev_i32_e32 v131, 31, v130
	v_lshlrev_b64 v[160:161], 1, v[130:131]
	v_or_b32_e32 v130, 16, v158
	v_ashrrev_i32_e32 v159, 31, v158
	v_ashrrev_i32_e32 v131, 31, v130
	v_lshlrev_b64 v[132:133], 12, v[158:159]
	v_lshlrev_b64 v[130:131], 12, v[130:131]
	v_lshl_add_u64 v[132:133], s[64:65], 0, v[132:133]
	v_lshl_add_u64 v[130:131], s[64:65], 0, v[130:131]
	v_lshl_add_u64 v[170:171], v[132:133], 0, v[160:161]
	v_lshl_add_u64 v[168:169], v[130:131], 0, v[160:161]
	s_waitcnt vmcnt(0)
	v_mov_b32_e32 v201, 0
	v_mov_b32_e32 v200, 0x10000
	v_lshl_add_u64 v[186:187], v[200:201], 0, v[170:171]
	v_mov_b32_e32 v200, 0x20000
	v_lshl_add_u64 v[188:189], v[200:201], 0, v[170:171]
	v_mov_b32_e32 v200, 0x30000
	v_lshl_add_u64 v[190:191], v[200:201], 0, v[170:171]
	v_mov_b32_e32 v200, 0x80000
	v_lshl_add_u64 v[192:193], v[200:201], 0, v[170:171]
	v_mov_b32_e32 v200, 0x90000
	v_lshl_add_u64 v[194:195], v[200:201], 0, v[170:171]
	v_mov_b32_e32 v200, 0xa0000
	v_lshl_add_u64 v[196:197], v[200:201], 0, v[170:171]
	v_mov_b32_e32 v200, 0xb0000
	v_lshl_add_u64 v[198:199], v[200:201], 0, v[170:171]
	v_lshlrev_b32_e32 v202, 4, v0
	v_add_u32_e32 v203, 0x10000, v202
	global_load_dwordx4 v[162:165], v[198:199], off
	global_load_dwordx4 v[166:169], v[198:199], off offset:256
	ds_read_b128 v[130:133], v203 offset:0
	ds_read_b128 v[134:137], v203 offset:8192
	ds_read_b128 v[138:141], v203 offset:16384
	ds_read_b128 v[158:161], v203 offset:24576
	s_waitcnt lgkmcnt(3)
	v_cvt_f32_f16_e32 v178, v130
	v_cvt_f32_f16_sdwa v179, v130 dst_sel:DWORD dst_unused:UNUSED_PAD src0_sel:WORD_1
	v_cvt_f32_f16_e32 v180, v131
	v_cvt_f32_f16_sdwa v181, v131 dst_sel:DWORD dst_unused:UNUSED_PAD src0_sel:WORD_1
	v_cvt_f32_f16_e32 v182, v132
	v_cvt_f32_f16_sdwa v183, v132 dst_sel:DWORD dst_unused:UNUSED_PAD src0_sel:WORD_1
	v_cvt_f32_f16_e32 v184, v133
	v_cvt_f32_f16_sdwa v185, v133 dst_sel:DWORD dst_unused:UNUSED_PAD src0_sel:WORD_1
	ds_read_b128 v[130:133], v202 offset:0
	v_pk_add_f32 v[126:127], v[178:179], v[126:127]
	v_pk_add_f32 v[128:129], v[180:181], v[128:129]
	v_pk_add_f32 v[122:123], v[182:183], v[122:123]
	v_pk_add_f32 v[124:125], v[184:185], v[124:125]
	v_cvt_pk_f16_f32 v125, v124, v125
	v_cvt_pk_f16_f32 v124, v122, v123
	v_cvt_pk_f16_f32 v123, v128, v129
	v_cvt_pk_f16_f32 v122, v126, v127
	global_store_dwordx4 v[170:171], v[122:125], off
	s_waitcnt lgkmcnt(3)
	v_cvt_f32_f16_e32 v178, v134
	v_cvt_f32_f16_sdwa v179, v134 dst_sel:DWORD dst_unused:UNUSED_PAD src0_sel:WORD_1
	v_cvt_f32_f16_e32 v180, v135
	v_cvt_f32_f16_sdwa v181, v135 dst_sel:DWORD dst_unused:UNUSED_PAD src0_sel:WORD_1
	v_cvt_f32_f16_e32 v182, v136
	v_cvt_f32_f16_sdwa v183, v136 dst_sel:DWORD dst_unused:UNUSED_PAD src0_sel:WORD_1
	v_cvt_f32_f16_e32 v184, v137
	v_cvt_f32_f16_sdwa v185, v137 dst_sel:DWORD dst_unused:UNUSED_PAD src0_sel:WORD_1
	ds_read_b128 v[134:137], v202 offset:8192
	v_pk_add_f32 v[118:119], v[178:179], v[118:119]
	v_pk_add_f32 v[120:121], v[180:181], v[120:121]
	v_pk_add_f32 v[114:115], v[182:183], v[114:115]
	v_pk_add_f32 v[116:117], v[184:185], v[116:117]
	v_cvt_pk_f16_f32 v117, v116, v117
	v_cvt_pk_f16_f32 v116, v114, v115
	v_cvt_pk_f16_f32 v115, v120, v121
	v_cvt_pk_f16_f32 v114, v118, v119
	global_store_dwordx4 v[170:171], v[114:117], off offset:256
	s_waitcnt lgkmcnt(3)
	v_cvt_f32_f16_e32 v178, v138
	v_cvt_f32_f16_sdwa v179, v138 dst_sel:DWORD dst_unused:UNUSED_PAD src0_sel:WORD_1
	v_cvt_f32_f16_e32 v180, v139
	v_cvt_f32_f16_sdwa v181, v139 dst_sel:DWORD dst_unused:UNUSED_PAD src0_sel:WORD_1
	v_cvt_f32_f16_e32 v182, v140
	v_cvt_f32_f16_sdwa v183, v140 dst_sel:DWORD dst_unused:UNUSED_PAD src0_sel:WORD_1
	v_cvt_f32_f16_e32 v184, v141
	v_cvt_f32_f16_sdwa v185, v141 dst_sel:DWORD dst_unused:UNUSED_PAD src0_sel:WORD_1
	ds_read_b128 v[138:141], v202 offset:16384
	v_pk_add_f32 v[110:111], v[178:179], v[110:111]
	v_pk_add_f32 v[112:113], v[180:181], v[112:113]
	v_pk_add_f32 v[106:107], v[182:183], v[106:107]
	v_pk_add_f32 v[108:109], v[184:185], v[108:109]
	v_cvt_pk_f16_f32 v109, v108, v109
	v_cvt_pk_f16_f32 v108, v106, v107
	v_cvt_pk_f16_f32 v107, v112, v113
	v_cvt_pk_f16_f32 v106, v110, v111
	global_store_dwordx4 v[186:187], v[106:109], off
	s_waitcnt lgkmcnt(3)
	v_cvt_f32_f16_e32 v178, v158
	v_cvt_f32_f16_sdwa v179, v158 dst_sel:DWORD dst_unused:UNUSED_PAD src0_sel:WORD_1
	v_cvt_f32_f16_e32 v180, v159
	v_cvt_f32_f16_sdwa v181, v159 dst_sel:DWORD dst_unused:UNUSED_PAD src0_sel:WORD_1
	v_cvt_f32_f16_e32 v182, v160
	v_cvt_f32_f16_sdwa v183, v160 dst_sel:DWORD dst_unused:UNUSED_PAD src0_sel:WORD_1
	v_cvt_f32_f16_e32 v184, v161
	v_cvt_f32_f16_sdwa v185, v161 dst_sel:DWORD dst_unused:UNUSED_PAD src0_sel:WORD_1
	ds_read_b128 v[158:161], v202 offset:24576
	v_pk_add_f32 v[102:103], v[178:179], v[102:103]
	v_pk_add_f32 v[104:105], v[180:181], v[104:105]
	v_pk_add_f32 v[98:99], v[182:183], v[98:99]
	v_pk_add_f32 v[100:101], v[184:185], v[100:101]
	v_cvt_pk_f16_f32 v101, v100, v101
	v_cvt_pk_f16_f32 v100, v98, v99
	v_cvt_pk_f16_f32 v99, v104, v105
	v_cvt_pk_f16_f32 v98, v102, v103
	global_store_dwordx4 v[186:187], v[98:101], off offset:256
	s_waitcnt lgkmcnt(3)
	v_cvt_f32_f16_e32 v178, v130
	v_cvt_f32_f16_sdwa v179, v130 dst_sel:DWORD dst_unused:UNUSED_PAD src0_sel:WORD_1
	v_cvt_f32_f16_e32 v180, v131
	v_cvt_f32_f16_sdwa v181, v131 dst_sel:DWORD dst_unused:UNUSED_PAD src0_sel:WORD_1
	v_cvt_f32_f16_e32 v182, v132
	v_cvt_f32_f16_sdwa v183, v132 dst_sel:DWORD dst_unused:UNUSED_PAD src0_sel:WORD_1
	v_cvt_f32_f16_e32 v184, v133
	v_cvt_f32_f16_sdwa v185, v133 dst_sel:DWORD dst_unused:UNUSED_PAD src0_sel:WORD_1
	ds_read_b128 v[130:133], v203 offset:32768
	v_pk_add_f32 v[94:95], v[178:179], v[94:95]
	v_pk_add_f32 v[96:97], v[180:181], v[96:97]
	v_pk_add_f32 v[90:91], v[182:183], v[90:91]
	v_pk_add_f32 v[92:93], v[184:185], v[92:93]
	v_cvt_pk_f16_f32 v93, v92, v93
	v_cvt_pk_f16_f32 v92, v90, v91
	v_cvt_pk_f16_f32 v91, v96, v97
	v_cvt_pk_f16_f32 v90, v94, v95
	global_store_dwordx4 v[188:189], v[90:93], off
	s_waitcnt lgkmcnt(3)
	v_cvt_f32_f16_e32 v178, v134
	v_cvt_f32_f16_sdwa v179, v134 dst_sel:DWORD dst_unused:UNUSED_PAD src0_sel:WORD_1
	v_cvt_f32_f16_e32 v180, v135
	v_cvt_f32_f16_sdwa v181, v135 dst_sel:DWORD dst_unused:UNUSED_PAD src0_sel:WORD_1
	v_cvt_f32_f16_e32 v182, v136
	v_cvt_f32_f16_sdwa v183, v136 dst_sel:DWORD dst_unused:UNUSED_PAD src0_sel:WORD_1
	v_cvt_f32_f16_e32 v184, v137
	v_cvt_f32_f16_sdwa v185, v137 dst_sel:DWORD dst_unused:UNUSED_PAD src0_sel:WORD_1
	ds_read_b128 v[134:137], v203 offset:40960
	v_pk_add_f32 v[86:87], v[178:179], v[86:87]
	v_pk_add_f32 v[88:89], v[180:181], v[88:89]
	v_pk_add_f32 v[82:83], v[182:183], v[82:83]
	v_pk_add_f32 v[84:85], v[184:185], v[84:85]
	v_cvt_pk_f16_f32 v85, v84, v85
	v_cvt_pk_f16_f32 v84, v82, v83
	v_cvt_pk_f16_f32 v83, v88, v89
	v_cvt_pk_f16_f32 v82, v86, v87
	global_store_dwordx4 v[188:189], v[82:85], off offset:256
	s_waitcnt lgkmcnt(3)
	v_cvt_f32_f16_e32 v178, v138
	v_cvt_f32_f16_sdwa v179, v138 dst_sel:DWORD dst_unused:UNUSED_PAD src0_sel:WORD_1
	v_cvt_f32_f16_e32 v180, v139
	v_cvt_f32_f16_sdwa v181, v139 dst_sel:DWORD dst_unused:UNUSED_PAD src0_sel:WORD_1
	v_cvt_f32_f16_e32 v182, v140
	v_cvt_f32_f16_sdwa v183, v140 dst_sel:DWORD dst_unused:UNUSED_PAD src0_sel:WORD_1
	v_cvt_f32_f16_e32 v184, v141
	v_cvt_f32_f16_sdwa v185, v141 dst_sel:DWORD dst_unused:UNUSED_PAD src0_sel:WORD_1
	ds_read_b128 v[138:141], v203 offset:49152
	v_pk_add_f32 v[78:79], v[178:179], v[78:79]
	v_pk_add_f32 v[80:81], v[180:181], v[80:81]
	v_pk_add_f32 v[74:75], v[182:183], v[74:75]
	v_pk_add_f32 v[76:77], v[184:185], v[76:77]
	v_cvt_pk_f16_f32 v77, v76, v77
	v_cvt_pk_f16_f32 v76, v74, v75
	v_cvt_pk_f16_f32 v75, v80, v81
	v_cvt_pk_f16_f32 v74, v78, v79
	global_store_dwordx4 v[190:191], v[74:77], off
	s_waitcnt lgkmcnt(3)
	v_cvt_f32_f16_e32 v178, v158
	v_cvt_f32_f16_sdwa v179, v158 dst_sel:DWORD dst_unused:UNUSED_PAD src0_sel:WORD_1
	v_cvt_f32_f16_e32 v180, v159
	v_cvt_f32_f16_sdwa v181, v159 dst_sel:DWORD dst_unused:UNUSED_PAD src0_sel:WORD_1
	v_cvt_f32_f16_e32 v182, v160
	v_cvt_f32_f16_sdwa v183, v160 dst_sel:DWORD dst_unused:UNUSED_PAD src0_sel:WORD_1
	v_cvt_f32_f16_e32 v184, v161
	v_cvt_f32_f16_sdwa v185, v161 dst_sel:DWORD dst_unused:UNUSED_PAD src0_sel:WORD_1
	ds_read_b128 v[158:161], v203 offset:57344
	v_pk_add_f32 v[70:71], v[178:179], v[70:71]
	v_pk_add_f32 v[72:73], v[180:181], v[72:73]
	v_pk_add_f32 v[66:67], v[182:183], v[66:67]
	v_pk_add_f32 v[68:69], v[184:185], v[68:69]
	v_cvt_pk_f16_f32 v69, v68, v69
	v_cvt_pk_f16_f32 v68, v66, v67
	v_cvt_pk_f16_f32 v67, v72, v73
	v_cvt_pk_f16_f32 v66, v70, v71
	global_store_dwordx4 v[190:191], v[66:69], off offset:256
	s_waitcnt lgkmcnt(3)
	v_cvt_f32_f16_e32 v178, v130
	v_cvt_f32_f16_sdwa v179, v130 dst_sel:DWORD dst_unused:UNUSED_PAD src0_sel:WORD_1
	v_cvt_f32_f16_e32 v180, v131
	v_cvt_f32_f16_sdwa v181, v131 dst_sel:DWORD dst_unused:UNUSED_PAD src0_sel:WORD_1
	v_cvt_f32_f16_e32 v182, v132
	v_cvt_f32_f16_sdwa v183, v132 dst_sel:DWORD dst_unused:UNUSED_PAD src0_sel:WORD_1
	v_cvt_f32_f16_e32 v184, v133
	v_cvt_f32_f16_sdwa v185, v133 dst_sel:DWORD dst_unused:UNUSED_PAD src0_sel:WORD_1
	ds_read_b128 v[130:133], v202 offset:32768
	v_pk_add_f32 v[62:63], v[178:179], v[62:63]
	v_pk_add_f32 v[64:65], v[180:181], v[64:65]
	v_pk_add_f32 v[58:59], v[182:183], v[58:59]
	v_pk_add_f32 v[60:61], v[184:185], v[60:61]
	v_cvt_pk_f16_f32 v61, v60, v61
	v_cvt_pk_f16_f32 v60, v58, v59
	v_cvt_pk_f16_f32 v59, v64, v65
	v_cvt_pk_f16_f32 v58, v62, v63
	global_store_dwordx4 v[192:193], v[58:61], off
	s_waitcnt lgkmcnt(3)
	v_cvt_f32_f16_e32 v178, v134
	v_cvt_f32_f16_sdwa v179, v134 dst_sel:DWORD dst_unused:UNUSED_PAD src0_sel:WORD_1
	v_cvt_f32_f16_e32 v180, v135
	v_cvt_f32_f16_sdwa v181, v135 dst_sel:DWORD dst_unused:UNUSED_PAD src0_sel:WORD_1
	v_cvt_f32_f16_e32 v182, v136
	v_cvt_f32_f16_sdwa v183, v136 dst_sel:DWORD dst_unused:UNUSED_PAD src0_sel:WORD_1
	v_cvt_f32_f16_e32 v184, v137
	v_cvt_f32_f16_sdwa v185, v137 dst_sel:DWORD dst_unused:UNUSED_PAD src0_sel:WORD_1
	ds_read_b128 v[134:137], v202 offset:40960
	v_pk_add_f32 v[54:55], v[178:179], v[54:55]
	v_pk_add_f32 v[56:57], v[180:181], v[56:57]
	v_pk_add_f32 v[46:47], v[182:183], v[46:47]
	v_pk_add_f32 v[48:49], v[184:185], v[48:49]
	v_cvt_pk_f16_f32 v49, v48, v49
	v_cvt_pk_f16_f32 v48, v46, v47
	v_cvt_pk_f16_f32 v47, v56, v57
	v_cvt_pk_f16_f32 v46, v54, v55
	global_store_dwordx4 v[192:193], v[46:49], off offset:256
	s_waitcnt lgkmcnt(3)
	v_cvt_f32_f16_e32 v178, v138
	v_cvt_f32_f16_sdwa v179, v138 dst_sel:DWORD dst_unused:UNUSED_PAD src0_sel:WORD_1
	v_cvt_f32_f16_e32 v180, v139
	v_cvt_f32_f16_sdwa v181, v139 dst_sel:DWORD dst_unused:UNUSED_PAD src0_sel:WORD_1
	v_cvt_f32_f16_e32 v182, v140
	v_cvt_f32_f16_sdwa v183, v140 dst_sel:DWORD dst_unused:UNUSED_PAD src0_sel:WORD_1
	v_cvt_f32_f16_e32 v184, v141
	v_cvt_f32_f16_sdwa v185, v141 dst_sel:DWORD dst_unused:UNUSED_PAD src0_sel:WORD_1
	v_pk_add_f32 v[50:51], v[178:179], v[50:51]
	v_pk_add_f32 v[52:53], v[180:181], v[52:53]
	v_pk_add_f32 v[42:43], v[182:183], v[42:43]
	v_pk_add_f32 v[44:45], v[184:185], v[44:45]
	v_cvt_pk_f16_f32 v45, v44, v45
	v_cvt_pk_f16_f32 v44, v42, v43
	v_cvt_pk_f16_f32 v43, v52, v53
	v_cvt_pk_f16_f32 v42, v50, v51
	global_store_dwordx4 v[194:195], v[42:45], off
	s_waitcnt lgkmcnt(2)
	v_cvt_f32_f16_e32 v178, v158
	v_cvt_f32_f16_sdwa v179, v158 dst_sel:DWORD dst_unused:UNUSED_PAD src0_sel:WORD_1
	v_cvt_f32_f16_e32 v180, v159
	v_cvt_f32_f16_sdwa v181, v159 dst_sel:DWORD dst_unused:UNUSED_PAD src0_sel:WORD_1
	v_cvt_f32_f16_e32 v182, v160
	v_cvt_f32_f16_sdwa v183, v160 dst_sel:DWORD dst_unused:UNUSED_PAD src0_sel:WORD_1
	v_cvt_f32_f16_e32 v184, v161
	v_cvt_f32_f16_sdwa v185, v161 dst_sel:DWORD dst_unused:UNUSED_PAD src0_sel:WORD_1
	v_pk_add_f32 v[30:31], v[178:179], v[30:31]
	v_pk_add_f32 v[32:33], v[180:181], v[32:33]
	v_pk_add_f32 v[26:27], v[182:183], v[26:27]
	v_pk_add_f32 v[28:29], v[184:185], v[28:29]
	v_cvt_pk_f16_f32 v29, v28, v29
	v_cvt_pk_f16_f32 v28, v26, v27
	v_cvt_pk_f16_f32 v27, v32, v33
	v_cvt_pk_f16_f32 v26, v30, v31
	global_store_dwordx4 v[194:195], v[26:29], off offset:256
	s_waitcnt lgkmcnt(1)
	v_cvt_f32_f16_e32 v178, v130
	v_cvt_f32_f16_sdwa v179, v130 dst_sel:DWORD dst_unused:UNUSED_PAD src0_sel:WORD_1
	v_cvt_f32_f16_e32 v180, v131
	v_cvt_f32_f16_sdwa v181, v131 dst_sel:DWORD dst_unused:UNUSED_PAD src0_sel:WORD_1
	v_cvt_f32_f16_e32 v182, v132
	v_cvt_f32_f16_sdwa v183, v132 dst_sel:DWORD dst_unused:UNUSED_PAD src0_sel:WORD_1
	v_cvt_f32_f16_e32 v184, v133
	v_cvt_f32_f16_sdwa v185, v133 dst_sel:DWORD dst_unused:UNUSED_PAD src0_sel:WORD_1
	v_pk_add_f32 v[38:39], v[178:179], v[38:39]
	v_pk_add_f32 v[40:41], v[180:181], v[40:41]
	v_pk_add_f32 v[34:35], v[182:183], v[34:35]
	v_pk_add_f32 v[36:37], v[184:185], v[36:37]
	v_cvt_pk_f16_f32 v37, v36, v37
	v_cvt_pk_f16_f32 v36, v34, v35
	v_cvt_pk_f16_f32 v35, v40, v41
	v_cvt_pk_f16_f32 v34, v38, v39
	global_store_dwordx4 v[196:197], v[34:37], off
	s_waitcnt lgkmcnt(0)
	v_cvt_f32_f16_e32 v178, v134
	v_cvt_f32_f16_sdwa v179, v134 dst_sel:DWORD dst_unused:UNUSED_PAD src0_sel:WORD_1
	v_cvt_f32_f16_e32 v180, v135
	v_cvt_f32_f16_sdwa v181, v135 dst_sel:DWORD dst_unused:UNUSED_PAD src0_sel:WORD_1
	v_cvt_f32_f16_e32 v182, v136
	v_cvt_f32_f16_sdwa v183, v136 dst_sel:DWORD dst_unused:UNUSED_PAD src0_sel:WORD_1
	v_cvt_f32_f16_e32 v184, v137
	v_cvt_f32_f16_sdwa v185, v137 dst_sel:DWORD dst_unused:UNUSED_PAD src0_sel:WORD_1
	v_pk_add_f32 v[22:23], v[178:179], v[22:23]
	v_pk_add_f32 v[24:25], v[180:181], v[24:25]
	v_pk_add_f32 v[18:19], v[182:183], v[18:19]
	v_pk_add_f32 v[20:21], v[184:185], v[20:21]
	v_cvt_pk_f16_f32 v21, v20, v21
	v_cvt_pk_f16_f32 v20, v18, v19
	v_cvt_pk_f16_f32 v19, v24, v25
	v_cvt_pk_f16_f32 v18, v22, v23
	global_store_dwordx4 v[196:197], v[18:21], off offset:256
	s_waitcnt vmcnt(15)
	v_cvt_f32_f16_e32 v178, v162
	v_cvt_f32_f16_sdwa v179, v162 dst_sel:DWORD dst_unused:UNUSED_PAD src0_sel:WORD_1
	v_cvt_f32_f16_e32 v180, v163
	v_cvt_f32_f16_sdwa v181, v163 dst_sel:DWORD dst_unused:UNUSED_PAD src0_sel:WORD_1
	v_cvt_f32_f16_e32 v182, v164
	v_cvt_f32_f16_sdwa v183, v164 dst_sel:DWORD dst_unused:UNUSED_PAD src0_sel:WORD_1
	v_cvt_f32_f16_e32 v184, v165
	v_cvt_f32_f16_sdwa v185, v165 dst_sel:DWORD dst_unused:UNUSED_PAD src0_sel:WORD_1
	v_pk_add_f32 v[14:15], v[178:179], v[14:15]
	v_pk_add_f32 v[16:17], v[180:181], v[16:17]
	v_pk_add_f32 v[10:11], v[182:183], v[10:11]
	v_pk_add_f32 v[12:13], v[184:185], v[12:13]
	v_cvt_pk_f16_f32 v13, v12, v13
	v_cvt_pk_f16_f32 v12, v10, v11
	v_cvt_pk_f16_f32 v11, v16, v17
	v_cvt_pk_f16_f32 v10, v14, v15
	global_store_dwordx4 v[198:199], v[10:13], off
	s_waitcnt vmcnt(15)
	v_cvt_f32_f16_e32 v178, v166
	v_cvt_f32_f16_sdwa v179, v166 dst_sel:DWORD dst_unused:UNUSED_PAD src0_sel:WORD_1
	v_cvt_f32_f16_e32 v180, v167
	v_cvt_f32_f16_sdwa v181, v167 dst_sel:DWORD dst_unused:UNUSED_PAD src0_sel:WORD_1
	v_cvt_f32_f16_e32 v182, v168
	v_cvt_f32_f16_sdwa v183, v168 dst_sel:DWORD dst_unused:UNUSED_PAD src0_sel:WORD_1
	v_cvt_f32_f16_e32 v184, v169
	v_cvt_f32_f16_sdwa v185, v169 dst_sel:DWORD dst_unused:UNUSED_PAD src0_sel:WORD_1
	v_pk_add_f32 v[6:7], v[178:179], v[6:7]
	v_pk_add_f32 v[8:9], v[180:181], v[8:9]
	v_pk_add_f32 v[2:3], v[182:183], v[2:3]
	v_pk_add_f32 v[4:5], v[184:185], v[4:5]
	v_cvt_pk_f16_f32 v5, v4, v5
	v_cvt_pk_f16_f32 v4, v2, v3
	v_cvt_pk_f16_f32 v3, v8, v9
	v_cvt_pk_f16_f32 v2, v6, v7
	global_store_dwordx4 v[198:199], v[2:5], off offset:256
	s_mov_b64 s[0:1], -1
	s_andn2_b64 vcc, exec, s[2:3]
	s_cbranch_vccnz .LBB0_2930
	s_andn2_b64 vcc, exec, s[8:9]
	s_cbranch_vccnz .LBB0_2929
	s_barrier
	s_branch .LBB0_2929

.LBB0_3180:
	ds_read_b128 v[130:133], v174
	ds_read_b128 v[134:137], v174 offset:1024
	ds_read_b128 v[138:141], v174 offset:2048
	ds_read_b128 v[158:161], v174 offset:3072
	ds_read_b128 v[162:165], v175
	ds_read_b128 v[166:169], v175 offset:1024
	ds_read_b128 v[178:181], v175 offset:2048
	ds_read_b128 v[182:185], v175 offset:3072
	s_add_u32 s34, s40, 0xffea0080
	s_addc_u32 s35, s41, -1
	s_cmpk_eq_i32 s60, 0x54
	s_cselect_b32 s43, s5, s35
	s_cselect_b32 s42, s4, s34
	s_cselect_b32 s35, s39, s1
	s_cselect_b32 s34, s38, s0
	v_lshl_add_u64 v[170:171], s[40:41], 0, v[150:151]
	s_add_i32 m0, s33, 0xc000
	ds_read_b128 v[186:189], v176
	ds_read_b128 v[190:193], v176 offset:1024
	ds_read_b128 v[194:197], v176 offset:2048
	ds_read_b128 v[198:201], v176 offset:3072
	ds_read_b128 v[202:205], v176 offset:4096
	ds_read_b128 v[206:209], v176 offset:5120
	ds_read_b128 v[210:213], v176 offset:6144
	ds_read_b128 v[218:221], v176 offset:7168
	global_load_lds_dwordx4 v[170:171], off
	v_lshl_add_u64 v[170:171], s[40:41], 0, v[152:153]
	s_add_i32 m0, s33, 0xe000
	s_nop 0
	global_load_lds_dwordx4 v[170:171], off
	s_waitcnt vmcnt(8)
	s_waitcnt lgkmcnt(0)
	s_barrier
	s_setprio 1
	s_waitcnt lgkmcnt(0)
	v_mfma_f32_16x16x32_bf16 v[126:129], v[130:133], v[186:189], v[126:129]
	v_mfma_f32_16x16x32_bf16 v[122:125], v[138:141], v[186:189], v[122:125]
	v_mfma_f32_16x16x32_bf16 v[110:113], v[130:133], v[194:197], v[110:113]
	v_mfma_f32_16x16x32_bf16 v[106:109], v[138:141], v[194:197], v[106:109]
	v_mfma_f32_16x16x32_bf16 v[94:97], v[130:133], v[202:205], v[94:97]
	v_mfma_f32_16x16x32_bf16 v[90:93], v[138:141], v[202:205], v[90:93]
	v_mfma_f32_16x16x32_bf16 v[78:81], v[130:133], v[210:213], v[78:81]
	v_mfma_f32_16x16x32_bf16 v[74:77], v[138:141], v[210:213], v[74:77]
	v_mfma_f32_16x16x32_bf16 v[126:129], v[134:137], v[190:193], v[126:129]
	v_mfma_f32_16x16x32_bf16 v[122:125], v[158:161], v[190:193], v[122:125]
	v_mfma_f32_16x16x32_bf16 v[110:113], v[134:137], v[198:201], v[110:113]
	v_mfma_f32_16x16x32_bf16 v[106:109], v[158:161], v[198:201], v[106:109]
	v_mfma_f32_16x16x32_bf16 v[94:97], v[134:137], v[206:209], v[94:97]
	v_mfma_f32_16x16x32_bf16 v[90:93], v[158:161], v[206:209], v[90:93]
	v_mfma_f32_16x16x32_bf16 v[78:81], v[134:137], v[218:221], v[78:81]
	v_mfma_f32_16x16x32_bf16 v[74:77], v[158:161], v[218:221], v[74:77]
	s_setprio 0
	s_setprio 1
	v_mfma_f32_16x16x32_bf16 v[118:121], v[162:165], v[186:189], v[118:121]
	v_mfma_f32_16x16x32_bf16 v[114:117], v[178:181], v[186:189], v[114:117]
	v_mfma_f32_16x16x32_bf16 v[102:105], v[162:165], v[194:197], v[102:105]
	v_mfma_f32_16x16x32_bf16 v[98:101], v[178:181], v[194:197], v[98:101]
	v_mfma_f32_16x16x32_bf16 v[86:89], v[162:165], v[202:205], v[86:89]
	v_mfma_f32_16x16x32_bf16 v[82:85], v[178:181], v[202:205], v[82:85]
	v_mfma_f32_16x16x32_bf16 v[70:73], v[162:165], v[210:213], v[70:73]
	v_mfma_f32_16x16x32_bf16 v[66:69], v[178:181], v[210:213], v[66:69]
	v_mfma_f32_16x16x32_bf16 v[118:121], v[166:169], v[190:193], v[118:121]
	v_mfma_f32_16x16x32_bf16 v[114:117], v[182:185], v[190:193], v[114:117]
	v_mfma_f32_16x16x32_bf16 v[102:105], v[166:169], v[198:201], v[102:105]
	v_mfma_f32_16x16x32_bf16 v[98:101], v[182:185], v[198:201], v[98:101]
	v_mfma_f32_16x16x32_bf16 v[86:89], v[166:169], v[206:209], v[86:89]
	v_mfma_f32_16x16x32_bf16 v[82:85], v[182:185], v[206:209], v[82:85]
	v_mfma_f32_16x16x32_bf16 v[70:73], v[166:169], v[218:221], v[70:73]
	v_mfma_f32_16x16x32_bf16 v[66:69], v[182:185], v[218:221], v[66:69]
	s_setprio 0
	s_barrier
	s_add_i32 s61, s53, s31
	v_lshl_add_u64 v[170:171], s[34:35], 0, v[144:145]
	s_mov_b32 m0, s61
	ds_read_b128 v[186:189], v176 offset:16384
	ds_read_b128 v[190:193], v176 offset:17408
	ds_read_b128 v[194:197], v176 offset:18432
	ds_read_b128 v[198:201], v176 offset:19456
	ds_read_b128 v[202:205], v176 offset:20480
	ds_read_b128 v[206:209], v176 offset:21504
	ds_read_b128 v[210:213], v176 offset:22528
	ds_read_b128 v[218:221], v176 offset:23552
	global_load_lds_dwordx4 v[170:171], off
	s_add_i32 m0, s61, 0x2000
	s_add_u32 s62, s34, 0x160000
	v_lshl_add_u64 v[214:215], s[34:35], 0, v[148:149]
	s_addc_u32 s63, s35, 0
	s_add_i32 s61, s54, s31
	global_load_lds_dwordx4 v[214:215], off
	v_lshl_add_u64 v[222:223], s[62:63], 0, v[144:145]
	s_mov_b32 m0, s61
	v_lshl_add_u64 v[224:225], s[42:43], 0, v[146:147]
	global_load_lds_dwordx4 v[222:223], off
	v_lshl_add_u64 v[222:223], s[62:63], 0, v[148:149]
	s_add_i32 m0, s61, 0x2000
	s_nop 0
	global_load_lds_dwordx4 v[222:223], off
	v_lshl_add_u64 v[222:223], s[42:43], 0, v[142:143]
	s_mov_b32 m0, s33
	s_nop 0
	global_load_lds_dwordx4 v[222:223], off
	s_mov_b32 m0, s44
	s_nop 0
	global_load_lds_dwordx4 v[224:225], off
	s_waitcnt vmcnt(8)
	s_waitcnt lgkmcnt(0)
	s_barrier
	s_setprio 1
	s_waitcnt lgkmcnt(0)
	v_mfma_f32_16x16x32_bf16 v[62:65], v[130:133], v[186:189], v[62:65]
	v_mfma_f32_16x16x32_bf16 v[58:61], v[138:141], v[186:189], v[58:61]
	v_mfma_f32_16x16x32_bf16 v[50:53], v[130:133], v[194:197], v[50:53]
	v_mfma_f32_16x16x32_bf16 v[42:45], v[138:141], v[194:197], v[42:45]
	v_mfma_f32_16x16x32_bf16 v[38:41], v[130:133], v[202:205], v[38:41]
	v_mfma_f32_16x16x32_bf16 v[34:37], v[138:141], v[202:205], v[34:37]
	v_mfma_f32_16x16x32_bf16 v[14:17], v[130:133], v[210:213], v[14:17]
	v_mfma_f32_16x16x32_bf16 v[10:13], v[138:141], v[210:213], v[10:13]
	v_mfma_f32_16x16x32_bf16 v[62:65], v[134:137], v[190:193], v[62:65]
	v_mfma_f32_16x16x32_bf16 v[58:61], v[158:161], v[190:193], v[58:61]
	v_mfma_f32_16x16x32_bf16 v[50:53], v[134:137], v[198:201], v[50:53]
	v_mfma_f32_16x16x32_bf16 v[42:45], v[158:161], v[198:201], v[42:45]
	v_mfma_f32_16x16x32_bf16 v[38:41], v[134:137], v[206:209], v[38:41]
	v_mfma_f32_16x16x32_bf16 v[34:37], v[158:161], v[206:209], v[34:37]
	v_mfma_f32_16x16x32_bf16 v[14:17], v[134:137], v[218:221], v[14:17]
	v_mfma_f32_16x16x32_bf16 v[10:13], v[158:161], v[218:221], v[10:13]
	s_setprio 0
	s_setprio 1
	v_mfma_f32_16x16x32_bf16 v[54:57], v[162:165], v[186:189], v[54:57]
	v_mfma_f32_16x16x32_bf16 v[46:49], v[178:181], v[186:189], v[46:49]
	v_mfma_f32_16x16x32_bf16 v[30:33], v[162:165], v[194:197], v[30:33]
	v_mfma_f32_16x16x32_bf16 v[26:29], v[178:181], v[194:197], v[26:29]
	v_mfma_f32_16x16x32_bf16 v[22:25], v[162:165], v[202:205], v[22:25]
	v_mfma_f32_16x16x32_bf16 v[18:21], v[178:181], v[202:205], v[18:21]
	v_mfma_f32_16x16x32_bf16 v[6:9], v[162:165], v[210:213], v[6:9]
	v_mfma_f32_16x16x32_bf16 v[2:5], v[178:181], v[210:213], v[2:5]
	v_mfma_f32_16x16x32_bf16 v[54:57], v[166:169], v[190:193], v[54:57]
	v_mfma_f32_16x16x32_bf16 v[46:49], v[182:185], v[190:193], v[46:49]
	v_mfma_f32_16x16x32_bf16 v[30:33], v[166:169], v[198:201], v[30:33]
	v_mfma_f32_16x16x32_bf16 v[26:29], v[182:185], v[198:201], v[26:29]
	v_mfma_f32_16x16x32_bf16 v[22:25], v[166:169], v[206:209], v[22:25]
	v_mfma_f32_16x16x32_bf16 v[18:21], v[182:185], v[206:209], v[18:21]
	v_mfma_f32_16x16x32_bf16 v[6:9], v[166:169], v[218:221], v[6:9]
	v_mfma_f32_16x16x32_bf16 v[2:5], v[182:185], v[218:221], v[2:5]
	s_setprio 0
	s_barrier
	s_add_i32 s61, 0, 0x18000
	s_add_i32 s62, 0, 0x1c000
	v_add_u32_e32 v158, s61, v172
	v_add_u32_e32 v177, s62, v172
	ds_read_b128 v[130:133], v158
	ds_read_b128 v[134:137], v158 offset:1024
	ds_read_b128 v[138:141], v158 offset:2048
	ds_read_b128 v[158:161], v158 offset:3072
	ds_read_b128 v[162:165], v177
	ds_read_b128 v[166:169], v177 offset:1024
	ds_read_b128 v[178:181], v177 offset:2048
	ds_read_b128 v[182:185], v177 offset:3072
	s_add_u32 s42, s42, 0x160000
	s_addc_u32 s43, s43, 0
	s_mov_b32 m0, s45
	v_lshl_add_u64 v[226:227], s[42:43], 0, v[142:143]
	ds_read_b128 v[186:189], v176 offset:32768
	ds_read_b128 v[190:193], v176 offset:33792
	ds_read_b128 v[194:197], v176 offset:34816
	ds_read_b128 v[198:201], v176 offset:35840
	ds_read_b128 v[202:205], v176 offset:36864
	ds_read_b128 v[206:209], v176 offset:37888
	ds_read_b128 v[210:213], v176 offset:38912
	ds_read_b128 v[218:221], v176 offset:39936
	global_load_lds_dwordx4 v[226:227], off
	v_lshl_add_u64 v[226:227], s[42:43], 0, v[146:147]
	s_mov_b32 m0, s46
	s_nop 0
	global_load_lds_dwordx4 v[226:227], off
	s_waitcnt vmcnt(8)
	s_waitcnt lgkmcnt(0)
	s_barrier
	s_setprio 1
	s_waitcnt lgkmcnt(0)
	v_mfma_f32_16x16x32_bf16 v[126:129], v[130:133], v[186:189], v[126:129]
	v_mfma_f32_16x16x32_bf16 v[122:125], v[138:141], v[186:189], v[122:125]
	v_mfma_f32_16x16x32_bf16 v[110:113], v[130:133], v[194:197], v[110:113]
	v_mfma_f32_16x16x32_bf16 v[106:109], v[138:141], v[194:197], v[106:109]
	v_mfma_f32_16x16x32_bf16 v[94:97], v[130:133], v[202:205], v[94:97]
	v_mfma_f32_16x16x32_bf16 v[90:93], v[138:141], v[202:205], v[90:93]
	v_mfma_f32_16x16x32_bf16 v[78:81], v[130:133], v[210:213], v[78:81]
	v_mfma_f32_16x16x32_bf16 v[74:77], v[138:141], v[210:213], v[74:77]
	v_mfma_f32_16x16x32_bf16 v[126:129], v[134:137], v[190:193], v[126:129]
	v_mfma_f32_16x16x32_bf16 v[122:125], v[158:161], v[190:193], v[122:125]
	v_mfma_f32_16x16x32_bf16 v[110:113], v[134:137], v[198:201], v[110:113]
	v_mfma_f32_16x16x32_bf16 v[106:109], v[158:161], v[198:201], v[106:109]
	v_mfma_f32_16x16x32_bf16 v[94:97], v[134:137], v[206:209], v[94:97]
	v_mfma_f32_16x16x32_bf16 v[90:93], v[158:161], v[206:209], v[90:93]
	v_mfma_f32_16x16x32_bf16 v[78:81], v[134:137], v[218:221], v[78:81]
	v_mfma_f32_16x16x32_bf16 v[74:77], v[158:161], v[218:221], v[74:77]
	s_setprio 0
	s_setprio 1
	v_mfma_f32_16x16x32_bf16 v[118:121], v[162:165], v[186:189], v[118:121]
	v_mfma_f32_16x16x32_bf16 v[114:117], v[178:181], v[186:189], v[114:117]
	v_mfma_f32_16x16x32_bf16 v[102:105], v[162:165], v[194:197], v[102:105]
	v_mfma_f32_16x16x32_bf16 v[98:101], v[178:181], v[194:197], v[98:101]
	v_mfma_f32_16x16x32_bf16 v[86:89], v[162:165], v[202:205], v[86:89]
	v_mfma_f32_16x16x32_bf16 v[82:85], v[178:181], v[202:205], v[82:85]
	v_mfma_f32_16x16x32_bf16 v[70:73], v[162:165], v[210:213], v[70:73]
	v_mfma_f32_16x16x32_bf16 v[66:69], v[178:181], v[210:213], v[66:69]
	v_mfma_f32_16x16x32_bf16 v[118:121], v[166:169], v[190:193], v[118:121]
	v_mfma_f32_16x16x32_bf16 v[114:117], v[182:185], v[190:193], v[114:117]
	v_mfma_f32_16x16x32_bf16 v[102:105], v[166:169], v[198:201], v[102:105]
	v_mfma_f32_16x16x32_bf16 v[98:101], v[182:185], v[198:201], v[98:101]
	v_mfma_f32_16x16x32_bf16 v[86:89], v[166:169], v[206:209], v[86:89]
	v_mfma_f32_16x16x32_bf16 v[82:85], v[182:185], v[206:209], v[82:85]
	v_mfma_f32_16x16x32_bf16 v[70:73], v[166:169], v[218:221], v[70:73]
	v_mfma_f32_16x16x32_bf16 v[66:69], v[182:185], v[218:221], v[66:69]
	s_setprio 0
	s_barrier
	s_add_i32 s42, s61, s31
	v_lshl_add_u64 v[170:171], v[170:171], 0, s[24:25]
	s_mov_b32 m0, s42
	ds_read_b128 v[186:189], v176 offset:49152
	ds_read_b128 v[190:193], v176 offset:50176
	ds_read_b128 v[194:197], v176 offset:51200
	ds_read_b128 v[198:201], v176 offset:52224
	ds_read_b128 v[202:205], v176 offset:53248
	ds_read_b128 v[206:209], v176 offset:54272
	ds_read_b128 v[210:213], v176 offset:55296
	ds_read_b128 v[218:221], v176 offset:56320
	global_load_lds_dwordx4 v[170:171], off
	s_add_i32 m0, s42, 0x2000
	s_add_u32 s34, s34, 0x160080
	v_lshl_add_u64 v[170:171], v[214:215], 0, s[24:25]
	s_addc_u32 s35, s35, 0
	s_add_i32 s42, s62, s31
	global_load_lds_dwordx4 v[170:171], off
	v_lshl_add_u64 v[170:171], s[34:35], 0, v[144:145]
	s_mov_b32 m0, s42
	s_nop 0
	global_load_lds_dwordx4 v[170:171], off
	v_lshl_add_u64 v[170:171], s[34:35], 0, v[148:149]
	s_add_i32 m0, s42, 0x2000
	s_nop 0
	global_load_lds_dwordx4 v[170:171], off
	v_lshl_add_u64 v[170:171], v[222:223], 0, s[24:25]
	s_mov_b32 m0, s48
	s_nop 0
	global_load_lds_dwordx4 v[170:171], off
	v_lshl_add_u64 v[170:171], v[224:225], 0, s[24:25]
	s_mov_b32 m0, s49
	s_nop 0
	global_load_lds_dwordx4 v[170:171], off
	s_waitcnt vmcnt(8)
	s_waitcnt lgkmcnt(0)
	s_barrier
	s_setprio 1
	s_waitcnt lgkmcnt(0)
	v_mfma_f32_16x16x32_bf16 v[62:65], v[130:133], v[186:189], v[62:65]
	v_mfma_f32_16x16x32_bf16 v[58:61], v[138:141], v[186:189], v[58:61]
	v_mfma_f32_16x16x32_bf16 v[50:53], v[130:133], v[194:197], v[50:53]
	v_mfma_f32_16x16x32_bf16 v[42:45], v[138:141], v[194:197], v[42:45]
	v_mfma_f32_16x16x32_bf16 v[38:41], v[130:133], v[202:205], v[38:41]
	v_mfma_f32_16x16x32_bf16 v[34:37], v[138:141], v[202:205], v[34:37]
	v_mfma_f32_16x16x32_bf16 v[14:17], v[130:133], v[210:213], v[14:17]
	v_mfma_f32_16x16x32_bf16 v[10:13], v[138:141], v[210:213], v[10:13]
	v_mfma_f32_16x16x32_bf16 v[62:65], v[134:137], v[190:193], v[62:65]
	v_mfma_f32_16x16x32_bf16 v[58:61], v[158:161], v[190:193], v[58:61]
	v_mfma_f32_16x16x32_bf16 v[50:53], v[134:137], v[198:201], v[50:53]
	v_mfma_f32_16x16x32_bf16 v[42:45], v[158:161], v[198:201], v[42:45]
	v_mfma_f32_16x16x32_bf16 v[38:41], v[134:137], v[206:209], v[38:41]
	v_mfma_f32_16x16x32_bf16 v[34:37], v[158:161], v[206:209], v[34:37]
	v_mfma_f32_16x16x32_bf16 v[14:17], v[134:137], v[218:221], v[14:17]
	v_mfma_f32_16x16x32_bf16 v[10:13], v[158:161], v[218:221], v[10:13]
	s_setprio 0
	s_setprio 1
	v_mfma_f32_16x16x32_bf16 v[54:57], v[162:165], v[186:189], v[54:57]
	v_mfma_f32_16x16x32_bf16 v[46:49], v[178:181], v[186:189], v[46:49]
	v_mfma_f32_16x16x32_bf16 v[30:33], v[162:165], v[194:197], v[30:33]
	v_mfma_f32_16x16x32_bf16 v[26:29], v[178:181], v[194:197], v[26:29]
	v_mfma_f32_16x16x32_bf16 v[22:25], v[162:165], v[202:205], v[22:25]
	v_mfma_f32_16x16x32_bf16 v[18:21], v[178:181], v[202:205], v[18:21]
	v_mfma_f32_16x16x32_bf16 v[6:9], v[162:165], v[210:213], v[6:9]
	v_mfma_f32_16x16x32_bf16 v[2:5], v[178:181], v[210:213], v[2:5]
	v_mfma_f32_16x16x32_bf16 v[54:57], v[166:169], v[190:193], v[54:57]
	v_mfma_f32_16x16x32_bf16 v[46:49], v[182:185], v[190:193], v[46:49]
	v_mfma_f32_16x16x32_bf16 v[30:33], v[166:169], v[198:201], v[30:33]
	v_mfma_f32_16x16x32_bf16 v[26:29], v[182:185], v[198:201], v[26:29]
	v_mfma_f32_16x16x32_bf16 v[22:25], v[166:169], v[206:209], v[22:25]
	v_mfma_f32_16x16x32_bf16 v[18:21], v[182:185], v[206:209], v[18:21]
	v_mfma_f32_16x16x32_bf16 v[6:9], v[166:169], v[218:221], v[6:9]
	v_mfma_f32_16x16x32_bf16 v[2:5], v[182:185], v[218:221], v[2:5]
	s_setprio 0
	s_barrier
	s_add_i32 s60, s60, 2
	s_add_u32 s40, s40, 0x100
	s_addc_u32 s41, s41, 0
	s_add_u32 s0, s0, 0x100
	s_addc_u32 s1, s1, 0
	s_cmpk_gt_u32 s60, 0x53
	s_cbranch_scc0 .LBB0_3180
	v_lshl_add_u32 v234, s58, 8, v1
	v_lshl_or_b32 v236, s59, 8, v173
	v_ashrrev_i32_e32 v235, 31, v234
	v_ashrrev_i32_e32 v237, 31, v236
	v_lshlrev_b64 v[228:229], 12, v[234:235]
	v_lshl_add_u64 v[228:229], s[64:65], 0, v[228:229]
	v_lshlrev_b64 v[236:237], 1, v[236:237]
	v_lshl_add_u64 v[228:229], v[228:229], 0, v[236:237]
	v_mov_b32_e32 v231, 0
	ds_read_b128 v[130:133], v174
	ds_read_b128 v[134:137], v174 offset:1024
	ds_read_b128 v[138:141], v174 offset:2048
	ds_read_b128 v[158:161], v174 offset:3072
	ds_read_b128 v[162:165], v175
	ds_read_b128 v[166:169], v175 offset:1024
	ds_read_b128 v[178:181], v175 offset:2048
	ds_read_b128 v[182:185], v175 offset:3072
	s_add_u32 s34, s40, 0xffea0080
	s_addc_u32 s35, s41, -1
	s_cmpk_eq_i32 s60, 0x54
	s_cselect_b32 s43, s5, s35
	s_cselect_b32 s42, s4, s34
	s_cselect_b32 s35, s39, s1
	s_cselect_b32 s34, s38, s0
	v_lshl_add_u64 v[170:171], s[40:41], 0, v[150:151]
	s_add_i32 m0, s33, 0xc000
	ds_read_b128 v[186:189], v176
	ds_read_b128 v[190:193], v176 offset:1024
	ds_read_b128 v[194:197], v176 offset:2048
	ds_read_b128 v[198:201], v176 offset:3072
	ds_read_b128 v[202:205], v176 offset:4096
	ds_read_b128 v[206:209], v176 offset:5120
	ds_read_b128 v[210:213], v176 offset:6144
	ds_read_b128 v[218:221], v176 offset:7168
	global_load_lds_dwordx4 v[170:171], off
	v_lshl_add_u64 v[170:171], s[40:41], 0, v[152:153]
	s_add_i32 m0, s33, 0xe000
	s_nop 0
	global_load_lds_dwordx4 v[170:171], off
	s_waitcnt vmcnt(8)
	s_waitcnt lgkmcnt(0)
	s_barrier
	s_setprio 1
	s_waitcnt lgkmcnt(0)
	v_mfma_f32_16x16x32_bf16 v[126:129], v[130:133], v[186:189], v[126:129]
	v_mfma_f32_16x16x32_bf16 v[122:125], v[138:141], v[186:189], v[122:125]
	v_mfma_f32_16x16x32_bf16 v[110:113], v[130:133], v[194:197], v[110:113]
	v_mfma_f32_16x16x32_bf16 v[106:109], v[138:141], v[194:197], v[106:109]
	v_mfma_f32_16x16x32_bf16 v[94:97], v[130:133], v[202:205], v[94:97]
	v_mfma_f32_16x16x32_bf16 v[90:93], v[138:141], v[202:205], v[90:93]
	v_mfma_f32_16x16x32_bf16 v[78:81], v[130:133], v[210:213], v[78:81]
	v_mfma_f32_16x16x32_bf16 v[74:77], v[138:141], v[210:213], v[74:77]
	v_mfma_f32_16x16x32_bf16 v[126:129], v[134:137], v[190:193], v[126:129]
	v_mfma_f32_16x16x32_bf16 v[122:125], v[158:161], v[190:193], v[122:125]
	v_mfma_f32_16x16x32_bf16 v[110:113], v[134:137], v[198:201], v[110:113]
	v_mfma_f32_16x16x32_bf16 v[106:109], v[158:161], v[198:201], v[106:109]
	v_mfma_f32_16x16x32_bf16 v[94:97], v[134:137], v[206:209], v[94:97]
	v_mfma_f32_16x16x32_bf16 v[90:93], v[158:161], v[206:209], v[90:93]
	v_mfma_f32_16x16x32_bf16 v[78:81], v[134:137], v[218:221], v[78:81]
	v_mfma_f32_16x16x32_bf16 v[74:77], v[158:161], v[218:221], v[74:77]
	s_setprio 0
	s_setprio 1
	v_mfma_f32_16x16x32_bf16 v[118:121], v[162:165], v[186:189], v[118:121]
	v_mfma_f32_16x16x32_bf16 v[114:117], v[178:181], v[186:189], v[114:117]
	v_mfma_f32_16x16x32_bf16 v[102:105], v[162:165], v[194:197], v[102:105]
	v_mfma_f32_16x16x32_bf16 v[98:101], v[178:181], v[194:197], v[98:101]
	v_mfma_f32_16x16x32_bf16 v[86:89], v[162:165], v[202:205], v[86:89]
	v_mfma_f32_16x16x32_bf16 v[82:85], v[178:181], v[202:205], v[82:85]
	v_mfma_f32_16x16x32_bf16 v[70:73], v[162:165], v[210:213], v[70:73]
	v_mfma_f32_16x16x32_bf16 v[66:69], v[178:181], v[210:213], v[66:69]
	v_mfma_f32_16x16x32_bf16 v[118:121], v[166:169], v[190:193], v[118:121]
	v_mfma_f32_16x16x32_bf16 v[114:117], v[182:185], v[190:193], v[114:117]
	v_mfma_f32_16x16x32_bf16 v[102:105], v[166:169], v[198:201], v[102:105]
	v_mfma_f32_16x16x32_bf16 v[98:101], v[182:185], v[198:201], v[98:101]
	v_mfma_f32_16x16x32_bf16 v[86:89], v[166:169], v[206:209], v[86:89]
	v_mfma_f32_16x16x32_bf16 v[82:85], v[182:185], v[206:209], v[82:85]
	v_mfma_f32_16x16x32_bf16 v[70:73], v[166:169], v[218:221], v[70:73]
	v_mfma_f32_16x16x32_bf16 v[66:69], v[182:185], v[218:221], v[66:69]
	s_setprio 0
	s_barrier
	s_add_i32 s61, s53, s31
	v_lshl_add_u64 v[170:171], s[34:35], 0, v[144:145]
	s_mov_b32 m0, s61
	ds_read_b128 v[186:189], v176 offset:16384
	ds_read_b128 v[190:193], v176 offset:17408
	ds_read_b128 v[194:197], v176 offset:18432
	ds_read_b128 v[198:201], v176 offset:19456
	ds_read_b128 v[202:205], v176 offset:20480
	ds_read_b128 v[206:209], v176 offset:21504
	ds_read_b128 v[210:213], v176 offset:22528
	ds_read_b128 v[218:221], v176 offset:23552
	v_mov_b32_e32 v230, 0x0
	v_lshl_add_u64 v[232:233], v[230:231], 0, v[228:229]
	global_load_lds_dwordx4 v[232:233], off
	s_add_i32 m0, s61, 0x2000
	s_add_u32 s62, s34, 0x160000
	v_lshl_add_u64 v[214:215], s[34:35], 0, v[148:149]
	s_addc_u32 s63, s35, 0
	s_add_i32 s61, s54, s31
	v_mov_b32_e32 v230, 0x100
	v_lshl_add_u64 v[232:233], v[230:231], 0, v[228:229]
	global_load_lds_dwordx4 v[232:233], off
	v_lshl_add_u64 v[222:223], s[62:63], 0, v[144:145]
	s_mov_b32 m0, s61
	v_lshl_add_u64 v[224:225], s[42:43], 0, v[146:147]
	v_mov_b32_e32 v230, 0x10000
	v_lshl_add_u64 v[232:233], v[230:231], 0, v[228:229]
	global_load_lds_dwordx4 v[232:233], off
	v_lshl_add_u64 v[222:223], s[62:63], 0, v[148:149]
	s_add_i32 m0, s61, 0x2000
	s_nop 0
	v_mov_b32_e32 v230, 0x10100
	v_lshl_add_u64 v[232:233], v[230:231], 0, v[228:229]
	global_load_lds_dwordx4 v[232:233], off
	v_lshl_add_u64 v[222:223], s[42:43], 0, v[142:143]
	s_mov_b32 m0, s33
	s_nop 0
	v_mov_b32_e32 v230, 0x20000
	v_lshl_add_u64 v[232:233], v[230:231], 0, v[228:229]
	global_load_lds_dwordx4 v[232:233], off
	s_mov_b32 m0, s44
	s_nop 0
	v_mov_b32_e32 v230, 0x20100
	v_lshl_add_u64 v[232:233], v[230:231], 0, v[228:229]
	global_load_lds_dwordx4 v[232:233], off
	s_waitcnt vmcnt(8)
	s_waitcnt lgkmcnt(0)
	s_barrier
	s_setprio 1
	s_waitcnt lgkmcnt(0)
	v_mfma_f32_16x16x32_bf16 v[62:65], v[130:133], v[186:189], v[62:65]
	v_mfma_f32_16x16x32_bf16 v[58:61], v[138:141], v[186:189], v[58:61]
	v_mfma_f32_16x16x32_bf16 v[50:53], v[130:133], v[194:197], v[50:53]
	v_mfma_f32_16x16x32_bf16 v[42:45], v[138:141], v[194:197], v[42:45]
	v_mfma_f32_16x16x32_bf16 v[38:41], v[130:133], v[202:205], v[38:41]
	v_mfma_f32_16x16x32_bf16 v[34:37], v[138:141], v[202:205], v[34:37]
	v_mfma_f32_16x16x32_bf16 v[14:17], v[130:133], v[210:213], v[14:17]
	v_mfma_f32_16x16x32_bf16 v[10:13], v[138:141], v[210:213], v[10:13]
	v_mfma_f32_16x16x32_bf16 v[62:65], v[134:137], v[190:193], v[62:65]
	v_mfma_f32_16x16x32_bf16 v[58:61], v[158:161], v[190:193], v[58:61]
	v_mfma_f32_16x16x32_bf16 v[50:53], v[134:137], v[198:201], v[50:53]
	v_mfma_f32_16x16x32_bf16 v[42:45], v[158:161], v[198:201], v[42:45]
	v_mfma_f32_16x16x32_bf16 v[38:41], v[134:137], v[206:209], v[38:41]
	v_mfma_f32_16x16x32_bf16 v[34:37], v[158:161], v[206:209], v[34:37]
	v_mfma_f32_16x16x32_bf16 v[14:17], v[134:137], v[218:221], v[14:17]
	v_mfma_f32_16x16x32_bf16 v[10:13], v[158:161], v[218:221], v[10:13]
	s_setprio 0
	s_setprio 1
	v_mfma_f32_16x16x32_bf16 v[54:57], v[162:165], v[186:189], v[54:57]
	v_mfma_f32_16x16x32_bf16 v[46:49], v[178:181], v[186:189], v[46:49]
	v_mfma_f32_16x16x32_bf16 v[30:33], v[162:165], v[194:197], v[30:33]
	v_mfma_f32_16x16x32_bf16 v[26:29], v[178:181], v[194:197], v[26:29]
	v_mfma_f32_16x16x32_bf16 v[22:25], v[162:165], v[202:205], v[22:25]
	v_mfma_f32_16x16x32_bf16 v[18:21], v[178:181], v[202:205], v[18:21]
	v_mfma_f32_16x16x32_bf16 v[6:9], v[162:165], v[210:213], v[6:9]
	v_mfma_f32_16x16x32_bf16 v[2:5], v[178:181], v[210:213], v[2:5]
	v_mfma_f32_16x16x32_bf16 v[54:57], v[166:169], v[190:193], v[54:57]
	v_mfma_f32_16x16x32_bf16 v[46:49], v[182:185], v[190:193], v[46:49]
	v_mfma_f32_16x16x32_bf16 v[30:33], v[166:169], v[198:201], v[30:33]
	v_mfma_f32_16x16x32_bf16 v[26:29], v[182:185], v[198:201], v[26:29]
	v_mfma_f32_16x16x32_bf16 v[22:25], v[166:169], v[206:209], v[22:25]
	v_mfma_f32_16x16x32_bf16 v[18:21], v[182:185], v[206:209], v[18:21]
	v_mfma_f32_16x16x32_bf16 v[6:9], v[166:169], v[218:221], v[6:9]
	v_mfma_f32_16x16x32_bf16 v[2:5], v[182:185], v[218:221], v[2:5]
	s_setprio 0
	s_barrier
	s_add_i32 s61, 0, 0x18000
	s_add_i32 s62, 0, 0x1c000
	v_add_u32_e32 v158, s61, v172
	v_add_u32_e32 v177, s62, v172
	ds_read_b128 v[130:133], v158
	ds_read_b128 v[134:137], v158 offset:1024
	ds_read_b128 v[138:141], v158 offset:2048
	ds_read_b128 v[158:161], v158 offset:3072
	ds_read_b128 v[162:165], v177
	ds_read_b128 v[166:169], v177 offset:1024
	ds_read_b128 v[178:181], v177 offset:2048
	ds_read_b128 v[182:185], v177 offset:3072
	s_add_u32 s42, s42, 0x160000
	s_addc_u32 s43, s43, 0
	s_mov_b32 m0, s45
	v_lshl_add_u64 v[226:227], s[42:43], 0, v[142:143]
	ds_read_b128 v[186:189], v176 offset:32768
	ds_read_b128 v[190:193], v176 offset:33792
	ds_read_b128 v[194:197], v176 offset:34816
	ds_read_b128 v[198:201], v176 offset:35840
	ds_read_b128 v[202:205], v176 offset:36864
	ds_read_b128 v[206:209], v176 offset:37888
	ds_read_b128 v[210:213], v176 offset:38912
	ds_read_b128 v[218:221], v176 offset:39936
	v_mov_b32_e32 v230, 0x30000
	v_lshl_add_u64 v[232:233], v[230:231], 0, v[228:229]
	global_load_lds_dwordx4 v[232:233], off
	v_lshl_add_u64 v[226:227], s[42:43], 0, v[146:147]
	s_mov_b32 m0, s46
	s_nop 0
	v_mov_b32_e32 v230, 0x30100
	v_lshl_add_u64 v[232:233], v[230:231], 0, v[228:229]
	global_load_lds_dwordx4 v[232:233], off
	s_waitcnt vmcnt(8)
	s_waitcnt lgkmcnt(0)
	s_barrier
	s_setprio 1
	s_waitcnt lgkmcnt(0)
	v_mfma_f32_16x16x32_bf16 v[126:129], v[130:133], v[186:189], v[126:129]
	v_mfma_f32_16x16x32_bf16 v[122:125], v[138:141], v[186:189], v[122:125]
	v_mfma_f32_16x16x32_bf16 v[110:113], v[130:133], v[194:197], v[110:113]
	v_mfma_f32_16x16x32_bf16 v[106:109], v[138:141], v[194:197], v[106:109]
	v_mfma_f32_16x16x32_bf16 v[94:97], v[130:133], v[202:205], v[94:97]
	v_mfma_f32_16x16x32_bf16 v[90:93], v[138:141], v[202:205], v[90:93]
	v_mfma_f32_16x16x32_bf16 v[78:81], v[130:133], v[210:213], v[78:81]
	v_mfma_f32_16x16x32_bf16 v[74:77], v[138:141], v[210:213], v[74:77]
	v_mfma_f32_16x16x32_bf16 v[126:129], v[134:137], v[190:193], v[126:129]
	v_mfma_f32_16x16x32_bf16 v[122:125], v[158:161], v[190:193], v[122:125]
	v_mfma_f32_16x16x32_bf16 v[110:113], v[134:137], v[198:201], v[110:113]
	v_mfma_f32_16x16x32_bf16 v[106:109], v[158:161], v[198:201], v[106:109]
	v_mfma_f32_16x16x32_bf16 v[94:97], v[134:137], v[206:209], v[94:97]
	v_mfma_f32_16x16x32_bf16 v[90:93], v[158:161], v[206:209], v[90:93]
	v_mfma_f32_16x16x32_bf16 v[78:81], v[134:137], v[218:221], v[78:81]
	v_mfma_f32_16x16x32_bf16 v[74:77], v[158:161], v[218:221], v[74:77]
	s_setprio 0
	s_setprio 1
	v_mfma_f32_16x16x32_bf16 v[118:121], v[162:165], v[186:189], v[118:121]
	v_mfma_f32_16x16x32_bf16 v[114:117], v[178:181], v[186:189], v[114:117]
	v_mfma_f32_16x16x32_bf16 v[102:105], v[162:165], v[194:197], v[102:105]
	v_mfma_f32_16x16x32_bf16 v[98:101], v[178:181], v[194:197], v[98:101]
	v_mfma_f32_16x16x32_bf16 v[86:89], v[162:165], v[202:205], v[86:89]
	v_mfma_f32_16x16x32_bf16 v[82:85], v[178:181], v[202:205], v[82:85]
	v_mfma_f32_16x16x32_bf16 v[70:73], v[162:165], v[210:213], v[70:73]
	v_mfma_f32_16x16x32_bf16 v[66:69], v[178:181], v[210:213], v[66:69]
	v_mfma_f32_16x16x32_bf16 v[118:121], v[166:169], v[190:193], v[118:121]
	v_mfma_f32_16x16x32_bf16 v[114:117], v[182:185], v[190:193], v[114:117]
	v_mfma_f32_16x16x32_bf16 v[102:105], v[166:169], v[198:201], v[102:105]
	v_mfma_f32_16x16x32_bf16 v[98:101], v[182:185], v[198:201], v[98:101]
	v_mfma_f32_16x16x32_bf16 v[86:89], v[166:169], v[206:209], v[86:89]
	v_mfma_f32_16x16x32_bf16 v[82:85], v[182:185], v[206:209], v[82:85]
	v_mfma_f32_16x16x32_bf16 v[70:73], v[166:169], v[218:221], v[70:73]
	v_mfma_f32_16x16x32_bf16 v[66:69], v[182:185], v[218:221], v[66:69]
	s_setprio 0
	s_barrier
	s_add_i32 s42, s61, s31
	v_lshl_add_u64 v[170:171], v[170:171], 0, s[24:25]
	s_mov_b32 m0, s42
	ds_read_b128 v[186:189], v176 offset:49152
	ds_read_b128 v[190:193], v176 offset:50176
	ds_read_b128 v[194:197], v176 offset:51200
	ds_read_b128 v[198:201], v176 offset:52224
	ds_read_b128 v[202:205], v176 offset:53248
	ds_read_b128 v[206:209], v176 offset:54272
	ds_read_b128 v[210:213], v176 offset:55296
	ds_read_b128 v[218:221], v176 offset:56320
	v_mov_b32_e32 v230, 0x80000
	v_lshl_add_u64 v[232:233], v[230:231], 0, v[228:229]
	global_load_lds_dwordx4 v[232:233], off
	s_add_i32 m0, s42, 0x2000
	s_add_u32 s34, s34, 0x160080
	v_lshl_add_u64 v[170:171], v[214:215], 0, s[24:25]
	s_addc_u32 s35, s35, 0
	s_add_i32 s42, s62, s31
	v_mov_b32_e32 v230, 0x80100
	v_lshl_add_u64 v[232:233], v[230:231], 0, v[228:229]
	global_load_lds_dwordx4 v[232:233], off
	v_lshl_add_u64 v[170:171], s[34:35], 0, v[144:145]
	s_mov_b32 m0, s42
	s_nop 0
	v_mov_b32_e32 v230, 0x90000
	v_lshl_add_u64 v[232:233], v[230:231], 0, v[228:229]
	global_load_lds_dwordx4 v[232:233], off
	v_lshl_add_u64 v[170:171], s[34:35], 0, v[148:149]
	s_add_i32 m0, s42, 0x2000
	s_nop 0
	v_mov_b32_e32 v230, 0x90100
	v_lshl_add_u64 v[232:233], v[230:231], 0, v[228:229]
	global_load_lds_dwordx4 v[232:233], off
	v_lshl_add_u64 v[170:171], v[222:223], 0, s[24:25]
	s_mov_b32 m0, s48
	s_nop 0
	v_mov_b32_e32 v230, 0xa0000
	v_lshl_add_u64 v[232:233], v[230:231], 0, v[228:229]
	global_load_lds_dwordx4 v[232:233], off
	v_lshl_add_u64 v[170:171], v[224:225], 0, s[24:25]
	s_mov_b32 m0, s49
	s_nop 0
	v_mov_b32_e32 v230, 0xa0100
	v_lshl_add_u64 v[232:233], v[230:231], 0, v[228:229]
	global_load_lds_dwordx4 v[232:233], off
	s_waitcnt vmcnt(8)
	s_waitcnt lgkmcnt(0)
	s_barrier
	s_setprio 1
	s_waitcnt lgkmcnt(0)
	v_mfma_f32_16x16x32_bf16 v[62:65], v[130:133], v[186:189], v[62:65]
	v_mfma_f32_16x16x32_bf16 v[58:61], v[138:141], v[186:189], v[58:61]
	v_mfma_f32_16x16x32_bf16 v[50:53], v[130:133], v[194:197], v[50:53]
	v_mfma_f32_16x16x32_bf16 v[42:45], v[138:141], v[194:197], v[42:45]
	v_mfma_f32_16x16x32_bf16 v[38:41], v[130:133], v[202:205], v[38:41]
	v_mfma_f32_16x16x32_bf16 v[34:37], v[138:141], v[202:205], v[34:37]
	v_mfma_f32_16x16x32_bf16 v[14:17], v[130:133], v[210:213], v[14:17]
	v_mfma_f32_16x16x32_bf16 v[10:13], v[138:141], v[210:213], v[10:13]
	v_mfma_f32_16x16x32_bf16 v[62:65], v[134:137], v[190:193], v[62:65]
	v_mfma_f32_16x16x32_bf16 v[58:61], v[158:161], v[190:193], v[58:61]
	v_mfma_f32_16x16x32_bf16 v[50:53], v[134:137], v[198:201], v[50:53]
	v_mfma_f32_16x16x32_bf16 v[42:45], v[158:161], v[198:201], v[42:45]
	v_mfma_f32_16x16x32_bf16 v[38:41], v[134:137], v[206:209], v[38:41]
	v_mfma_f32_16x16x32_bf16 v[34:37], v[158:161], v[206:209], v[34:37]
	v_mfma_f32_16x16x32_bf16 v[14:17], v[134:137], v[218:221], v[14:17]
	v_mfma_f32_16x16x32_bf16 v[10:13], v[158:161], v[218:221], v[10:13]
	s_setprio 0
	s_setprio 1
	v_mfma_f32_16x16x32_bf16 v[54:57], v[162:165], v[186:189], v[54:57]
	v_mfma_f32_16x16x32_bf16 v[46:49], v[178:181], v[186:189], v[46:49]
	v_mfma_f32_16x16x32_bf16 v[30:33], v[162:165], v[194:197], v[30:33]
	v_mfma_f32_16x16x32_bf16 v[26:29], v[178:181], v[194:197], v[26:29]
	v_mfma_f32_16x16x32_bf16 v[22:25], v[162:165], v[202:205], v[22:25]
	v_mfma_f32_16x16x32_bf16 v[18:21], v[178:181], v[202:205], v[18:21]
	v_mfma_f32_16x16x32_bf16 v[6:9], v[162:165], v[210:213], v[6:9]
	v_mfma_f32_16x16x32_bf16 v[2:5], v[178:181], v[210:213], v[2:5]
	v_mfma_f32_16x16x32_bf16 v[54:57], v[166:169], v[190:193], v[54:57]
	v_mfma_f32_16x16x32_bf16 v[46:49], v[182:185], v[190:193], v[46:49]
	v_mfma_f32_16x16x32_bf16 v[30:33], v[166:169], v[198:201], v[30:33]
	v_mfma_f32_16x16x32_bf16 v[26:29], v[182:185], v[198:201], v[26:29]
	v_mfma_f32_16x16x32_bf16 v[22:25], v[166:169], v[206:209], v[22:25]
	v_mfma_f32_16x16x32_bf16 v[18:21], v[182:185], v[206:209], v[18:21]
	v_mfma_f32_16x16x32_bf16 v[6:9], v[166:169], v[218:221], v[6:9]
	v_mfma_f32_16x16x32_bf16 v[2:5], v[182:185], v[218:221], v[2:5]
	s_setprio 0
	s_barrier
	s_add_i32 s60, s60, 2
	s_add_u32 s40, s40, 0x100
	s_addc_u32 s41, s41, 0
	s_add_u32 s0, s0, 0x100
	s_addc_u32 s1, s1, 0
	s_and_b64 vcc, exec, s[26:27]
	s_cbranch_vccz .LBB0_3183
	s_barrier
.LBB0_3183:
	v_lshl_or_b32 v130, s59, 8, v173
	v_lshl_add_u32 v158, s58, 8, v1
	v_ashrrev_i32_e32 v131, 31, v130
	v_lshlrev_b64 v[160:161], 1, v[130:131]
	v_or_b32_e32 v130, 16, v158
	v_ashrrev_i32_e32 v159, 31, v158
	v_ashrrev_i32_e32 v131, 31, v130
	v_lshlrev_b64 v[132:133], 12, v[158:159]
	v_lshlrev_b64 v[130:131], 12, v[130:131]
	v_lshl_add_u64 v[132:133], s[64:65], 0, v[132:133]
	v_lshl_add_u64 v[130:131], s[64:65], 0, v[130:131]
	v_lshl_add_u64 v[170:171], v[132:133], 0, v[160:161]
	v_lshl_add_u64 v[168:169], v[130:131], 0, v[160:161]
	s_waitcnt vmcnt(0)
	v_mov_b32_e32 v201, 0
	v_mov_b32_e32 v200, 0x10000
	v_lshl_add_u64 v[186:187], v[200:201], 0, v[170:171]
	v_mov_b32_e32 v200, 0x20000
	v_lshl_add_u64 v[188:189], v[200:201], 0, v[170:171]
	v_mov_b32_e32 v200, 0x30000
	v_lshl_add_u64 v[190:191], v[200:201], 0, v[170:171]
	v_mov_b32_e32 v200, 0x80000
	v_lshl_add_u64 v[192:193], v[200:201], 0, v[170:171]
	v_mov_b32_e32 v200, 0x90000
	v_lshl_add_u64 v[194:195], v[200:201], 0, v[170:171]
	v_mov_b32_e32 v200, 0xa0000
	v_lshl_add_u64 v[196:197], v[200:201], 0, v[170:171]
	v_mov_b32_e32 v200, 0xb0000
	v_lshl_add_u64 v[198:199], v[200:201], 0, v[170:171]
	v_lshlrev_b32_e32 v202, 4, v0
	v_add_u32_e32 v203, 0x10000, v202
	global_load_dwordx4 v[162:165], v[198:199], off
	global_load_dwordx4 v[166:169], v[198:199], off offset:256
	ds_read_b128 v[130:133], v203 offset:0
	ds_read_b128 v[134:137], v203 offset:8192
	ds_read_b128 v[138:141], v203 offset:16384
	ds_read_b128 v[158:161], v203 offset:24576
	s_waitcnt lgkmcnt(3)
	v_cvt_f32_f16_e32 v178, v130
	v_cvt_f32_f16_sdwa v179, v130 dst_sel:DWORD dst_unused:UNUSED_PAD src0_sel:WORD_1
	v_cvt_f32_f16_e32 v180, v131
	v_cvt_f32_f16_sdwa v181, v131 dst_sel:DWORD dst_unused:UNUSED_PAD src0_sel:WORD_1
	v_cvt_f32_f16_e32 v182, v132
	v_cvt_f32_f16_sdwa v183, v132 dst_sel:DWORD dst_unused:UNUSED_PAD src0_sel:WORD_1
	v_cvt_f32_f16_e32 v184, v133
	v_cvt_f32_f16_sdwa v185, v133 dst_sel:DWORD dst_unused:UNUSED_PAD src0_sel:WORD_1
	ds_read_b128 v[130:133], v202 offset:0
	v_pk_fma_f32 v[126:127], v[126:127], 0.5, v[178:179] op_sel_hi:[1,0,1]
	v_pk_fma_f32 v[128:129], v[128:129], 0.5, v[180:181] op_sel_hi:[1,0,1]
	v_pk_fma_f32 v[122:123], v[122:123], 0.5, v[182:183] op_sel_hi:[1,0,1]
	v_pk_fma_f32 v[124:125], v[124:125], 0.5, v[184:185] op_sel_hi:[1,0,1]
	v_cvt_pk_f16_f32 v125, v124, v125
	v_cvt_pk_f16_f32 v124, v122, v123
	v_cvt_pk_f16_f32 v123, v128, v129
	v_cvt_pk_f16_f32 v122, v126, v127
	global_store_dwordx4 v[170:171], v[122:125], off
	s_waitcnt lgkmcnt(3)
	v_cvt_f32_f16_e32 v178, v134
	v_cvt_f32_f16_sdwa v179, v134 dst_sel:DWORD dst_unused:UNUSED_PAD src0_sel:WORD_1
	v_cvt_f32_f16_e32 v180, v135
	v_cvt_f32_f16_sdwa v181, v135 dst_sel:DWORD dst_unused:UNUSED_PAD src0_sel:WORD_1
	v_cvt_f32_f16_e32 v182, v136
	v_cvt_f32_f16_sdwa v183, v136 dst_sel:DWORD dst_unused:UNUSED_PAD src0_sel:WORD_1
	v_cvt_f32_f16_e32 v184, v137
	v_cvt_f32_f16_sdwa v185, v137 dst_sel:DWORD dst_unused:UNUSED_PAD src0_sel:WORD_1
	ds_read_b128 v[134:137], v202 offset:8192
	v_pk_fma_f32 v[118:119], v[118:119], 0.5, v[178:179] op_sel_hi:[1,0,1]
	v_pk_fma_f32 v[120:121], v[120:121], 0.5, v[180:181] op_sel_hi:[1,0,1]
	v_pk_fma_f32 v[114:115], v[114:115], 0.5, v[182:183] op_sel_hi:[1,0,1]
	v_pk_fma_f32 v[116:117], v[116:117], 0.5, v[184:185] op_sel_hi:[1,0,1]
	v_cvt_pk_f16_f32 v117, v116, v117
	v_cvt_pk_f16_f32 v116, v114, v115
	v_cvt_pk_f16_f32 v115, v120, v121
	v_cvt_pk_f16_f32 v114, v118, v119
	global_store_dwordx4 v[170:171], v[114:117], off offset:256
	s_waitcnt lgkmcnt(3)
	v_cvt_f32_f16_e32 v178, v138
	v_cvt_f32_f16_sdwa v179, v138 dst_sel:DWORD dst_unused:UNUSED_PAD src0_sel:WORD_1
	v_cvt_f32_f16_e32 v180, v139
	v_cvt_f32_f16_sdwa v181, v139 dst_sel:DWORD dst_unused:UNUSED_PAD src0_sel:WORD_1
	v_cvt_f32_f16_e32 v182, v140
	v_cvt_f32_f16_sdwa v183, v140 dst_sel:DWORD dst_unused:UNUSED_PAD src0_sel:WORD_1
	v_cvt_f32_f16_e32 v184, v141
	v_cvt_f32_f16_sdwa v185, v141 dst_sel:DWORD dst_unused:UNUSED_PAD src0_sel:WORD_1
	ds_read_b128 v[138:141], v202 offset:16384
	v_pk_fma_f32 v[110:111], v[110:111], 0.5, v[178:179] op_sel_hi:[1,0,1]
	v_pk_fma_f32 v[112:113], v[112:113], 0.5, v[180:181] op_sel_hi:[1,0,1]
	v_pk_fma_f32 v[106:107], v[106:107], 0.5, v[182:183] op_sel_hi:[1,0,1]
	v_pk_fma_f32 v[108:109], v[108:109], 0.5, v[184:185] op_sel_hi:[1,0,1]
	v_cvt_pk_f16_f32 v109, v108, v109
	v_cvt_pk_f16_f32 v108, v106, v107
	v_cvt_pk_f16_f32 v107, v112, v113
	v_cvt_pk_f16_f32 v106, v110, v111
	global_store_dwordx4 v[186:187], v[106:109], off
	s_waitcnt lgkmcnt(3)
	v_cvt_f32_f16_e32 v178, v158
	v_cvt_f32_f16_sdwa v179, v158 dst_sel:DWORD dst_unused:UNUSED_PAD src0_sel:WORD_1
	v_cvt_f32_f16_e32 v180, v159
	v_cvt_f32_f16_sdwa v181, v159 dst_sel:DWORD dst_unused:UNUSED_PAD src0_sel:WORD_1
	v_cvt_f32_f16_e32 v182, v160
	v_cvt_f32_f16_sdwa v183, v160 dst_sel:DWORD dst_unused:UNUSED_PAD src0_sel:WORD_1
	v_cvt_f32_f16_e32 v184, v161
	v_cvt_f32_f16_sdwa v185, v161 dst_sel:DWORD dst_unused:UNUSED_PAD src0_sel:WORD_1
	ds_read_b128 v[158:161], v202 offset:24576
	v_pk_fma_f32 v[102:103], v[102:103], 0.5, v[178:179] op_sel_hi:[1,0,1]
	v_pk_fma_f32 v[104:105], v[104:105], 0.5, v[180:181] op_sel_hi:[1,0,1]
	v_pk_fma_f32 v[98:99], v[98:99], 0.5, v[182:183] op_sel_hi:[1,0,1]
	v_pk_fma_f32 v[100:101], v[100:101], 0.5, v[184:185] op_sel_hi:[1,0,1]
	v_cvt_pk_f16_f32 v101, v100, v101
	v_cvt_pk_f16_f32 v100, v98, v99
	v_cvt_pk_f16_f32 v99, v104, v105
	v_cvt_pk_f16_f32 v98, v102, v103
	global_store_dwordx4 v[186:187], v[98:101], off offset:256
	s_waitcnt lgkmcnt(3)
	v_cvt_f32_f16_e32 v178, v130
	v_cvt_f32_f16_sdwa v179, v130 dst_sel:DWORD dst_unused:UNUSED_PAD src0_sel:WORD_1
	v_cvt_f32_f16_e32 v180, v131
	v_cvt_f32_f16_sdwa v181, v131 dst_sel:DWORD dst_unused:UNUSED_PAD src0_sel:WORD_1
	v_cvt_f32_f16_e32 v182, v132
	v_cvt_f32_f16_sdwa v183, v132 dst_sel:DWORD dst_unused:UNUSED_PAD src0_sel:WORD_1
	v_cvt_f32_f16_e32 v184, v133
	v_cvt_f32_f16_sdwa v185, v133 dst_sel:DWORD dst_unused:UNUSED_PAD src0_sel:WORD_1
	ds_read_b128 v[130:133], v203 offset:32768
	v_pk_fma_f32 v[94:95], v[94:95], 0.5, v[178:179] op_sel_hi:[1,0,1]
	v_pk_fma_f32 v[96:97], v[96:97], 0.5, v[180:181] op_sel_hi:[1,0,1]
	v_pk_fma_f32 v[90:91], v[90:91], 0.5, v[182:183] op_sel_hi:[1,0,1]
	v_pk_fma_f32 v[92:93], v[92:93], 0.5, v[184:185] op_sel_hi:[1,0,1]
	v_cvt_pk_f16_f32 v93, v92, v93
	v_cvt_pk_f16_f32 v92, v90, v91
	v_cvt_pk_f16_f32 v91, v96, v97
	v_cvt_pk_f16_f32 v90, v94, v95
	global_store_dwordx4 v[188:189], v[90:93], off
	s_waitcnt lgkmcnt(3)
	v_cvt_f32_f16_e32 v178, v134
	v_cvt_f32_f16_sdwa v179, v134 dst_sel:DWORD dst_unused:UNUSED_PAD src0_sel:WORD_1
	v_cvt_f32_f16_e32 v180, v135
	v_cvt_f32_f16_sdwa v181, v135 dst_sel:DWORD dst_unused:UNUSED_PAD src0_sel:WORD_1
	v_cvt_f32_f16_e32 v182, v136
	v_cvt_f32_f16_sdwa v183, v136 dst_sel:DWORD dst_unused:UNUSED_PAD src0_sel:WORD_1
	v_cvt_f32_f16_e32 v184, v137
	v_cvt_f32_f16_sdwa v185, v137 dst_sel:DWORD dst_unused:UNUSED_PAD src0_sel:WORD_1
	ds_read_b128 v[134:137], v203 offset:40960
	v_pk_fma_f32 v[86:87], v[86:87], 0.5, v[178:179] op_sel_hi:[1,0,1]
	v_pk_fma_f32 v[88:89], v[88:89], 0.5, v[180:181] op_sel_hi:[1,0,1]
	v_pk_fma_f32 v[82:83], v[82:83], 0.5, v[182:183] op_sel_hi:[1,0,1]
	v_pk_fma_f32 v[84:85], v[84:85], 0.5, v[184:185] op_sel_hi:[1,0,1]
	v_cvt_pk_f16_f32 v85, v84, v85
	v_cvt_pk_f16_f32 v84, v82, v83
	v_cvt_pk_f16_f32 v83, v88, v89
	v_cvt_pk_f16_f32 v82, v86, v87
	global_store_dwordx4 v[188:189], v[82:85], off offset:256
	s_waitcnt lgkmcnt(3)
	v_cvt_f32_f16_e32 v178, v138
	v_cvt_f32_f16_sdwa v179, v138 dst_sel:DWORD dst_unused:UNUSED_PAD src0_sel:WORD_1
	v_cvt_f32_f16_e32 v180, v139
	v_cvt_f32_f16_sdwa v181, v139 dst_sel:DWORD dst_unused:UNUSED_PAD src0_sel:WORD_1
	v_cvt_f32_f16_e32 v182, v140
	v_cvt_f32_f16_sdwa v183, v140 dst_sel:DWORD dst_unused:UNUSED_PAD src0_sel:WORD_1
	v_cvt_f32_f16_e32 v184, v141
	v_cvt_f32_f16_sdwa v185, v141 dst_sel:DWORD dst_unused:UNUSED_PAD src0_sel:WORD_1
	ds_read_b128 v[138:141], v203 offset:49152
	v_pk_fma_f32 v[78:79], v[78:79], 0.5, v[178:179] op_sel_hi:[1,0,1]
	v_pk_fma_f32 v[80:81], v[80:81], 0.5, v[180:181] op_sel_hi:[1,0,1]
	v_pk_fma_f32 v[74:75], v[74:75], 0.5, v[182:183] op_sel_hi:[1,0,1]
	v_pk_fma_f32 v[76:77], v[76:77], 0.5, v[184:185] op_sel_hi:[1,0,1]
	v_cvt_pk_f16_f32 v77, v76, v77
	v_cvt_pk_f16_f32 v76, v74, v75
	v_cvt_pk_f16_f32 v75, v80, v81
	v_cvt_pk_f16_f32 v74, v78, v79
	global_store_dwordx4 v[190:191], v[74:77], off
	s_waitcnt lgkmcnt(3)
	v_cvt_f32_f16_e32 v178, v158
	v_cvt_f32_f16_sdwa v179, v158 dst_sel:DWORD dst_unused:UNUSED_PAD src0_sel:WORD_1
	v_cvt_f32_f16_e32 v180, v159
	v_cvt_f32_f16_sdwa v181, v159 dst_sel:DWORD dst_unused:UNUSED_PAD src0_sel:WORD_1
	v_cvt_f32_f16_e32 v182, v160
	v_cvt_f32_f16_sdwa v183, v160 dst_sel:DWORD dst_unused:UNUSED_PAD src0_sel:WORD_1
	v_cvt_f32_f16_e32 v184, v161
	v_cvt_f32_f16_sdwa v185, v161 dst_sel:DWORD dst_unused:UNUSED_PAD src0_sel:WORD_1
	ds_read_b128 v[158:161], v203 offset:57344
	v_pk_fma_f32 v[70:71], v[70:71], 0.5, v[178:179] op_sel_hi:[1,0,1]
	v_pk_fma_f32 v[72:73], v[72:73], 0.5, v[180:181] op_sel_hi:[1,0,1]
	v_pk_fma_f32 v[66:67], v[66:67], 0.5, v[182:183] op_sel_hi:[1,0,1]
	v_pk_fma_f32 v[68:69], v[68:69], 0.5, v[184:185] op_sel_hi:[1,0,1]
	v_cvt_pk_f16_f32 v69, v68, v69
	v_cvt_pk_f16_f32 v68, v66, v67
	v_cvt_pk_f16_f32 v67, v72, v73
	v_cvt_pk_f16_f32 v66, v70, v71
	global_store_dwordx4 v[190:191], v[66:69], off offset:256
	s_waitcnt lgkmcnt(3)
	v_cvt_f32_f16_e32 v178, v130
	v_cvt_f32_f16_sdwa v179, v130 dst_sel:DWORD dst_unused:UNUSED_PAD src0_sel:WORD_1
	v_cvt_f32_f16_e32 v180, v131
	v_cvt_f32_f16_sdwa v181, v131 dst_sel:DWORD dst_unused:UNUSED_PAD src0_sel:WORD_1
	v_cvt_f32_f16_e32 v182, v132
	v_cvt_f32_f16_sdwa v183, v132 dst_sel:DWORD dst_unused:UNUSED_PAD src0_sel:WORD_1
	v_cvt_f32_f16_e32 v184, v133
	v_cvt_f32_f16_sdwa v185, v133 dst_sel:DWORD dst_unused:UNUSED_PAD src0_sel:WORD_1
	ds_read_b128 v[130:133], v202 offset:32768
	v_pk_fma_f32 v[62:63], v[62:63], 0.5, v[178:179] op_sel_hi:[1,0,1]
	v_pk_fma_f32 v[64:65], v[64:65], 0.5, v[180:181] op_sel_hi:[1,0,1]
	v_pk_fma_f32 v[58:59], v[58:59], 0.5, v[182:183] op_sel_hi:[1,0,1]
	v_pk_fma_f32 v[60:61], v[60:61], 0.5, v[184:185] op_sel_hi:[1,0,1]
	v_cvt_pk_f16_f32 v61, v60, v61
	v_cvt_pk_f16_f32 v60, v58, v59
	v_cvt_pk_f16_f32 v59, v64, v65
	v_cvt_pk_f16_f32 v58, v62, v63
	global_store_dwordx4 v[192:193], v[58:61], off
	s_waitcnt lgkmcnt(3)
	v_cvt_f32_f16_e32 v178, v134
	v_cvt_f32_f16_sdwa v179, v134 dst_sel:DWORD dst_unused:UNUSED_PAD src0_sel:WORD_1
	v_cvt_f32_f16_e32 v180, v135
	v_cvt_f32_f16_sdwa v181, v135 dst_sel:DWORD dst_unused:UNUSED_PAD src0_sel:WORD_1
	v_cvt_f32_f16_e32 v182, v136
	v_cvt_f32_f16_sdwa v183, v136 dst_sel:DWORD dst_unused:UNUSED_PAD src0_sel:WORD_1
	v_cvt_f32_f16_e32 v184, v137
	v_cvt_f32_f16_sdwa v185, v137 dst_sel:DWORD dst_unused:UNUSED_PAD src0_sel:WORD_1
	ds_read_b128 v[134:137], v202 offset:40960
	v_pk_fma_f32 v[54:55], v[54:55], 0.5, v[178:179] op_sel_hi:[1,0,1]
	v_pk_fma_f32 v[56:57], v[56:57], 0.5, v[180:181] op_sel_hi:[1,0,1]
	v_pk_fma_f32 v[46:47], v[46:47], 0.5, v[182:183] op_sel_hi:[1,0,1]
	v_pk_fma_f32 v[48:49], v[48:49], 0.5, v[184:185] op_sel_hi:[1,0,1]
	v_cvt_pk_f16_f32 v49, v48, v49
	v_cvt_pk_f16_f32 v48, v46, v47
	v_cvt_pk_f16_f32 v47, v56, v57
	v_cvt_pk_f16_f32 v46, v54, v55
	global_store_dwordx4 v[192:193], v[46:49], off offset:256
	s_waitcnt lgkmcnt(3)
	v_cvt_f32_f16_e32 v178, v138
	v_cvt_f32_f16_sdwa v179, v138 dst_sel:DWORD dst_unused:UNUSED_PAD src0_sel:WORD_1
	v_cvt_f32_f16_e32 v180, v139
	v_cvt_f32_f16_sdwa v181, v139 dst_sel:DWORD dst_unused:UNUSED_PAD src0_sel:WORD_1
	v_cvt_f32_f16_e32 v182, v140
	v_cvt_f32_f16_sdwa v183, v140 dst_sel:DWORD dst_unused:UNUSED_PAD src0_sel:WORD_1
	v_cvt_f32_f16_e32 v184, v141
	v_cvt_f32_f16_sdwa v185, v141 dst_sel:DWORD dst_unused:UNUSED_PAD src0_sel:WORD_1
	v_pk_fma_f32 v[50:51], v[50:51], 0.5, v[178:179] op_sel_hi:[1,0,1]
	v_pk_fma_f32 v[52:53], v[52:53], 0.5, v[180:181] op_sel_hi:[1,0,1]
	v_pk_fma_f32 v[42:43], v[42:43], 0.5, v[182:183] op_sel_hi:[1,0,1]
	v_pk_fma_f32 v[44:45], v[44:45], 0.5, v[184:185] op_sel_hi:[1,0,1]
	v_cvt_pk_f16_f32 v45, v44, v45
	v_cvt_pk_f16_f32 v44, v42, v43
	v_cvt_pk_f16_f32 v43, v52, v53
	v_cvt_pk_f16_f32 v42, v50, v51
	global_store_dwordx4 v[194:195], v[42:45], off
	s_waitcnt lgkmcnt(2)
	v_cvt_f32_f16_e32 v178, v158
	v_cvt_f32_f16_sdwa v179, v158 dst_sel:DWORD dst_unused:UNUSED_PAD src0_sel:WORD_1
	v_cvt_f32_f16_e32 v180, v159
	v_cvt_f32_f16_sdwa v181, v159 dst_sel:DWORD dst_unused:UNUSED_PAD src0_sel:WORD_1
	v_cvt_f32_f16_e32 v182, v160
	v_cvt_f32_f16_sdwa v183, v160 dst_sel:DWORD dst_unused:UNUSED_PAD src0_sel:WORD_1
	v_cvt_f32_f16_e32 v184, v161
	v_cvt_f32_f16_sdwa v185, v161 dst_sel:DWORD dst_unused:UNUSED_PAD src0_sel:WORD_1
	v_pk_fma_f32 v[30:31], v[30:31], 0.5, v[178:179] op_sel_hi:[1,0,1]
	v_pk_fma_f32 v[32:33], v[32:33], 0.5, v[180:181] op_sel_hi:[1,0,1]
	v_pk_fma_f32 v[26:27], v[26:27], 0.5, v[182:183] op_sel_hi:[1,0,1]
	v_pk_fma_f32 v[28:29], v[28:29], 0.5, v[184:185] op_sel_hi:[1,0,1]
	v_cvt_pk_f16_f32 v29, v28, v29
	v_cvt_pk_f16_f32 v28, v26, v27
	v_cvt_pk_f16_f32 v27, v32, v33
	v_cvt_pk_f16_f32 v26, v30, v31
	global_store_dwordx4 v[194:195], v[26:29], off offset:256
	s_waitcnt lgkmcnt(1)
	v_cvt_f32_f16_e32 v178, v130
	v_cvt_f32_f16_sdwa v179, v130 dst_sel:DWORD dst_unused:UNUSED_PAD src0_sel:WORD_1
	v_cvt_f32_f16_e32 v180, v131
	v_cvt_f32_f16_sdwa v181, v131 dst_sel:DWORD dst_unused:UNUSED_PAD src0_sel:WORD_1
	v_cvt_f32_f16_e32 v182, v132
	v_cvt_f32_f16_sdwa v183, v132 dst_sel:DWORD dst_unused:UNUSED_PAD src0_sel:WORD_1
	v_cvt_f32_f16_e32 v184, v133
	v_cvt_f32_f16_sdwa v185, v133 dst_sel:DWORD dst_unused:UNUSED_PAD src0_sel:WORD_1
	v_pk_fma_f32 v[38:39], v[38:39], 0.5, v[178:179] op_sel_hi:[1,0,1]
	v_pk_fma_f32 v[40:41], v[40:41], 0.5, v[180:181] op_sel_hi:[1,0,1]
	v_pk_fma_f32 v[34:35], v[34:35], 0.5, v[182:183] op_sel_hi:[1,0,1]
	v_pk_fma_f32 v[36:37], v[36:37], 0.5, v[184:185] op_sel_hi:[1,0,1]
	v_cvt_pk_f16_f32 v37, v36, v37
	v_cvt_pk_f16_f32 v36, v34, v35
	v_cvt_pk_f16_f32 v35, v40, v41
	v_cvt_pk_f16_f32 v34, v38, v39
	global_store_dwordx4 v[196:197], v[34:37], off
	s_waitcnt lgkmcnt(0)
	v_cvt_f32_f16_e32 v178, v134
	v_cvt_f32_f16_sdwa v179, v134 dst_sel:DWORD dst_unused:UNUSED_PAD src0_sel:WORD_1
	v_cvt_f32_f16_e32 v180, v135
	v_cvt_f32_f16_sdwa v181, v135 dst_sel:DWORD dst_unused:UNUSED_PAD src0_sel:WORD_1
	v_cvt_f32_f16_e32 v182, v136
	v_cvt_f32_f16_sdwa v183, v136 dst_sel:DWORD dst_unused:UNUSED_PAD src0_sel:WORD_1
	v_cvt_f32_f16_e32 v184, v137
	v_cvt_f32_f16_sdwa v185, v137 dst_sel:DWORD dst_unused:UNUSED_PAD src0_sel:WORD_1
	v_pk_fma_f32 v[22:23], v[22:23], 0.5, v[178:179] op_sel_hi:[1,0,1]
	v_pk_fma_f32 v[24:25], v[24:25], 0.5, v[180:181] op_sel_hi:[1,0,1]
	v_pk_fma_f32 v[18:19], v[18:19], 0.5, v[182:183] op_sel_hi:[1,0,1]
	v_pk_fma_f32 v[20:21], v[20:21], 0.5, v[184:185] op_sel_hi:[1,0,1]
	v_cvt_pk_f16_f32 v21, v20, v21
	v_cvt_pk_f16_f32 v20, v18, v19
	v_cvt_pk_f16_f32 v19, v24, v25
	v_cvt_pk_f16_f32 v18, v22, v23
	global_store_dwordx4 v[196:197], v[18:21], off offset:256
	s_waitcnt vmcnt(15)
	v_cvt_f32_f16_e32 v178, v162
	v_cvt_f32_f16_sdwa v179, v162 dst_sel:DWORD dst_unused:UNUSED_PAD src0_sel:WORD_1
	v_cvt_f32_f16_e32 v180, v163
	v_cvt_f32_f16_sdwa v181, v163 dst_sel:DWORD dst_unused:UNUSED_PAD src0_sel:WORD_1
	v_cvt_f32_f16_e32 v182, v164
	v_cvt_f32_f16_sdwa v183, v164 dst_sel:DWORD dst_unused:UNUSED_PAD src0_sel:WORD_1
	v_cvt_f32_f16_e32 v184, v165
	v_cvt_f32_f16_sdwa v185, v165 dst_sel:DWORD dst_unused:UNUSED_PAD src0_sel:WORD_1
	v_pk_fma_f32 v[14:15], v[14:15], 0.5, v[178:179] op_sel_hi:[1,0,1]
	v_pk_fma_f32 v[16:17], v[16:17], 0.5, v[180:181] op_sel_hi:[1,0,1]
	v_pk_fma_f32 v[10:11], v[10:11], 0.5, v[182:183] op_sel_hi:[1,0,1]
	v_pk_fma_f32 v[12:13], v[12:13], 0.5, v[184:185] op_sel_hi:[1,0,1]
	v_cvt_pk_f16_f32 v13, v12, v13
	v_cvt_pk_f16_f32 v12, v10, v11
	v_cvt_pk_f16_f32 v11, v16, v17
	v_cvt_pk_f16_f32 v10, v14, v15
	global_store_dwordx4 v[198:199], v[10:13], off
	s_waitcnt vmcnt(15)
	v_cvt_f32_f16_e32 v178, v166
	v_cvt_f32_f16_sdwa v179, v166 dst_sel:DWORD dst_unused:UNUSED_PAD src0_sel:WORD_1
	v_cvt_f32_f16_e32 v180, v167
	v_cvt_f32_f16_sdwa v181, v167 dst_sel:DWORD dst_unused:UNUSED_PAD src0_sel:WORD_1
	v_cvt_f32_f16_e32 v182, v168
	v_cvt_f32_f16_sdwa v183, v168 dst_sel:DWORD dst_unused:UNUSED_PAD src0_sel:WORD_1
	v_cvt_f32_f16_e32 v184, v169
	v_cvt_f32_f16_sdwa v185, v169 dst_sel:DWORD dst_unused:UNUSED_PAD src0_sel:WORD_1
	v_pk_fma_f32 v[6:7], v[6:7], 0.5, v[178:179] op_sel_hi:[1,0,1]
	v_pk_fma_f32 v[8:9], v[8:9], 0.5, v[180:181] op_sel_hi:[1,0,1]
	v_pk_fma_f32 v[2:3], v[2:3], 0.5, v[182:183] op_sel_hi:[1,0,1]
	v_pk_fma_f32 v[4:5], v[4:5], 0.5, v[184:185] op_sel_hi:[1,0,1]
	v_cvt_pk_f16_f32 v5, v4, v5
	v_cvt_pk_f16_f32 v4, v2, v3
	v_cvt_pk_f16_f32 v3, v8, v9
	v_cvt_pk_f16_f32 v2, v6, v7
	global_store_dwordx4 v[198:199], v[2:5], off offset:256
	s_mov_b64 s[0:1], -1
	s_and_b64 vcc, exec, s[2:3]
	s_cbranch_vccnz .LBB0_3168
	s_andn2_b64 vcc, exec, s[8:9]
	s_cbranch_vccnz .LBB0_3167
	s_barrier
	s_branch .LBB0_3167

.LBB0_3706:
	ds_read_b128 v[130:133], v174
	ds_read_b128 v[134:137], v174 offset:1024
	ds_read_b128 v[138:141], v174 offset:2048
	ds_read_b128 v[158:161], v174 offset:3072
	ds_read_b128 v[162:165], v175
	ds_read_b128 v[166:169], v175 offset:1024
	ds_read_b128 v[178:181], v175 offset:2048
	ds_read_b128 v[182:185], v175 offset:3072
	s_add_u32 s34, s42, 0xfff80080
	s_addc_u32 s35, s43, -1
	s_cmp_eq_u32 s60, 28
	s_cselect_b32 s45, s0, s35
	s_cselect_b32 s44, s1, s34
	s_cselect_b32 s35, s25, s59
	s_cselect_b32 s34, s27, s58
	v_lshl_add_u64 v[170:171], s[42:43], 0, v[150:151]
	s_add_i32 m0, s41, 0xc000
	ds_read_b128 v[186:189], v176
	ds_read_b128 v[190:193], v176 offset:1024
	ds_read_b128 v[194:197], v176 offset:2048
	ds_read_b128 v[198:201], v176 offset:3072
	ds_read_b128 v[202:205], v176 offset:4096
	ds_read_b128 v[206:209], v176 offset:5120
	ds_read_b128 v[210:213], v176 offset:6144
	ds_read_b128 v[218:221], v176 offset:7168
	global_load_lds_dwordx4 v[170:171], off
	v_lshl_add_u64 v[170:171], s[42:43], 0, v[152:153]
	s_add_i32 m0, s41, 0xe000
	s_nop 0
	global_load_lds_dwordx4 v[170:171], off
	s_waitcnt vmcnt(8)
	s_waitcnt lgkmcnt(0)
	s_barrier
	s_setprio 1
	s_waitcnt lgkmcnt(0)
	v_mfma_f32_16x16x32_bf16 v[126:129], v[130:133], v[186:189], v[126:129]
	v_mfma_f32_16x16x32_bf16 v[122:125], v[138:141], v[186:189], v[122:125]
	v_mfma_f32_16x16x32_bf16 v[110:113], v[130:133], v[194:197], v[110:113]
	v_mfma_f32_16x16x32_bf16 v[106:109], v[138:141], v[194:197], v[106:109]
	v_mfma_f32_16x16x32_bf16 v[94:97], v[130:133], v[202:205], v[94:97]
	v_mfma_f32_16x16x32_bf16 v[90:93], v[138:141], v[202:205], v[90:93]
	v_mfma_f32_16x16x32_bf16 v[78:81], v[130:133], v[210:213], v[78:81]
	v_mfma_f32_16x16x32_bf16 v[74:77], v[138:141], v[210:213], v[74:77]
	v_mfma_f32_16x16x32_bf16 v[126:129], v[134:137], v[190:193], v[126:129]
	v_mfma_f32_16x16x32_bf16 v[122:125], v[158:161], v[190:193], v[122:125]
	v_mfma_f32_16x16x32_bf16 v[110:113], v[134:137], v[198:201], v[110:113]
	v_mfma_f32_16x16x32_bf16 v[106:109], v[158:161], v[198:201], v[106:109]
	v_mfma_f32_16x16x32_bf16 v[94:97], v[134:137], v[206:209], v[94:97]
	v_mfma_f32_16x16x32_bf16 v[90:93], v[158:161], v[206:209], v[90:93]
	v_mfma_f32_16x16x32_bf16 v[78:81], v[134:137], v[218:221], v[78:81]
	v_mfma_f32_16x16x32_bf16 v[74:77], v[158:161], v[218:221], v[74:77]
	s_setprio 0
	s_setprio 1
	v_mfma_f32_16x16x32_bf16 v[118:121], v[162:165], v[186:189], v[118:121]
	v_mfma_f32_16x16x32_bf16 v[114:117], v[178:181], v[186:189], v[114:117]
	v_mfma_f32_16x16x32_bf16 v[102:105], v[162:165], v[194:197], v[102:105]
	v_mfma_f32_16x16x32_bf16 v[98:101], v[178:181], v[194:197], v[98:101]
	v_mfma_f32_16x16x32_bf16 v[86:89], v[162:165], v[202:205], v[86:89]
	v_mfma_f32_16x16x32_bf16 v[82:85], v[178:181], v[202:205], v[82:85]
	v_mfma_f32_16x16x32_bf16 v[70:73], v[162:165], v[210:213], v[70:73]
	v_mfma_f32_16x16x32_bf16 v[66:69], v[178:181], v[210:213], v[66:69]
	v_mfma_f32_16x16x32_bf16 v[118:121], v[166:169], v[190:193], v[118:121]
	v_mfma_f32_16x16x32_bf16 v[114:117], v[182:185], v[190:193], v[114:117]
	v_mfma_f32_16x16x32_bf16 v[102:105], v[166:169], v[198:201], v[102:105]
	v_mfma_f32_16x16x32_bf16 v[98:101], v[182:185], v[198:201], v[98:101]
	v_mfma_f32_16x16x32_bf16 v[86:89], v[166:169], v[206:209], v[86:89]
	v_mfma_f32_16x16x32_bf16 v[82:85], v[182:185], v[206:209], v[82:85]
	v_mfma_f32_16x16x32_bf16 v[70:73], v[166:169], v[218:221], v[70:73]
	v_mfma_f32_16x16x32_bf16 v[66:69], v[182:185], v[218:221], v[66:69]
	s_setprio 0
	s_barrier
	s_add_i32 s61, s54, s46
	v_lshl_add_u64 v[170:171], s[34:35], 0, v[144:145]
	s_mov_b32 m0, s61
	ds_read_b128 v[186:189], v176 offset:16384
	ds_read_b128 v[190:193], v176 offset:17408
	ds_read_b128 v[194:197], v176 offset:18432
	ds_read_b128 v[198:201], v176 offset:19456
	ds_read_b128 v[202:205], v176 offset:20480
	ds_read_b128 v[206:209], v176 offset:21504
	ds_read_b128 v[210:213], v176 offset:22528
	ds_read_b128 v[218:221], v176 offset:23552
	global_load_lds_dwordx4 v[170:171], off
	s_add_i32 m0, s61, 0x2000
	s_add_u32 s62, s34, 0x80000
	v_lshl_add_u64 v[214:215], s[34:35], 0, v[148:149]
	s_addc_u32 s63, s35, 0
	s_add_i32 s61, s55, s46
	global_load_lds_dwordx4 v[214:215], off
	v_lshl_add_u64 v[222:223], s[62:63], 0, v[144:145]
	s_mov_b32 m0, s61
	v_lshl_add_u64 v[224:225], s[44:45], 0, v[146:147]
	global_load_lds_dwordx4 v[222:223], off
	v_lshl_add_u64 v[222:223], s[62:63], 0, v[148:149]
	s_add_i32 m0, s61, 0x2000
	s_nop 0
	global_load_lds_dwordx4 v[222:223], off
	v_lshl_add_u64 v[222:223], s[44:45], 0, v[142:143]
	s_mov_b32 m0, s41
	s_nop 0
	global_load_lds_dwordx4 v[222:223], off
	s_mov_b32 m0, s47
	s_nop 0
	global_load_lds_dwordx4 v[224:225], off
	s_waitcnt vmcnt(8)
	s_waitcnt lgkmcnt(0)
	s_barrier
	s_setprio 1
	s_waitcnt lgkmcnt(0)
	v_mfma_f32_16x16x32_bf16 v[62:65], v[130:133], v[186:189], v[62:65]
	v_mfma_f32_16x16x32_bf16 v[58:61], v[138:141], v[186:189], v[58:61]
	v_mfma_f32_16x16x32_bf16 v[50:53], v[130:133], v[194:197], v[50:53]
	v_mfma_f32_16x16x32_bf16 v[42:45], v[138:141], v[194:197], v[42:45]
	v_mfma_f32_16x16x32_bf16 v[38:41], v[130:133], v[202:205], v[38:41]
	v_mfma_f32_16x16x32_bf16 v[34:37], v[138:141], v[202:205], v[34:37]
	v_mfma_f32_16x16x32_bf16 v[14:17], v[130:133], v[210:213], v[14:17]
	v_mfma_f32_16x16x32_bf16 v[10:13], v[138:141], v[210:213], v[10:13]
	v_mfma_f32_16x16x32_bf16 v[62:65], v[134:137], v[190:193], v[62:65]
	v_mfma_f32_16x16x32_bf16 v[58:61], v[158:161], v[190:193], v[58:61]
	v_mfma_f32_16x16x32_bf16 v[50:53], v[134:137], v[198:201], v[50:53]
	v_mfma_f32_16x16x32_bf16 v[42:45], v[158:161], v[198:201], v[42:45]
	v_mfma_f32_16x16x32_bf16 v[38:41], v[134:137], v[206:209], v[38:41]
	v_mfma_f32_16x16x32_bf16 v[34:37], v[158:161], v[206:209], v[34:37]
	v_mfma_f32_16x16x32_bf16 v[14:17], v[134:137], v[218:221], v[14:17]
	v_mfma_f32_16x16x32_bf16 v[10:13], v[158:161], v[218:221], v[10:13]
	s_setprio 0
	s_setprio 1
	v_mfma_f32_16x16x32_bf16 v[54:57], v[162:165], v[186:189], v[54:57]
	v_mfma_f32_16x16x32_bf16 v[46:49], v[178:181], v[186:189], v[46:49]
	v_mfma_f32_16x16x32_bf16 v[30:33], v[162:165], v[194:197], v[30:33]
	v_mfma_f32_16x16x32_bf16 v[26:29], v[178:181], v[194:197], v[26:29]
	v_mfma_f32_16x16x32_bf16 v[22:25], v[162:165], v[202:205], v[22:25]
	v_mfma_f32_16x16x32_bf16 v[18:21], v[178:181], v[202:205], v[18:21]
	v_mfma_f32_16x16x32_bf16 v[6:9], v[162:165], v[210:213], v[6:9]
	v_mfma_f32_16x16x32_bf16 v[2:5], v[178:181], v[210:213], v[2:5]
	v_mfma_f32_16x16x32_bf16 v[54:57], v[166:169], v[190:193], v[54:57]
	v_mfma_f32_16x16x32_bf16 v[46:49], v[182:185], v[190:193], v[46:49]
	v_mfma_f32_16x16x32_bf16 v[30:33], v[166:169], v[198:201], v[30:33]
	v_mfma_f32_16x16x32_bf16 v[26:29], v[182:185], v[198:201], v[26:29]
	v_mfma_f32_16x16x32_bf16 v[22:25], v[166:169], v[206:209], v[22:25]
	v_mfma_f32_16x16x32_bf16 v[18:21], v[182:185], v[206:209], v[18:21]
	v_mfma_f32_16x16x32_bf16 v[6:9], v[166:169], v[218:221], v[6:9]
	v_mfma_f32_16x16x32_bf16 v[2:5], v[182:185], v[218:221], v[2:5]
	s_setprio 0
	s_barrier
	s_add_i32 s61, 0, 0x18000
	s_add_i32 s62, 0, 0x1c000
	v_add_u32_e32 v158, s61, v172
	v_add_u32_e32 v177, s62, v172
	ds_read_b128 v[130:133], v158
	ds_read_b128 v[134:137], v158 offset:1024
	ds_read_b128 v[138:141], v158 offset:2048
	ds_read_b128 v[158:161], v158 offset:3072
	ds_read_b128 v[162:165], v177
	ds_read_b128 v[166:169], v177 offset:1024
	ds_read_b128 v[178:181], v177 offset:2048
	ds_read_b128 v[182:185], v177 offset:3072
	s_add_u32 s44, s44, 0x80000
	s_addc_u32 s45, s45, 0
	s_mov_b32 m0, s48
	v_lshl_add_u64 v[226:227], s[44:45], 0, v[142:143]
	ds_read_b128 v[186:189], v176 offset:32768
	ds_read_b128 v[190:193], v176 offset:33792
	ds_read_b128 v[194:197], v176 offset:34816
	ds_read_b128 v[198:201], v176 offset:35840
	ds_read_b128 v[202:205], v176 offset:36864
	ds_read_b128 v[206:209], v176 offset:37888
	ds_read_b128 v[210:213], v176 offset:38912
	ds_read_b128 v[218:221], v176 offset:39936
	global_load_lds_dwordx4 v[226:227], off
	v_lshl_add_u64 v[226:227], s[44:45], 0, v[146:147]
	s_mov_b32 m0, s49
	s_nop 0
	global_load_lds_dwordx4 v[226:227], off
	s_waitcnt vmcnt(8)
	s_waitcnt lgkmcnt(0)
	s_barrier
	s_setprio 1
	s_waitcnt lgkmcnt(0)
	v_mfma_f32_16x16x32_bf16 v[126:129], v[130:133], v[186:189], v[126:129]
	v_mfma_f32_16x16x32_bf16 v[122:125], v[138:141], v[186:189], v[122:125]
	v_mfma_f32_16x16x32_bf16 v[110:113], v[130:133], v[194:197], v[110:113]
	v_mfma_f32_16x16x32_bf16 v[106:109], v[138:141], v[194:197], v[106:109]
	v_mfma_f32_16x16x32_bf16 v[94:97], v[130:133], v[202:205], v[94:97]
	v_mfma_f32_16x16x32_bf16 v[90:93], v[138:141], v[202:205], v[90:93]
	v_mfma_f32_16x16x32_bf16 v[78:81], v[130:133], v[210:213], v[78:81]
	v_mfma_f32_16x16x32_bf16 v[74:77], v[138:141], v[210:213], v[74:77]
	v_mfma_f32_16x16x32_bf16 v[126:129], v[134:137], v[190:193], v[126:129]
	v_mfma_f32_16x16x32_bf16 v[122:125], v[158:161], v[190:193], v[122:125]
	v_mfma_f32_16x16x32_bf16 v[110:113], v[134:137], v[198:201], v[110:113]
	v_mfma_f32_16x16x32_bf16 v[106:109], v[158:161], v[198:201], v[106:109]
	v_mfma_f32_16x16x32_bf16 v[94:97], v[134:137], v[206:209], v[94:97]
	v_mfma_f32_16x16x32_bf16 v[90:93], v[158:161], v[206:209], v[90:93]
	v_mfma_f32_16x16x32_bf16 v[78:81], v[134:137], v[218:221], v[78:81]
	v_mfma_f32_16x16x32_bf16 v[74:77], v[158:161], v[218:221], v[74:77]
	s_setprio 0
	s_setprio 1
	v_mfma_f32_16x16x32_bf16 v[118:121], v[162:165], v[186:189], v[118:121]
	v_mfma_f32_16x16x32_bf16 v[114:117], v[178:181], v[186:189], v[114:117]
	v_mfma_f32_16x16x32_bf16 v[102:105], v[162:165], v[194:197], v[102:105]
	v_mfma_f32_16x16x32_bf16 v[98:101], v[178:181], v[194:197], v[98:101]
	v_mfma_f32_16x16x32_bf16 v[86:89], v[162:165], v[202:205], v[86:89]
	v_mfma_f32_16x16x32_bf16 v[82:85], v[178:181], v[202:205], v[82:85]
	v_mfma_f32_16x16x32_bf16 v[70:73], v[162:165], v[210:213], v[70:73]
	v_mfma_f32_16x16x32_bf16 v[66:69], v[178:181], v[210:213], v[66:69]
	v_mfma_f32_16x16x32_bf16 v[118:121], v[166:169], v[190:193], v[118:121]
	v_mfma_f32_16x16x32_bf16 v[114:117], v[182:185], v[190:193], v[114:117]
	v_mfma_f32_16x16x32_bf16 v[102:105], v[166:169], v[198:201], v[102:105]
	v_mfma_f32_16x16x32_bf16 v[98:101], v[182:185], v[198:201], v[98:101]
	v_mfma_f32_16x16x32_bf16 v[86:89], v[166:169], v[206:209], v[86:89]
	v_mfma_f32_16x16x32_bf16 v[82:85], v[182:185], v[206:209], v[82:85]
	v_mfma_f32_16x16x32_bf16 v[70:73], v[166:169], v[218:221], v[70:73]
	v_mfma_f32_16x16x32_bf16 v[66:69], v[182:185], v[218:221], v[66:69]
	s_setprio 0
	s_barrier
	s_add_i32 s44, s61, s46
	v_lshl_add_u64 v[170:171], v[170:171], 0, s[12:13]
	s_mov_b32 m0, s44
	ds_read_b128 v[186:189], v176 offset:49152
	ds_read_b128 v[190:193], v176 offset:50176
	ds_read_b128 v[194:197], v176 offset:51200
	ds_read_b128 v[198:201], v176 offset:52224
	ds_read_b128 v[202:205], v176 offset:53248
	ds_read_b128 v[206:209], v176 offset:54272
	ds_read_b128 v[210:213], v176 offset:55296
	ds_read_b128 v[218:221], v176 offset:56320
	global_load_lds_dwordx4 v[170:171], off
	s_add_i32 m0, s44, 0x2000
	s_add_u32 s34, s34, 0x80080
	v_lshl_add_u64 v[170:171], v[214:215], 0, s[12:13]
	s_addc_u32 s35, s35, 0
	s_add_i32 s44, s62, s46
	global_load_lds_dwordx4 v[170:171], off
	v_lshl_add_u64 v[170:171], s[34:35], 0, v[144:145]
	s_mov_b32 m0, s44
	s_nop 0
	global_load_lds_dwordx4 v[170:171], off
	v_lshl_add_u64 v[170:171], s[34:35], 0, v[148:149]
	s_add_i32 m0, s44, 0x2000
	s_nop 0
	global_load_lds_dwordx4 v[170:171], off
	v_lshl_add_u64 v[170:171], v[222:223], 0, s[12:13]
	s_mov_b32 m0, s51
	s_nop 0
	global_load_lds_dwordx4 v[170:171], off
	v_lshl_add_u64 v[170:171], v[224:225], 0, s[12:13]
	s_mov_b32 m0, s52
	s_nop 0
	global_load_lds_dwordx4 v[170:171], off
	s_waitcnt vmcnt(8)
	s_waitcnt lgkmcnt(0)
	s_barrier
	s_setprio 1
	s_waitcnt lgkmcnt(0)
	v_mfma_f32_16x16x32_bf16 v[62:65], v[130:133], v[186:189], v[62:65]
	v_mfma_f32_16x16x32_bf16 v[58:61], v[138:141], v[186:189], v[58:61]
	v_mfma_f32_16x16x32_bf16 v[50:53], v[130:133], v[194:197], v[50:53]
	v_mfma_f32_16x16x32_bf16 v[42:45], v[138:141], v[194:197], v[42:45]
	v_mfma_f32_16x16x32_bf16 v[38:41], v[130:133], v[202:205], v[38:41]
	v_mfma_f32_16x16x32_bf16 v[34:37], v[138:141], v[202:205], v[34:37]
	v_mfma_f32_16x16x32_bf16 v[14:17], v[130:133], v[210:213], v[14:17]
	v_mfma_f32_16x16x32_bf16 v[10:13], v[138:141], v[210:213], v[10:13]
	v_mfma_f32_16x16x32_bf16 v[62:65], v[134:137], v[190:193], v[62:65]
	v_mfma_f32_16x16x32_bf16 v[58:61], v[158:161], v[190:193], v[58:61]
	v_mfma_f32_16x16x32_bf16 v[50:53], v[134:137], v[198:201], v[50:53]
	v_mfma_f32_16x16x32_bf16 v[42:45], v[158:161], v[198:201], v[42:45]
	v_mfma_f32_16x16x32_bf16 v[38:41], v[134:137], v[206:209], v[38:41]
	v_mfma_f32_16x16x32_bf16 v[34:37], v[158:161], v[206:209], v[34:37]
	v_mfma_f32_16x16x32_bf16 v[14:17], v[134:137], v[218:221], v[14:17]
	v_mfma_f32_16x16x32_bf16 v[10:13], v[158:161], v[218:221], v[10:13]
	s_setprio 0
	s_setprio 1
	v_mfma_f32_16x16x32_bf16 v[54:57], v[162:165], v[186:189], v[54:57]
	v_mfma_f32_16x16x32_bf16 v[46:49], v[178:181], v[186:189], v[46:49]
	v_mfma_f32_16x16x32_bf16 v[30:33], v[162:165], v[194:197], v[30:33]
	v_mfma_f32_16x16x32_bf16 v[26:29], v[178:181], v[194:197], v[26:29]
	v_mfma_f32_16x16x32_bf16 v[22:25], v[162:165], v[202:205], v[22:25]
	v_mfma_f32_16x16x32_bf16 v[18:21], v[178:181], v[202:205], v[18:21]
	v_mfma_f32_16x16x32_bf16 v[6:9], v[162:165], v[210:213], v[6:9]
	v_mfma_f32_16x16x32_bf16 v[2:5], v[178:181], v[210:213], v[2:5]
	v_mfma_f32_16x16x32_bf16 v[54:57], v[166:169], v[190:193], v[54:57]
	v_mfma_f32_16x16x32_bf16 v[46:49], v[182:185], v[190:193], v[46:49]
	v_mfma_f32_16x16x32_bf16 v[30:33], v[166:169], v[198:201], v[30:33]
	v_mfma_f32_16x16x32_bf16 v[26:29], v[182:185], v[198:201], v[26:29]
	v_mfma_f32_16x16x32_bf16 v[22:25], v[166:169], v[206:209], v[22:25]
	v_mfma_f32_16x16x32_bf16 v[18:21], v[182:185], v[206:209], v[18:21]
	v_mfma_f32_16x16x32_bf16 v[6:9], v[166:169], v[218:221], v[6:9]
	v_mfma_f32_16x16x32_bf16 v[2:5], v[182:185], v[218:221], v[2:5]
	s_setprio 0
	s_barrier
	s_add_i32 s60, s60, 2
	s_add_u32 s42, s42, 0x100
	s_addc_u32 s43, s43, 0
	s_add_u32 s58, s58, 0x100
	s_addc_u32 s59, s59, 0
	s_cmp_gt_u32 s60, 27
	s_cbranch_scc0 .LBB0_3706
	v_lshl_add_u32 v234, s40, 8, v1
	v_lshl_or_b32 v236, s57, 8, v173
	v_ashrrev_i32_e32 v235, 31, v234
	v_ashrrev_i32_e32 v237, 31, v236
	v_lshlrev_b64 v[228:229], 12, v[234:235]
	v_lshl_add_u64 v[228:229], s[64:65], 0, v[228:229]
	v_lshlrev_b64 v[236:237], 1, v[236:237]
	v_lshl_add_u64 v[228:229], v[228:229], 0, v[236:237]
	v_mov_b32_e32 v231, 0
	ds_read_b128 v[130:133], v174
	ds_read_b128 v[134:137], v174 offset:1024
	ds_read_b128 v[138:141], v174 offset:2048
	ds_read_b128 v[158:161], v174 offset:3072
	ds_read_b128 v[162:165], v175
	ds_read_b128 v[166:169], v175 offset:1024
	ds_read_b128 v[178:181], v175 offset:2048
	ds_read_b128 v[182:185], v175 offset:3072
	s_add_u32 s34, s42, 0xfff80080
	s_addc_u32 s35, s43, -1
	s_cmp_eq_u32 s60, 28
	s_cselect_b32 s45, s0, s35
	s_cselect_b32 s44, s1, s34
	s_cselect_b32 s35, s25, s59
	s_cselect_b32 s34, s27, s58
	v_lshl_add_u64 v[170:171], s[42:43], 0, v[150:151]
	s_add_i32 m0, s41, 0xc000
	ds_read_b128 v[186:189], v176
	ds_read_b128 v[190:193], v176 offset:1024
	ds_read_b128 v[194:197], v176 offset:2048
	ds_read_b128 v[198:201], v176 offset:3072
	ds_read_b128 v[202:205], v176 offset:4096
	ds_read_b128 v[206:209], v176 offset:5120
	ds_read_b128 v[210:213], v176 offset:6144
	ds_read_b128 v[218:221], v176 offset:7168
	global_load_lds_dwordx4 v[170:171], off
	v_lshl_add_u64 v[170:171], s[42:43], 0, v[152:153]
	s_add_i32 m0, s41, 0xe000
	s_nop 0
	global_load_lds_dwordx4 v[170:171], off
	s_waitcnt vmcnt(8)
	s_waitcnt lgkmcnt(0)
	s_barrier
	s_setprio 1
	s_waitcnt lgkmcnt(0)
	v_mfma_f32_16x16x32_bf16 v[126:129], v[130:133], v[186:189], v[126:129]
	v_mfma_f32_16x16x32_bf16 v[122:125], v[138:141], v[186:189], v[122:125]
	v_mfma_f32_16x16x32_bf16 v[110:113], v[130:133], v[194:197], v[110:113]
	v_mfma_f32_16x16x32_bf16 v[106:109], v[138:141], v[194:197], v[106:109]
	v_mfma_f32_16x16x32_bf16 v[94:97], v[130:133], v[202:205], v[94:97]
	v_mfma_f32_16x16x32_bf16 v[90:93], v[138:141], v[202:205], v[90:93]
	v_mfma_f32_16x16x32_bf16 v[78:81], v[130:133], v[210:213], v[78:81]
	v_mfma_f32_16x16x32_bf16 v[74:77], v[138:141], v[210:213], v[74:77]
	v_mfma_f32_16x16x32_bf16 v[126:129], v[134:137], v[190:193], v[126:129]
	v_mfma_f32_16x16x32_bf16 v[122:125], v[158:161], v[190:193], v[122:125]
	v_mfma_f32_16x16x32_bf16 v[110:113], v[134:137], v[198:201], v[110:113]
	v_mfma_f32_16x16x32_bf16 v[106:109], v[158:161], v[198:201], v[106:109]
	v_mfma_f32_16x16x32_bf16 v[94:97], v[134:137], v[206:209], v[94:97]
	v_mfma_f32_16x16x32_bf16 v[90:93], v[158:161], v[206:209], v[90:93]
	v_mfma_f32_16x16x32_bf16 v[78:81], v[134:137], v[218:221], v[78:81]
	v_mfma_f32_16x16x32_bf16 v[74:77], v[158:161], v[218:221], v[74:77]
	s_setprio 0
	s_setprio 1
	v_mfma_f32_16x16x32_bf16 v[118:121], v[162:165], v[186:189], v[118:121]
	v_mfma_f32_16x16x32_bf16 v[114:117], v[178:181], v[186:189], v[114:117]
	v_mfma_f32_16x16x32_bf16 v[102:105], v[162:165], v[194:197], v[102:105]
	v_mfma_f32_16x16x32_bf16 v[98:101], v[178:181], v[194:197], v[98:101]
	v_mfma_f32_16x16x32_bf16 v[86:89], v[162:165], v[202:205], v[86:89]
	v_mfma_f32_16x16x32_bf16 v[82:85], v[178:181], v[202:205], v[82:85]
	v_mfma_f32_16x16x32_bf16 v[70:73], v[162:165], v[210:213], v[70:73]
	v_mfma_f32_16x16x32_bf16 v[66:69], v[178:181], v[210:213], v[66:69]
	v_mfma_f32_16x16x32_bf16 v[118:121], v[166:169], v[190:193], v[118:121]
	v_mfma_f32_16x16x32_bf16 v[114:117], v[182:185], v[190:193], v[114:117]
	v_mfma_f32_16x16x32_bf16 v[102:105], v[166:169], v[198:201], v[102:105]
	v_mfma_f32_16x16x32_bf16 v[98:101], v[182:185], v[198:201], v[98:101]
	v_mfma_f32_16x16x32_bf16 v[86:89], v[166:169], v[206:209], v[86:89]
	v_mfma_f32_16x16x32_bf16 v[82:85], v[182:185], v[206:209], v[82:85]
	v_mfma_f32_16x16x32_bf16 v[70:73], v[166:169], v[218:221], v[70:73]
	v_mfma_f32_16x16x32_bf16 v[66:69], v[182:185], v[218:221], v[66:69]
	s_setprio 0
	s_barrier
	s_add_i32 s61, s54, s46
	v_lshl_add_u64 v[170:171], s[34:35], 0, v[144:145]
	s_mov_b32 m0, s61
	ds_read_b128 v[186:189], v176 offset:16384
	ds_read_b128 v[190:193], v176 offset:17408
	ds_read_b128 v[194:197], v176 offset:18432
	ds_read_b128 v[198:201], v176 offset:19456
	ds_read_b128 v[202:205], v176 offset:20480
	ds_read_b128 v[206:209], v176 offset:21504
	ds_read_b128 v[210:213], v176 offset:22528
	ds_read_b128 v[218:221], v176 offset:23552
	v_mov_b32_e32 v230, 0x0
	v_lshl_add_u64 v[232:233], v[230:231], 0, v[228:229]
	global_load_lds_dwordx4 v[232:233], off
	s_add_i32 m0, s61, 0x2000
	s_add_u32 s62, s34, 0x80000
	v_lshl_add_u64 v[214:215], s[34:35], 0, v[148:149]
	s_addc_u32 s63, s35, 0
	s_add_i32 s61, s55, s46
	v_mov_b32_e32 v230, 0x100
	v_lshl_add_u64 v[232:233], v[230:231], 0, v[228:229]
	global_load_lds_dwordx4 v[232:233], off
	v_lshl_add_u64 v[222:223], s[62:63], 0, v[144:145]
	s_mov_b32 m0, s61
	v_lshl_add_u64 v[224:225], s[44:45], 0, v[146:147]
	v_mov_b32_e32 v230, 0x10000
	v_lshl_add_u64 v[232:233], v[230:231], 0, v[228:229]
	global_load_lds_dwordx4 v[232:233], off
	v_lshl_add_u64 v[222:223], s[62:63], 0, v[148:149]
	s_add_i32 m0, s61, 0x2000
	s_nop 0
	v_mov_b32_e32 v230, 0x10100
	v_lshl_add_u64 v[232:233], v[230:231], 0, v[228:229]
	global_load_lds_dwordx4 v[232:233], off
	v_lshl_add_u64 v[222:223], s[44:45], 0, v[142:143]
	s_mov_b32 m0, s41
	s_nop 0
	v_mov_b32_e32 v230, 0x20000
	v_lshl_add_u64 v[232:233], v[230:231], 0, v[228:229]
	global_load_lds_dwordx4 v[232:233], off
	s_mov_b32 m0, s47
	s_nop 0
	v_mov_b32_e32 v230, 0x20100
	v_lshl_add_u64 v[232:233], v[230:231], 0, v[228:229]
	global_load_lds_dwordx4 v[232:233], off
	s_waitcnt vmcnt(8)
	s_waitcnt lgkmcnt(0)
	s_barrier
	s_setprio 1
	s_waitcnt lgkmcnt(0)
	v_mfma_f32_16x16x32_bf16 v[62:65], v[130:133], v[186:189], v[62:65]
	v_mfma_f32_16x16x32_bf16 v[58:61], v[138:141], v[186:189], v[58:61]
	v_mfma_f32_16x16x32_bf16 v[50:53], v[130:133], v[194:197], v[50:53]
	v_mfma_f32_16x16x32_bf16 v[42:45], v[138:141], v[194:197], v[42:45]
	v_mfma_f32_16x16x32_bf16 v[38:41], v[130:133], v[202:205], v[38:41]
	v_mfma_f32_16x16x32_bf16 v[34:37], v[138:141], v[202:205], v[34:37]
	v_mfma_f32_16x16x32_bf16 v[14:17], v[130:133], v[210:213], v[14:17]
	v_mfma_f32_16x16x32_bf16 v[10:13], v[138:141], v[210:213], v[10:13]
	v_mfma_f32_16x16x32_bf16 v[62:65], v[134:137], v[190:193], v[62:65]
	v_mfma_f32_16x16x32_bf16 v[58:61], v[158:161], v[190:193], v[58:61]
	v_mfma_f32_16x16x32_bf16 v[50:53], v[134:137], v[198:201], v[50:53]
	v_mfma_f32_16x16x32_bf16 v[42:45], v[158:161], v[198:201], v[42:45]
	v_mfma_f32_16x16x32_bf16 v[38:41], v[134:137], v[206:209], v[38:41]
	v_mfma_f32_16x16x32_bf16 v[34:37], v[158:161], v[206:209], v[34:37]
	v_mfma_f32_16x16x32_bf16 v[14:17], v[134:137], v[218:221], v[14:17]
	v_mfma_f32_16x16x32_bf16 v[10:13], v[158:161], v[218:221], v[10:13]
	s_setprio 0
	s_setprio 1
	v_mfma_f32_16x16x32_bf16 v[54:57], v[162:165], v[186:189], v[54:57]
	v_mfma_f32_16x16x32_bf16 v[46:49], v[178:181], v[186:189], v[46:49]
	v_mfma_f32_16x16x32_bf16 v[30:33], v[162:165], v[194:197], v[30:33]
	v_mfma_f32_16x16x32_bf16 v[26:29], v[178:181], v[194:197], v[26:29]
	v_mfma_f32_16x16x32_bf16 v[22:25], v[162:165], v[202:205], v[22:25]
	v_mfma_f32_16x16x32_bf16 v[18:21], v[178:181], v[202:205], v[18:21]
	v_mfma_f32_16x16x32_bf16 v[6:9], v[162:165], v[210:213], v[6:9]
	v_mfma_f32_16x16x32_bf16 v[2:5], v[178:181], v[210:213], v[2:5]
	v_mfma_f32_16x16x32_bf16 v[54:57], v[166:169], v[190:193], v[54:57]
	v_mfma_f32_16x16x32_bf16 v[46:49], v[182:185], v[190:193], v[46:49]
	v_mfma_f32_16x16x32_bf16 v[30:33], v[166:169], v[198:201], v[30:33]
	v_mfma_f32_16x16x32_bf16 v[26:29], v[182:185], v[198:201], v[26:29]
	v_mfma_f32_16x16x32_bf16 v[22:25], v[166:169], v[206:209], v[22:25]
	v_mfma_f32_16x16x32_bf16 v[18:21], v[182:185], v[206:209], v[18:21]
	v_mfma_f32_16x16x32_bf16 v[6:9], v[166:169], v[218:221], v[6:9]
	v_mfma_f32_16x16x32_bf16 v[2:5], v[182:185], v[218:221], v[2:5]
	s_setprio 0
	s_barrier
	s_add_i32 s61, 0, 0x18000
	s_add_i32 s62, 0, 0x1c000
	v_add_u32_e32 v158, s61, v172
	v_add_u32_e32 v177, s62, v172
	ds_read_b128 v[130:133], v158
	ds_read_b128 v[134:137], v158 offset:1024
	ds_read_b128 v[138:141], v158 offset:2048
	ds_read_b128 v[158:161], v158 offset:3072
	ds_read_b128 v[162:165], v177
	ds_read_b128 v[166:169], v177 offset:1024
	ds_read_b128 v[178:181], v177 offset:2048
	ds_read_b128 v[182:185], v177 offset:3072
	s_add_u32 s44, s44, 0x80000
	s_addc_u32 s45, s45, 0
	s_mov_b32 m0, s48
	v_lshl_add_u64 v[226:227], s[44:45], 0, v[142:143]
	ds_read_b128 v[186:189], v176 offset:32768
	ds_read_b128 v[190:193], v176 offset:33792
	ds_read_b128 v[194:197], v176 offset:34816
	ds_read_b128 v[198:201], v176 offset:35840
	ds_read_b128 v[202:205], v176 offset:36864
	ds_read_b128 v[206:209], v176 offset:37888
	ds_read_b128 v[210:213], v176 offset:38912
	ds_read_b128 v[218:221], v176 offset:39936
	v_mov_b32_e32 v230, 0x30000
	v_lshl_add_u64 v[232:233], v[230:231], 0, v[228:229]
	global_load_lds_dwordx4 v[232:233], off
	v_lshl_add_u64 v[226:227], s[44:45], 0, v[146:147]
	s_mov_b32 m0, s49
	s_nop 0
	v_mov_b32_e32 v230, 0x30100
	v_lshl_add_u64 v[232:233], v[230:231], 0, v[228:229]
	global_load_lds_dwordx4 v[232:233], off
	s_waitcnt vmcnt(8)
	s_waitcnt lgkmcnt(0)
	s_barrier
	s_setprio 1
	s_waitcnt lgkmcnt(0)
	v_mfma_f32_16x16x32_bf16 v[126:129], v[130:133], v[186:189], v[126:129]
	v_mfma_f32_16x16x32_bf16 v[122:125], v[138:141], v[186:189], v[122:125]
	v_mfma_f32_16x16x32_bf16 v[110:113], v[130:133], v[194:197], v[110:113]
	v_mfma_f32_16x16x32_bf16 v[106:109], v[138:141], v[194:197], v[106:109]
	v_mfma_f32_16x16x32_bf16 v[94:97], v[130:133], v[202:205], v[94:97]
	v_mfma_f32_16x16x32_bf16 v[90:93], v[138:141], v[202:205], v[90:93]
	v_mfma_f32_16x16x32_bf16 v[78:81], v[130:133], v[210:213], v[78:81]
	v_mfma_f32_16x16x32_bf16 v[74:77], v[138:141], v[210:213], v[74:77]
	v_mfma_f32_16x16x32_bf16 v[126:129], v[134:137], v[190:193], v[126:129]
	v_mfma_f32_16x16x32_bf16 v[122:125], v[158:161], v[190:193], v[122:125]
	v_mfma_f32_16x16x32_bf16 v[110:113], v[134:137], v[198:201], v[110:113]
	v_mfma_f32_16x16x32_bf16 v[106:109], v[158:161], v[198:201], v[106:109]
	v_mfma_f32_16x16x32_bf16 v[94:97], v[134:137], v[206:209], v[94:97]
	v_mfma_f32_16x16x32_bf16 v[90:93], v[158:161], v[206:209], v[90:93]
	v_mfma_f32_16x16x32_bf16 v[78:81], v[134:137], v[218:221], v[78:81]
	v_mfma_f32_16x16x32_bf16 v[74:77], v[158:161], v[218:221], v[74:77]
	s_setprio 0
	s_setprio 1
	v_mfma_f32_16x16x32_bf16 v[118:121], v[162:165], v[186:189], v[118:121]
	v_mfma_f32_16x16x32_bf16 v[114:117], v[178:181], v[186:189], v[114:117]
	v_mfma_f32_16x16x32_bf16 v[102:105], v[162:165], v[194:197], v[102:105]
	v_mfma_f32_16x16x32_bf16 v[98:101], v[178:181], v[194:197], v[98:101]
	v_mfma_f32_16x16x32_bf16 v[86:89], v[162:165], v[202:205], v[86:89]
	v_mfma_f32_16x16x32_bf16 v[82:85], v[178:181], v[202:205], v[82:85]
	v_mfma_f32_16x16x32_bf16 v[70:73], v[162:165], v[210:213], v[70:73]
	v_mfma_f32_16x16x32_bf16 v[66:69], v[178:181], v[210:213], v[66:69]
	v_mfma_f32_16x16x32_bf16 v[118:121], v[166:169], v[190:193], v[118:121]
	v_mfma_f32_16x16x32_bf16 v[114:117], v[182:185], v[190:193], v[114:117]
	v_mfma_f32_16x16x32_bf16 v[102:105], v[166:169], v[198:201], v[102:105]
	v_mfma_f32_16x16x32_bf16 v[98:101], v[182:185], v[198:201], v[98:101]
	v_mfma_f32_16x16x32_bf16 v[86:89], v[166:169], v[206:209], v[86:89]
	v_mfma_f32_16x16x32_bf16 v[82:85], v[182:185], v[206:209], v[82:85]
	v_mfma_f32_16x16x32_bf16 v[70:73], v[166:169], v[218:221], v[70:73]
	v_mfma_f32_16x16x32_bf16 v[66:69], v[182:185], v[218:221], v[66:69]
	s_setprio 0
	s_barrier
	s_add_i32 s44, s61, s46
	v_lshl_add_u64 v[170:171], v[170:171], 0, s[12:13]
	s_mov_b32 m0, s44
	ds_read_b128 v[186:189], v176 offset:49152
	ds_read_b128 v[190:193], v176 offset:50176
	ds_read_b128 v[194:197], v176 offset:51200
	ds_read_b128 v[198:201], v176 offset:52224
	ds_read_b128 v[202:205], v176 offset:53248
	ds_read_b128 v[206:209], v176 offset:54272
	ds_read_b128 v[210:213], v176 offset:55296
	ds_read_b128 v[218:221], v176 offset:56320
	v_mov_b32_e32 v230, 0x80000
	v_lshl_add_u64 v[232:233], v[230:231], 0, v[228:229]
	global_load_lds_dwordx4 v[232:233], off
	s_add_i32 m0, s44, 0x2000
	s_add_u32 s34, s34, 0x80080
	v_lshl_add_u64 v[170:171], v[214:215], 0, s[12:13]
	s_addc_u32 s35, s35, 0
	s_add_i32 s44, s62, s46
	v_mov_b32_e32 v230, 0x80100
	v_lshl_add_u64 v[232:233], v[230:231], 0, v[228:229]
	global_load_lds_dwordx4 v[232:233], off
	v_lshl_add_u64 v[170:171], s[34:35], 0, v[144:145]
	s_mov_b32 m0, s44
	s_nop 0
	v_mov_b32_e32 v230, 0x90000
	v_lshl_add_u64 v[232:233], v[230:231], 0, v[228:229]
	global_load_lds_dwordx4 v[232:233], off
	v_lshl_add_u64 v[170:171], s[34:35], 0, v[148:149]
	s_add_i32 m0, s44, 0x2000
	s_nop 0
	v_mov_b32_e32 v230, 0x90100
	v_lshl_add_u64 v[232:233], v[230:231], 0, v[228:229]
	global_load_lds_dwordx4 v[232:233], off
	v_lshl_add_u64 v[170:171], v[222:223], 0, s[12:13]
	s_mov_b32 m0, s51
	s_nop 0
	v_mov_b32_e32 v230, 0xa0000
	v_lshl_add_u64 v[232:233], v[230:231], 0, v[228:229]
	global_load_lds_dwordx4 v[232:233], off
	v_lshl_add_u64 v[170:171], v[224:225], 0, s[12:13]
	s_mov_b32 m0, s52
	s_nop 0
	v_mov_b32_e32 v230, 0xa0100
	v_lshl_add_u64 v[232:233], v[230:231], 0, v[228:229]
	global_load_lds_dwordx4 v[232:233], off
	s_waitcnt vmcnt(8)
	s_waitcnt lgkmcnt(0)
	s_barrier
	s_setprio 1
	s_waitcnt lgkmcnt(0)
	v_mfma_f32_16x16x32_bf16 v[62:65], v[130:133], v[186:189], v[62:65]
	v_mfma_f32_16x16x32_bf16 v[58:61], v[138:141], v[186:189], v[58:61]
	v_mfma_f32_16x16x32_bf16 v[50:53], v[130:133], v[194:197], v[50:53]
	v_mfma_f32_16x16x32_bf16 v[42:45], v[138:141], v[194:197], v[42:45]
	v_mfma_f32_16x16x32_bf16 v[38:41], v[130:133], v[202:205], v[38:41]
	v_mfma_f32_16x16x32_bf16 v[34:37], v[138:141], v[202:205], v[34:37]
	v_mfma_f32_16x16x32_bf16 v[14:17], v[130:133], v[210:213], v[14:17]
	v_mfma_f32_16x16x32_bf16 v[10:13], v[138:141], v[210:213], v[10:13]
	v_mfma_f32_16x16x32_bf16 v[62:65], v[134:137], v[190:193], v[62:65]
	v_mfma_f32_16x16x32_bf16 v[58:61], v[158:161], v[190:193], v[58:61]
	v_mfma_f32_16x16x32_bf16 v[50:53], v[134:137], v[198:201], v[50:53]
	v_mfma_f32_16x16x32_bf16 v[42:45], v[158:161], v[198:201], v[42:45]
	v_mfma_f32_16x16x32_bf16 v[38:41], v[134:137], v[206:209], v[38:41]
	v_mfma_f32_16x16x32_bf16 v[34:37], v[158:161], v[206:209], v[34:37]
	v_mfma_f32_16x16x32_bf16 v[14:17], v[134:137], v[218:221], v[14:17]
	v_mfma_f32_16x16x32_bf16 v[10:13], v[158:161], v[218:221], v[10:13]
	s_setprio 0
	s_setprio 1
	v_mfma_f32_16x16x32_bf16 v[54:57], v[162:165], v[186:189], v[54:57]
	v_mfma_f32_16x16x32_bf16 v[46:49], v[178:181], v[186:189], v[46:49]
	v_mfma_f32_16x16x32_bf16 v[30:33], v[162:165], v[194:197], v[30:33]
	v_mfma_f32_16x16x32_bf16 v[26:29], v[178:181], v[194:197], v[26:29]
	v_mfma_f32_16x16x32_bf16 v[22:25], v[162:165], v[202:205], v[22:25]
	v_mfma_f32_16x16x32_bf16 v[18:21], v[178:181], v[202:205], v[18:21]
	v_mfma_f32_16x16x32_bf16 v[6:9], v[162:165], v[210:213], v[6:9]
	v_mfma_f32_16x16x32_bf16 v[2:5], v[178:181], v[210:213], v[2:5]
	v_mfma_f32_16x16x32_bf16 v[54:57], v[166:169], v[190:193], v[54:57]
	v_mfma_f32_16x16x32_bf16 v[46:49], v[182:185], v[190:193], v[46:49]
	v_mfma_f32_16x16x32_bf16 v[30:33], v[166:169], v[198:201], v[30:33]
	v_mfma_f32_16x16x32_bf16 v[26:29], v[182:185], v[198:201], v[26:29]
	v_mfma_f32_16x16x32_bf16 v[22:25], v[166:169], v[206:209], v[22:25]
	v_mfma_f32_16x16x32_bf16 v[18:21], v[182:185], v[206:209], v[18:21]
	v_mfma_f32_16x16x32_bf16 v[6:9], v[166:169], v[218:221], v[6:9]
	v_mfma_f32_16x16x32_bf16 v[2:5], v[182:185], v[218:221], v[2:5]
	s_setprio 0
	s_barrier
	s_add_i32 s60, s60, 2
	s_add_u32 s42, s42, 0x100
	s_addc_u32 s43, s43, 0
	s_add_u32 s58, s58, 0x100
	s_addc_u32 s59, s59, 0
	s_and_b64 vcc, exec, s[14:15]
	s_cbranch_vccz .LBB0_3709
	s_barrier
.LBB0_3709:
	v_lshl_or_b32 v130, s57, 8, v173
	v_lshl_add_u32 v158, s40, 8, v1
	v_ashrrev_i32_e32 v131, 31, v130
	v_lshlrev_b64 v[160:161], 1, v[130:131]
	v_or_b32_e32 v130, 16, v158
	v_ashrrev_i32_e32 v159, 31, v158
	v_ashrrev_i32_e32 v131, 31, v130
	v_lshlrev_b64 v[132:133], 12, v[158:159]
	v_lshlrev_b64 v[130:131], 12, v[130:131]
	v_lshl_add_u64 v[132:133], s[64:65], 0, v[132:133]
	v_lshl_add_u64 v[130:131], s[64:65], 0, v[130:131]
	v_lshl_add_u64 v[170:171], v[132:133], 0, v[160:161]
	v_lshl_add_u64 v[168:169], v[130:131], 0, v[160:161]
	s_waitcnt vmcnt(0)
	v_mov_b32_e32 v201, 0
	v_mov_b32_e32 v200, 0x10000
	v_lshl_add_u64 v[186:187], v[200:201], 0, v[170:171]
	v_mov_b32_e32 v200, 0x20000
	v_lshl_add_u64 v[188:189], v[200:201], 0, v[170:171]
	v_mov_b32_e32 v200, 0x30000
	v_lshl_add_u64 v[190:191], v[200:201], 0, v[170:171]
	v_mov_b32_e32 v200, 0x80000
	v_lshl_add_u64 v[192:193], v[200:201], 0, v[170:171]
	v_mov_b32_e32 v200, 0x90000
	v_lshl_add_u64 v[194:195], v[200:201], 0, v[170:171]
	v_mov_b32_e32 v200, 0xa0000
	v_lshl_add_u64 v[196:197], v[200:201], 0, v[170:171]
	v_mov_b32_e32 v200, 0xb0000
	v_lshl_add_u64 v[198:199], v[200:201], 0, v[170:171]
	v_lshlrev_b32_e32 v202, 4, v0
	v_add_u32_e32 v203, 0x10000, v202
	global_load_dwordx4 v[162:165], v[198:199], off
	global_load_dwordx4 v[166:169], v[198:199], off offset:256
	ds_read_b128 v[130:133], v203 offset:0
	ds_read_b128 v[134:137], v203 offset:8192
	ds_read_b128 v[138:141], v203 offset:16384
	ds_read_b128 v[158:161], v203 offset:24576
	s_waitcnt lgkmcnt(3)
	v_cvt_f32_f16_e32 v178, v130
	v_cvt_f32_f16_sdwa v179, v130 dst_sel:DWORD dst_unused:UNUSED_PAD src0_sel:WORD_1
	v_cvt_f32_f16_e32 v180, v131
	v_cvt_f32_f16_sdwa v181, v131 dst_sel:DWORD dst_unused:UNUSED_PAD src0_sel:WORD_1
	v_cvt_f32_f16_e32 v182, v132
	v_cvt_f32_f16_sdwa v183, v132 dst_sel:DWORD dst_unused:UNUSED_PAD src0_sel:WORD_1
	v_cvt_f32_f16_e32 v184, v133
	v_cvt_f32_f16_sdwa v185, v133 dst_sel:DWORD dst_unused:UNUSED_PAD src0_sel:WORD_1
	ds_read_b128 v[130:133], v202 offset:0
	v_pk_add_f32 v[126:127], v[178:179], v[126:127]
	v_pk_add_f32 v[128:129], v[180:181], v[128:129]
	v_pk_add_f32 v[122:123], v[182:183], v[122:123]
	v_pk_add_f32 v[124:125], v[184:185], v[124:125]
	v_cvt_pk_f16_f32 v125, v124, v125
	v_cvt_pk_f16_f32 v124, v122, v123
	v_cvt_pk_f16_f32 v123, v128, v129
	v_cvt_pk_f16_f32 v122, v126, v127
	global_store_dwordx4 v[170:171], v[122:125], off
	s_waitcnt lgkmcnt(3)
	v_cvt_f32_f16_e32 v178, v134
	v_cvt_f32_f16_sdwa v179, v134 dst_sel:DWORD dst_unused:UNUSED_PAD src0_sel:WORD_1
	v_cvt_f32_f16_e32 v180, v135
	v_cvt_f32_f16_sdwa v181, v135 dst_sel:DWORD dst_unused:UNUSED_PAD src0_sel:WORD_1
	v_cvt_f32_f16_e32 v182, v136
	v_cvt_f32_f16_sdwa v183, v136 dst_sel:DWORD dst_unused:UNUSED_PAD src0_sel:WORD_1
	v_cvt_f32_f16_e32 v184, v137
	v_cvt_f32_f16_sdwa v185, v137 dst_sel:DWORD dst_unused:UNUSED_PAD src0_sel:WORD_1
	ds_read_b128 v[134:137], v202 offset:8192
	v_pk_add_f32 v[118:119], v[178:179], v[118:119]
	v_pk_add_f32 v[120:121], v[180:181], v[120:121]
	v_pk_add_f32 v[114:115], v[182:183], v[114:115]
	v_pk_add_f32 v[116:117], v[184:185], v[116:117]
	v_cvt_pk_f16_f32 v117, v116, v117
	v_cvt_pk_f16_f32 v116, v114, v115
	v_cvt_pk_f16_f32 v115, v120, v121
	v_cvt_pk_f16_f32 v114, v118, v119
	global_store_dwordx4 v[170:171], v[114:117], off offset:256
	s_waitcnt lgkmcnt(3)
	v_cvt_f32_f16_e32 v178, v138
	v_cvt_f32_f16_sdwa v179, v138 dst_sel:DWORD dst_unused:UNUSED_PAD src0_sel:WORD_1
	v_cvt_f32_f16_e32 v180, v139
	v_cvt_f32_f16_sdwa v181, v139 dst_sel:DWORD dst_unused:UNUSED_PAD src0_sel:WORD_1
	v_cvt_f32_f16_e32 v182, v140
	v_cvt_f32_f16_sdwa v183, v140 dst_sel:DWORD dst_unused:UNUSED_PAD src0_sel:WORD_1
	v_cvt_f32_f16_e32 v184, v141
	v_cvt_f32_f16_sdwa v185, v141 dst_sel:DWORD dst_unused:UNUSED_PAD src0_sel:WORD_1
	ds_read_b128 v[138:141], v202 offset:16384
	v_pk_add_f32 v[110:111], v[178:179], v[110:111]
	v_pk_add_f32 v[112:113], v[180:181], v[112:113]
	v_pk_add_f32 v[106:107], v[182:183], v[106:107]
	v_pk_add_f32 v[108:109], v[184:185], v[108:109]
	v_cvt_pk_f16_f32 v109, v108, v109
	v_cvt_pk_f16_f32 v108, v106, v107
	v_cvt_pk_f16_f32 v107, v112, v113
	v_cvt_pk_f16_f32 v106, v110, v111
	global_store_dwordx4 v[186:187], v[106:109], off
	s_waitcnt lgkmcnt(3)
	v_cvt_f32_f16_e32 v178, v158
	v_cvt_f32_f16_sdwa v179, v158 dst_sel:DWORD dst_unused:UNUSED_PAD src0_sel:WORD_1
	v_cvt_f32_f16_e32 v180, v159
	v_cvt_f32_f16_sdwa v181, v159 dst_sel:DWORD dst_unused:UNUSED_PAD src0_sel:WORD_1
	v_cvt_f32_f16_e32 v182, v160
	v_cvt_f32_f16_sdwa v183, v160 dst_sel:DWORD dst_unused:UNUSED_PAD src0_sel:WORD_1
	v_cvt_f32_f16_e32 v184, v161
	v_cvt_f32_f16_sdwa v185, v161 dst_sel:DWORD dst_unused:UNUSED_PAD src0_sel:WORD_1
	ds_read_b128 v[158:161], v202 offset:24576
	v_pk_add_f32 v[102:103], v[178:179], v[102:103]
	v_pk_add_f32 v[104:105], v[180:181], v[104:105]
	v_pk_add_f32 v[98:99], v[182:183], v[98:99]
	v_pk_add_f32 v[100:101], v[184:185], v[100:101]
	v_cvt_pk_f16_f32 v101, v100, v101
	v_cvt_pk_f16_f32 v100, v98, v99
	v_cvt_pk_f16_f32 v99, v104, v105
	v_cvt_pk_f16_f32 v98, v102, v103
	global_store_dwordx4 v[186:187], v[98:101], off offset:256
	s_waitcnt lgkmcnt(3)
	v_cvt_f32_f16_e32 v178, v130
	v_cvt_f32_f16_sdwa v179, v130 dst_sel:DWORD dst_unused:UNUSED_PAD src0_sel:WORD_1
	v_cvt_f32_f16_e32 v180, v131
	v_cvt_f32_f16_sdwa v181, v131 dst_sel:DWORD dst_unused:UNUSED_PAD src0_sel:WORD_1
	v_cvt_f32_f16_e32 v182, v132
	v_cvt_f32_f16_sdwa v183, v132 dst_sel:DWORD dst_unused:UNUSED_PAD src0_sel:WORD_1
	v_cvt_f32_f16_e32 v184, v133
	v_cvt_f32_f16_sdwa v185, v133 dst_sel:DWORD dst_unused:UNUSED_PAD src0_sel:WORD_1
	ds_read_b128 v[130:133], v203 offset:32768
	v_pk_add_f32 v[94:95], v[178:179], v[94:95]
	v_pk_add_f32 v[96:97], v[180:181], v[96:97]
	v_pk_add_f32 v[90:91], v[182:183], v[90:91]
	v_pk_add_f32 v[92:93], v[184:185], v[92:93]
	v_cvt_pk_f16_f32 v93, v92, v93
	v_cvt_pk_f16_f32 v92, v90, v91
	v_cvt_pk_f16_f32 v91, v96, v97
	v_cvt_pk_f16_f32 v90, v94, v95
	global_store_dwordx4 v[188:189], v[90:93], off
	s_waitcnt lgkmcnt(3)
	v_cvt_f32_f16_e32 v178, v134
	v_cvt_f32_f16_sdwa v179, v134 dst_sel:DWORD dst_unused:UNUSED_PAD src0_sel:WORD_1
	v_cvt_f32_f16_e32 v180, v135
	v_cvt_f32_f16_sdwa v181, v135 dst_sel:DWORD dst_unused:UNUSED_PAD src0_sel:WORD_1
	v_cvt_f32_f16_e32 v182, v136
	v_cvt_f32_f16_sdwa v183, v136 dst_sel:DWORD dst_unused:UNUSED_PAD src0_sel:WORD_1
	v_cvt_f32_f16_e32 v184, v137
	v_cvt_f32_f16_sdwa v185, v137 dst_sel:DWORD dst_unused:UNUSED_PAD src0_sel:WORD_1
	ds_read_b128 v[134:137], v203 offset:40960
	v_pk_add_f32 v[86:87], v[178:179], v[86:87]
	v_pk_add_f32 v[88:89], v[180:181], v[88:89]
	v_pk_add_f32 v[82:83], v[182:183], v[82:83]
	v_pk_add_f32 v[84:85], v[184:185], v[84:85]
	v_cvt_pk_f16_f32 v85, v84, v85
	v_cvt_pk_f16_f32 v84, v82, v83
	v_cvt_pk_f16_f32 v83, v88, v89
	v_cvt_pk_f16_f32 v82, v86, v87
	global_store_dwordx4 v[188:189], v[82:85], off offset:256
	s_waitcnt lgkmcnt(3)
	v_cvt_f32_f16_e32 v178, v138
	v_cvt_f32_f16_sdwa v179, v138 dst_sel:DWORD dst_unused:UNUSED_PAD src0_sel:WORD_1
	v_cvt_f32_f16_e32 v180, v139
	v_cvt_f32_f16_sdwa v181, v139 dst_sel:DWORD dst_unused:UNUSED_PAD src0_sel:WORD_1
	v_cvt_f32_f16_e32 v182, v140
	v_cvt_f32_f16_sdwa v183, v140 dst_sel:DWORD dst_unused:UNUSED_PAD src0_sel:WORD_1
	v_cvt_f32_f16_e32 v184, v141
	v_cvt_f32_f16_sdwa v185, v141 dst_sel:DWORD dst_unused:UNUSED_PAD src0_sel:WORD_1
	ds_read_b128 v[138:141], v203 offset:49152
	v_pk_add_f32 v[78:79], v[178:179], v[78:79]
	v_pk_add_f32 v[80:81], v[180:181], v[80:81]
	v_pk_add_f32 v[74:75], v[182:183], v[74:75]
	v_pk_add_f32 v[76:77], v[184:185], v[76:77]
	v_cvt_pk_f16_f32 v77, v76, v77
	v_cvt_pk_f16_f32 v76, v74, v75
	v_cvt_pk_f16_f32 v75, v80, v81
	v_cvt_pk_f16_f32 v74, v78, v79
	global_store_dwordx4 v[190:191], v[74:77], off
	s_waitcnt lgkmcnt(3)
	v_cvt_f32_f16_e32 v178, v158
	v_cvt_f32_f16_sdwa v179, v158 dst_sel:DWORD dst_unused:UNUSED_PAD src0_sel:WORD_1
	v_cvt_f32_f16_e32 v180, v159
	v_cvt_f32_f16_sdwa v181, v159 dst_sel:DWORD dst_unused:UNUSED_PAD src0_sel:WORD_1
	v_cvt_f32_f16_e32 v182, v160
	v_cvt_f32_f16_sdwa v183, v160 dst_sel:DWORD dst_unused:UNUSED_PAD src0_sel:WORD_1
	v_cvt_f32_f16_e32 v184, v161
	v_cvt_f32_f16_sdwa v185, v161 dst_sel:DWORD dst_unused:UNUSED_PAD src0_sel:WORD_1
	ds_read_b128 v[158:161], v203 offset:57344
	v_pk_add_f32 v[70:71], v[178:179], v[70:71]
	v_pk_add_f32 v[72:73], v[180:181], v[72:73]
	v_pk_add_f32 v[66:67], v[182:183], v[66:67]
	v_pk_add_f32 v[68:69], v[184:185], v[68:69]
	v_cvt_pk_f16_f32 v69, v68, v69
	v_cvt_pk_f16_f32 v68, v66, v67
	v_cvt_pk_f16_f32 v67, v72, v73
	v_cvt_pk_f16_f32 v66, v70, v71
	global_store_dwordx4 v[190:191], v[66:69], off offset:256
	s_waitcnt lgkmcnt(3)
	v_cvt_f32_f16_e32 v178, v130
	v_cvt_f32_f16_sdwa v179, v130 dst_sel:DWORD dst_unused:UNUSED_PAD src0_sel:WORD_1
	v_cvt_f32_f16_e32 v180, v131
	v_cvt_f32_f16_sdwa v181, v131 dst_sel:DWORD dst_unused:UNUSED_PAD src0_sel:WORD_1
	v_cvt_f32_f16_e32 v182, v132
	v_cvt_f32_f16_sdwa v183, v132 dst_sel:DWORD dst_unused:UNUSED_PAD src0_sel:WORD_1
	v_cvt_f32_f16_e32 v184, v133
	v_cvt_f32_f16_sdwa v185, v133 dst_sel:DWORD dst_unused:UNUSED_PAD src0_sel:WORD_1
	ds_read_b128 v[130:133], v202 offset:32768
	v_pk_add_f32 v[62:63], v[178:179], v[62:63]
	v_pk_add_f32 v[64:65], v[180:181], v[64:65]
	v_pk_add_f32 v[58:59], v[182:183], v[58:59]
	v_pk_add_f32 v[60:61], v[184:185], v[60:61]
	v_cvt_pk_f16_f32 v61, v60, v61
	v_cvt_pk_f16_f32 v60, v58, v59
	v_cvt_pk_f16_f32 v59, v64, v65
	v_cvt_pk_f16_f32 v58, v62, v63
	global_store_dwordx4 v[192:193], v[58:61], off
	s_waitcnt lgkmcnt(3)
	v_cvt_f32_f16_e32 v178, v134
	v_cvt_f32_f16_sdwa v179, v134 dst_sel:DWORD dst_unused:UNUSED_PAD src0_sel:WORD_1
	v_cvt_f32_f16_e32 v180, v135
	v_cvt_f32_f16_sdwa v181, v135 dst_sel:DWORD dst_unused:UNUSED_PAD src0_sel:WORD_1
	v_cvt_f32_f16_e32 v182, v136
	v_cvt_f32_f16_sdwa v183, v136 dst_sel:DWORD dst_unused:UNUSED_PAD src0_sel:WORD_1
	v_cvt_f32_f16_e32 v184, v137
	v_cvt_f32_f16_sdwa v185, v137 dst_sel:DWORD dst_unused:UNUSED_PAD src0_sel:WORD_1
	ds_read_b128 v[134:137], v202 offset:40960
	v_pk_add_f32 v[54:55], v[178:179], v[54:55]
	v_pk_add_f32 v[56:57], v[180:181], v[56:57]
	v_pk_add_f32 v[46:47], v[182:183], v[46:47]
	v_pk_add_f32 v[48:49], v[184:185], v[48:49]
	v_cvt_pk_f16_f32 v49, v48, v49
	v_cvt_pk_f16_f32 v48, v46, v47
	v_cvt_pk_f16_f32 v47, v56, v57
	v_cvt_pk_f16_f32 v46, v54, v55
	global_store_dwordx4 v[192:193], v[46:49], off offset:256
	s_waitcnt lgkmcnt(3)
	v_cvt_f32_f16_e32 v178, v138
	v_cvt_f32_f16_sdwa v179, v138 dst_sel:DWORD dst_unused:UNUSED_PAD src0_sel:WORD_1
	v_cvt_f32_f16_e32 v180, v139
	v_cvt_f32_f16_sdwa v181, v139 dst_sel:DWORD dst_unused:UNUSED_PAD src0_sel:WORD_1
	v_cvt_f32_f16_e32 v182, v140
	v_cvt_f32_f16_sdwa v183, v140 dst_sel:DWORD dst_unused:UNUSED_PAD src0_sel:WORD_1
	v_cvt_f32_f16_e32 v184, v141
	v_cvt_f32_f16_sdwa v185, v141 dst_sel:DWORD dst_unused:UNUSED_PAD src0_sel:WORD_1
	v_pk_add_f32 v[50:51], v[178:179], v[50:51]
	v_pk_add_f32 v[52:53], v[180:181], v[52:53]
	v_pk_add_f32 v[42:43], v[182:183], v[42:43]
	v_pk_add_f32 v[44:45], v[184:185], v[44:45]
	v_cvt_pk_f16_f32 v45, v44, v45
	v_cvt_pk_f16_f32 v44, v42, v43
	v_cvt_pk_f16_f32 v43, v52, v53
	v_cvt_pk_f16_f32 v42, v50, v51
	global_store_dwordx4 v[194:195], v[42:45], off
	s_waitcnt lgkmcnt(2)
	v_cvt_f32_f16_e32 v178, v158
	v_cvt_f32_f16_sdwa v179, v158 dst_sel:DWORD dst_unused:UNUSED_PAD src0_sel:WORD_1
	v_cvt_f32_f16_e32 v180, v159
	v_cvt_f32_f16_sdwa v181, v159 dst_sel:DWORD dst_unused:UNUSED_PAD src0_sel:WORD_1
	v_cvt_f32_f16_e32 v182, v160
	v_cvt_f32_f16_sdwa v183, v160 dst_sel:DWORD dst_unused:UNUSED_PAD src0_sel:WORD_1
	v_cvt_f32_f16_e32 v184, v161
	v_cvt_f32_f16_sdwa v185, v161 dst_sel:DWORD dst_unused:UNUSED_PAD src0_sel:WORD_1
	v_pk_add_f32 v[30:31], v[178:179], v[30:31]
	v_pk_add_f32 v[32:33], v[180:181], v[32:33]
	v_pk_add_f32 v[26:27], v[182:183], v[26:27]
	v_pk_add_f32 v[28:29], v[184:185], v[28:29]
	v_cvt_pk_f16_f32 v29, v28, v29
	v_cvt_pk_f16_f32 v28, v26, v27
	v_cvt_pk_f16_f32 v27, v32, v33
	v_cvt_pk_f16_f32 v26, v30, v31
	global_store_dwordx4 v[194:195], v[26:29], off offset:256
	s_waitcnt lgkmcnt(1)
	v_cvt_f32_f16_e32 v178, v130
	v_cvt_f32_f16_sdwa v179, v130 dst_sel:DWORD dst_unused:UNUSED_PAD src0_sel:WORD_1
	v_cvt_f32_f16_e32 v180, v131
	v_cvt_f32_f16_sdwa v181, v131 dst_sel:DWORD dst_unused:UNUSED_PAD src0_sel:WORD_1
	v_cvt_f32_f16_e32 v182, v132
	v_cvt_f32_f16_sdwa v183, v132 dst_sel:DWORD dst_unused:UNUSED_PAD src0_sel:WORD_1
	v_cvt_f32_f16_e32 v184, v133
	v_cvt_f32_f16_sdwa v185, v133 dst_sel:DWORD dst_unused:UNUSED_PAD src0_sel:WORD_1
	v_pk_add_f32 v[38:39], v[178:179], v[38:39]
	v_pk_add_f32 v[40:41], v[180:181], v[40:41]
	v_pk_add_f32 v[34:35], v[182:183], v[34:35]
	v_pk_add_f32 v[36:37], v[184:185], v[36:37]
	v_cvt_pk_f16_f32 v37, v36, v37
	v_cvt_pk_f16_f32 v36, v34, v35
	v_cvt_pk_f16_f32 v35, v40, v41
	v_cvt_pk_f16_f32 v34, v38, v39
	global_store_dwordx4 v[196:197], v[34:37], off
	s_waitcnt lgkmcnt(0)
	v_cvt_f32_f16_e32 v178, v134
	v_cvt_f32_f16_sdwa v179, v134 dst_sel:DWORD dst_unused:UNUSED_PAD src0_sel:WORD_1
	v_cvt_f32_f16_e32 v180, v135
	v_cvt_f32_f16_sdwa v181, v135 dst_sel:DWORD dst_unused:UNUSED_PAD src0_sel:WORD_1
	v_cvt_f32_f16_e32 v182, v136
	v_cvt_f32_f16_sdwa v183, v136 dst_sel:DWORD dst_unused:UNUSED_PAD src0_sel:WORD_1
	v_cvt_f32_f16_e32 v184, v137
	v_cvt_f32_f16_sdwa v185, v137 dst_sel:DWORD dst_unused:UNUSED_PAD src0_sel:WORD_1
	v_pk_add_f32 v[22:23], v[178:179], v[22:23]
	v_pk_add_f32 v[24:25], v[180:181], v[24:25]
	v_pk_add_f32 v[18:19], v[182:183], v[18:19]
	v_pk_add_f32 v[20:21], v[184:185], v[20:21]
	v_cvt_pk_f16_f32 v21, v20, v21
	v_cvt_pk_f16_f32 v20, v18, v19
	v_cvt_pk_f16_f32 v19, v24, v25
	v_cvt_pk_f16_f32 v18, v22, v23
	global_store_dwordx4 v[196:197], v[18:21], off offset:256
	s_waitcnt vmcnt(15)
	v_cvt_f32_f16_e32 v178, v162
	v_cvt_f32_f16_sdwa v179, v162 dst_sel:DWORD dst_unused:UNUSED_PAD src0_sel:WORD_1
	v_cvt_f32_f16_e32 v180, v163
	v_cvt_f32_f16_sdwa v181, v163 dst_sel:DWORD dst_unused:UNUSED_PAD src0_sel:WORD_1
	v_cvt_f32_f16_e32 v182, v164
	v_cvt_f32_f16_sdwa v183, v164 dst_sel:DWORD dst_unused:UNUSED_PAD src0_sel:WORD_1
	v_cvt_f32_f16_e32 v184, v165
	v_cvt_f32_f16_sdwa v185, v165 dst_sel:DWORD dst_unused:UNUSED_PAD src0_sel:WORD_1
	v_pk_add_f32 v[14:15], v[178:179], v[14:15]
	v_pk_add_f32 v[16:17], v[180:181], v[16:17]
	v_pk_add_f32 v[10:11], v[182:183], v[10:11]
	v_pk_add_f32 v[12:13], v[184:185], v[12:13]
	v_cvt_pk_f16_f32 v13, v12, v13
	v_cvt_pk_f16_f32 v12, v10, v11
	v_cvt_pk_f16_f32 v11, v16, v17
	v_cvt_pk_f16_f32 v10, v14, v15
	global_store_dwordx4 v[198:199], v[10:13], off
	s_waitcnt vmcnt(15)
	v_cvt_f32_f16_e32 v178, v166
	v_cvt_f32_f16_sdwa v179, v166 dst_sel:DWORD dst_unused:UNUSED_PAD src0_sel:WORD_1
	v_cvt_f32_f16_e32 v180, v167
	v_cvt_f32_f16_sdwa v181, v167 dst_sel:DWORD dst_unused:UNUSED_PAD src0_sel:WORD_1
	v_cvt_f32_f16_e32 v182, v168
	v_cvt_f32_f16_sdwa v183, v168 dst_sel:DWORD dst_unused:UNUSED_PAD src0_sel:WORD_1
	v_cvt_f32_f16_e32 v184, v169
	v_cvt_f32_f16_sdwa v185, v169 dst_sel:DWORD dst_unused:UNUSED_PAD src0_sel:WORD_1
	v_pk_add_f32 v[6:7], v[178:179], v[6:7]
	v_pk_add_f32 v[8:9], v[180:181], v[8:9]
	v_pk_add_f32 v[2:3], v[182:183], v[2:3]
	v_pk_add_f32 v[4:5], v[184:185], v[4:5]
	v_cvt_pk_f16_f32 v5, v4, v5
	v_cvt_pk_f16_f32 v4, v2, v3
	v_cvt_pk_f16_f32 v3, v8, v9
	v_cvt_pk_f16_f32 v2, v6, v7
	global_store_dwordx4 v[198:199], v[2:5], off offset:256
	s_mov_b64 s[0:1], -1
	s_andn2_b64 vcc, exec, s[2:3]
	s_cbranch_vccnz .LBB0_3698
	s_andn2_b64 vcc, exec, s[8:9]
	s_cbranch_vccnz .LBB0_3697
	s_barrier
	s_branch .LBB0_3697
